# FFT stages that read their LDS inputs one pair at a time now rotate 4 register sets and read 3 groups ahead
# baseline (speedup 1.0000x reference)
.LBB0_236:
	s_add_u32 s4, s4, s0
	s_addc_u32 s5, s5, s1
	s_lshl_b64 s[4:5], s[4:5], 14
	s_add_u32 s6, s68, s4
	v_lshlrev_b32_e32 v0, 1, v146
	v_ashrrev_i32_e32 v1, 31, v0
	s_addc_u32 s7, s69, s5
	v_lshlrev_b64 v[68:69], 1, v[0:1]
	v_lshl_add_u64 v[50:51], s[6:7], 0, v[68:69]
	global_load_dword v1, v[50:51], off
	v_add_u32_e32 v8, 0x1000, v0
	s_add_u32 s8, s6, 0x1000000
	v_add_u32_e32 v2, 0x400, v0
	v_add_u32_e32 v4, 0x800, v0
	v_add_u32_e32 v6, 0xc00, v0
	v_ashrrev_i32_e32 v9, 31, v8
	v_add_u32_e32 v10, 0x1400, v0
	v_add_u32_e32 v12, 0x1800, v0
	v_add_u32_e32 v14, 0x1c00, v0
	s_addc_u32 s9, s7, 0
	v_ashrrev_i32_e32 v3, 31, v2
	v_ashrrev_i32_e32 v5, 31, v4
	v_ashrrev_i32_e32 v7, 31, v6
	v_lshlrev_b64 v[62:63], 1, v[8:9]
	v_ashrrev_i32_e32 v11, 31, v10
	v_ashrrev_i32_e32 v13, 31, v12
	v_ashrrev_i32_e32 v15, 31, v14
	v_lshl_add_u64 v[54:55], s[8:9], 0, v[68:69]
	v_lshlrev_b64 v[70:71], 1, v[2:3]
	v_lshlrev_b64 v[66:67], 1, v[4:5]
	v_lshlrev_b64 v[64:65], 1, v[6:7]
	v_lshl_add_u64 v[42:43], s[6:7], 0, v[62:63]
	v_lshlrev_b64 v[60:61], 1, v[10:11]
	v_lshlrev_b64 v[58:59], 1, v[12:13]
	v_lshlrev_b64 v[56:57], 1, v[14:15]
	v_lshl_add_u64 v[52:53], s[8:9], 0, v[70:71]
	v_lshl_add_u64 v[46:47], s[6:7], 0, v[66:67]
	v_lshl_add_u64 v[48:49], s[8:9], 0, v[66:67]
	v_lshl_add_u64 v[38:39], s[6:7], 0, v[64:65]
	v_lshl_add_u64 v[40:41], s[8:9], 0, v[64:65]
	global_load_dword v3, v[54:55], off
	global_load_dword v5, v[52:53], off
	global_load_dword v7, v[46:47], off
	global_load_dword v80, v[48:49], off
	global_load_dword v81, v[38:39], off
	global_load_dword v82, v[40:41], off
	global_load_dword v83, v[50:51], off offset:2048
	v_lshl_add_u64 v[44:45], s[8:9], 0, v[62:63]
	v_lshl_add_u64 v[34:35], s[6:7], 0, v[60:61]
	v_lshl_add_u64 v[36:37], s[8:9], 0, v[60:61]
	v_lshl_add_u64 v[30:31], s[6:7], 0, v[58:59]
	v_lshl_add_u64 v[32:33], s[8:9], 0, v[58:59]
	v_lshl_add_u64 v[26:27], s[6:7], 0, v[56:57]
	v_lshl_add_u64 v[28:29], s[8:9], 0, v[56:57]
	global_load_dword v9, v[42:43], off
	global_load_dword v11, v[44:45], off
	global_load_dword v13, v[34:35], off
	global_load_dword v15, v[36:37], off
	global_load_dword v104, v[30:31], off
	global_load_dword v105, v[32:33], off
	global_load_dword v106, v[26:27], off
	global_load_dword v107, v[28:29], off
	s_add_u32 s12, s6, 0x4000000
	s_addc_u32 s13, s7, 0
	s_add_u32 s4, s6, 0x8000000
	s_addc_u32 s5, s7, 0
	s_add_u32 s14, s6, 0x5000000
	s_addc_u32 s15, s7, 0
	v_lshl_add_u64 v[16:17], s[12:13], 0, v[68:69]
	v_lshl_add_u64 v[72:73], s[12:13], 0, v[66:67]
	v_lshl_add_u64 v[74:75], s[14:15], 0, v[66:67]
	v_lshl_add_u64 v[76:77], s[12:13], 0, v[64:65]
	v_lshl_add_u64 v[78:79], s[14:15], 0, v[64:65]
	v_lshl_add_u64 v[18:19], s[14:15], 0, v[68:69]
	v_lshl_add_u64 v[20:21], s[12:13], 0, v[70:71]
	v_lshl_add_u64 v[22:23], s[14:15], 0, v[70:71]
	global_load_dword v186, v[16:17], off
	global_load_dword v185, v[18:19], off
	global_load_dword v184, v[20:21], off
	global_load_dword v183, v[22:23], off
	global_load_dword v182, v[72:73], off
	global_load_dword v181, v[74:75], off
	global_load_dword v180, v[76:77], off
	global_load_dword v178, v[78:79], off
	v_lshl_add_u64 v[16:17], s[12:13], 0, v[62:63]
	v_lshl_add_u64 v[72:73], s[12:13], 0, v[58:59]
	v_lshl_add_u64 v[74:75], s[14:15], 0, v[58:59]
	v_lshl_add_u64 v[76:77], s[12:13], 0, v[56:57]
	v_lshl_add_u64 v[78:79], s[14:15], 0, v[56:57]
	v_lshl_add_u64 v[18:19], s[14:15], 0, v[62:63]
	v_lshl_add_u64 v[20:21], s[12:13], 0, v[60:61]
	v_lshl_add_u64 v[22:23], s[14:15], 0, v[60:61]
	global_load_dword v179, v[16:17], off
	global_load_dword v177, v[18:19], off
	global_load_dword v176, v[20:21], off
	global_load_dword v175, v[22:23], off
	global_load_dword v174, v[72:73], off
	global_load_dword v171, v[74:75], off
	global_load_dword v170, v[76:77], off
	global_load_dword v168, v[78:79], off
	s_add_u32 s6, s6, 0x9000000
	s_addc_u32 s7, s7, 0
	s_waitcnt vmcnt(31)
	v_lshlrev_b32_e32 v100, 16, v1
	v_and_b32_e32 v101, 0xffff0000, v1
	v_bfe_i32 v1, v146, 3, 28
	v_and_b32_e32 v1, 0x3ffffffc, v1
	v_add_lshl_u32 v1, v1, v0, 2
	v_add_u32_e32 v172, 0, v1
	v_add_u32_e32 v173, s91, v1
	v_ashrrev_i32_e32 v1, 4, v2
	v_and_b32_e32 v1, -4, v1
	v_add_u32_e32 v2, v1, v2
	v_add_u32_e32 v1, v1, v0
	v_lshl_add_u32 v160, v1, 2, 0
	v_ashrrev_i32_e32 v1, 4, v4
	v_and_b32_e32 v1, -4, v1
	v_lshl_add_u32 v169, v2, 2, s91
	v_add_u32_e32 v2, v1, v4
	v_add_u32_e32 v1, v1, v0
	v_lshl_add_u32 v158, v1, 2, 0
	v_ashrrev_i32_e32 v1, 4, v6
	v_and_b32_e32 v1, -4, v1
	v_lshl_add_u32 v159, v2, 2, s91
	v_add_u32_e32 v2, v1, v6
	v_add_u32_e32 v1, v1, v0
	v_lshl_add_u32 v156, v1, 2, 0
	v_ashrrev_i32_e32 v1, 4, v8
	v_and_b32_e32 v1, -4, v1
	v_lshl_add_u32 v157, v2, 2, s91
	v_add_u32_e32 v2, v1, v8
	v_add_u32_e32 v1, v1, v0
	v_lshl_add_u32 v154, v1, 2, 0
	v_ashrrev_i32_e32 v1, 4, v10
	v_and_b32_e32 v1, -4, v1
	v_lshl_add_u32 v155, v2, 2, s91
	v_add_u32_e32 v2, v1, v10
	v_add_u32_e32 v1, v1, v0
	v_lshl_add_u32 v152, v1, 2, 0
	v_ashrrev_i32_e32 v1, 4, v12
	v_and_b32_e32 v1, -4, v1
	v_lshl_add_u32 v153, v2, 2, s91
	v_add_u32_e32 v2, v1, v12
	v_add_u32_e32 v1, v1, v0
	v_lshl_add_u32 v150, v1, 2, 0
	v_ashrrev_i32_e32 v1, 4, v14
	v_and_b32_e32 v1, -4, v1
	v_lshl_add_u32 v151, v2, 2, s91
	v_add_u32_e32 v2, v1, v14
	v_add_u32_e32 v0, v1, v0
	s_waitcnt vmcnt(30)
	v_lshlrev_b32_e32 v102, 16, v3
	v_and_b32_e32 v103, 0xffff0000, v3
	s_waitcnt vmcnt(24)
	v_lshlrev_b32_e32 v96, 16, v83
	v_and_b32_e32 v97, 0xffff0000, v83
	v_lshlrev_b32_e32 v98, 16, v5
	v_and_b32_e32 v99, 0xffff0000, v5
	v_lshlrev_b32_e32 v92, 16, v7
	v_and_b32_e32 v93, 0xffff0000, v7
	v_lshlrev_b32_e32 v94, 16, v80
	v_and_b32_e32 v95, 0xffff0000, v80
	v_lshlrev_b32_e32 v88, 16, v81
	v_and_b32_e32 v89, 0xffff0000, v81
	v_lshlrev_b32_e32 v90, 16, v82
	v_and_b32_e32 v91, 0xffff0000, v82
	s_waitcnt vmcnt(23)
	v_lshlrev_b32_e32 v84, 16, v9
	v_and_b32_e32 v85, 0xffff0000, v9
	s_waitcnt vmcnt(22)
	v_lshlrev_b32_e32 v86, 16, v11
	v_and_b32_e32 v87, 0xffff0000, v11
	s_waitcnt vmcnt(21)
	v_lshlrev_b32_e32 v80, 16, v13
	v_and_b32_e32 v81, 0xffff0000, v13
	s_waitcnt vmcnt(20)
	v_lshlrev_b32_e32 v82, 16, v15
	v_and_b32_e32 v83, 0xffff0000, v15
	s_waitcnt vmcnt(19)
	v_lshlrev_b32_e32 v76, 16, v104
	v_and_b32_e32 v77, 0xffff0000, v104
	s_waitcnt vmcnt(18)
	v_lshlrev_b32_e32 v78, 16, v105
	v_and_b32_e32 v79, 0xffff0000, v105
	s_waitcnt vmcnt(17)
	v_lshlrev_b32_e32 v72, 16, v106
	v_and_b32_e32 v73, 0xffff0000, v106
	v_lshl_add_u32 v148, v0, 2, 0
	s_waitcnt vmcnt(16)
	v_lshlrev_b32_e32 v74, 16, v107
	v_and_b32_e32 v75, 0xffff0000, v107
	v_lshl_add_u32 v149, v2, 2, s91
	v_mov_b32_e32 v0, v163
	ds_write_b64 v172, v[100:101]
	ds_write_b64 v173, v[102:103]
	ds_write_b64 v160, v[96:97] offset:4096
	ds_write_b64 v169, v[98:99]
	ds_write_b64 v158, v[92:93] offset:8192
	ds_write_b64 v159, v[94:95]
	ds_write_b64 v156, v[88:89] offset:12288
	ds_write_b64 v157, v[90:91]
	ds_write_b64 v154, v[84:85] offset:16384
	ds_write_b64 v155, v[86:87]
	ds_write_b64 v152, v[80:81] offset:20480
	ds_write_b64 v153, v[82:83]
	ds_write_b64 v150, v[76:77] offset:24576
	ds_write_b64 v151, v[78:79]
	ds_write_b64 v148, v[72:73] offset:28672
	ds_write_b64 v149, v[74:75]
	s_waitcnt lgkmcnt(0)
	s_barrier
	s_nop 0
	s_nop 0
	v_ashrrev_i32_e32 v2, 31, v0
	v_lshlrev_b32_e32 v1, 1, v0
	v_lshrrev_b32_e32 v2, 23, v2
	v_and_b32_e32 v1, 0x3fe, v1
	v_add_lshl_u32 v0, v0, v2, 5
	v_and_or_b32 v0, v0, s85, v1
	v_cvt_f32_u32_e32 v3, v1
	v_or_b32_e32 v1, 1, v1
	v_ashrrev_i32_e32 v2, 4, v0
	v_cvt_f32_u32_e32 v1, v1
	v_and_b32_e32 v2, 0x3ffffc3c, v2
	v_add_lshl_u32 v136, v2, v0, 2
	v_add_u32_e32 v164, 0, v136
	v_mul_f32_e32 v3, 0x38800000, v3
	v_mul_f32_e32 v1, 0x38800000, v1
	v_add_u32_e32 v165, s91, v136
	ds_read_b64 v[136:137], v164
	ds_read_b64 v[138:139], v164 offset:4352
	ds_read_b64 v[140:141], v164 offset:8704
	ds_read_b64 v[142:143], v164 offset:13056
	ds_read_b64 v[144:145], v165
	ds_read_b64 v[188:189], v165 offset:4352
	ds_read_b64 v[190:191], v165 offset:8704
	ds_read_b64 v[192:193], v165 offset:13056
	ds_read_b64 v[194:195], v164 offset:17408
	ds_read_b64 v[196:197], v164 offset:21760
	ds_read_b64 v[198:199], v164 offset:26112
	ds_read_b64 v[200:201], v164 offset:30464
	ds_read_b64 v[202:203], v165 offset:17408
	ds_read_b64 v[204:205], v165 offset:21760
	ds_read_b64 v[206:207], v165 offset:26112
	ds_read_b64 v[208:209], v165 offset:30464
	v_sin_f32_e64 v14, -v3
	v_sin_f32_e64 v15, -v1
	s_waitcnt lgkmcnt(10)
	v_pk_mul_f32 v[218:219], v[188:189], s[80:81] op_sel_hi:[1,0]
	v_cos_f32_e32 v12, v3
	v_cos_f32_e32 v13, v1
	v_pk_add_f32 v[214:215], v[138:139], 0 op_sel_hi:[1,0]
	v_pk_fma_f32 v[218:219], v[138:139], s[72:73], v[218:219] op_sel_hi:[1,0,1]
	v_pk_mul_f32 v[138:139], v[138:139], s[80:81] op_sel_hi:[1,0]
	v_pk_add_f32 v[216:217], v[188:189], 0 op_sel_hi:[1,0]
	v_pk_fma_f32 v[138:139], v[188:189], s[72:73], v[138:139] op_sel_hi:[1,0,1] neg_lo:[0,0,1] neg_hi:[0,0,1]
	v_pk_add_f32 v[188:189], v[140:141], 0 op_sel_hi:[1,0]
	v_pk_mul_f32 v[140:141], v[140:141], s[82:83] op_sel_hi:[1,0]
	s_waitcnt lgkmcnt(8)
	v_pk_mul_f32 v[226:227], v[192:193], s[72:73] op_sel_hi:[1,0]
	v_pk_add_f32 v[220:221], v[190:191], 0 op_sel_hi:[1,0]
	v_pk_fma_f32 v[222:223], v[190:191], s[82:83], v[140:141] op_sel_hi:[1,0,1]
	v_pk_fma_f32 v[140:141], v[190:191], s[82:83], v[140:141] op_sel_hi:[1,0,1] neg_lo:[0,0,1] neg_hi:[0,0,1]
	v_pk_add_f32 v[190:191], v[142:143], 0 op_sel_hi:[1,0]
	v_pk_fma_f32 v[226:227], v[142:143], s[80:81], v[226:227] op_sel_hi:[1,0,1]
	v_pk_mul_f32 v[142:143], v[142:143], s[72:73] op_sel_hi:[1,0]
	s_waitcnt lgkmcnt(6)
	v_pk_mul_f32 v[234:235], v[196:197], s[80:81] op_sel_hi:[1,0]
	s_waitcnt lgkmcnt(4)
	v_pk_mul_f32 v[242:243], v[200:201], s[72:73] op_sel_hi:[1,0]
	v_pk_mul_f32 v[0:1], v[14:15], v[14:15]
	v_pk_add_f32 v[210:211], v[136:137], 0 op_sel_hi:[1,0]
	v_pk_add_f32 v[212:213], v[144:145], 0 op_sel_hi:[1,0]
	v_pk_add_f32 v[224:225], v[192:193], 0 op_sel_hi:[1,0]
	v_pk_fma_f32 v[142:143], v[192:193], s[80:81], v[142:143] op_sel_hi:[1,0,1] neg_lo:[0,0,1] neg_hi:[0,0,1]
	v_pk_add_f32 v[192:193], v[194:195], 0 op_sel_hi:[1,0]
	s_waitcnt lgkmcnt(3)
	v_pk_add_f32 v[228:229], v[202:203], 0 op_sel_hi:[1,0]
	v_pk_add_f32 v[230:231], v[196:197], 0 op_sel_hi:[1,0]
	s_waitcnt lgkmcnt(2)
	v_pk_add_f32 v[232:233], v[204:205], 0 op_sel_hi:[1,0]
	v_pk_fma_f32 v[234:235], v[204:205], s[72:73], v[234:235] op_sel_hi:[1,0,1] neg_lo:[0,0,1] neg_hi:[0,0,1]
	v_pk_mul_f32 v[204:205], v[204:205], s[80:81] op_sel_hi:[1,0]
	s_waitcnt lgkmcnt(1)
	v_pk_add_f32 v[236:237], v[206:207], 0 op_sel_hi:[1,0]
	v_pk_mul_f32 v[206:207], v[206:207], s[54:55] op_sel_hi:[1,0]
	s_waitcnt lgkmcnt(0)
	v_pk_add_f32 v[240:241], v[208:209], 0 op_sel_hi:[1,0]
	v_pk_fma_f32 v[242:243], v[208:209], s[80:81], v[242:243] op_sel_hi:[1,0,1] neg_lo:[0,0,1] neg_hi:[0,0,1]
	v_pk_mul_f32 v[208:209], v[208:209], s[72:73] op_sel_hi:[1,0]
	v_pk_fma_f32 v[106:107], v[12:13], v[12:13], v[0:1] neg_lo:[0,0,1] neg_hi:[0,0,1]
	v_pk_mul_f32 v[0:1], v[12:13], v[14:15]
	v_pk_fma_f32 v[196:197], v[196:197], s[52:53], v[204:205] op_sel_hi:[1,0,1] neg_lo:[0,0,1] neg_hi:[0,0,1]
	v_pk_add_f32 v[204:205], v[198:199], 0 op_sel_hi:[1,0]
	v_pk_fma_f32 v[238:239], v[198:199], s[54:55], v[206:207] op_sel_hi:[1,0,1] neg_lo:[0,0,1] neg_hi:[0,0,1]
	v_pk_fma_f32 v[198:199], v[198:199], s[54:55], v[206:207] op_sel_hi:[1,0,1]
	v_pk_add_f32 v[206:207], v[200:201], 0 op_sel_hi:[1,0]
	v_pk_fma_f32 v[200:201], v[200:201], s[84:85], v[208:209] op_sel_hi:[1,0,1] neg_lo:[0,0,1] neg_hi:[0,0,1]
	v_pk_add_f32 v[208:209], v[210:211], v[192:193]
	v_pk_add_f32 v[244:245], v[212:213], v[228:229]
	v_pk_add_f32 v[192:193], v[210:211], v[192:193] neg_lo:[0,1] neg_hi:[0,1]
	v_pk_add_f32 v[210:211], v[212:213], v[228:229] neg_lo:[0,1] neg_hi:[0,1]
	v_pk_add_f32 v[212:213], v[214:215], v[230:231]
	v_pk_add_f32 v[214:215], v[214:215], v[230:231] neg_lo:[0,1] neg_hi:[0,1]
	v_pk_add_f32 v[108:109], v[0:1], v[0:1]
	v_pk_add_f32 v[228:229], v[216:217], v[232:233]
	v_pk_add_f32 v[216:217], v[216:217], v[232:233] neg_lo:[0,1] neg_hi:[0,1]
	v_pk_mul_f32 v[214:215], v[214:215], s[82:83] op_sel_hi:[1,0]
	v_pk_mul_f32 v[0:1], v[14:15], v[108:109]
	v_pk_fma_f32 v[230:231], v[216:217], s[82:83], v[214:215] op_sel_hi:[1,0,1]
	v_pk_fma_f32 v[214:215], v[216:217], s[82:83], v[214:215] op_sel_hi:[1,0,1] neg_lo:[0,0,1] neg_hi:[0,0,1]
	v_pk_add_f32 v[216:217], v[188:189], v[204:205]
	v_pk_add_f32 v[232:233], v[220:221], v[236:237]
	v_pk_add_f32 v[188:189], v[188:189], v[204:205] neg_lo:[0,1] neg_hi:[0,1]
	v_pk_add_f32 v[204:205], v[220:221], v[236:237] neg_lo:[0,1] neg_hi:[0,1]
	v_pk_add_f32 v[220:221], v[190:191], v[206:207]
	v_pk_add_f32 v[190:191], v[190:191], v[206:207] neg_lo:[0,1] neg_hi:[0,1]
	v_pk_add_f32 v[206:207], v[224:225], v[240:241] neg_lo:[0,1] neg_hi:[0,1]
	v_pk_fma_f32 v[4:5], v[12:13], v[106:107], v[0:1] neg_lo:[0,0,1] neg_hi:[0,0,1]
	v_pk_mul_f32 v[0:1], v[14:15], v[106:107]
	v_pk_add_f32 v[236:237], v[224:225], v[240:241]
	v_pk_mul_f32 v[206:207], v[206:207], s[54:55] op_sel_hi:[1,0]
	v_pk_add_f32 v[240:241], v[144:145], v[194:195] neg_lo:[0,1] neg_hi:[0,1]
	v_pk_add_f32 v[144:145], v[144:145], v[194:195]
	v_pk_add_f32 v[194:195], v[218:219], v[234:235]
	v_pk_add_f32 v[218:219], v[218:219], v[234:235] neg_lo:[0,1] neg_hi:[0,1]
	v_pk_fma_f32 v[10:11], v[12:13], v[108:109], v[0:1]
	v_pk_mul_f32 v[0:1], v[108:109], v[108:109]
	v_pk_fma_f32 v[224:225], v[190:191], s[54:55], v[206:207] op_sel_hi:[1,0,1] neg_lo:[0,0,1] neg_hi:[0,0,1]
	v_pk_fma_f32 v[190:191], v[190:191], s[54:55], v[206:207] op_sel_hi:[1,0,1]
	v_pk_add_f32 v[206:207], v[136:137], v[202:203]
	v_pk_add_f32 v[136:137], v[136:137], v[202:203] neg_lo:[0,1] neg_hi:[0,1]
	v_pk_add_f32 v[202:203], v[138:139], v[196:197]
	v_pk_add_f32 v[138:139], v[138:139], v[196:197] neg_lo:[0,1] neg_hi:[0,1]
	v_pk_mul_f32 v[196:197], v[218:219], s[82:83] op_sel_hi:[1,0]
	v_pk_fma_f32 v[110:111], v[106:107], v[106:107], v[0:1] neg_lo:[0,0,1] neg_hi:[0,0,1]
	v_pk_mul_f32 v[0:1], v[106:107], v[108:109]
	v_pk_fma_f32 v[218:219], v[138:139], s[82:83], v[196:197] op_sel_hi:[1,0,1]
	v_pk_fma_f32 v[138:139], v[138:139], s[82:83], v[196:197] op_sel_hi:[1,0,1] neg_lo:[0,0,1] neg_hi:[0,0,1]
	v_pk_add_f32 v[196:197], v[222:223], v[238:239]
	v_pk_add_f32 v[222:223], v[222:223], v[238:239] neg_lo:[0,1] neg_hi:[0,1]
	v_pk_add_f32 v[238:239], v[142:143], v[200:201]
	v_pk_add_f32 v[142:143], v[142:143], v[200:201] neg_lo:[0,1] neg_hi:[0,1]
	v_pk_add_f32 v[112:113], v[0:1], v[0:1]
	v_pk_add_f32 v[234:235], v[140:141], v[198:199]
	v_pk_add_f32 v[140:141], v[140:141], v[198:199] neg_lo:[0,1] neg_hi:[0,1]
	v_pk_add_f32 v[198:199], v[226:227], v[242:243]
	v_pk_add_f32 v[226:227], v[226:227], v[242:243] neg_lo:[0,1] neg_hi:[0,1]
	v_pk_mul_f32 v[142:143], v[142:143], s[54:55] op_sel_hi:[1,0]
	v_pk_mul_f32 v[0:1], v[14:15], v[112:113]
	v_pk_mul_f32 v[6:7], v[112:113], v[112:113]
	v_pk_mul_f32 v[8:9], v[110:111], v[112:113]
	v_pk_fma_f32 v[200:201], v[226:227], s[54:55], v[142:143] op_sel_hi:[1,0,1] neg_lo:[0,0,1] neg_hi:[0,0,1]
	v_pk_fma_f32 v[142:143], v[226:227], s[54:55], v[142:143] op_sel_hi:[1,0,1]
	v_pk_add_f32 v[226:227], v[208:209], v[216:217]
	v_pk_add_f32 v[242:243], v[244:245], v[232:233]
	v_pk_add_f32 v[208:209], v[208:209], v[216:217] neg_lo:[0,1] neg_hi:[0,1]
	v_pk_add_f32 v[216:217], v[244:245], v[232:233] neg_lo:[0,1] neg_hi:[0,1]
	v_pk_add_f32 v[232:233], v[212:213], v[220:221]
	v_pk_add_f32 v[244:245], v[228:229], v[236:237]
	v_pk_fma_f32 v[16:17], v[12:13], v[110:111], v[0:1] neg_lo:[0,0,1] neg_hi:[0,0,1]
	v_pk_mul_f32 v[0:1], v[14:15], v[110:111]
	v_pk_fma_f32 v[6:7], v[110:111], v[110:111], v[6:7] neg_lo:[0,0,1] neg_hi:[0,0,1]
	v_pk_add_f32 v[8:9], v[8:9], v[8:9]
	v_pk_add_f32 v[212:213], v[212:213], v[220:221] neg_lo:[0,1] neg_hi:[0,1]
	v_pk_add_f32 v[220:221], v[228:229], v[236:237] neg_lo:[0,1] neg_hi:[0,1]
	v_pk_add_f32 v[228:229], v[192:193], v[204:205]
	v_pk_add_f32 v[236:237], v[210:211], v[188:189] neg_lo:[0,1] neg_hi:[0,1]
	v_pk_add_f32 v[192:193], v[192:193], v[204:205] neg_lo:[0,1] neg_hi:[0,1]
	v_pk_add_f32 v[188:189], v[210:211], v[188:189]
	v_pk_add_f32 v[204:205], v[230:231], v[224:225]
	v_pk_add_f32 v[210:211], v[214:215], v[190:191]
	v_pk_add_f32 v[224:225], v[230:231], v[224:225] neg_lo:[0,1] neg_hi:[0,1]
	v_pk_add_f32 v[190:191], v[214:215], v[190:191] neg_lo:[0,1] neg_hi:[0,1]
	v_pk_add_f32 v[214:215], v[206:207], v[196:197]
	v_pk_add_f32 v[230:231], v[240:241], v[234:235]
	v_pk_add_f32 v[196:197], v[206:207], v[196:197] neg_lo:[0,1] neg_hi:[0,1]
	v_pk_add_f32 v[206:207], v[240:241], v[234:235] neg_lo:[0,1] neg_hi:[0,1]
	v_pk_add_f32 v[234:235], v[194:195], v[198:199]
	v_pk_add_f32 v[240:241], v[202:203], v[238:239]
	v_pk_add_f32 v[194:195], v[194:195], v[198:199] neg_lo:[0,1] neg_hi:[0,1]
	v_pk_add_f32 v[198:199], v[202:203], v[238:239] neg_lo:[0,1] neg_hi:[0,1]
	v_pk_add_f32 v[202:203], v[136:137], v[140:141]
	v_pk_add_f32 v[238:239], v[144:145], v[222:223] neg_lo:[0,1] neg_hi:[0,1]
	v_pk_add_f32 v[136:137], v[136:137], v[140:141] neg_lo:[0,1] neg_hi:[0,1]
	v_pk_add_f32 v[140:141], v[144:145], v[222:223]
	v_pk_add_f32 v[144:145], v[218:219], v[200:201]
	v_pk_add_f32 v[222:223], v[138:139], v[142:143]
	v_pk_add_f32 v[200:201], v[218:219], v[200:201] neg_lo:[0,1] neg_hi:[0,1]
	v_pk_add_f32 v[138:139], v[138:139], v[142:143] neg_lo:[0,1] neg_hi:[0,1]
	v_pk_add_f32 v[142:143], v[226:227], v[232:233]
	v_pk_add_f32 v[218:219], v[242:243], v[244:245]
	v_pk_add_f32 v[226:227], v[226:227], v[232:233] neg_lo:[0,1] neg_hi:[0,1]
	v_pk_add_f32 v[232:233], v[242:243], v[244:245] neg_lo:[0,1] neg_hi:[0,1]
	v_pk_fma_f32 v[18:19], v[12:13], v[112:113], v[0:1]
	v_pk_mul_f32 v[0:1], v[108:109], v[112:113]
	ds_write_b64 v164, v[142:143]
	ds_write_b64 v165, v[218:219]
	v_pk_mul_f32 v[142:143], v[6:7], v[232:233]
	v_pk_mul_f32 v[218:219], v[8:9], v[232:233]
	v_pk_fma_f32 v[114:115], v[106:107], v[110:111], v[0:1] neg_lo:[0,0,1] neg_hi:[0,0,1]
	v_pk_mul_f32 v[0:1], v[108:109], v[110:111]
	v_pk_mul_f32 v[2:3], v[110:111], v[10:11]
	v_pk_add_f32 v[242:243], v[208:209], v[220:221]
	v_pk_add_f32 v[244:245], v[216:217], v[212:213] neg_lo:[0,1] neg_hi:[0,1]
	v_pk_fma_f32 v[142:143], v[8:9], v[226:227], v[142:143]
	v_pk_fma_f32 v[218:219], v[6:7], v[226:227], v[218:219] neg_lo:[0,0,1] neg_hi:[0,0,1]
	v_pk_fma_f32 v[116:117], v[106:107], v[112:113], v[0:1]
	v_pk_mul_f32 v[0:1], v[112:113], v[10:11]
	v_pk_fma_f32 v[2:3], v[112:113], v[4:5], v[2:3]
	v_pk_mul_f32 v[124:125], v[112:113], v[8:9]
	v_pk_mul_f32 v[126:127], v[112:113], v[6:7]
	ds_write_b64 v164, v[218:219] offset:34816
	ds_write_b64 v165, v[142:143] offset:34816
	v_pk_mul_f32 v[142:143], v[112:113], v[242:243]
	v_pk_mul_f32 v[112:113], v[112:113], v[244:245]
	v_pk_fma_f32 v[0:1], v[110:111], v[4:5], v[0:1] neg_lo:[0,0,1] neg_hi:[0,0,1]
	v_pk_mul_f32 v[20:21], v[14:15], v[8:9]
	v_pk_fma_f32 v[124:125], v[110:111], v[6:7], v[124:125] neg_lo:[0,0,1] neg_hi:[0,0,1]
	v_pk_fma_f32 v[126:127], v[110:111], v[8:9], v[126:127]
	v_pk_add_f32 v[208:209], v[208:209], v[220:221] neg_lo:[0,1] neg_hi:[0,1]
	v_pk_add_f32 v[212:213], v[216:217], v[212:213]
	v_pk_fma_f32 v[142:143], v[110:111], v[244:245], v[142:143]
	v_pk_fma_f32 v[110:111], v[110:111], v[242:243], v[112:113] neg_lo:[0,0,1] neg_hi:[0,0,1]
	v_pk_fma_f32 v[104:105], v[12:13], v[6:7], v[20:21] neg_lo:[0,0,1] neg_hi:[0,0,1]
	v_pk_mul_f32 v[20:21], v[14:15], v[6:7]
	ds_write_b64 v164, v[110:111] offset:17408
	ds_write_b64 v165, v[142:143] offset:17408
	v_pk_mul_f32 v[110:111], v[126:127], v[208:209]
	v_pk_mul_f32 v[112:113], v[126:127], v[212:213]
	v_pk_fma_f32 v[118:119], v[12:13], v[8:9], v[20:21]
	v_pk_mul_f32 v[20:21], v[108:109], v[8:9]
	v_pk_add_f32 v[216:217], v[228:229], v[204:205]
	v_pk_add_f32 v[220:221], v[236:237], v[210:211]
	v_pk_fma_f32 v[110:111], v[124:125], v[212:213], v[110:111]
	v_pk_fma_f32 v[112:113], v[124:125], v[208:209], v[112:113] neg_lo:[0,0,1] neg_hi:[0,0,1]
	v_pk_fma_f32 v[120:121], v[106:107], v[6:7], v[20:21] neg_lo:[0,0,1] neg_hi:[0,0,1]
	v_pk_mul_f32 v[20:21], v[108:109], v[6:7]
	ds_write_b64 v164, v[112:113] offset:52224
	ds_write_b64 v165, v[110:111] offset:52224
	v_pk_mul_f32 v[110:111], v[108:109], v[216:217]
	v_pk_mul_f32 v[108:109], v[108:109], v[220:221]
	v_pk_fma_f32 v[122:123], v[106:107], v[8:9], v[20:21]
	v_pk_add_f32 v[204:205], v[228:229], v[204:205] neg_lo:[0,1] neg_hi:[0,1]
	v_pk_add_f32 v[210:211], v[236:237], v[210:211] neg_lo:[0,1] neg_hi:[0,1]
	v_pk_fma_f32 v[110:111], v[106:107], v[220:221], v[110:111]
	v_pk_fma_f32 v[106:107], v[106:107], v[216:217], v[108:109] neg_lo:[0,0,1] neg_hi:[0,0,1]
	ds_write_b64 v164, v[106:107] offset:8704
	ds_write_b64 v165, v[110:111] offset:8704
	v_pk_mul_f32 v[106:107], v[122:123], v[204:205]
	v_pk_mul_f32 v[108:109], v[122:123], v[210:211]
	v_pk_add_f32 v[228:229], v[192:193], v[190:191]
	v_pk_add_f32 v[236:237], v[188:189], v[224:225] neg_lo:[0,1] neg_hi:[0,1]
	v_pk_fma_f32 v[106:107], v[120:121], v[210:211], v[106:107]
	v_pk_fma_f32 v[108:109], v[120:121], v[204:205], v[108:109] neg_lo:[0,0,1] neg_hi:[0,0,1]
	v_pk_mul_f32 v[134:135], v[6:7], v[116:117]
	ds_write_b64 v164, v[108:109] offset:43520
	ds_write_b64 v165, v[106:107] offset:43520
	v_pk_mul_f32 v[106:107], v[116:117], v[228:229]
	v_pk_mul_f32 v[108:109], v[116:117], v[236:237]
	v_pk_mul_f32 v[132:133], v[8:9], v[116:117]
	v_pk_fma_f32 v[134:135], v[8:9], v[114:115], v[134:135]
	v_pk_add_f32 v[190:191], v[192:193], v[190:191] neg_lo:[0,1] neg_hi:[0,1]
	v_pk_add_f32 v[188:189], v[188:189], v[224:225]
	v_pk_fma_f32 v[106:107], v[114:115], v[236:237], v[106:107]
	v_pk_fma_f32 v[108:109], v[114:115], v[228:229], v[108:109] neg_lo:[0,0,1] neg_hi:[0,0,1]
	v_pk_fma_f32 v[132:133], v[6:7], v[114:115], v[132:133] neg_lo:[0,0,1] neg_hi:[0,0,1]
	ds_write_b64 v164, v[108:109] offset:26112
	ds_write_b64 v165, v[106:107] offset:26112
	v_pk_mul_f32 v[106:107], v[134:135], v[190:191]
	v_pk_mul_f32 v[108:109], v[134:135], v[188:189]
	v_pk_add_f32 v[192:193], v[214:215], v[234:235]
	v_pk_add_f32 v[224:225], v[230:231], v[240:241]
	v_pk_fma_f32 v[106:107], v[132:133], v[188:189], v[106:107]
	v_pk_fma_f32 v[108:109], v[132:133], v[190:191], v[108:109] neg_lo:[0,0,1] neg_hi:[0,0,1]
	ds_write_b64 v164, v[108:109] offset:60928
	ds_write_b64 v165, v[106:107] offset:60928
	v_pk_mul_f32 v[106:107], v[14:15], v[192:193]
	v_pk_mul_f32 v[14:15], v[14:15], v[224:225]
	v_pk_add_f32 v[214:215], v[214:215], v[234:235] neg_lo:[0,1] neg_hi:[0,1]
	v_pk_add_f32 v[230:231], v[230:231], v[240:241] neg_lo:[0,1] neg_hi:[0,1]
	v_pk_fma_f32 v[106:107], v[12:13], v[224:225], v[106:107]
	v_pk_fma_f32 v[12:13], v[12:13], v[192:193], v[14:15] neg_lo:[0,0,1] neg_hi:[0,0,1]
	ds_write_b64 v164, v[12:13] offset:4352
	ds_write_b64 v165, v[106:107] offset:4352
	v_pk_mul_f32 v[12:13], v[118:119], v[214:215]
	v_pk_mul_f32 v[14:15], v[118:119], v[230:231]
	v_pk_add_f32 v[234:235], v[196:197], v[198:199]
	v_pk_add_f32 v[240:241], v[206:207], v[194:195] neg_lo:[0,1] neg_hi:[0,1]
	v_pk_fma_f32 v[12:13], v[104:105], v[230:231], v[12:13]
	v_pk_fma_f32 v[14:15], v[104:105], v[214:215], v[14:15] neg_lo:[0,0,1] neg_hi:[0,0,1]
	v_pk_mul_f32 v[130:131], v[6:7], v[18:19]
	ds_write_b64 v164, v[14:15] offset:39168
	ds_write_b64 v165, v[12:13] offset:39168
	v_pk_mul_f32 v[12:13], v[18:19], v[234:235]
	v_pk_mul_f32 v[14:15], v[18:19], v[240:241]
	v_pk_mul_f32 v[128:129], v[8:9], v[18:19]
	v_pk_fma_f32 v[130:131], v[8:9], v[16:17], v[130:131]
	v_pk_add_f32 v[196:197], v[196:197], v[198:199] neg_lo:[0,1] neg_hi:[0,1]
	v_pk_add_f32 v[194:195], v[206:207], v[194:195]
	v_pk_fma_f32 v[12:13], v[16:17], v[240:241], v[12:13]
	v_pk_fma_f32 v[14:15], v[16:17], v[234:235], v[14:15] neg_lo:[0,0,1] neg_hi:[0,0,1]
	v_pk_fma_f32 v[128:129], v[6:7], v[16:17], v[128:129] neg_lo:[0,0,1] neg_hi:[0,0,1]
	ds_write_b64 v164, v[14:15] offset:21760
	ds_write_b64 v165, v[12:13] offset:21760
	v_pk_mul_f32 v[12:13], v[130:131], v[196:197]
	v_pk_mul_f32 v[14:15], v[130:131], v[194:195]
	v_pk_mul_f32 v[22:23], v[10:11], v[6:7]
	v_pk_add_f32 v[198:199], v[202:203], v[144:145]
	v_pk_add_f32 v[206:207], v[238:239], v[222:223]
	v_pk_fma_f32 v[12:13], v[128:129], v[194:195], v[12:13]
	v_pk_fma_f32 v[14:15], v[128:129], v[196:197], v[14:15] neg_lo:[0,0,1] neg_hi:[0,0,1]
	v_pk_mul_f32 v[20:21], v[10:11], v[8:9]
	v_pk_fma_f32 v[22:23], v[4:5], v[8:9], v[22:23]
	v_pk_add_f32 v[144:145], v[202:203], v[144:145] neg_lo:[0,1] neg_hi:[0,1]
	v_pk_add_f32 v[202:203], v[238:239], v[222:223] neg_lo:[0,1] neg_hi:[0,1]
	ds_write_b64 v164, v[14:15] offset:56576
	ds_write_b64 v165, v[12:13] offset:56576
	v_pk_mul_f32 v[12:13], v[10:11], v[198:199]
	v_pk_mul_f32 v[10:11], v[10:11], v[206:207]
	v_pk_fma_f32 v[20:21], v[4:5], v[6:7], v[20:21] neg_lo:[0,0,1] neg_hi:[0,0,1]
	v_pk_fma_f32 v[12:13], v[4:5], v[206:207], v[12:13]
	v_pk_fma_f32 v[4:5], v[4:5], v[198:199], v[10:11] neg_lo:[0,0,1] neg_hi:[0,0,1]
	v_pk_mul_f32 v[10:11], v[22:23], v[202:203]
	v_pk_add_f32 v[238:239], v[140:141], v[200:201] neg_lo:[0,1] neg_hi:[0,1]
	ds_write_b64 v164, v[4:5] offset:13056
	ds_write_b64 v165, v[12:13] offset:13056
	v_pk_mul_f32 v[4:5], v[22:23], v[144:145]
	v_pk_fma_f32 v[10:11], v[20:21], v[144:145], v[10:11] neg_lo:[0,0,1] neg_hi:[0,0,1]
	v_pk_add_f32 v[222:223], v[136:137], v[138:139]
	v_pk_fma_f32 v[4:5], v[20:21], v[202:203], v[4:5]
	ds_write_b64 v164, v[10:11] offset:47872
	ds_write_b64 v165, v[4:5] offset:47872
	v_pk_mul_f32 v[10:11], v[2:3], v[238:239]
	v_pk_mul_f32 v[4:5], v[2:3], v[222:223]
	v_pk_fma_f32 v[10:11], v[0:1], v[222:223], v[10:11] neg_lo:[0,0,1] neg_hi:[0,0,1]
	v_pk_fma_f32 v[4:5], v[0:1], v[238:239], v[4:5]
	ds_write_b64 v164, v[10:11] offset:30464
	ds_write_b64 v165, v[4:5] offset:30464
	v_pk_mul_f32 v[10:11], v[8:9], v[2:3]
	v_pk_mul_f32 v[2:3], v[6:7], v[2:3]
	v_pk_add_f32 v[4:5], v[140:141], v[200:201]
	v_pk_fma_f32 v[10:11], v[6:7], v[0:1], v[10:11] neg_lo:[0,0,1] neg_hi:[0,0,1]
	v_pk_add_f32 v[12:13], v[136:137], v[138:139] neg_lo:[0,1] neg_hi:[0,1]
	v_pk_fma_f32 v[0:1], v[8:9], v[0:1], v[2:3]
	s_nop 0
	v_pk_mul_f32 v[2:3], v[0:1], v[12:13]
	v_pk_mul_f32 v[0:1], v[0:1], v[4:5]
	v_pk_fma_f32 v[2:3], v[10:11], v[4:5], v[2:3]
	v_pk_fma_f32 v[0:1], v[10:11], v[12:13], v[0:1] neg_lo:[0,0,1] neg_hi:[0,0,1]
	ds_write_b64 v164, v[0:1] offset:65280
	ds_write_b64 v165, v[2:3] offset:65280
	v_mov_b32_e32 v0, v163
	s_waitcnt lgkmcnt(0)
	s_barrier
	s_nop 0
	s_nop 0
	v_ashrrev_i32_e32 v2, 31, v0
	v_lshrrev_b32_e32 v2, 27, v2
	v_lshlrev_b32_e32 v1, 1, v0
	v_add_u32_e32 v0, v0, v2
	v_and_b32_e32 v1, 62, v1
	v_ashrrev_i32_e32 v0, 5, v0
	v_lshl_or_b32 v2, v0, 10, v1
	v_cvt_f32_ubyte0_e32 v3, v1
	v_or_b32_e32 v1, 1, v1
	v_cvt_f32_ubyte0_e32 v1, v1
	v_mul_f32_e32 v3, 0x3a800000, v3
	v_mul_f32_e32 v1, 0x3a800000, v1
	v_sin_f32_e64 v14, -v3
	v_sin_f32_e64 v15, -v1
	v_cos_f32_e32 v12, v3
	v_cos_f32_e32 v13, v1
	v_lshlrev_b32_e32 v0, 6, v0
	v_add_lshl_u32 v118, v2, v0, 2
	v_pk_mul_f32 v[0:1], v[14:15], v[14:15]
	v_add_u32_e32 v164, 0, v118
	v_pk_fma_f32 v[104:105], v[12:13], v[12:13], v[0:1] neg_lo:[0,0,1] neg_hi:[0,0,1]
	v_pk_mul_f32 v[0:1], v[12:13], v[14:15]
	v_add_u32_e32 v166, 0x800, v164
	v_pk_add_f32 v[106:107], v[0:1], v[0:1]
	v_add_u32_e32 v165, s91, v118
	v_pk_mul_f32 v[0:1], v[14:15], v[106:107]
	v_add_u32_e32 v167, 0x800, v165
	v_pk_fma_f32 v[4:5], v[12:13], v[104:105], v[0:1] neg_lo:[0,0,1] neg_hi:[0,0,1]
	v_pk_mul_f32 v[0:1], v[14:15], v[104:105]
	s_nop 0
	v_pk_fma_f32 v[10:11], v[12:13], v[106:107], v[0:1]
	v_pk_mul_f32 v[0:1], v[106:107], v[106:107]
	s_nop 0
	v_pk_fma_f32 v[144:145], v[104:105], v[104:105], v[0:1] neg_lo:[0,0,1] neg_hi:[0,0,1]
	v_pk_mul_f32 v[0:1], v[104:105], v[106:107]
	v_pk_mul_f32 v[2:3], v[144:145], v[10:11]
	v_pk_add_f32 v[224:225], v[0:1], v[0:1]
	s_nop 0
	v_pk_mul_f32 v[0:1], v[14:15], v[224:225]
	v_pk_mul_f32 v[6:7], v[224:225], v[224:225]
	v_pk_fma_f32 v[16:17], v[12:13], v[144:145], v[0:1] neg_lo:[0,0,1] neg_hi:[0,0,1]
	v_pk_mul_f32 v[0:1], v[14:15], v[144:145]
	v_pk_fma_f32 v[6:7], v[144:145], v[144:145], v[6:7] neg_lo:[0,0,1] neg_hi:[0,0,1]
	v_pk_fma_f32 v[18:19], v[12:13], v[224:225], v[0:1]
	v_pk_mul_f32 v[0:1], v[106:107], v[224:225]
	v_pk_mul_f32 v[8:9], v[144:145], v[224:225]
	v_pk_fma_f32 v[110:111], v[104:105], v[144:145], v[0:1] neg_lo:[0,0,1] neg_hi:[0,0,1]
	v_pk_mul_f32 v[0:1], v[106:107], v[144:145]
	v_pk_add_f32 v[8:9], v[8:9], v[8:9]
	v_pk_fma_f32 v[226:227], v[104:105], v[224:225], v[0:1]
	v_pk_mul_f32 v[116:117], v[6:7], v[18:19]
	v_pk_mul_f32 v[114:115], v[224:225], v[8:9]
	v_pk_fma_f32 v[236:237], v[8:9], v[16:17], v[116:117]
	v_pk_mul_f32 v[116:117], v[8:9], v[226:227]
	v_pk_mul_f32 v[20:21], v[14:15], v[8:9]
	v_pk_fma_f32 v[238:239], v[6:7], v[110:111], v[116:117] neg_lo:[0,0,1] neg_hi:[0,0,1]
	v_pk_mul_f32 v[116:117], v[6:7], v[226:227]
	v_pk_fma_f32 v[232:233], v[144:145], v[6:7], v[114:115] neg_lo:[0,0,1] neg_hi:[0,0,1]
	v_pk_fma_f32 v[240:241], v[8:9], v[110:111], v[116:117]
	ds_read2_b64 v[116:119], v164 offset1:34
	ds_read2_b64 v[120:123], v165 offset1:34
	ds_read2_b64 v[124:127], v164 offset0:68 offset1:102
	ds_read2_b64 v[128:131], v165 offset0:68 offset1:102
	ds_read2_b64 v[132:135], v164 offset0:136 offset1:170
	ds_read2_b64 v[136:139], v165 offset0:136 offset1:170
	ds_read2_b64 v[140:143], v164 offset0:204 offset1:238
	ds_read2_b64 v[188:191], v165 offset0:204 offset1:238
	ds_read2_b64 v[192:195], v166 offset0:16 offset1:50
	ds_read2_b64 v[196:199], v167 offset0:16 offset1:50
	ds_read2_b64 v[200:203], v166 offset0:84 offset1:118
	ds_read2_b64 v[204:207], v167 offset0:84 offset1:118
	ds_read2_b64 v[208:211], v166 offset0:152 offset1:186
	ds_read2_b64 v[212:215], v167 offset0:152 offset1:186
	ds_read2_b64 v[216:219], v166 offset0:220 offset1:254
	ds_read2_b64 v[220:223], v167 offset0:220 offset1:254
	s_waitcnt lgkmcnt(6)
	v_pk_add_f32 v[244:245], v[120:121], v[196:197]
	v_pk_add_f32 v[120:121], v[120:121], v[196:197] neg_lo:[0,1] neg_hi:[0,1]
	v_pk_mul_f32 v[114:115], v[224:225], v[6:7]
	v_pk_add_f32 v[242:243], v[116:117], v[192:193]
	v_pk_add_f32 v[116:117], v[116:117], v[192:193] neg_lo:[0,1] neg_hi:[0,1]
	v_pk_add_f32 v[192:193], v[118:119], v[194:195]
	v_pk_add_f32 v[118:119], v[118:119], v[194:195] neg_lo:[0,1] neg_hi:[0,1]
	v_pk_add_f32 v[194:195], v[122:123], v[198:199]
	v_pk_add_f32 v[122:123], v[122:123], v[198:199] neg_lo:[0,1] neg_hi:[0,1]
	s_waitcnt lgkmcnt(4)
	v_pk_add_f32 v[198:199], v[128:129], v[204:205]
	v_pk_mul_f32 v[196:197], v[122:123], s[80:81] op_sel_hi:[1,0]
	v_pk_add_f32 v[128:129], v[128:129], v[204:205] neg_lo:[0,1] neg_hi:[0,1]
	v_pk_fma_f32 v[196:197], v[118:119], s[72:73], v[196:197] op_sel_hi:[1,0,1]
	v_pk_mul_f32 v[118:119], v[118:119], s[80:81] op_sel_hi:[1,0]
	v_pk_mul_f32 v[0:1], v[224:225], v[10:11]
	v_pk_fma_f32 v[118:119], v[122:123], s[72:73], v[118:119] op_sel_hi:[1,0,1] neg_lo:[0,0,1] neg_hi:[0,0,1]
	v_pk_add_f32 v[122:123], v[124:125], v[200:201]
	v_pk_add_f32 v[124:125], v[124:125], v[200:201] neg_lo:[0,1] neg_hi:[0,1]
	v_pk_add_f32 v[200:201], v[126:127], v[202:203]
	v_pk_mul_f32 v[124:125], v[124:125], s[82:83] op_sel_hi:[1,0]
	v_pk_add_f32 v[126:127], v[126:127], v[202:203] neg_lo:[0,1] neg_hi:[0,1]
	v_pk_fma_f32 v[202:203], v[128:129], s[82:83], v[124:125] op_sel_hi:[1,0,1]
	v_pk_fma_f32 v[124:125], v[128:129], s[82:83], v[124:125] op_sel_hi:[1,0,1] neg_lo:[0,0,1] neg_hi:[0,0,1]
	v_pk_add_f32 v[128:129], v[130:131], v[206:207]
	v_pk_add_f32 v[130:131], v[130:131], v[206:207] neg_lo:[0,1] neg_hi:[0,1]
	s_waitcnt lgkmcnt(2)
	v_pk_add_f32 v[206:207], v[136:137], v[212:213]
	v_pk_mul_f32 v[204:205], v[130:131], s[72:73] op_sel_hi:[1,0]
	v_pk_add_f32 v[136:137], v[136:137], v[212:213] neg_lo:[0,1] neg_hi:[0,1]
	v_pk_fma_f32 v[204:205], v[126:127], s[80:81], v[204:205] op_sel_hi:[1,0,1]
	v_pk_mul_f32 v[126:127], v[126:127], s[72:73] op_sel_hi:[1,0]
	v_pk_fma_f32 v[108:109], v[12:13], v[6:7], v[20:21] neg_lo:[0,0,1] neg_hi:[0,0,1]
	v_pk_fma_f32 v[126:127], v[130:131], s[80:81], v[126:127] op_sel_hi:[1,0,1] neg_lo:[0,0,1] neg_hi:[0,0,1]
	v_pk_add_f32 v[130:131], v[132:133], v[208:209]
	v_pk_add_f32 v[132:133], v[132:133], v[208:209] neg_lo:[0,1] neg_hi:[0,1]
	v_pk_add_f32 v[208:209], v[134:135], v[210:211]
	v_pk_add_f32 v[134:135], v[134:135], v[210:211] neg_lo:[0,1] neg_hi:[0,1]
	v_pk_add_f32 v[210:211], v[138:139], v[214:215]
	v_pk_add_f32 v[138:139], v[138:139], v[214:215] neg_lo:[0,1] neg_hi:[0,1]
	v_pk_mul_f32 v[212:213], v[134:135], s[80:81] op_sel_hi:[1,0]
	s_waitcnt lgkmcnt(0)
	v_pk_add_f32 v[214:215], v[188:189], v[220:221]
	v_pk_fma_f32 v[212:213], v[138:139], s[72:73], v[212:213] op_sel_hi:[1,0,1] neg_lo:[0,0,1] neg_hi:[0,0,1]
	v_pk_mul_f32 v[138:139], v[138:139], s[80:81] op_sel_hi:[1,0]
	v_pk_add_f32 v[188:189], v[188:189], v[220:221] neg_lo:[0,1] neg_hi:[0,1]
	v_pk_fma_f32 v[134:135], v[134:135], s[52:53], v[138:139] op_sel_hi:[1,0,1] neg_lo:[0,0,1] neg_hi:[0,0,1]
	v_pk_add_f32 v[138:139], v[140:141], v[216:217]
	v_pk_add_f32 v[140:141], v[140:141], v[216:217] neg_lo:[0,1] neg_hi:[0,1]
	v_pk_add_f32 v[216:217], v[142:143], v[218:219]
	v_pk_add_f32 v[142:143], v[142:143], v[218:219] neg_lo:[0,1] neg_hi:[0,1]
	v_pk_mul_f32 v[188:189], v[188:189], s[54:55] op_sel_hi:[1,0]
	v_pk_mul_f32 v[220:221], v[142:143], s[72:73] op_sel_hi:[1,0]
	v_pk_fma_f32 v[218:219], v[140:141], s[54:55], v[188:189] op_sel_hi:[1,0,1] neg_lo:[0,0,1] neg_hi:[0,0,1]
	v_pk_fma_f32 v[140:141], v[140:141], s[54:55], v[188:189] op_sel_hi:[1,0,1]
	v_pk_add_f32 v[188:189], v[190:191], v[222:223]
	v_pk_add_f32 v[190:191], v[190:191], v[222:223] neg_lo:[0,1] neg_hi:[0,1]
	v_pk_add_f32 v[222:223], v[244:245], v[206:207]
	v_pk_fma_f32 v[220:221], v[190:191], s[80:81], v[220:221] op_sel_hi:[1,0,1] neg_lo:[0,0,1] neg_hi:[0,0,1]
	v_pk_mul_f32 v[190:191], v[190:191], s[72:73] op_sel_hi:[1,0]
	v_pk_add_f32 v[206:207], v[244:245], v[206:207] neg_lo:[0,1] neg_hi:[0,1]
	v_pk_fma_f32 v[142:143], v[142:143], s[84:85], v[190:191] op_sel_hi:[1,0,1] neg_lo:[0,0,1] neg_hi:[0,0,1]
	v_pk_add_f32 v[190:191], v[242:243], v[130:131]
	v_pk_add_f32 v[130:131], v[242:243], v[130:131] neg_lo:[0,1] neg_hi:[0,1]
	v_pk_add_f32 v[242:243], v[192:193], v[208:209]
	v_pk_add_f32 v[192:193], v[192:193], v[208:209] neg_lo:[0,1] neg_hi:[0,1]
	v_pk_add_f32 v[244:245], v[194:195], v[210:211]
	v_pk_add_f32 v[194:195], v[194:195], v[210:211] neg_lo:[0,1] neg_hi:[0,1]
	v_pk_mul_f32 v[192:193], v[192:193], s[82:83] op_sel_hi:[1,0]
	v_pk_add_f32 v[210:211], v[198:199], v[214:215]
	v_pk_fma_f32 v[208:209], v[194:195], s[82:83], v[192:193] op_sel_hi:[1,0,1]
	v_pk_fma_f32 v[192:193], v[194:195], s[82:83], v[192:193] op_sel_hi:[1,0,1] neg_lo:[0,0,1] neg_hi:[0,0,1]
	v_pk_add_f32 v[194:195], v[122:123], v[138:139]
	v_pk_add_f32 v[122:123], v[122:123], v[138:139] neg_lo:[0,1] neg_hi:[0,1]
	v_pk_add_f32 v[138:139], v[198:199], v[214:215] neg_lo:[0,1] neg_hi:[0,1]
	v_pk_add_f32 v[214:215], v[128:129], v[188:189]
	v_pk_add_f32 v[128:129], v[128:129], v[188:189] neg_lo:[0,1] neg_hi:[0,1]
	v_pk_add_f32 v[198:199], v[200:201], v[216:217]
	v_pk_add_f32 v[200:201], v[200:201], v[216:217] neg_lo:[0,1] neg_hi:[0,1]
	v_pk_mul_f32 v[128:129], v[128:129], s[54:55] op_sel_hi:[1,0]
	v_pk_add_f32 v[216:217], v[120:121], v[132:133] neg_lo:[0,1] neg_hi:[0,1]
	v_pk_add_f32 v[120:121], v[120:121], v[132:133]
	v_pk_add_f32 v[132:133], v[196:197], v[212:213]
	v_pk_add_f32 v[196:197], v[196:197], v[212:213] neg_lo:[0,1] neg_hi:[0,1]
	v_pk_fma_f32 v[188:189], v[200:201], s[54:55], v[128:129] op_sel_hi:[1,0,1] neg_lo:[0,0,1] neg_hi:[0,0,1]
	v_pk_fma_f32 v[128:129], v[200:201], s[54:55], v[128:129] op_sel_hi:[1,0,1]
	v_pk_add_f32 v[200:201], v[116:117], v[136:137]
	v_pk_add_f32 v[116:117], v[116:117], v[136:137] neg_lo:[0,1] neg_hi:[0,1]
	v_pk_add_f32 v[136:137], v[118:119], v[134:135]
	v_pk_add_f32 v[118:119], v[118:119], v[134:135] neg_lo:[0,1] neg_hi:[0,1]
	v_pk_mul_f32 v[134:135], v[196:197], s[82:83] op_sel_hi:[1,0]
	v_pk_add_f32 v[212:213], v[124:125], v[140:141]
	v_pk_fma_f32 v[196:197], v[118:119], s[82:83], v[134:135] op_sel_hi:[1,0,1]
	v_pk_fma_f32 v[118:119], v[118:119], s[82:83], v[134:135] op_sel_hi:[1,0,1] neg_lo:[0,0,1] neg_hi:[0,0,1]
	v_pk_add_f32 v[134:135], v[202:203], v[218:219]
	v_pk_add_f32 v[202:203], v[202:203], v[218:219] neg_lo:[0,1] neg_hi:[0,1]
	v_pk_add_f32 v[218:219], v[126:127], v[142:143]
	v_pk_add_f32 v[126:127], v[126:127], v[142:143] neg_lo:[0,1] neg_hi:[0,1]
	v_pk_add_f32 v[124:125], v[124:125], v[140:141] neg_lo:[0,1] neg_hi:[0,1]
	v_pk_add_f32 v[140:141], v[204:205], v[220:221]
	v_pk_add_f32 v[204:205], v[204:205], v[220:221] neg_lo:[0,1] neg_hi:[0,1]
	v_pk_mul_f32 v[126:127], v[126:127], s[54:55] op_sel_hi:[1,0]
	v_pk_add_f32 v[220:221], v[222:223], v[210:211]
	v_pk_fma_f32 v[142:143], v[204:205], s[54:55], v[126:127] op_sel_hi:[1,0,1] neg_lo:[0,0,1] neg_hi:[0,0,1]
	v_pk_fma_f32 v[126:127], v[204:205], s[54:55], v[126:127] op_sel_hi:[1,0,1]
	v_pk_add_f32 v[204:205], v[190:191], v[194:195]
	v_pk_add_f32 v[190:191], v[190:191], v[194:195] neg_lo:[0,1] neg_hi:[0,1]
	v_pk_add_f32 v[194:195], v[222:223], v[210:211] neg_lo:[0,1] neg_hi:[0,1]
	v_pk_add_f32 v[210:211], v[242:243], v[198:199]
	v_pk_add_f32 v[222:223], v[244:245], v[214:215]
	v_pk_add_f32 v[198:199], v[242:243], v[198:199] neg_lo:[0,1] neg_hi:[0,1]
	v_pk_add_f32 v[214:215], v[244:245], v[214:215] neg_lo:[0,1] neg_hi:[0,1]
	v_pk_add_f32 v[242:243], v[130:131], v[138:139]
	v_pk_add_f32 v[244:245], v[206:207], v[122:123] neg_lo:[0,1] neg_hi:[0,1]
	v_pk_add_f32 v[130:131], v[130:131], v[138:139] neg_lo:[0,1] neg_hi:[0,1]
	v_pk_add_f32 v[122:123], v[206:207], v[122:123]
	v_pk_add_f32 v[138:139], v[208:209], v[188:189]
	v_pk_add_f32 v[206:207], v[192:193], v[128:129]
	v_pk_add_f32 v[188:189], v[208:209], v[188:189] neg_lo:[0,1] neg_hi:[0,1]
	v_pk_add_f32 v[128:129], v[192:193], v[128:129] neg_lo:[0,1] neg_hi:[0,1]
	v_pk_add_f32 v[192:193], v[200:201], v[134:135]
	v_pk_add_f32 v[208:209], v[216:217], v[212:213]
	v_pk_add_f32 v[134:135], v[200:201], v[134:135] neg_lo:[0,1] neg_hi:[0,1]
	v_pk_add_f32 v[200:201], v[216:217], v[212:213] neg_lo:[0,1] neg_hi:[0,1]
	v_pk_add_f32 v[216:217], v[136:137], v[218:219]
	v_pk_add_f32 v[136:137], v[136:137], v[218:219] neg_lo:[0,1] neg_hi:[0,1]
	v_pk_add_f32 v[218:219], v[120:121], v[202:203] neg_lo:[0,1] neg_hi:[0,1]
	v_pk_add_f32 v[120:121], v[120:121], v[202:203]
	v_pk_add_f32 v[202:203], v[118:119], v[126:127]
	v_pk_add_f32 v[118:119], v[118:119], v[126:127] neg_lo:[0,1] neg_hi:[0,1]
	v_pk_add_f32 v[126:127], v[204:205], v[210:211]
	v_pk_add_f32 v[204:205], v[204:205], v[210:211] neg_lo:[0,1] neg_hi:[0,1]
	v_pk_add_f32 v[210:211], v[220:221], v[222:223] neg_lo:[0,1] neg_hi:[0,1]
	v_pk_add_f32 v[212:213], v[132:133], v[140:141]
	v_pk_add_f32 v[132:133], v[132:133], v[140:141] neg_lo:[0,1] neg_hi:[0,1]
	v_pk_add_f32 v[140:141], v[116:117], v[124:125]
	v_pk_add_f32 v[116:117], v[116:117], v[124:125] neg_lo:[0,1] neg_hi:[0,1]
	v_pk_add_f32 v[124:125], v[196:197], v[142:143]
	v_pk_add_f32 v[142:143], v[196:197], v[142:143] neg_lo:[0,1] neg_hi:[0,1]
	v_pk_add_f32 v[196:197], v[220:221], v[222:223]
	v_pk_add_f32 v[220:221], v[190:191], v[214:215]
	v_pk_mul_f32 v[246:247], v[6:7], v[210:211]
	v_pk_mul_f32 v[210:211], v[8:9], v[210:211]
	v_pk_add_f32 v[222:223], v[194:195], v[198:199] neg_lo:[0,1] neg_hi:[0,1]
	v_pk_fma_f32 v[246:247], v[8:9], v[204:205], v[246:247]
	v_pk_fma_f32 v[204:205], v[6:7], v[204:205], v[210:211] neg_lo:[0,0,1] neg_hi:[0,0,1]
	v_pk_mul_f32 v[210:211], v[224:225], v[220:221]
	v_pk_mul_f32 v[20:21], v[14:15], v[6:7]
	v_pk_fma_f32 v[234:235], v[144:145], v[8:9], v[114:115]
	v_pk_add_f32 v[190:191], v[190:191], v[214:215] neg_lo:[0,1] neg_hi:[0,1]
	v_pk_fma_f32 v[210:211], v[144:145], v[222:223], v[210:211]
	v_pk_mul_f32 v[222:223], v[224:225], v[222:223]
	v_pk_fma_f32 v[0:1], v[144:145], v[4:5], v[0:1] neg_lo:[0,0,1] neg_hi:[0,0,1]
	v_pk_fma_f32 v[112:113], v[12:13], v[8:9], v[20:21]
	v_pk_mul_f32 v[20:21], v[106:107], v[8:9]
	v_pk_add_f32 v[194:195], v[194:195], v[198:199]
	v_pk_fma_f32 v[144:145], v[144:145], v[220:221], v[222:223] neg_lo:[0,0,1] neg_hi:[0,0,1]
	v_pk_mul_f32 v[220:221], v[234:235], v[190:191]
	v_pk_fma_f32 v[228:229], v[104:105], v[6:7], v[20:21] neg_lo:[0,0,1] neg_hi:[0,0,1]
	v_pk_mul_f32 v[20:21], v[106:107], v[6:7]
	v_pk_add_f32 v[198:199], v[242:243], v[138:139]
	v_pk_add_f32 v[214:215], v[244:245], v[206:207]
	v_pk_fma_f32 v[220:221], v[232:233], v[194:195], v[220:221]
	v_pk_mul_f32 v[194:195], v[234:235], v[194:195]
	v_pk_fma_f32 v[230:231], v[104:105], v[8:9], v[20:21]
	v_pk_add_f32 v[138:139], v[242:243], v[138:139] neg_lo:[0,1] neg_hi:[0,1]
	v_pk_add_f32 v[206:207], v[244:245], v[206:207] neg_lo:[0,1] neg_hi:[0,1]
	v_pk_fma_f32 v[190:191], v[232:233], v[190:191], v[194:195] neg_lo:[0,0,1] neg_hi:[0,0,1]
	v_pk_mul_f32 v[194:195], v[106:107], v[198:199]
	v_pk_mul_f32 v[106:107], v[106:107], v[214:215]
	v_pk_add_f32 v[242:243], v[130:131], v[128:129]
	v_pk_add_f32 v[244:245], v[122:123], v[188:189] neg_lo:[0,1] neg_hi:[0,1]
	v_pk_fma_f32 v[194:195], v[104:105], v[214:215], v[194:195]
	v_pk_fma_f32 v[104:105], v[104:105], v[198:199], v[106:107] neg_lo:[0,0,1] neg_hi:[0,0,1]
	v_pk_mul_f32 v[106:107], v[230:231], v[138:139]
	v_pk_mul_f32 v[198:199], v[230:231], v[206:207]
	v_pk_add_f32 v[128:129], v[130:131], v[128:129] neg_lo:[0,1] neg_hi:[0,1]
	v_pk_fma_f32 v[106:107], v[228:229], v[206:207], v[106:107]
	v_pk_fma_f32 v[138:139], v[228:229], v[138:139], v[198:199] neg_lo:[0,0,1] neg_hi:[0,0,1]
	v_pk_mul_f32 v[198:199], v[226:227], v[242:243]
	v_pk_mul_f32 v[206:207], v[226:227], v[244:245]
	v_pk_add_f32 v[122:123], v[122:123], v[188:189]
	v_pk_fma_f32 v[198:199], v[110:111], v[244:245], v[198:199]
	v_pk_fma_f32 v[110:111], v[110:111], v[242:243], v[206:207] neg_lo:[0,0,1] neg_hi:[0,0,1]
	v_pk_mul_f32 v[206:207], v[240:241], v[128:129]
	v_pk_add_f32 v[130:131], v[192:193], v[212:213]
	v_pk_add_f32 v[188:189], v[208:209], v[216:217]
	v_pk_fma_f32 v[206:207], v[238:239], v[122:123], v[206:207]
	v_pk_mul_f32 v[122:123], v[240:241], v[122:123]
	v_pk_add_f32 v[192:193], v[192:193], v[212:213] neg_lo:[0,1] neg_hi:[0,1]
	v_pk_fma_f32 v[122:123], v[238:239], v[128:129], v[122:123] neg_lo:[0,0,1] neg_hi:[0,0,1]
	v_pk_mul_f32 v[128:129], v[14:15], v[130:131]
	v_pk_mul_f32 v[14:15], v[14:15], v[188:189]
	v_pk_add_f32 v[208:209], v[208:209], v[216:217] neg_lo:[0,1] neg_hi:[0,1]
	v_pk_fma_f32 v[128:129], v[12:13], v[188:189], v[128:129]
	v_pk_fma_f32 v[12:13], v[12:13], v[130:131], v[14:15] neg_lo:[0,0,1] neg_hi:[0,0,1]
	ds_write2_b64 v164, v[126:127], v[12:13] offset1:34
	ds_write2_b64 v165, v[196:197], v[128:129] offset1:34
	v_pk_mul_f32 v[12:13], v[112:113], v[192:193]
	v_pk_mul_f32 v[14:15], v[112:113], v[208:209]
	v_pk_add_f32 v[212:213], v[134:135], v[136:137]
	v_pk_add_f32 v[216:217], v[200:201], v[132:133] neg_lo:[0,1] neg_hi:[0,1]
	v_pk_fma_f32 v[12:13], v[108:109], v[208:209], v[12:13]
	v_pk_fma_f32 v[14:15], v[108:109], v[192:193], v[14:15] neg_lo:[0,0,1] neg_hi:[0,0,1]
	ds_write2_b64 v166, v[204:205], v[14:15] offset0:16 offset1:50
	ds_write2_b64 v167, v[246:247], v[12:13] offset0:16 offset1:50
	v_pk_mul_f32 v[12:13], v[18:19], v[212:213]
	v_pk_mul_f32 v[14:15], v[18:19], v[216:217]
	v_pk_mul_f32 v[114:115], v[8:9], v[18:19]
	v_pk_add_f32 v[134:135], v[134:135], v[136:137] neg_lo:[0,1] neg_hi:[0,1]
	v_pk_add_f32 v[132:133], v[200:201], v[132:133]
	v_pk_fma_f32 v[12:13], v[16:17], v[216:217], v[12:13]
	v_pk_fma_f32 v[14:15], v[16:17], v[212:213], v[14:15] neg_lo:[0,0,1] neg_hi:[0,0,1]
	v_pk_fma_f32 v[114:115], v[6:7], v[16:17], v[114:115] neg_lo:[0,0,1] neg_hi:[0,0,1]
	ds_write2_b64 v164, v[144:145], v[14:15] offset0:136 offset1:170
	ds_write2_b64 v165, v[210:211], v[12:13] offset0:136 offset1:170
	v_pk_mul_f32 v[12:13], v[236:237], v[134:135]
	v_pk_mul_f32 v[14:15], v[236:237], v[132:133]
	v_pk_mul_f32 v[22:23], v[10:11], v[6:7]
	v_pk_add_f32 v[136:137], v[140:141], v[124:125]
	v_pk_add_f32 v[200:201], v[218:219], v[202:203]
	v_pk_fma_f32 v[12:13], v[114:115], v[132:133], v[12:13]
	v_pk_fma_f32 v[14:15], v[114:115], v[134:135], v[14:15] neg_lo:[0,0,1] neg_hi:[0,0,1]
	v_pk_mul_f32 v[20:21], v[10:11], v[8:9]
	v_pk_fma_f32 v[22:23], v[4:5], v[8:9], v[22:23]
	v_pk_add_f32 v[124:125], v[140:141], v[124:125] neg_lo:[0,1] neg_hi:[0,1]
	v_pk_add_f32 v[140:141], v[218:219], v[202:203] neg_lo:[0,1] neg_hi:[0,1]
	ds_write2_b64 v166, v[190:191], v[14:15] offset0:152 offset1:186
	ds_write2_b64 v167, v[220:221], v[12:13] offset0:152 offset1:186
	v_pk_mul_f32 v[12:13], v[10:11], v[136:137]
	v_pk_mul_f32 v[10:11], v[10:11], v[200:201]
	v_pk_fma_f32 v[2:3], v[224:225], v[4:5], v[2:3]
	v_pk_fma_f32 v[20:21], v[4:5], v[6:7], v[20:21] neg_lo:[0,0,1] neg_hi:[0,0,1]
	v_pk_fma_f32 v[12:13], v[4:5], v[200:201], v[12:13]
	v_pk_fma_f32 v[4:5], v[4:5], v[136:137], v[10:11] neg_lo:[0,0,1] neg_hi:[0,0,1]
	v_pk_mul_f32 v[10:11], v[22:23], v[140:141]
	v_pk_add_f32 v[218:219], v[120:121], v[142:143] neg_lo:[0,1] neg_hi:[0,1]
	ds_write2_b64 v164, v[104:105], v[4:5] offset0:68 offset1:102
	ds_write2_b64 v165, v[194:195], v[12:13] offset0:68 offset1:102
	v_pk_mul_f32 v[4:5], v[22:23], v[124:125]
	v_pk_fma_f32 v[10:11], v[20:21], v[124:125], v[10:11] neg_lo:[0,0,1] neg_hi:[0,0,1]
	v_pk_add_f32 v[202:203], v[116:117], v[118:119]
	v_pk_fma_f32 v[4:5], v[20:21], v[140:141], v[4:5]
	ds_write2_b64 v166, v[138:139], v[10:11] offset0:84 offset1:118
	ds_write2_b64 v167, v[106:107], v[4:5] offset0:84 offset1:118
	v_pk_mul_f32 v[10:11], v[2:3], v[218:219]
	v_pk_mul_f32 v[4:5], v[2:3], v[202:203]
	v_pk_fma_f32 v[10:11], v[0:1], v[202:203], v[10:11] neg_lo:[0,0,1] neg_hi:[0,0,1]
	v_pk_fma_f32 v[4:5], v[0:1], v[218:219], v[4:5]
	ds_write2_b64 v164, v[110:111], v[10:11] offset0:204 offset1:238
	ds_write2_b64 v165, v[198:199], v[4:5] offset0:204 offset1:238
	v_pk_mul_f32 v[10:11], v[8:9], v[2:3]
	v_pk_mul_f32 v[2:3], v[6:7], v[2:3]
	v_pk_add_f32 v[4:5], v[120:121], v[142:143]
	v_pk_fma_f32 v[10:11], v[6:7], v[0:1], v[10:11] neg_lo:[0,0,1] neg_hi:[0,0,1]
	v_pk_add_f32 v[12:13], v[116:117], v[118:119] neg_lo:[0,1] neg_hi:[0,1]
	v_pk_fma_f32 v[0:1], v[8:9], v[0:1], v[2:3]
	s_nop 0
	v_pk_mul_f32 v[2:3], v[0:1], v[12:13]
	v_pk_mul_f32 v[0:1], v[0:1], v[4:5]
	v_pk_fma_f32 v[2:3], v[10:11], v[4:5], v[2:3]
	v_pk_fma_f32 v[0:1], v[10:11], v[12:13], v[0:1] neg_lo:[0,0,1] neg_hi:[0,0,1]
	ds_write2_b64 v166, v[122:123], v[0:1] offset0:220 offset1:254
	ds_write2_b64 v167, v[206:207], v[2:3] offset0:220 offset1:254
	v_mov_b32_e32 v0, v163
	s_waitcnt lgkmcnt(0)
	s_barrier
	s_nop 0
	s_nop 0
	v_lshlrev_b32_e32 v1, 1, v0
	v_and_b32_e32 v187, 2, v1
	v_lshrrev_b32_e32 v1, 31, v0
	v_add_u32_e32 v0, v0, v1
	v_ashrrev_i32_e32 v164, 1, v0
	v_lshl_or_b32 v0, v164, 6, v187
	v_lshlrev_b32_e32 v1, 2, v164
	v_add_lshl_u32 v128, v0, v1, 2
	v_add_u32_e32 v165, 0, v128
	v_add_u32_e32 v162, s91, v128
	ds_read2_b64 v[128:131], v165 offset1:2
	ds_read2_b64 v[132:135], v165 offset0:4 offset1:6
	ds_read2_b64 v[136:139], v162 offset1:2
	ds_read2_b64 v[140:143], v162 offset0:4 offset1:6
	ds_read2_b64 v[188:191], v165 offset0:8 offset1:10
	ds_read2_b64 v[192:195], v162 offset0:8 offset1:10
	ds_read2_b64 v[196:199], v165 offset0:12 offset1:14
	ds_read2_b64 v[200:203], v162 offset0:12 offset1:14
	ds_read2_b64 v[204:207], v165 offset0:16 offset1:18
	ds_read2_b64 v[208:211], v162 offset0:16 offset1:18
	ds_read2_b64 v[212:215], v165 offset0:20 offset1:22
	ds_read2_b64 v[216:219], v162 offset0:20 offset1:22
	ds_read2_b64 v[220:223], v165 offset0:24 offset1:26
	ds_read2_b64 v[224:227], v162 offset0:24 offset1:26
	ds_read2_b64 v[228:231], v165 offset0:28 offset1:30
	ds_read2_b64 v[232:235], v162 offset0:28 offset1:30
	s_waitcnt lgkmcnt(6)
	v_pk_add_f32 v[240:241], v[136:137], v[208:209]
	v_pk_add_f32 v[136:137], v[136:137], v[208:209] neg_lo:[0,1] neg_hi:[0,1]
	v_pk_add_f32 v[208:209], v[138:139], v[210:211]
	v_pk_add_f32 v[138:139], v[138:139], v[210:211] neg_lo:[0,1] neg_hi:[0,1]
	v_pk_add_f32 v[238:239], v[128:129], v[204:205]
	v_pk_add_f32 v[128:129], v[128:129], v[204:205] neg_lo:[0,1] neg_hi:[0,1]
	v_pk_add_f32 v[204:205], v[130:131], v[206:207]
	v_pk_add_f32 v[130:131], v[130:131], v[206:207] neg_lo:[0,1] neg_hi:[0,1]
	v_pk_mul_f32 v[206:207], v[138:139], s[80:81] op_sel_hi:[1,0]
	s_waitcnt lgkmcnt(4)
	v_pk_add_f32 v[210:211], v[140:141], v[216:217]
	v_pk_fma_f32 v[206:207], v[130:131], s[72:73], v[206:207] op_sel_hi:[1,0,1]
	v_pk_mul_f32 v[130:131], v[130:131], s[80:81] op_sel_hi:[1,0]
	v_pk_add_f32 v[140:141], v[140:141], v[216:217] neg_lo:[0,1] neg_hi:[0,1]
	v_pk_fma_f32 v[130:131], v[138:139], s[72:73], v[130:131] op_sel_hi:[1,0,1] neg_lo:[0,0,1] neg_hi:[0,0,1]
	v_pk_add_f32 v[138:139], v[132:133], v[212:213]
	v_pk_add_f32 v[132:133], v[132:133], v[212:213] neg_lo:[0,1] neg_hi:[0,1]
	v_pk_add_f32 v[216:217], v[142:143], v[218:219]
	v_pk_mul_f32 v[132:133], v[132:133], s[82:83] op_sel_hi:[1,0]
	v_pk_add_f32 v[142:143], v[142:143], v[218:219] neg_lo:[0,1] neg_hi:[0,1]
	v_pk_fma_f32 v[212:213], v[140:141], s[82:83], v[132:133] op_sel_hi:[1,0,1]
	v_pk_fma_f32 v[132:133], v[140:141], s[82:83], v[132:133] op_sel_hi:[1,0,1] neg_lo:[0,0,1] neg_hi:[0,0,1]
	v_pk_add_f32 v[140:141], v[134:135], v[214:215]
	v_pk_add_f32 v[134:135], v[134:135], v[214:215] neg_lo:[0,1] neg_hi:[0,1]
	v_pk_mul_f32 v[214:215], v[142:143], s[72:73] op_sel_hi:[1,0]
	v_or_b32_e32 v3, 1, v187
	v_pk_fma_f32 v[214:215], v[134:135], s[80:81], v[214:215] op_sel_hi:[1,0,1]
	v_pk_mul_f32 v[134:135], v[134:135], s[72:73] op_sel_hi:[1,0]
	v_cvt_f32_ubyte0_e32 v2, v187
	v_cvt_f32_ubyte0_e32 v3, v3
	v_pk_fma_f32 v[134:135], v[142:143], s[80:81], v[134:135] op_sel_hi:[1,0,1] neg_lo:[0,0,1] neg_hi:[0,0,1]
	s_waitcnt lgkmcnt(3)
	v_pk_add_f32 v[142:143], v[188:189], v[220:221]
	v_pk_add_f32 v[188:189], v[188:189], v[220:221] neg_lo:[0,1] neg_hi:[0,1]
	v_pk_add_f32 v[220:221], v[190:191], v[222:223]
	v_pk_add_f32 v[190:191], v[190:191], v[222:223] neg_lo:[0,1] neg_hi:[0,1]
	v_mul_f32_e32 v2, 0x3c800000, v2
	v_mul_f32_e32 v3, 0x3c800000, v3
	s_waitcnt lgkmcnt(2)
	v_pk_add_f32 v[218:219], v[192:193], v[224:225]
	v_pk_add_f32 v[192:193], v[192:193], v[224:225] neg_lo:[0,1] neg_hi:[0,1]
	v_pk_add_f32 v[224:225], v[194:195], v[226:227]
	v_pk_add_f32 v[194:195], v[194:195], v[226:227] neg_lo:[0,1] neg_hi:[0,1]
	v_pk_mul_f32 v[222:223], v[190:191], s[80:81] op_sel_hi:[1,0]
	v_sin_f32_e64 v236, -v2
	v_sin_f32_e64 v237, -v3
	v_pk_fma_f32 v[222:223], v[194:195], s[72:73], v[222:223] op_sel_hi:[1,0,1] neg_lo:[0,0,1] neg_hi:[0,0,1]
	v_pk_mul_f32 v[194:195], v[194:195], s[80:81] op_sel_hi:[1,0]
	s_waitcnt lgkmcnt(0)
	v_pk_add_f32 v[226:227], v[200:201], v[232:233]
	v_pk_add_f32 v[200:201], v[200:201], v[232:233] neg_lo:[0,1] neg_hi:[0,1]
	v_cos_f32_e32 v144, v2
	v_cos_f32_e32 v145, v3
	v_pk_fma_f32 v[190:191], v[190:191], s[52:53], v[194:195] op_sel_hi:[1,0,1] neg_lo:[0,0,1] neg_hi:[0,0,1]
	v_pk_add_f32 v[194:195], v[196:197], v[228:229]
	v_pk_add_f32 v[196:197], v[196:197], v[228:229] neg_lo:[0,1] neg_hi:[0,1]
	v_pk_mul_f32 v[200:201], v[200:201], s[54:55] op_sel_hi:[1,0]
	v_pk_add_f32 v[232:233], v[202:203], v[234:235]
	v_pk_fma_f32 v[228:229], v[196:197], s[54:55], v[200:201] op_sel_hi:[1,0,1] neg_lo:[0,0,1] neg_hi:[0,0,1]
	v_pk_fma_f32 v[196:197], v[196:197], s[54:55], v[200:201] op_sel_hi:[1,0,1]
	v_pk_add_f32 v[200:201], v[198:199], v[230:231]
	v_pk_add_f32 v[198:199], v[198:199], v[230:231] neg_lo:[0,1] neg_hi:[0,1]
	v_pk_add_f32 v[202:203], v[202:203], v[234:235] neg_lo:[0,1] neg_hi:[0,1]
	v_pk_mul_f32 v[230:231], v[198:199], s[72:73] op_sel_hi:[1,0]
	v_pk_mul_f32 v[0:1], v[236:237], v[236:237]
	v_pk_fma_f32 v[230:231], v[202:203], s[80:81], v[230:231] op_sel_hi:[1,0,1] neg_lo:[0,0,1] neg_hi:[0,0,1]
	v_pk_mul_f32 v[202:203], v[202:203], s[72:73] op_sel_hi:[1,0]
	v_pk_fma_f32 v[120:121], v[144:145], v[144:145], v[0:1] neg_lo:[0,0,1] neg_hi:[0,0,1]
	v_pk_mul_f32 v[0:1], v[144:145], v[236:237]
	v_pk_fma_f32 v[198:199], v[198:199], s[84:85], v[202:203] op_sel_hi:[1,0,1] neg_lo:[0,0,1] neg_hi:[0,0,1]
	v_pk_add_f32 v[202:203], v[238:239], v[142:143]
	v_pk_add_f32 v[142:143], v[238:239], v[142:143] neg_lo:[0,1] neg_hi:[0,1]
	v_pk_add_f32 v[238:239], v[204:205], v[220:221]
	v_pk_add_f32 v[204:205], v[204:205], v[220:221] neg_lo:[0,1] neg_hi:[0,1]
	v_pk_add_f32 v[124:125], v[0:1], v[0:1]
	v_pk_add_f32 v[234:235], v[240:241], v[218:219]
	v_pk_add_f32 v[218:219], v[240:241], v[218:219] neg_lo:[0,1] neg_hi:[0,1]
	v_pk_add_f32 v[240:241], v[208:209], v[224:225]
	v_pk_add_f32 v[208:209], v[208:209], v[224:225] neg_lo:[0,1] neg_hi:[0,1]
	v_pk_mul_f32 v[204:205], v[204:205], s[82:83] op_sel_hi:[1,0]
	v_pk_mul_f32 v[0:1], v[236:237], v[124:125]
	v_pk_fma_f32 v[220:221], v[208:209], s[82:83], v[204:205] op_sel_hi:[1,0,1]
	v_pk_fma_f32 v[204:205], v[208:209], s[82:83], v[204:205] op_sel_hi:[1,0,1] neg_lo:[0,0,1] neg_hi:[0,0,1]
	v_pk_add_f32 v[208:209], v[138:139], v[194:195]
	v_pk_add_f32 v[224:225], v[210:211], v[226:227]
	v_pk_add_f32 v[138:139], v[138:139], v[194:195] neg_lo:[0,1] neg_hi:[0,1]
	v_pk_add_f32 v[194:195], v[210:211], v[226:227] neg_lo:[0,1] neg_hi:[0,1]
	v_pk_add_f32 v[210:211], v[140:141], v[200:201]
	v_pk_add_f32 v[140:141], v[140:141], v[200:201] neg_lo:[0,1] neg_hi:[0,1]
	v_pk_add_f32 v[200:201], v[216:217], v[232:233] neg_lo:[0,1] neg_hi:[0,1]
	v_pk_fma_f32 v[122:123], v[144:145], v[120:121], v[0:1] neg_lo:[0,0,1] neg_hi:[0,0,1]
	v_pk_mul_f32 v[0:1], v[236:237], v[120:121]
	v_pk_add_f32 v[226:227], v[216:217], v[232:233]
	v_pk_mul_f32 v[200:201], v[200:201], s[54:55] op_sel_hi:[1,0]
	v_pk_add_f32 v[232:233], v[136:137], v[188:189] neg_lo:[0,1] neg_hi:[0,1]
	v_pk_add_f32 v[136:137], v[136:137], v[188:189]
	v_pk_add_f32 v[188:189], v[206:207], v[222:223]
	v_pk_add_f32 v[206:207], v[206:207], v[222:223] neg_lo:[0,1] neg_hi:[0,1]
	v_pk_fma_f32 v[126:127], v[144:145], v[124:125], v[0:1]
	v_pk_mul_f32 v[0:1], v[124:125], v[124:125]
	v_pk_fma_f32 v[216:217], v[140:141], s[54:55], v[200:201] op_sel_hi:[1,0,1] neg_lo:[0,0,1] neg_hi:[0,0,1]
	v_pk_fma_f32 v[140:141], v[140:141], s[54:55], v[200:201] op_sel_hi:[1,0,1]
	v_pk_add_f32 v[200:201], v[128:129], v[192:193]
	v_pk_add_f32 v[128:129], v[128:129], v[192:193] neg_lo:[0,1] neg_hi:[0,1]
	v_pk_add_f32 v[192:193], v[130:131], v[190:191]
	v_pk_add_f32 v[130:131], v[130:131], v[190:191] neg_lo:[0,1] neg_hi:[0,1]
	v_pk_mul_f32 v[190:191], v[206:207], s[82:83] op_sel_hi:[1,0]
	v_pk_fma_f32 v[112:113], v[120:121], v[120:121], v[0:1] neg_lo:[0,0,1] neg_hi:[0,0,1]
	v_pk_mul_f32 v[0:1], v[120:121], v[124:125]
	v_pk_fma_f32 v[206:207], v[130:131], s[82:83], v[190:191] op_sel_hi:[1,0,1]
	v_pk_fma_f32 v[130:131], v[130:131], s[82:83], v[190:191] op_sel_hi:[1,0,1] neg_lo:[0,0,1] neg_hi:[0,0,1]
	v_pk_add_f32 v[190:191], v[212:213], v[228:229]
	v_pk_add_f32 v[212:213], v[212:213], v[228:229] neg_lo:[0,1] neg_hi:[0,1]
	v_pk_add_f32 v[228:229], v[134:135], v[198:199]
	v_pk_add_f32 v[134:135], v[134:135], v[198:199] neg_lo:[0,1] neg_hi:[0,1]
	v_pk_add_f32 v[116:117], v[0:1], v[0:1]
	v_pk_add_f32 v[222:223], v[132:133], v[196:197]
	v_pk_add_f32 v[132:133], v[132:133], v[196:197] neg_lo:[0,1] neg_hi:[0,1]
	v_pk_add_f32 v[196:197], v[214:215], v[230:231]
	v_pk_add_f32 v[214:215], v[214:215], v[230:231] neg_lo:[0,1] neg_hi:[0,1]
	v_pk_mul_f32 v[134:135], v[134:135], s[54:55] op_sel_hi:[1,0]
	v_pk_mul_f32 v[8:9], v[112:113], v[116:117]
	v_pk_fma_f32 v[198:199], v[214:215], s[54:55], v[134:135] op_sel_hi:[1,0,1] neg_lo:[0,0,1] neg_hi:[0,0,1]
	v_pk_fma_f32 v[134:135], v[214:215], s[54:55], v[134:135] op_sel_hi:[1,0,1]
	v_pk_add_f32 v[214:215], v[202:203], v[208:209]
	v_pk_add_f32 v[230:231], v[234:235], v[224:225]
	v_pk_add_f32 v[202:203], v[202:203], v[208:209] neg_lo:[0,1] neg_hi:[0,1]
	v_pk_add_f32 v[208:209], v[234:235], v[224:225] neg_lo:[0,1] neg_hi:[0,1]
	v_pk_add_f32 v[224:225], v[238:239], v[210:211]
	v_pk_add_f32 v[234:235], v[240:241], v[226:227]
	v_pk_add_f32 v[210:211], v[238:239], v[210:211] neg_lo:[0,1] neg_hi:[0,1]
	v_pk_add_f32 v[226:227], v[240:241], v[226:227] neg_lo:[0,1] neg_hi:[0,1]
	v_pk_add_f32 v[238:239], v[142:143], v[194:195]
	v_pk_add_f32 v[240:241], v[218:219], v[138:139] neg_lo:[0,1] neg_hi:[0,1]
	v_pk_add_f32 v[142:143], v[142:143], v[194:195] neg_lo:[0,1] neg_hi:[0,1]
	v_pk_add_f32 v[138:139], v[218:219], v[138:139]
	v_pk_add_f32 v[194:195], v[220:221], v[216:217]
	v_pk_add_f32 v[218:219], v[204:205], v[140:141]
	v_pk_add_f32 v[216:217], v[220:221], v[216:217] neg_lo:[0,1] neg_hi:[0,1]
	v_pk_add_f32 v[140:141], v[204:205], v[140:141] neg_lo:[0,1] neg_hi:[0,1]
	v_pk_add_f32 v[204:205], v[200:201], v[190:191]
	v_pk_add_f32 v[220:221], v[232:233], v[222:223]
	v_pk_add_f32 v[190:191], v[200:201], v[190:191] neg_lo:[0,1] neg_hi:[0,1]
	v_pk_add_f32 v[200:201], v[232:233], v[222:223] neg_lo:[0,1] neg_hi:[0,1]
	v_pk_add_f32 v[232:233], v[192:193], v[228:229]
	v_pk_mul_f32 v[4:5], v[116:117], v[116:117]
	v_pk_add_f32 v[8:9], v[8:9], v[8:9]
	v_mul_lo_u32 v248, v164, s49
	v_pk_add_f32 v[222:223], v[188:189], v[196:197]
	v_pk_add_f32 v[164:165], v[220:221], v[232:233] neg_lo:[0,1] neg_hi:[0,1]
	v_pk_add_f32 v[220:221], v[220:221], v[232:233]
	v_pk_mul_f32 v[0:1], v[236:237], v[116:117]
	v_pk_fma_f32 v[4:5], v[112:113], v[112:113], v[4:5] neg_lo:[0,0,1] neg_hi:[0,0,1]
	v_pk_mul_f32 v[12:13], v[236:237], v[8:9]
	v_pk_add_f32 v[188:189], v[188:189], v[196:197] neg_lo:[0,1] neg_hi:[0,1]
	v_pk_add_f32 v[192:193], v[192:193], v[228:229] neg_lo:[0,1] neg_hi:[0,1]
	v_pk_add_f32 v[196:197], v[128:129], v[132:133]
	v_pk_add_f32 v[228:229], v[136:137], v[212:213] neg_lo:[0,1] neg_hi:[0,1]
	v_pk_add_f32 v[128:129], v[128:129], v[132:133] neg_lo:[0,1] neg_hi:[0,1]
	v_pk_add_f32 v[132:133], v[136:137], v[212:213]
	v_pk_add_f32 v[212:213], v[130:131], v[134:135]
	v_pk_add_f32 v[130:131], v[130:131], v[134:135] neg_lo:[0,1] neg_hi:[0,1]
	v_pk_add_f32 v[134:135], v[214:215], v[224:225] neg_lo:[0,1] neg_hi:[0,1]
	v_pk_add_f32 v[246:247], v[204:205], v[222:223] neg_lo:[0,1] neg_hi:[0,1]
	v_or_b32_e32 v187, v248, v187
	v_pk_add_f32 v[204:205], v[204:205], v[222:223]
	v_pk_add_f32 v[214:215], v[214:215], v[224:225]
	v_pk_mul_f32 v[224:225], v[236:237], v[220:221]
	v_pk_fma_f32 v[114:115], v[144:145], v[112:113], v[0:1] neg_lo:[0,0,1] neg_hi:[0,0,1]
	v_pk_mul_f32 v[0:1], v[236:237], v[112:113]
	v_pk_fma_f32 v[108:109], v[144:145], v[4:5], v[12:13] neg_lo:[0,0,1] neg_hi:[0,0,1]
	v_pk_mul_f32 v[12:13], v[236:237], v[4:5]
	v_pk_fma_f32 v[224:225], v[144:145], v[204:205], v[224:225] neg_lo:[0,0,1] neg_hi:[0,0,1]
	v_pk_mul_f32 v[204:205], v[236:237], v[204:205]
	v_lshlrev_b32_e32 v187, 2, v187
	v_pk_fma_f32 v[118:119], v[144:145], v[116:117], v[0:1]
	v_pk_fma_f32 v[110:111], v[144:145], v[8:9], v[12:13]
	v_pk_mul_f32 v[12:13], v[124:125], v[8:9]
	v_pk_add_f32 v[222:223], v[230:231], v[234:235]
	v_pk_fma_f32 v[144:145], v[144:145], v[220:221], v[204:205]
	v_mov_b32_e32 v204, v214
	v_mov_b32_e32 v205, v224
	v_add_u32_e32 v214, 0, v187
	v_mov_b32_e32 v224, v215
	v_pk_mul_f32 v[0:1], v[124:125], v[116:117]
	v_pk_fma_f32 v[20:21], v[120:121], v[4:5], v[12:13] neg_lo:[0,0,1] neg_hi:[0,0,1]
	v_pk_mul_f32 v[12:13], v[124:125], v[4:5]
	v_pk_add_f32 v[136:137], v[206:207], v[198:199]
	v_pk_add_f32 v[242:243], v[202:203], v[226:227]
	v_pk_add_f32 v[244:245], v[208:209], v[210:211] neg_lo:[0,1] neg_hi:[0,1]
	v_pk_add_f32 v[202:203], v[202:203], v[226:227] neg_lo:[0,1] neg_hi:[0,1]
	v_pk_add_f32 v[208:209], v[208:209], v[210:211]
	v_pk_add_f32 v[210:211], v[238:239], v[194:195]
	v_pk_add_f32 v[226:227], v[240:241], v[218:219]
	ds_write2_b64 v214, v[204:205], v[224:225] offset1:2
	v_mov_b32_e32 v204, v222
	v_mov_b32_e32 v205, v144
	v_add_u32_e32 v187, s91, v187
	v_mov_b32_e32 v144, v223
	v_pk_fma_f32 v[6:7], v[120:121], v[112:113], v[0:1] neg_lo:[0,0,1] neg_hi:[0,0,1]
	v_pk_mul_f32 v[0:1], v[124:125], v[112:113]
	v_pk_fma_f32 v[104:105], v[120:121], v[8:9], v[12:13]
	v_pk_mul_f32 v[12:13], v[126:127], v[8:9]
	v_pk_add_f32 v[166:167], v[190:191], v[192:193]
	v_pk_add_f32 v[190:191], v[190:191], v[192:193] neg_lo:[0,1] neg_hi:[0,1]
	v_pk_add_f32 v[192:193], v[200:201], v[188:189] neg_lo:[0,1] neg_hi:[0,1]
	v_pk_add_f32 v[188:189], v[200:201], v[188:189]
	v_pk_add_f32 v[200:201], v[196:197], v[136:137]
	v_pk_add_f32 v[136:137], v[196:197], v[136:137] neg_lo:[0,1] neg_hi:[0,1]
	v_pk_add_f32 v[196:197], v[228:229], v[212:213]
	ds_write2_b64 v187, v[204:205], v[144:145] offset1:2
	v_pk_mul_f32 v[144:145], v[124:125], v[210:211]
	v_pk_mul_f32 v[124:125], v[124:125], v[226:227]
	v_pk_fma_f32 v[10:11], v[120:121], v[116:117], v[0:1]
	v_pk_mul_f32 v[0:1], v[116:117], v[126:127]
	v_pk_mul_f32 v[2:3], v[112:113], v[126:127]
	v_pk_fma_f32 v[22:23], v[122:123], v[4:5], v[12:13] neg_lo:[0,0,1] neg_hi:[0,0,1]
	v_pk_mul_f32 v[12:13], v[126:127], v[4:5]
	v_pk_fma_f32 v[144:145], v[120:121], v[226:227], v[144:145]
	v_pk_fma_f32 v[120:121], v[120:121], v[210:211], v[124:125] neg_lo:[0,0,1] neg_hi:[0,0,1]
	v_pk_mul_f32 v[124:125], v[126:127], v[196:197]
	v_pk_mul_f32 v[126:127], v[126:127], v[200:201]
	v_pk_fma_f32 v[0:1], v[112:113], v[122:123], v[0:1] neg_lo:[0,0,1] neg_hi:[0,0,1]
	v_pk_fma_f32 v[2:3], v[116:117], v[122:123], v[2:3]
	v_pk_fma_f32 v[106:107], v[122:123], v[8:9], v[12:13]
	v_pk_fma_f32 v[124:125], v[122:123], v[200:201], v[124:125] neg_lo:[0,0,1] neg_hi:[0,0,1]
	v_pk_fma_f32 v[122:123], v[122:123], v[196:197], v[126:127]
	v_mov_b32_e32 v126, v120
	v_mov_b32_e32 v127, v124
	v_mov_b32_e32 v124, v121
	v_mov_b32_e32 v120, v144
	v_mov_b32_e32 v121, v122
	v_mov_b32_e32 v122, v145
	v_pk_mul_f32 v[12:13], v[116:117], v[8:9]
	v_pk_mul_f32 v[14:15], v[116:117], v[4:5]
	ds_write2_b64 v187, v[120:121], v[122:123] offset0:4 offset1:6
	v_pk_mul_f32 v[120:121], v[116:117], v[242:243]
	v_pk_mul_f32 v[116:117], v[116:117], v[244:245]
	v_pk_fma_f32 v[12:13], v[112:113], v[4:5], v[12:13] neg_lo:[0,0,1] neg_hi:[0,0,1]
	v_pk_fma_f32 v[16:17], v[112:113], v[8:9], v[14:15]
	v_pk_mul_f32 v[14:15], v[8:9], v[118:119]
	v_pk_mul_f32 v[18:19], v[4:5], v[118:119]
	v_pk_fma_f32 v[120:121], v[112:113], v[244:245], v[120:121]
	v_pk_fma_f32 v[112:113], v[112:113], v[242:243], v[116:117] neg_lo:[0,0,1] neg_hi:[0,0,1]
	v_pk_mul_f32 v[116:117], v[118:119], v[192:193]
	v_pk_mul_f32 v[118:119], v[118:119], v[166:167]
	v_pk_fma_f32 v[14:15], v[4:5], v[114:115], v[14:15] neg_lo:[0,0,1] neg_hi:[0,0,1]
	v_pk_fma_f32 v[18:19], v[8:9], v[114:115], v[18:19]
	v_pk_add_f32 v[198:199], v[206:207], v[198:199] neg_lo:[0,1] neg_hi:[0,1]
	v_pk_fma_f32 v[116:117], v[114:115], v[166:167], v[116:117] neg_lo:[0,0,1] neg_hi:[0,0,1]
	v_pk_fma_f32 v[114:115], v[114:115], v[192:193], v[118:119]
	v_pk_add_f32 v[194:195], v[238:239], v[194:195] neg_lo:[0,1] neg_hi:[0,1]
	v_pk_add_f32 v[218:219], v[240:241], v[218:219] neg_lo:[0,1] neg_hi:[0,1]
	v_pk_add_f32 v[238:239], v[142:143], v[140:141]
	v_pk_add_f32 v[240:241], v[138:139], v[216:217] neg_lo:[0,1] neg_hi:[0,1]
	v_pk_add_f32 v[212:213], v[228:229], v[212:213] neg_lo:[0,1] neg_hi:[0,1]
	v_pk_add_f32 v[228:229], v[128:129], v[130:131]
	v_pk_add_f32 v[232:233], v[132:133], v[198:199] neg_lo:[0,1] neg_hi:[0,1]
	v_mov_b32_e32 v118, v112
	v_mov_b32_e32 v119, v116
	v_mov_b32_e32 v116, v113
	v_mov_b32_e32 v112, v120
	v_mov_b32_e32 v113, v114
	v_mov_b32_e32 v114, v121
	ds_write2_b64 v214, v[126:127], v[124:125] offset0:4 offset1:6
	ds_write2_b64 v214, v[118:119], v[116:117] offset0:8 offset1:10
	ds_write2_b64 v162, v[112:113], v[114:115] offset0:8 offset1:10
	v_pk_mul_f32 v[112:113], v[10:11], v[238:239]
	v_pk_mul_f32 v[114:115], v[10:11], v[240:241]
	v_pk_mul_f32 v[116:117], v[2:3], v[232:233]
	v_pk_mul_f32 v[118:119], v[2:3], v[228:229]
	v_pk_fma_f32 v[112:113], v[6:7], v[240:241], v[112:113]
	v_pk_fma_f32 v[114:115], v[6:7], v[238:239], v[114:115] neg_lo:[0,0,1] neg_hi:[0,0,1]
	v_pk_fma_f32 v[116:117], v[0:1], v[228:229], v[116:117] neg_lo:[0,0,1] neg_hi:[0,0,1]
	v_pk_fma_f32 v[118:119], v[0:1], v[232:233], v[118:119]
	v_pk_add_f32 v[206:207], v[230:231], v[234:235] neg_lo:[0,1] neg_hi:[0,1]
	v_mov_b32_e32 v120, v114
	v_mov_b32_e32 v121, v116
	v_mov_b32_e32 v116, v115
	v_mov_b32_e32 v114, v112
	v_mov_b32_e32 v115, v118
	v_mov_b32_e32 v118, v113
	ds_write2_b64 v214, v[120:121], v[116:117] offset0:12 offset1:14
	ds_write2_b64 v187, v[114:115], v[118:119] offset0:12 offset1:14
	v_pk_mul_f32 v[114:115], v[8:9], v[206:207]
	v_pk_mul_f32 v[116:117], v[110:111], v[164:165]
	v_pk_mul_f32 v[112:113], v[4:5], v[206:207]
	v_pk_fma_f32 v[114:115], v[4:5], v[134:135], v[114:115] neg_lo:[0,0,1] neg_hi:[0,0,1]
	v_pk_fma_f32 v[116:117], v[108:109], v[246:247], v[116:117] neg_lo:[0,0,1] neg_hi:[0,0,1]
	v_pk_mul_f32 v[110:111], v[110:111], v[246:247]
	v_pk_fma_f32 v[112:113], v[8:9], v[134:135], v[112:113]
	v_pk_fma_f32 v[108:109], v[108:109], v[164:165], v[110:111]
	v_mov_b32_e32 v110, v114
	v_mov_b32_e32 v111, v116
	v_mov_b32_e32 v116, v115
	ds_write2_b64 v214, v[110:111], v[116:117] offset0:16 offset1:18
	v_mov_b32_e32 v110, v112
	v_mov_b32_e32 v111, v108
	v_mov_b32_e32 v108, v113
	ds_write2_b64 v162, v[110:111], v[108:109] offset0:16 offset1:18
	v_pk_mul_f32 v[108:109], v[104:105], v[194:195]
	v_pk_mul_f32 v[104:105], v[104:105], v[218:219]
	v_pk_fma_f32 v[108:109], v[20:21], v[218:219], v[108:109]
	v_pk_fma_f32 v[20:21], v[20:21], v[194:195], v[104:105] neg_lo:[0,0,1] neg_hi:[0,0,1]
	v_pk_mul_f32 v[104:105], v[106:107], v[212:213]
	v_pk_mul_f32 v[106:107], v[106:107], v[136:137]
	v_pk_fma_f32 v[104:105], v[22:23], v[136:137], v[104:105] neg_lo:[0,0,1] neg_hi:[0,0,1]
	v_pk_fma_f32 v[22:23], v[22:23], v[212:213], v[106:107]
	v_mov_b32_e32 v106, v20
	v_mov_b32_e32 v107, v104
	v_mov_b32_e32 v104, v21
	v_mov_b32_e32 v20, v108
	v_mov_b32_e32 v21, v22
	v_mov_b32_e32 v22, v109
	ds_write2_b64 v187, v[20:21], v[22:23] offset0:20 offset1:22
	v_pk_mul_f32 v[20:21], v[16:17], v[202:203]
	v_pk_mul_f32 v[16:17], v[16:17], v[208:209]
	v_pk_fma_f32 v[20:21], v[12:13], v[208:209], v[20:21]
	v_pk_fma_f32 v[12:13], v[12:13], v[202:203], v[16:17] neg_lo:[0,0,1] neg_hi:[0,0,1]
	v_pk_mul_f32 v[16:17], v[18:19], v[188:189]
	v_pk_mul_f32 v[18:19], v[18:19], v[190:191]
	v_pk_fma_f32 v[16:17], v[14:15], v[190:191], v[16:17] neg_lo:[0,0,1] neg_hi:[0,0,1]
	v_pk_fma_f32 v[14:15], v[14:15], v[188:189], v[18:19]
	v_mov_b32_e32 v18, v12
	v_mov_b32_e32 v19, v16
	v_mov_b32_e32 v16, v13
	v_mov_b32_e32 v12, v20
	v_mov_b32_e32 v13, v14
	v_mov_b32_e32 v14, v21
	ds_write2_b64 v214, v[106:107], v[104:105] offset0:20 offset1:22
	ds_write2_b64 v214, v[18:19], v[16:17] offset0:24 offset1:26
	ds_write2_b64 v162, v[12:13], v[14:15] offset0:24 offset1:26
	v_pk_mul_f32 v[14:15], v[8:9], v[10:11]
	v_pk_mul_f32 v[10:11], v[4:5], v[10:11]
	v_pk_add_f32 v[12:13], v[138:139], v[216:217]
	v_pk_fma_f32 v[14:15], v[4:5], v[6:7], v[14:15] neg_lo:[0,0,1] neg_hi:[0,0,1]
	v_pk_add_f32 v[16:17], v[142:143], v[140:141] neg_lo:[0,1] neg_hi:[0,1]
	v_pk_fma_f32 v[6:7], v[8:9], v[6:7], v[10:11]
	v_mov_b32_e32 v134, v163
	v_pk_mul_f32 v[10:11], v[6:7], v[16:17]
	v_pk_mul_f32 v[6:7], v[6:7], v[12:13]
	v_pk_fma_f32 v[10:11], v[14:15], v[12:13], v[10:11]
	v_pk_fma_f32 v[6:7], v[14:15], v[16:17], v[6:7] neg_lo:[0,0,1] neg_hi:[0,0,1]
	v_pk_mul_f32 v[16:17], v[4:5], v[2:3]
	v_pk_add_f32 v[12:13], v[132:133], v[198:199]
	v_pk_fma_f32 v[16:17], v[8:9], v[0:1], v[16:17]
	v_pk_mul_f32 v[2:3], v[8:9], v[2:3]
	v_pk_add_f32 v[14:15], v[128:129], v[130:131] neg_lo:[0,1] neg_hi:[0,1]
	v_pk_fma_f32 v[0:1], v[4:5], v[0:1], v[2:3] neg_lo:[0,0,1] neg_hi:[0,0,1]
	v_pk_mul_f32 v[2:3], v[16:17], v[12:13]
	v_pk_mul_f32 v[4:5], v[16:17], v[14:15]
	v_pk_fma_f32 v[2:3], v[0:1], v[14:15], v[2:3] neg_lo:[0,0,1] neg_hi:[0,0,1]
	v_pk_fma_f32 v[0:1], v[0:1], v[12:13], v[4:5]
	v_mov_b32_e32 v4, v6
	v_mov_b32_e32 v5, v2
	v_mov_b32_e32 v2, v7
	ds_write2_b64 v214, v[4:5], v[2:3] offset0:28 offset1:30
	v_mov_b32_e32 v2, v10
	v_mov_b32_e32 v3, v0
	v_mov_b32_e32 v0, v11
	ds_write2_b64 v187, v[2:3], v[0:1] offset0:28 offset1:30
	s_waitcnt lgkmcnt(0)
	s_barrier
	s_nop 0
	s_nop 0
	v_lshlrev_b32_e32 v0, 3, v134
	v_ashrrev_i32_e32 v1, 31, v0
	v_lshlrev_b64 v[2:3], 2, v[0:1]
	v_lshl_add_u64 v[14:15], s[88:89], 0, v[2:3]
	v_lshl_add_u64 v[10:11], s[34:35], 0, v[2:3]
	global_load_dwordx4 v[2:5], v[10:11], off
	global_load_dwordx4 v[6:9], v[14:15], off
	s_nop 0
	global_load_dwordx4 v[10:13], v[10:11], off offset:16
	s_nop 0
	global_load_dwordx4 v[14:17], v[14:15], off offset:16
	v_ashrrev_i32_e32 v1, 3, v134
	v_and_b32_e32 v0, 56, v0
	v_mul_lo_u32 v1, v1, s49
	v_add_lshl_u32 v1, v1, v0, 2
	v_add_u32_e32 v135, 0, v1
	ds_read_b128 v[18:21], v135
	v_add_u32_e32 v1, s91, v1
	ds_read_b128 v[104:107], v1
	ds_read_b128 v[108:111], v135 offset:16
	ds_read_b128 v[112:115], v1 offset:16
	v_add_u32_e32 v136, 0x200, v134
	s_waitcnt lgkmcnt(3)
	v_pk_add_f32 v[22:23], v[18:19], v[20:21]
	v_pk_add_f32 v[118:119], v[18:19], v[20:21] neg_lo:[0,1] neg_hi:[0,1]
	v_lshlrev_b32_e32 v18, 3, v136
	v_ashrrev_i32_e32 v19, 31, v18
	v_lshlrev_b64 v[18:19], 2, v[18:19]
	s_waitcnt lgkmcnt(2)
	v_pk_add_f32 v[116:117], v[104:105], v[106:107]
	v_pk_add_f32 v[120:121], v[104:105], v[106:107] neg_lo:[0,1] neg_hi:[0,1]
	s_waitcnt lgkmcnt(0)
	v_pk_add_f32 v[124:125], v[112:113], v[114:115]
	v_pk_add_f32 v[128:129], v[112:113], v[114:115] neg_lo:[0,1] neg_hi:[0,1]
	v_lshl_add_u64 v[112:113], s[88:89], 0, v[18:19]
	v_lshl_add_u64 v[104:105], s[34:35], 0, v[18:19]
	v_pk_add_f32 v[122:123], v[108:109], v[110:111]
	v_pk_add_f32 v[126:127], v[108:109], v[110:111] neg_lo:[0,1] neg_hi:[0,1]
	global_load_dwordx4 v[18:21], v[104:105], off offset:16
	s_nop 0
	global_load_dwordx4 v[104:107], v[104:105], off
	s_nop 0
	global_load_dwordx4 v[108:111], v[112:113], off offset:16
	s_nop 0
	global_load_dwordx4 v[112:115], v[112:113], off
	v_pk_add_f32 v[130:131], v[22:23], v[122:123]
	v_pk_add_f32 v[132:133], v[116:117], v[124:125]
	v_pk_add_f32 v[22:23], v[22:23], v[122:123] neg_lo:[0,1] neg_hi:[0,1]
	v_pk_add_f32 v[116:117], v[116:117], v[124:125] neg_lo:[0,1] neg_hi:[0,1]
	v_pk_add_f32 v[124:125], v[120:121], v[126:127] neg_lo:[0,1] neg_hi:[0,1]
	v_pk_add_f32 v[120:121], v[126:127], v[120:121]
	v_pk_add_f32 v[122:123], v[118:119], v[128:129]
	v_pk_add_f32 v[118:119], v[118:119], v[128:129] neg_lo:[0,1] neg_hi:[0,1]
	s_waitcnt vmcnt(7)
	v_pk_mul_f32 v[126:127], v[132:133], v[2:3]
	v_pk_mul_f32 v[2:3], v[130:131], v[2:3]
	s_waitcnt vmcnt(6)
	v_pk_fma_f32 v[126:127], v[130:131], v[6:7], v[126:127] neg_lo:[0,0,1] neg_hi:[0,0,1]
	v_pk_fma_f32 v[2:3], v[6:7], v[132:133], v[2:3]
	v_pk_mul_f32 v[6:7], v[116:117], v[4:5]
	v_pk_mul_f32 v[4:5], v[22:23], v[4:5]
	v_pk_fma_f32 v[6:7], v[22:23], v[8:9], v[6:7] neg_lo:[0,0,1] neg_hi:[0,0,1]
	v_pk_fma_f32 v[4:5], v[8:9], v[116:117], v[4:5]
	s_waitcnt vmcnt(5)
	v_pk_mul_f32 v[8:9], v[124:125], v[10:11]
	v_pk_mul_f32 v[10:11], v[122:123], v[10:11]
	s_waitcnt vmcnt(4)
	v_pk_fma_f32 v[8:9], v[122:123], v[14:15], v[8:9] neg_lo:[0,0,1] neg_hi:[0,0,1]
	v_pk_fma_f32 v[10:11], v[124:125], v[14:15], v[10:11]
	v_pk_mul_f32 v[14:15], v[120:121], v[12:13]
	v_pk_mul_f32 v[12:13], v[118:119], v[12:13]
	v_pk_fma_f32 v[14:15], v[118:119], v[16:17], v[14:15] neg_lo:[0,0,1] neg_hi:[0,0,1]
	v_pk_fma_f32 v[12:13], v[120:121], v[16:17], v[12:13]
	v_pk_add_f32 v[16:17], v[126:127], v[6:7]
	v_pk_add_f32 v[22:23], v[2:3], v[4:5]
	v_pk_add_f32 v[118:119], v[2:3], v[4:5] neg_lo:[0,1] neg_hi:[0,1]
	v_pk_add_f32 v[4:5], v[8:9], v[14:15]
	v_pk_add_f32 v[116:117], v[126:127], v[6:7] neg_lo:[0,1] neg_hi:[0,1]
	v_pk_add_f32 v[120:121], v[10:11], v[12:13]
	v_pk_add_f32 v[122:123], v[8:9], v[14:15] neg_lo:[0,1] neg_hi:[0,1]
	v_pk_add_f32 v[12:13], v[10:11], v[12:13] neg_lo:[0,1] neg_hi:[0,1]
	v_pk_add_f32 v[2:3], v[16:17], v[4:5]
	v_pk_add_f32 v[4:5], v[16:17], v[4:5] neg_lo:[0,1] neg_hi:[0,1]
	v_pk_add_f32 v[6:7], v[22:23], v[120:121]
	v_pk_add_f32 v[8:9], v[22:23], v[120:121] neg_lo:[0,1] neg_hi:[0,1]
	v_pk_add_f32 v[10:11], v[116:117], v[12:13] neg_lo:[0,1] neg_hi:[0,1]
	v_pk_add_f32 v[14:15], v[118:119], v[122:123]
	v_pk_add_f32 v[12:13], v[116:117], v[12:13]
	v_pk_add_f32 v[16:17], v[118:119], v[122:123] neg_lo:[0,1] neg_hi:[0,1]
	ds_write_b128 v135, v[2:5]
	ds_write_b128 v135, v[10:13] offset:16
	ds_write_b128 v1, v[6:9]
	ds_write_b128 v1, v[14:17] offset:16
	v_ashrrev_i32_e32 v1, 3, v136
	v_mul_lo_u32 v1, v1, s49
	v_add_lshl_u32 v1, v1, v0, 2
	v_add_u32_e32 v135, 0, v1
	ds_read_b128 v[2:5], v135
	v_add_u32_e32 v1, s91, v1
	ds_read_b128 v[6:9], v1
	ds_read_b128 v[10:13], v135 offset:16
	ds_read_b128 v[14:17], v1 offset:16
	v_add_u32_e32 v136, 0x400, v134
	v_add_u32_e32 v134, 0x600, v134
	s_waitcnt lgkmcnt(3)
	v_pk_add_f32 v[22:23], v[2:3], v[4:5]
	v_pk_add_f32 v[118:119], v[2:3], v[4:5] neg_lo:[0,1] neg_hi:[0,1]
	v_lshlrev_b32_e32 v2, 3, v136
	v_ashrrev_i32_e32 v3, 31, v2
	v_lshlrev_b64 v[2:3], 2, v[2:3]
	s_waitcnt lgkmcnt(2)
	v_pk_add_f32 v[116:117], v[6:7], v[8:9]
	v_pk_add_f32 v[120:121], v[6:7], v[8:9] neg_lo:[0,1] neg_hi:[0,1]
	s_waitcnt lgkmcnt(0)
	v_pk_add_f32 v[124:125], v[14:15], v[16:17]
	v_pk_add_f32 v[128:129], v[14:15], v[16:17] neg_lo:[0,1] neg_hi:[0,1]
	v_lshl_add_u64 v[14:15], s[88:89], 0, v[2:3]
	v_lshl_add_u64 v[6:7], s[34:35], 0, v[2:3]
	v_pk_add_f32 v[122:123], v[10:11], v[12:13]
	v_pk_add_f32 v[126:127], v[10:11], v[12:13] neg_lo:[0,1] neg_hi:[0,1]
	global_load_dwordx4 v[2:5], v[6:7], off offset:16
	s_nop 0
	global_load_dwordx4 v[6:9], v[6:7], off
	s_nop 0
	global_load_dwordx4 v[10:13], v[14:15], off offset:16
	s_nop 0
	global_load_dwordx4 v[14:17], v[14:15], off
	v_pk_add_f32 v[130:131], v[22:23], v[122:123]
	v_pk_add_f32 v[132:133], v[116:117], v[124:125]
	v_pk_add_f32 v[116:117], v[116:117], v[124:125] neg_lo:[0,1] neg_hi:[0,1]
	v_pk_add_f32 v[124:125], v[120:121], v[126:127] neg_lo:[0,1] neg_hi:[0,1]
	v_pk_add_f32 v[120:121], v[126:127], v[120:121]
	s_waitcnt vmcnt(6)
	v_pk_mul_f32 v[126:127], v[132:133], v[104:105]
	v_pk_mul_f32 v[104:105], v[130:131], v[104:105]
	v_pk_add_f32 v[22:23], v[22:23], v[122:123] neg_lo:[0,1] neg_hi:[0,1]
	v_pk_add_f32 v[122:123], v[118:119], v[128:129]
	s_waitcnt vmcnt(4)
	v_pk_fma_f32 v[126:127], v[130:131], v[112:113], v[126:127] neg_lo:[0,0,1] neg_hi:[0,0,1]
	v_pk_fma_f32 v[104:105], v[112:113], v[132:133], v[104:105]
	v_pk_mul_f32 v[112:113], v[116:117], v[106:107]
	v_pk_add_f32 v[118:119], v[118:119], v[128:129] neg_lo:[0,1] neg_hi:[0,1]
	v_pk_fma_f32 v[112:113], v[22:23], v[114:115], v[112:113] neg_lo:[0,0,1] neg_hi:[0,0,1]
	v_pk_mul_f32 v[22:23], v[22:23], v[106:107]
	v_pk_mul_f32 v[106:107], v[124:125], v[18:19]
	v_pk_mul_f32 v[18:19], v[122:123], v[18:19]
	v_pk_fma_f32 v[106:107], v[122:123], v[108:109], v[106:107] neg_lo:[0,0,1] neg_hi:[0,0,1]
	v_pk_fma_f32 v[18:19], v[124:125], v[108:109], v[18:19]
	v_pk_mul_f32 v[108:109], v[120:121], v[20:21]
	v_pk_mul_f32 v[20:21], v[118:119], v[20:21]
	v_pk_fma_f32 v[108:109], v[118:119], v[110:111], v[108:109] neg_lo:[0,0,1] neg_hi:[0,0,1]
	v_pk_fma_f32 v[22:23], v[114:115], v[116:117], v[22:23]
	v_pk_fma_f32 v[20:21], v[120:121], v[110:111], v[20:21]
	v_pk_add_f32 v[110:111], v[126:127], v[112:113]
	v_pk_add_f32 v[116:117], v[126:127], v[112:113] neg_lo:[0,1] neg_hi:[0,1]
	v_pk_add_f32 v[112:113], v[106:107], v[108:109]
	v_pk_add_f32 v[114:115], v[104:105], v[22:23]
	v_pk_add_f32 v[22:23], v[104:105], v[22:23] neg_lo:[0,1] neg_hi:[0,1]
	v_pk_add_f32 v[118:119], v[18:19], v[20:21]
	v_pk_add_f32 v[120:121], v[106:107], v[108:109] neg_lo:[0,1] neg_hi:[0,1]
	v_pk_add_f32 v[122:123], v[18:19], v[20:21] neg_lo:[0,1] neg_hi:[0,1]
	v_pk_add_f32 v[18:19], v[110:111], v[112:113]
	v_pk_add_f32 v[20:21], v[110:111], v[112:113] neg_lo:[0,1] neg_hi:[0,1]
	v_pk_add_f32 v[104:105], v[114:115], v[118:119]
	v_pk_add_f32 v[106:107], v[114:115], v[118:119] neg_lo:[0,1] neg_hi:[0,1]
	v_pk_add_f32 v[108:109], v[116:117], v[122:123] neg_lo:[0,1] neg_hi:[0,1]
	v_pk_add_f32 v[112:113], v[22:23], v[120:121]
	v_pk_add_f32 v[110:111], v[116:117], v[122:123]
	v_pk_add_f32 v[114:115], v[22:23], v[120:121] neg_lo:[0,1] neg_hi:[0,1]
	ds_write_b128 v135, v[18:21]
	ds_write_b128 v135, v[108:111] offset:16
	ds_write_b128 v1, v[104:107]
	ds_write_b128 v1, v[112:115] offset:16
	v_ashrrev_i32_e32 v1, 3, v136
	v_lshlrev_b32_e32 v22, 3, v134
	v_mul_lo_u32 v1, v1, s49
	v_ashrrev_i32_e32 v23, 31, v22
	v_add_lshl_u32 v1, v1, v0, 2
	v_lshlrev_b64 v[22:23], 2, v[22:23]
	v_add_u32_e32 v135, 0, v1
	v_add_u32_e32 v1, s91, v1
	v_lshl_add_u64 v[128:129], s[88:89], 0, v[22:23]
	v_lshl_add_u64 v[22:23], s[34:35], 0, v[22:23]
	ds_read_b128 v[18:21], v135
	ds_read_b128 v[104:107], v135 offset:16
	ds_read_b128 v[108:111], v1
	ds_read_b128 v[112:115], v1 offset:16
	global_load_dwordx4 v[116:119], v[22:23], off offset:16
	global_load_dwordx4 v[120:123], v[22:23], off
	global_load_dwordx4 v[124:127], v[128:129], off offset:16
	s_nop 0
	global_load_dwordx4 v[128:131], v[128:129], off
	s_waitcnt lgkmcnt(3)
	v_pk_add_f32 v[22:23], v[18:19], v[20:21]
	s_waitcnt lgkmcnt(1)
	v_pk_add_f32 v[132:133], v[108:109], v[110:111]
	v_pk_add_f32 v[18:19], v[18:19], v[20:21] neg_lo:[0,1] neg_hi:[0,1]
	v_pk_add_f32 v[20:21], v[108:109], v[110:111] neg_lo:[0,1] neg_hi:[0,1]
	v_pk_add_f32 v[108:109], v[104:105], v[106:107]
	s_waitcnt lgkmcnt(0)
	v_pk_add_f32 v[110:111], v[112:113], v[114:115]
	v_pk_add_f32 v[104:105], v[104:105], v[106:107] neg_lo:[0,1] neg_hi:[0,1]
	v_pk_add_f32 v[106:107], v[112:113], v[114:115] neg_lo:[0,1] neg_hi:[0,1]
	v_pk_add_f32 v[112:113], v[22:23], v[108:109]
	v_pk_add_f32 v[114:115], v[132:133], v[110:111]
	v_pk_add_f32 v[22:23], v[22:23], v[108:109] neg_lo:[0,1] neg_hi:[0,1]
	v_pk_add_f32 v[108:109], v[132:133], v[110:111] neg_lo:[0,1] neg_hi:[0,1]
	v_pk_add_f32 v[132:133], v[20:21], v[104:105] neg_lo:[0,1] neg_hi:[0,1]
	v_pk_add_f32 v[20:21], v[104:105], v[20:21]
	v_pk_add_f32 v[110:111], v[18:19], v[106:107]
	v_pk_add_f32 v[18:19], v[18:19], v[106:107] neg_lo:[0,1] neg_hi:[0,1]
	s_waitcnt vmcnt(6)
	v_pk_mul_f32 v[104:105], v[114:115], v[6:7]
	v_pk_mul_f32 v[6:7], v[112:113], v[6:7]
	s_waitcnt vmcnt(4)
	v_pk_fma_f32 v[104:105], v[112:113], v[14:15], v[104:105] neg_lo:[0,0,1] neg_hi:[0,0,1]
	v_pk_fma_f32 v[6:7], v[14:15], v[114:115], v[6:7]
	v_pk_mul_f32 v[14:15], v[108:109], v[8:9]
	v_pk_mul_f32 v[8:9], v[22:23], v[8:9]
	v_pk_fma_f32 v[14:15], v[22:23], v[16:17], v[14:15] neg_lo:[0,0,1] neg_hi:[0,0,1]
	v_pk_fma_f32 v[8:9], v[16:17], v[108:109], v[8:9]
	v_pk_mul_f32 v[16:17], v[132:133], v[2:3]
	v_pk_mul_f32 v[2:3], v[110:111], v[2:3]
	v_pk_fma_f32 v[16:17], v[110:111], v[10:11], v[16:17] neg_lo:[0,0,1] neg_hi:[0,0,1]
	v_pk_fma_f32 v[2:3], v[132:133], v[10:11], v[2:3]
	v_pk_mul_f32 v[10:11], v[20:21], v[4:5]
	v_pk_mul_f32 v[4:5], v[18:19], v[4:5]
	v_pk_fma_f32 v[10:11], v[18:19], v[12:13], v[10:11] neg_lo:[0,0,1] neg_hi:[0,0,1]
	v_pk_fma_f32 v[4:5], v[20:21], v[12:13], v[4:5]
	v_pk_add_f32 v[12:13], v[104:105], v[14:15]
	v_pk_add_f32 v[18:19], v[6:7], v[8:9]
	v_pk_add_f32 v[22:23], v[6:7], v[8:9] neg_lo:[0,1] neg_hi:[0,1]
	v_pk_add_f32 v[8:9], v[16:17], v[10:11]
	v_pk_add_f32 v[20:21], v[104:105], v[14:15] neg_lo:[0,1] neg_hi:[0,1]
	v_pk_add_f32 v[14:15], v[2:3], v[4:5]
	v_pk_add_f32 v[16:17], v[16:17], v[10:11] neg_lo:[0,1] neg_hi:[0,1]
	v_pk_add_f32 v[104:105], v[2:3], v[4:5] neg_lo:[0,1] neg_hi:[0,1]
	v_pk_add_f32 v[2:3], v[12:13], v[8:9]
	v_pk_add_f32 v[4:5], v[12:13], v[8:9] neg_lo:[0,1] neg_hi:[0,1]
	v_pk_add_f32 v[6:7], v[18:19], v[14:15]
	v_pk_add_f32 v[8:9], v[18:19], v[14:15] neg_lo:[0,1] neg_hi:[0,1]
	v_pk_add_f32 v[10:11], v[20:21], v[104:105] neg_lo:[0,1] neg_hi:[0,1]
	v_pk_add_f32 v[14:15], v[22:23], v[16:17]
	v_pk_add_f32 v[12:13], v[20:21], v[104:105]
	v_pk_add_f32 v[16:17], v[22:23], v[16:17] neg_lo:[0,1] neg_hi:[0,1]
	ds_write_b128 v135, v[2:5]
	ds_write_b128 v135, v[10:13] offset:16
	ds_write_b128 v1, v[6:9]
	ds_write_b128 v1, v[14:17] offset:16
	v_ashrrev_i32_e32 v1, 3, v134
	v_mul_lo_u32 v1, v1, s49
	v_add_lshl_u32 v4, v1, v0, 2
	v_add_u32_e32 v104, 0, v4
	v_add_u32_e32 v105, s91, v4
	ds_read_b128 v[0:3], v104
	ds_read_b128 v[4:7], v105
	ds_read_b128 v[8:11], v104 offset:16
	ds_read_b128 v[12:15], v105 offset:16
	s_waitcnt lgkmcnt(2)
	v_pk_add_f32 v[18:19], v[4:5], v[6:7]
	v_pk_add_f32 v[16:17], v[0:1], v[2:3]
	v_pk_add_f32 v[0:1], v[0:1], v[2:3] neg_lo:[0,1] neg_hi:[0,1]
	v_pk_add_f32 v[2:3], v[4:5], v[6:7] neg_lo:[0,1] neg_hi:[0,1]
	s_waitcnt lgkmcnt(0)
	v_pk_add_f32 v[6:7], v[12:13], v[14:15]
	v_pk_add_f32 v[4:5], v[8:9], v[10:11]
	v_pk_add_f32 v[8:9], v[8:9], v[10:11] neg_lo:[0,1] neg_hi:[0,1]
	v_pk_add_f32 v[10:11], v[12:13], v[14:15] neg_lo:[0,1] neg_hi:[0,1]
	v_pk_add_f32 v[14:15], v[18:19], v[6:7]
	v_pk_add_f32 v[12:13], v[16:17], v[4:5]
	v_pk_add_f32 v[6:7], v[18:19], v[6:7] neg_lo:[0,1] neg_hi:[0,1]
	v_pk_add_f32 v[18:19], v[2:3], v[8:9] neg_lo:[0,1] neg_hi:[0,1]
	v_pk_add_f32 v[2:3], v[8:9], v[2:3]
	s_waitcnt vmcnt(2)
	v_pk_mul_f32 v[8:9], v[14:15], v[120:121]
	v_pk_add_f32 v[4:5], v[16:17], v[4:5] neg_lo:[0,1] neg_hi:[0,1]
	v_pk_add_f32 v[16:17], v[0:1], v[10:11]
	v_pk_add_f32 v[0:1], v[0:1], v[10:11] neg_lo:[0,1] neg_hi:[0,1]
	s_waitcnt vmcnt(0)
	v_pk_fma_f32 v[8:9], v[12:13], v[128:129], v[8:9] neg_lo:[0,0,1] neg_hi:[0,0,1]
	v_pk_mul_f32 v[10:11], v[12:13], v[120:121]
	v_pk_mul_f32 v[12:13], v[6:7], v[122:123]
	v_pk_fma_f32 v[10:11], v[128:129], v[14:15], v[10:11]
	v_pk_fma_f32 v[12:13], v[4:5], v[130:131], v[12:13] neg_lo:[0,0,1] neg_hi:[0,0,1]
	v_pk_mul_f32 v[4:5], v[4:5], v[122:123]
	v_pk_mul_f32 v[14:15], v[16:17], v[116:117]
	v_pk_fma_f32 v[4:5], v[130:131], v[6:7], v[4:5]
	v_pk_mul_f32 v[6:7], v[18:19], v[116:117]
	v_pk_fma_f32 v[14:15], v[18:19], v[124:125], v[14:15]
	v_pk_fma_f32 v[6:7], v[16:17], v[124:125], v[6:7] neg_lo:[0,0,1] neg_hi:[0,0,1]
	v_pk_mul_f32 v[16:17], v[2:3], v[118:119]
	v_pk_add_f32 v[20:21], v[8:9], v[12:13] neg_lo:[0,1] neg_hi:[0,1]
	v_pk_fma_f32 v[16:17], v[0:1], v[126:127], v[16:17] neg_lo:[0,0,1] neg_hi:[0,0,1]
	v_pk_mul_f32 v[0:1], v[0:1], v[118:119]
	v_pk_add_f32 v[18:19], v[10:11], v[4:5]
	v_pk_fma_f32 v[0:1], v[2:3], v[126:127], v[0:1]
	v_pk_add_f32 v[2:3], v[8:9], v[12:13]
	v_pk_add_f32 v[8:9], v[6:7], v[16:17]
	v_pk_add_f32 v[22:23], v[10:11], v[4:5] neg_lo:[0,1] neg_hi:[0,1]
	v_pk_add_f32 v[10:11], v[14:15], v[0:1]
	v_pk_add_f32 v[16:17], v[6:7], v[16:17] neg_lo:[0,1] neg_hi:[0,1]
	v_pk_add_f32 v[14:15], v[14:15], v[0:1] neg_lo:[0,1] neg_hi:[0,1]
	v_pk_add_f32 v[0:1], v[2:3], v[8:9]
	v_pk_add_f32 v[2:3], v[2:3], v[8:9] neg_lo:[0,1] neg_hi:[0,1]
	v_pk_add_f32 v[4:5], v[18:19], v[10:11]
	v_pk_add_f32 v[6:7], v[18:19], v[10:11] neg_lo:[0,1] neg_hi:[0,1]
	v_pk_add_f32 v[8:9], v[20:21], v[14:15] neg_lo:[0,1] neg_hi:[0,1]
	v_pk_add_f32 v[12:13], v[22:23], v[16:17]
	v_pk_add_f32 v[10:11], v[20:21], v[14:15]
	v_pk_add_f32 v[14:15], v[22:23], v[16:17] neg_lo:[0,1] neg_hi:[0,1]
	ds_write_b128 v104, v[0:3]
	ds_write_b128 v104, v[8:11] offset:16
	ds_write_b128 v105, v[4:7]
	ds_write_b128 v105, v[12:15] offset:16
	v_mov_b32_e32 v0, v163
	s_waitcnt lgkmcnt(0)
	s_barrier
	s_nop 0
	s_nop 0
	v_lshlrev_b32_e32 v1, 1, v0
	v_and_b32_e32 v162, 2, v1
	v_lshrrev_b32_e32 v1, 31, v0
	v_add_u32_e32 v0, v0, v1
	v_ashrrev_i32_e32 v187, 1, v0
	v_mul_lo_u32 v0, v187, s49
	v_or_b32_e32 v0, v0, v162
	v_lshlrev_b32_e32 v0, 2, v0
	v_add_u32_e32 v136, 0, v0
	v_add_u32_e32 v140, s91, v0
	ds_read2_b64 v[0:3], v136 offset1:2
	ds_read2_b64 v[8:11], v136 offset0:4 offset1:6
	ds_read2_b64 v[4:7], v140 offset1:2
	ds_read2_b64 v[12:15], v140 offset0:4 offset1:6
	ds_read2_b64 v[16:19], v136 offset0:8 offset1:10
	ds_read2_b64 v[20:23], v140 offset0:8 offset1:10
	ds_read2_b64 v[104:107], v136 offset0:12 offset1:14
	ds_read2_b64 v[108:111], v140 offset0:12 offset1:14
	ds_read2_b64 v[112:115], v136 offset0:16 offset1:18
	ds_read2_b64 v[116:119], v136 offset0:20 offset1:22
	ds_read2_b64 v[120:123], v140 offset0:16 offset1:18
	ds_read2_b64 v[124:127], v140 offset0:20 offset1:22
	ds_read2_b64 v[128:131], v136 offset0:24 offset1:26
	ds_read2_b64 v[132:135], v140 offset0:24 offset1:26
	ds_read2_b64 v[136:139], v136 offset0:28 offset1:30
	ds_read2_b64 v[140:143], v140 offset0:28 offset1:30
	s_waitcnt lgkmcnt(3)
	v_mov_b32_e32 v218, v129
	v_mov_b32_e32 v219, v131
	s_waitcnt lgkmcnt(1)
	v_mov_b32_e32 v210, v137
	s_waitcnt lgkmcnt(0)
	v_mov_b32_e32 v145, v143
	v_or_b32_e32 v143, 1, v162
	v_mov_b32_e32 v144, v141
	v_cvt_f32_ubyte0_e32 v141, v162
	v_cvt_f32_ubyte0_e32 v143, v143
	v_mul_f32_e32 v141, 0x3c800000, v141
	v_mul_f32_e32 v143, 0x3c800000, v143
	v_cos_f32_e32 v164, v141
	v_cos_f32_e32 v165, v143
	v_sin_f32_e64 v166, -v141
	v_sin_f32_e64 v167, -v143
	v_mov_b32_e32 v211, v139
	v_mov_b32_e32 v141, v142
	v_mov_b32_e32 v137, v138
	v_pk_mul_f32 v[188:189], v[166:167], v[166:167]
	v_pk_mul_f32 v[190:191], v[164:165], v[166:167]
	v_pk_fma_f32 v[188:189], v[164:165], v[164:165], v[188:189] neg_lo:[0,0,1] neg_hi:[0,0,1]
	v_pk_add_f32 v[190:191], v[190:191], v[190:191]
	v_pk_mul_f32 v[200:201], v[166:167], v[188:189]
	v_pk_mul_f32 v[192:193], v[190:191], v[190:191]
	v_pk_mul_f32 v[194:195], v[188:189], v[190:191]
	v_pk_fma_f32 v[192:193], v[188:189], v[188:189], v[192:193] neg_lo:[0,0,1] neg_hi:[0,0,1]
	v_pk_add_f32 v[194:195], v[194:195], v[194:195]
	v_pk_mul_f32 v[198:199], v[166:167], v[190:191]
	v_pk_fma_f32 v[200:201], v[164:165], v[190:191], v[200:201]
	v_pk_mul_f32 v[196:197], v[194:195], v[194:195]
	v_pk_fma_f32 v[198:199], v[164:165], v[188:189], v[198:199] neg_lo:[0,0,1] neg_hi:[0,0,1]
	v_pk_mul_f32 v[206:207], v[192:193], v[200:201]
	v_pk_fma_f32 v[196:197], v[192:193], v[192:193], v[196:197] neg_lo:[0,0,1] neg_hi:[0,0,1]
	v_pk_mul_f32 v[202:203], v[194:195], v[200:201]
	v_pk_mul_f32 v[204:205], v[192:193], v[194:195]
	v_pk_fma_f32 v[206:207], v[194:195], v[198:199], v[206:207]
	v_pk_fma_f32 v[202:203], v[192:193], v[198:199], v[202:203] neg_lo:[0,0,1] neg_hi:[0,0,1]
	v_pk_add_f32 v[204:205], v[204:205], v[204:205]
	v_pk_mul_f32 v[212:213], v[196:197], v[206:207]
	v_pk_mul_f32 v[208:209], v[204:205], v[206:207]
	v_pk_fma_f32 v[212:213], v[204:205], v[202:203], v[212:213]
	v_pk_fma_f32 v[208:209], v[196:197], v[202:203], v[208:209] neg_lo:[0,0,1] neg_hi:[0,0,1]
	v_pk_mul_f32 v[214:215], v[212:213], v[210:211]
	v_pk_mul_f32 v[142:143], v[190:191], v[194:195]
	v_pk_fma_f32 v[214:215], v[208:209], v[144:145], v[214:215] neg_lo:[0,0,1] neg_hi:[0,0,1]
	v_pk_mul_f32 v[144:145], v[212:213], v[144:145]
	v_pk_fma_f32 v[142:143], v[188:189], v[192:193], v[142:143] neg_lo:[0,0,1] neg_hi:[0,0,1]
	v_pk_fma_f32 v[144:145], v[208:209], v[210:211], v[144:145]
	v_pk_mul_f32 v[208:209], v[190:191], v[192:193]
	v_mov_b32_e32 v129, v130
	v_pk_fma_f32 v[208:209], v[188:189], v[194:195], v[208:209]
	v_pk_mul_f32 v[130:131], v[194:195], v[196:197]
	v_pk_mul_f32 v[138:139], v[196:197], v[208:209]
	v_pk_mul_f32 v[210:211], v[204:205], v[208:209]
	v_pk_fma_f32 v[138:139], v[204:205], v[142:143], v[138:139]
	v_pk_fma_f32 v[210:211], v[196:197], v[142:143], v[210:211] neg_lo:[0,0,1] neg_hi:[0,0,1]
	v_pk_mul_f32 v[212:213], v[138:139], v[136:137]
	v_pk_mul_f32 v[138:139], v[138:139], v[140:141]
	v_pk_fma_f32 v[212:213], v[210:211], v[140:141], v[212:213] neg_lo:[0,0,1] neg_hi:[0,0,1]
	v_pk_fma_f32 v[136:137], v[210:211], v[136:137], v[138:139]
	v_pk_mul_f32 v[210:211], v[166:167], v[192:193]
	v_pk_mul_f32 v[140:141], v[166:167], v[194:195]
	v_pk_fma_f32 v[210:211], v[164:165], v[194:195], v[210:211]
	v_pk_fma_f32 v[140:141], v[164:165], v[192:193], v[140:141] neg_lo:[0,0,1] neg_hi:[0,0,1]
	v_pk_mul_f32 v[220:221], v[196:197], v[210:211]
	v_pk_mul_f32 v[216:217], v[204:205], v[210:211]
	v_pk_fma_f32 v[220:221], v[204:205], v[140:141], v[220:221]
	v_mov_b32_e32 v138, v133
	v_mov_b32_e32 v139, v135
	v_pk_fma_f32 v[216:217], v[196:197], v[140:141], v[216:217] neg_lo:[0,0,1] neg_hi:[0,0,1]
	v_pk_mul_f32 v[222:223], v[220:221], v[218:219]
	v_mov_b32_e32 v133, v134
	v_pk_fma_f32 v[222:223], v[216:217], v[138:139], v[222:223] neg_lo:[0,0,1] neg_hi:[0,0,1]
	v_pk_mul_f32 v[138:139], v[220:221], v[138:139]
	v_pk_mul_f32 v[134:135], v[194:195], v[204:205]
	v_pk_fma_f32 v[130:131], v[192:193], v[204:205], v[130:131]
	v_pk_fma_f32 v[138:139], v[216:217], v[218:219], v[138:139]
	v_pk_fma_f32 v[134:135], v[192:193], v[196:197], v[134:135] neg_lo:[0,0,1] neg_hi:[0,0,1]
	v_pk_mul_f32 v[216:217], v[130:131], v[128:129]
	v_pk_mul_f32 v[130:131], v[130:131], v[132:133]
	v_pk_mul_f32 v[218:219], v[200:201], v[196:197]
	v_pk_fma_f32 v[216:217], v[134:135], v[132:133], v[216:217] neg_lo:[0,0,1] neg_hi:[0,0,1]
	v_pk_fma_f32 v[128:129], v[134:135], v[128:129], v[130:131]
	v_pk_mul_f32 v[132:133], v[200:201], v[204:205]
	v_mov_b32_e32 v134, v117
	v_mov_b32_e32 v135, v119
	v_pk_fma_f32 v[218:219], v[198:199], v[204:205], v[218:219]
	v_mov_b32_e32 v130, v125
	v_mov_b32_e32 v131, v127
	v_pk_fma_f32 v[132:133], v[198:199], v[196:197], v[132:133] neg_lo:[0,0,1] neg_hi:[0,0,1]
	v_pk_mul_f32 v[220:221], v[218:219], v[134:135]
	v_mov_b32_e32 v117, v118
	v_pk_mul_f32 v[118:119], v[190:191], v[196:197]
	v_pk_fma_f32 v[220:221], v[132:133], v[130:131], v[220:221] neg_lo:[0,0,1] neg_hi:[0,0,1]
	v_pk_mul_f32 v[130:131], v[218:219], v[130:131]
	v_mov_b32_e32 v125, v126
	v_pk_mul_f32 v[126:127], v[190:191], v[204:205]
	v_pk_fma_f32 v[118:119], v[188:189], v[204:205], v[118:119]
	v_pk_fma_f32 v[130:131], v[132:133], v[134:135], v[130:131]
	v_pk_fma_f32 v[126:127], v[188:189], v[196:197], v[126:127] neg_lo:[0,0,1] neg_hi:[0,0,1]
	v_pk_mul_f32 v[132:133], v[118:119], v[116:117]
	v_pk_mul_f32 v[118:119], v[118:119], v[124:125]
	v_pk_mul_f32 v[134:135], v[166:167], v[196:197]
	v_pk_fma_f32 v[132:133], v[126:127], v[124:125], v[132:133] neg_lo:[0,0,1] neg_hi:[0,0,1]
	v_pk_fma_f32 v[116:117], v[126:127], v[116:117], v[118:119]
	v_pk_mul_f32 v[124:125], v[166:167], v[204:205]
	v_mov_b32_e32 v126, v113
	v_mov_b32_e32 v127, v115
	v_pk_fma_f32 v[134:135], v[164:165], v[204:205], v[134:135]
	v_mov_b32_e32 v113, v114
	v_mov_b32_e32 v118, v121
	v_mov_b32_e32 v119, v123
	v_pk_fma_f32 v[124:125], v[164:165], v[196:197], v[124:125] neg_lo:[0,0,1] neg_hi:[0,0,1]
	v_pk_mul_f32 v[218:219], v[134:135], v[126:127]
	v_mov_b32_e32 v121, v122
	v_pk_mul_f32 v[114:115], v[204:205], v[112:113]
	v_pk_fma_f32 v[218:219], v[124:125], v[118:119], v[218:219] neg_lo:[0,0,1] neg_hi:[0,0,1]
	v_pk_mul_f32 v[118:119], v[134:135], v[118:119]
	v_pk_fma_f32 v[114:115], v[196:197], v[120:121], v[114:115] neg_lo:[0,0,1] neg_hi:[0,0,1]
	v_pk_mul_f32 v[120:121], v[204:205], v[120:121]
	v_mov_b32_e32 v122, v105
	v_mov_b32_e32 v123, v107
	v_mov_b32_e32 v105, v106
	v_pk_fma_f32 v[118:119], v[124:125], v[126:127], v[118:119]
	v_pk_fma_f32 v[112:113], v[196:197], v[112:113], v[120:121]
	v_mov_b32_e32 v120, v109
	v_mov_b32_e32 v121, v111
	v_pk_mul_f32 v[124:125], v[206:207], v[122:123]
	v_mov_b32_e32 v109, v110
	v_pk_mul_f32 v[106:107], v[208:209], v[104:105]
	v_pk_fma_f32 v[124:125], v[202:203], v[120:121], v[124:125] neg_lo:[0,0,1] neg_hi:[0,0,1]
	v_pk_mul_f32 v[120:121], v[206:207], v[120:121]
	v_pk_fma_f32 v[106:107], v[142:143], v[108:109], v[106:107] neg_lo:[0,0,1] neg_hi:[0,0,1]
	v_pk_mul_f32 v[108:109], v[208:209], v[108:109]
	v_mov_b32_e32 v110, v17
	v_mov_b32_e32 v111, v19
	v_mov_b32_e32 v17, v18
	v_pk_fma_f32 v[120:121], v[202:203], v[122:123], v[120:121]
	v_pk_fma_f32 v[104:105], v[142:143], v[104:105], v[108:109]
	v_mov_b32_e32 v108, v21
	v_mov_b32_e32 v109, v23
	v_pk_mul_f32 v[122:123], v[110:111], v[210:211]
	v_mov_b32_e32 v21, v22
	v_pk_mul_f32 v[18:19], v[16:17], v[194:195]
	v_pk_fma_f32 v[122:123], v[108:109], v[140:141], v[122:123] neg_lo:[0,0,1] neg_hi:[0,0,1]
	v_pk_mul_f32 v[108:109], v[108:109], v[210:211]
	v_pk_fma_f32 v[18:19], v[192:193], v[20:21], v[18:19] neg_lo:[0,0,1] neg_hi:[0,0,1]
	v_pk_mul_f32 v[20:21], v[194:195], v[20:21]
	v_mov_b32_e32 v22, v9
	v_mov_b32_e32 v23, v11
	v_mov_b32_e32 v9, v10
	v_pk_fma_f32 v[108:109], v[110:111], v[140:141], v[108:109]
	v_pk_fma_f32 v[16:17], v[16:17], v[192:193], v[20:21]
	v_mov_b32_e32 v20, v13
	v_mov_b32_e32 v21, v15
	v_pk_mul_f32 v[110:111], v[22:23], v[200:201]
	v_mov_b32_e32 v13, v14
	v_pk_mul_f32 v[10:11], v[8:9], v[190:191]
	v_pk_fma_f32 v[110:111], v[20:21], v[198:199], v[110:111] neg_lo:[0,0,1] neg_hi:[0,0,1]
	v_pk_mul_f32 v[20:21], v[20:21], v[200:201]
	v_pk_fma_f32 v[10:11], v[12:13], v[188:189], v[10:11] neg_lo:[0,0,1] neg_hi:[0,0,1]
	v_pk_mul_f32 v[12:13], v[12:13], v[190:191]
	v_mov_b32_e32 v14, v1
	v_mov_b32_e32 v15, v3
	v_pk_fma_f32 v[20:21], v[22:23], v[198:199], v[20:21]
	v_pk_fma_f32 v[8:9], v[8:9], v[188:189], v[12:13]
	v_mov_b32_e32 v12, v5
	v_mov_b32_e32 v13, v7
	v_pk_mul_f32 v[22:23], v[14:15], v[166:167]
	v_mov_b32_e32 v1, v2
	v_lshl_or_b32 v2, v187, 6, v162
	v_lshlrev_b32_e32 v3, 2, v187
	v_pk_fma_f32 v[22:23], v[12:13], v[164:165], v[22:23] neg_lo:[0,0,1] neg_hi:[0,0,1]
	v_pk_mul_f32 v[12:13], v[12:13], v[166:167]
	v_mov_b32_e32 v5, v6
	v_add_lshl_u32 v2, v2, v3, 2
	v_pk_fma_f32 v[12:13], v[14:15], v[164:165], v[12:13]
	v_add_u32_e32 v162, 0, v2
	v_add_u32_e32 v166, s91, v2
	v_pk_add_f32 v[2:3], v[0:1], v[112:113]
	v_pk_add_f32 v[6:7], v[4:5], v[114:115]
	v_pk_add_f32 v[0:1], v[0:1], v[112:113] neg_lo:[0,1] neg_hi:[0,1]
	v_pk_add_f32 v[4:5], v[4:5], v[114:115] neg_lo:[0,1] neg_hi:[0,1]
	v_pk_add_f32 v[14:15], v[16:17], v[128:129]
	v_pk_add_f32 v[112:113], v[18:19], v[216:217]
	v_pk_add_f32 v[16:17], v[16:17], v[128:129] neg_lo:[0,1] neg_hi:[0,1]
	v_pk_add_f32 v[18:19], v[18:19], v[216:217] neg_lo:[0,1] neg_hi:[0,1]
	v_pk_add_f32 v[114:115], v[8:9], v[116:117]
	v_pk_add_f32 v[126:127], v[10:11], v[132:133]
	v_pk_add_f32 v[8:9], v[8:9], v[116:117] neg_lo:[0,1] neg_hi:[0,1]
	v_pk_add_f32 v[116:117], v[104:105], v[136:137]
	v_pk_add_f32 v[128:129], v[106:107], v[212:213]
	v_pk_add_f32 v[106:107], v[106:107], v[212:213] neg_lo:[0,1] neg_hi:[0,1]
	v_pk_add_f32 v[10:11], v[10:11], v[132:133] neg_lo:[0,1] neg_hi:[0,1]
	v_pk_add_f32 v[104:105], v[104:105], v[136:137] neg_lo:[0,1] neg_hi:[0,1]
	v_pk_add_f32 v[132:133], v[12:13], v[118:119]
	v_pk_add_f32 v[12:13], v[12:13], v[118:119] neg_lo:[0,1] neg_hi:[0,1]
	v_pk_add_f32 v[118:119], v[108:109], v[138:139]
	v_pk_add_f32 v[108:109], v[108:109], v[138:139] neg_lo:[0,1] neg_hi:[0,1]
	v_pk_add_f32 v[138:139], v[20:21], v[130:131]
	v_pk_add_f32 v[20:21], v[20:21], v[130:131] neg_lo:[0,1] neg_hi:[0,1]
	v_pk_add_f32 v[130:131], v[120:121], v[144:145]
	v_pk_add_f32 v[120:121], v[120:121], v[144:145] neg_lo:[0,1] neg_hi:[0,1]
	v_pk_add_f32 v[144:145], v[2:3], v[14:15]
	v_pk_add_f32 v[164:165], v[6:7], v[112:113]
	v_pk_add_f32 v[2:3], v[2:3], v[14:15] neg_lo:[0,1] neg_hi:[0,1]
	v_pk_add_f32 v[6:7], v[6:7], v[112:113] neg_lo:[0,1] neg_hi:[0,1]
	v_pk_add_f32 v[14:15], v[0:1], v[18:19] neg_lo:[0,1] neg_hi:[0,1]
	v_pk_add_f32 v[112:113], v[4:5], v[16:17]
	v_pk_add_f32 v[0:1], v[0:1], v[18:19]
	v_pk_add_f32 v[4:5], v[4:5], v[16:17] neg_lo:[0,1] neg_hi:[0,1]
	v_pk_add_f32 v[16:17], v[114:115], v[116:117]
	v_pk_add_f32 v[18:19], v[126:127], v[128:129]
	v_pk_add_f32 v[114:115], v[114:115], v[116:117] neg_lo:[0,1] neg_hi:[0,1]
	v_pk_add_f32 v[116:117], v[126:127], v[128:129] neg_lo:[0,1] neg_hi:[0,1]
	v_pk_add_f32 v[126:127], v[8:9], v[106:107] neg_lo:[0,1] neg_hi:[0,1]
	v_pk_add_f32 v[134:135], v[22:23], v[218:219]
	v_pk_add_f32 v[22:23], v[22:23], v[218:219] neg_lo:[0,1] neg_hi:[0,1]
	v_pk_add_f32 v[136:137], v[122:123], v[222:223]
	v_pk_add_f32 v[122:123], v[122:123], v[222:223] neg_lo:[0,1] neg_hi:[0,1]
	v_pk_add_f32 v[140:141], v[110:111], v[220:221]
	v_pk_add_f32 v[110:111], v[110:111], v[220:221] neg_lo:[0,1] neg_hi:[0,1]
	v_pk_add_f32 v[142:143], v[124:125], v[214:215]
	v_pk_add_f32 v[128:129], v[10:11], v[104:105]
	v_pk_add_f32 v[10:11], v[10:11], v[104:105] neg_lo:[0,1] neg_hi:[0,1]
	v_pk_mul_f32 v[126:127], v[126:127], s[82:83] op_sel_hi:[1,0]
	v_pk_add_f32 v[124:125], v[124:125], v[214:215] neg_lo:[0,1] neg_hi:[0,1]
	v_pk_add_f32 v[8:9], v[8:9], v[106:107]
	v_pk_add_f32 v[104:105], v[132:133], v[118:119]
	v_pk_add_f32 v[106:107], v[134:135], v[136:137]
	v_pk_add_f32 v[118:119], v[132:133], v[118:119] neg_lo:[0,1] neg_hi:[0,1]
	v_pk_add_f32 v[132:133], v[134:135], v[136:137] neg_lo:[0,1] neg_hi:[0,1]
	v_pk_add_f32 v[134:135], v[12:13], v[122:123] neg_lo:[0,1] neg_hi:[0,1]
	v_pk_add_f32 v[136:137], v[22:23], v[108:109]
	v_pk_add_f32 v[12:13], v[12:13], v[122:123]
	v_pk_add_f32 v[22:23], v[22:23], v[108:109] neg_lo:[0,1] neg_hi:[0,1]
	v_pk_add_f32 v[108:109], v[138:139], v[130:131]
	v_pk_add_f32 v[122:123], v[140:141], v[142:143]
	v_pk_add_f32 v[130:131], v[138:139], v[130:131] neg_lo:[0,1] neg_hi:[0,1]
	v_pk_add_f32 v[138:139], v[140:141], v[142:143] neg_lo:[0,1] neg_hi:[0,1]
	v_pk_add_f32 v[142:143], v[110:111], v[120:121]
	v_pk_add_f32 v[110:111], v[110:111], v[120:121] neg_lo:[0,1] neg_hi:[0,1]
	v_pk_add_f32 v[120:121], v[144:145], v[16:17]
	v_pk_add_f32 v[16:17], v[144:145], v[16:17] neg_lo:[0,1] neg_hi:[0,1]
	v_pk_fma_f32 v[144:145], v[128:129], s[82:83], v[126:127] op_sel_hi:[1,0,1] neg_lo:[1,0,0] neg_hi:[1,0,0]
	v_pk_mul_f32 v[10:11], v[10:11], s[82:83] op_sel_hi:[1,0]
	v_pk_add_f32 v[140:141], v[20:21], v[124:125] neg_lo:[0,1] neg_hi:[0,1]
	v_pk_fma_f32 v[126:127], v[128:129], s[82:83], v[126:127] op_sel_hi:[1,0,1]
	v_pk_add_f32 v[128:129], v[14:15], v[144:145]
	v_pk_add_f32 v[14:15], v[14:15], v[144:145] neg_lo:[0,1] neg_hi:[0,1]
	v_pk_add_f32 v[144:145], v[6:7], v[114:115]
	v_pk_add_f32 v[6:7], v[6:7], v[114:115] neg_lo:[0,1] neg_hi:[0,1]
	v_pk_fma_f32 v[114:115], v[8:9], s[54:55], v[10:11] op_sel_hi:[1,0,1] neg_lo:[0,0,1] neg_hi:[0,0,1]
	v_pk_fma_f32 v[8:9], v[8:9], s[82:83], v[10:11] op_sel_hi:[1,0,1] neg_lo:[0,0,1] neg_hi:[0,0,1]
	v_pk_add_f32 v[20:21], v[20:21], v[124:125]
	v_pk_add_f32 v[124:125], v[164:165], v[18:19]
	v_pk_add_f32 v[18:19], v[164:165], v[18:19] neg_lo:[0,1] neg_hi:[0,1]
	v_pk_add_f32 v[164:165], v[112:113], v[126:127]
	v_pk_add_f32 v[112:113], v[112:113], v[126:127] neg_lo:[0,1] neg_hi:[0,1]
	v_pk_add_f32 v[126:127], v[2:3], v[116:117] neg_lo:[0,1] neg_hi:[0,1]
	v_pk_add_f32 v[2:3], v[2:3], v[116:117]
	v_pk_add_f32 v[116:117], v[4:5], v[8:9]
	v_pk_add_f32 v[4:5], v[4:5], v[8:9] neg_lo:[0,1] neg_hi:[0,1]
	v_pk_add_f32 v[8:9], v[104:105], v[108:109]
	v_pk_add_f32 v[104:105], v[104:105], v[108:109] neg_lo:[0,1] neg_hi:[0,1]
	v_pk_mul_f32 v[108:109], v[140:141], s[82:83] op_sel_hi:[1,0]
	v_pk_add_f32 v[10:11], v[0:1], v[114:115]
	v_pk_add_f32 v[0:1], v[0:1], v[114:115] neg_lo:[0,1] neg_hi:[0,1]
	v_pk_add_f32 v[114:115], v[106:107], v[122:123]
	v_pk_add_f32 v[106:107], v[106:107], v[122:123] neg_lo:[0,1] neg_hi:[0,1]
	v_pk_fma_f32 v[122:123], v[142:143], s[82:83], v[108:109] op_sel_hi:[1,0,1] neg_lo:[1,0,0] neg_hi:[1,0,0]
	v_pk_fma_f32 v[108:109], v[142:143], s[82:83], v[108:109] op_sel_hi:[1,0,1]
	v_pk_mul_f32 v[110:111], v[110:111], s[82:83] op_sel_hi:[1,0]
	v_pk_add_f32 v[142:143], v[136:137], v[108:109]
	v_pk_add_f32 v[108:109], v[136:137], v[108:109] neg_lo:[0,1] neg_hi:[0,1]
	v_pk_add_f32 v[136:137], v[132:133], v[130:131]
	v_pk_add_f32 v[130:131], v[132:133], v[130:131] neg_lo:[0,1] neg_hi:[0,1]
	v_pk_fma_f32 v[132:133], v[20:21], s[54:55], v[110:111] op_sel_hi:[1,0,1] neg_lo:[0,0,1] neg_hi:[0,0,1]
	v_pk_fma_f32 v[20:21], v[20:21], s[82:83], v[110:111] op_sel_hi:[1,0,1] neg_lo:[0,0,1] neg_hi:[0,0,1]
	v_pk_add_f32 v[140:141], v[134:135], v[122:123]
	v_pk_add_f32 v[122:123], v[134:135], v[122:123] neg_lo:[0,1] neg_hi:[0,1]
	v_pk_add_f32 v[134:135], v[118:119], v[138:139] neg_lo:[0,1] neg_hi:[0,1]
	v_pk_add_f32 v[118:119], v[118:119], v[138:139]
	v_pk_add_f32 v[138:139], v[22:23], v[20:21]
	v_pk_add_f32 v[20:21], v[22:23], v[20:21] neg_lo:[0,1] neg_hi:[0,1]
	v_pk_add_f32 v[22:23], v[120:121], v[8:9]
	v_pk_add_f32 v[8:9], v[120:121], v[8:9] neg_lo:[0,1] neg_hi:[0,1]
	v_pk_mul_f32 v[120:121], v[142:143], s[80:81] op_sel_hi:[1,0]
	v_pk_add_f32 v[110:111], v[12:13], v[132:133]
	v_pk_add_f32 v[12:13], v[12:13], v[132:133] neg_lo:[0,1] neg_hi:[0,1]
	v_pk_add_f32 v[132:133], v[124:125], v[114:115]
	v_pk_add_f32 v[114:115], v[124:125], v[114:115] neg_lo:[0,1] neg_hi:[0,1]
	v_pk_fma_f32 v[120:121], v[140:141], s[72:73], v[120:121] op_sel_hi:[1,0,1] neg_lo:[0,0,1] neg_hi:[0,0,1]
	v_pk_mul_f32 v[124:125], v[142:143], s[72:73] op_sel_hi:[1,0]
	s_nop 0
	v_pk_fma_f32 v[124:125], v[140:141], s[80:81], v[124:125] op_sel_hi:[1,0,1]
	v_pk_add_f32 v[140:141], v[128:129], v[120:121]
	v_pk_add_f32 v[120:121], v[128:129], v[120:121] neg_lo:[0,1] neg_hi:[0,1]
	v_pk_mul_f32 v[128:129], v[134:135], s[82:83] op_sel_hi:[1,0]
	v_pk_add_f32 v[142:143], v[164:165], v[124:125]
	v_pk_fma_f32 v[134:135], v[136:137], s[82:83], v[128:129] op_sel_hi:[1,0,1] neg_lo:[1,0,0] neg_hi:[1,0,0]
	v_pk_fma_f32 v[128:129], v[136:137], s[82:83], v[128:129] op_sel_hi:[1,0,1]
	v_pk_add_f32 v[136:137], v[126:127], v[134:135]
	v_pk_add_f32 v[126:127], v[126:127], v[134:135] neg_lo:[0,1] neg_hi:[0,1]
	v_pk_mul_f32 v[134:135], v[138:139], s[72:73] op_sel_hi:[1,0]
	v_pk_mul_f32 v[138:139], v[138:139], s[80:81] op_sel_hi:[1,0]
	v_pk_fma_f32 v[134:135], v[110:111], s[80:81], v[134:135] op_sel_hi:[1,0,1] neg_lo:[0,0,1] neg_hi:[0,0,1]
	v_pk_fma_f32 v[110:111], v[110:111], s[72:73], v[138:139] op_sel_hi:[1,0,1]
	v_pk_add_f32 v[124:125], v[164:165], v[124:125] neg_lo:[0,1] neg_hi:[0,1]
	v_pk_add_f32 v[164:165], v[144:145], v[128:129]
	v_pk_add_f32 v[128:129], v[144:145], v[128:129] neg_lo:[0,1] neg_hi:[0,1]
	v_pk_add_f32 v[138:139], v[10:11], v[134:135]
	v_pk_add_f32 v[144:145], v[116:117], v[110:111]
	v_pk_add_f32 v[10:11], v[10:11], v[134:135] neg_lo:[0,1] neg_hi:[0,1]
	v_pk_add_f32 v[110:111], v[116:117], v[110:111] neg_lo:[0,1] neg_hi:[0,1]
	v_pk_add_f32 v[116:117], v[16:17], v[106:107] neg_lo:[0,1] neg_hi:[0,1]
	v_pk_add_f32 v[134:135], v[18:19], v[104:105]
	v_pk_add_f32 v[16:17], v[16:17], v[106:107]
	v_pk_add_f32 v[18:19], v[18:19], v[104:105] neg_lo:[0,1] neg_hi:[0,1]
	v_pk_mul_f32 v[104:105], v[108:109], s[72:73] op_sel_hi:[1,0]
	v_pk_mul_f32 v[106:107], v[108:109], s[80:81] op_sel_hi:[1,0]
	v_pk_fma_f32 v[104:105], v[122:123], s[84:85], v[104:105] op_sel_hi:[1,0,1] neg_lo:[0,0,1] neg_hi:[0,0,1]
	v_pk_fma_f32 v[106:107], v[122:123], s[72:73], v[106:107] op_sel_hi:[1,0,1] neg_lo:[0,0,1] neg_hi:[0,0,1]
	v_pk_add_f32 v[108:109], v[14:15], v[104:105]
	v_pk_add_f32 v[122:123], v[112:113], v[106:107]
	v_pk_add_f32 v[14:15], v[14:15], v[104:105] neg_lo:[0,1] neg_hi:[0,1]
	v_pk_add_f32 v[104:105], v[112:113], v[106:107] neg_lo:[0,1] neg_hi:[0,1]
	v_pk_mul_f32 v[106:107], v[130:131], s[82:83] op_sel_hi:[1,0]
	s_nop 0
	v_pk_fma_f32 v[112:113], v[118:119], s[54:55], v[106:107] op_sel_hi:[1,0,1] neg_lo:[0,0,1] neg_hi:[0,0,1]
	v_pk_fma_f32 v[106:107], v[118:119], s[82:83], v[106:107] op_sel_hi:[1,0,1] neg_lo:[0,0,1] neg_hi:[0,0,1]
	v_pk_add_f32 v[118:119], v[2:3], v[112:113]
	v_pk_add_f32 v[130:131], v[6:7], v[106:107]
	v_pk_add_f32 v[6:7], v[6:7], v[106:107] neg_lo:[0,1] neg_hi:[0,1]
	v_pk_mul_f32 v[106:107], v[20:21], s[80:81] op_sel_hi:[1,0]
	v_pk_mul_f32 v[20:21], v[20:21], s[72:73] op_sel_hi:[1,0]
	v_pk_fma_f32 v[106:107], v[12:13], s[52:53], v[106:107] op_sel_hi:[1,0,1] neg_lo:[0,0,1] neg_hi:[0,0,1]
	v_pk_fma_f32 v[12:13], v[12:13], s[80:81], v[20:21] op_sel_hi:[1,0,1] neg_lo:[0,0,1] neg_hi:[0,0,1]
	v_pk_add_f32 v[20:21], v[0:1], v[106:107]
	v_pk_add_f32 v[0:1], v[0:1], v[106:107] neg_lo:[0,1] neg_hi:[0,1]
	v_pk_add_f32 v[2:3], v[2:3], v[112:113] neg_lo:[0,1] neg_hi:[0,1]
	v_pk_add_f32 v[112:113], v[4:5], v[12:13]
	v_pk_add_f32 v[4:5], v[4:5], v[12:13] neg_lo:[0,1] neg_hi:[0,1]
	ds_write2_b64 v162, v[22:23], v[140:141] offset1:2
	ds_write2_b64 v166, v[132:133], v[142:143] offset1:2
	ds_write2_b64 v162, v[136:137], v[138:139] offset0:4 offset1:6
	ds_write2_b64 v166, v[164:165], v[144:145] offset0:4 offset1:6
	ds_write2_b64 v162, v[116:117], v[108:109] offset0:8 offset1:10
	ds_write2_b64 v166, v[134:135], v[122:123] offset0:8 offset1:10
	ds_write2_b64 v162, v[118:119], v[20:21] offset0:12 offset1:14
	ds_write2_b64 v166, v[130:131], v[112:113] offset0:12 offset1:14
	ds_write2_b64 v162, v[8:9], v[120:121] offset0:16 offset1:18
	ds_write2_b64 v166, v[114:115], v[124:125] offset0:16 offset1:18
	ds_write2_b64 v162, v[126:127], v[10:11] offset0:20 offset1:22
	ds_write2_b64 v166, v[128:129], v[110:111] offset0:20 offset1:22
	ds_write2_b64 v162, v[16:17], v[14:15] offset0:24 offset1:26
	ds_write2_b64 v166, v[18:19], v[104:105] offset0:24 offset1:26
	ds_write2_b64 v162, v[2:3], v[0:1] offset0:28 offset1:30
	ds_write2_b64 v166, v[6:7], v[4:5] offset0:28 offset1:30
	v_mov_b32_e32 v0, v163
	s_waitcnt lgkmcnt(0)
	s_barrier
	s_nop 0
	s_nop 0
	v_lshlrev_b32_e32 v1, 1, v0
	v_and_b32_e32 v145, 62, v1
	v_ashrrev_i32_e32 v1, 31, v0
	v_lshrrev_b32_e32 v1, 27, v1
	v_add_u32_e32 v0, v0, v1
	v_ashrrev_i32_e32 v0, 5, v0
	v_lshl_or_b32 v1, v0, 10, v145
	v_cvt_f32_ubyte0_e32 v144, v145
	v_or_b32_e32 v145, 1, v145
	v_cvt_f32_ubyte0_e32 v145, v145
	v_mul_f32_e32 v164, 0x3a800000, v144
	v_mul_f32_e32 v165, 0x3a800000, v145
	v_cos_f32_e32 v144, v164
	v_cos_f32_e32 v145, v165
	v_sin_f32_e64 v164, -v164
	v_sin_f32_e64 v165, -v165
	v_lshlrev_b32_e32 v0, 6, v0
	v_add_lshl_u32 v0, v1, v0, 2
	v_add_u32_e32 v162, 0, v0
	v_pk_mul_f32 v[166:167], v[164:165], v[164:165]
	v_pk_mul_f32 v[188:189], v[144:145], v[164:165]
	v_add_u32_e32 v187, s91, v0
	v_pk_fma_f32 v[166:167], v[144:145], v[144:145], v[166:167] neg_lo:[0,0,1] neg_hi:[0,0,1]
	v_pk_add_f32 v[188:189], v[188:189], v[188:189]
	v_add_u32_e32 v212, 0x800, v187
	v_add_u32_e32 v213, 0x800, v162
	v_pk_mul_f32 v[190:191], v[188:189], v[188:189]
	v_pk_mul_f32 v[192:193], v[166:167], v[188:189]
	v_pk_mul_f32 v[198:199], v[164:165], v[166:167]
	ds_read2_b64 v[0:3], v162 offset1:34
	ds_read2_b64 v[4:7], v187 offset1:34
	ds_read2_b64 v[8:11], v212 offset0:16 offset1:50
	ds_read2_b64 v[12:15], v213 offset0:16 offset1:50
	ds_read2_b64 v[16:19], v187 offset0:136 offset1:170
	ds_read2_b64 v[20:23], v162 offset0:136 offset1:170
	ds_read2_b64 v[104:107], v212 offset0:152 offset1:186
	ds_read2_b64 v[108:111], v213 offset0:152 offset1:186
	ds_read2_b64 v[112:115], v187 offset0:68 offset1:102
	ds_read2_b64 v[116:119], v162 offset0:68 offset1:102
	ds_read2_b64 v[120:123], v212 offset0:84 offset1:118
	ds_read2_b64 v[124:127], v213 offset0:84 offset1:118
	ds_read2_b64 v[128:131], v187 offset0:204 offset1:238
	ds_read2_b64 v[132:135], v162 offset0:204 offset1:238
	ds_read2_b64 v[136:139], v212 offset0:220 offset1:254
	ds_read2_b64 v[140:143], v213 offset0:220 offset1:254
	v_pk_fma_f32 v[190:191], v[166:167], v[166:167], v[190:191] neg_lo:[0,0,1] neg_hi:[0,0,1]
	v_pk_add_f32 v[192:193], v[192:193], v[192:193]
	v_pk_mul_f32 v[196:197], v[164:165], v[188:189]
	v_pk_fma_f32 v[198:199], v[144:145], v[188:189], v[198:199]
	v_pk_mul_f32 v[194:195], v[192:193], v[192:193]
	v_pk_fma_f32 v[196:197], v[144:145], v[166:167], v[196:197] neg_lo:[0,0,1] neg_hi:[0,0,1]
	v_pk_mul_f32 v[202:203], v[190:191], v[192:193]
	v_pk_mul_f32 v[204:205], v[190:191], v[198:199]
	v_pk_fma_f32 v[194:195], v[190:191], v[190:191], v[194:195] neg_lo:[0,0,1] neg_hi:[0,0,1]
	v_pk_mul_f32 v[200:201], v[192:193], v[198:199]
	v_pk_add_f32 v[202:203], v[202:203], v[202:203]
	v_pk_fma_f32 v[204:205], v[192:193], v[196:197], v[204:205]
	v_pk_fma_f32 v[200:201], v[190:191], v[196:197], v[200:201] neg_lo:[0,0,1] neg_hi:[0,0,1]
	v_pk_mul_f32 v[206:207], v[202:203], v[204:205]
	v_pk_mul_f32 v[208:209], v[194:195], v[204:205]
	v_pk_fma_f32 v[206:207], v[194:195], v[200:201], v[206:207] neg_lo:[0,0,1] neg_hi:[0,0,1]
	v_pk_fma_f32 v[208:209], v[202:203], v[200:201], v[208:209]
	s_waitcnt lgkmcnt(0)
	v_pk_mul_f32 v[210:211], v[208:209], v[142:143]
	v_pk_mul_f32 v[142:143], v[206:207], v[142:143]
	v_pk_fma_f32 v[210:211], v[206:207], v[138:139], v[210:211] neg_lo:[0,0,1] neg_hi:[0,0,1]
	v_pk_fma_f32 v[138:139], v[208:209], v[138:139], v[142:143]
	v_pk_mul_f32 v[142:143], v[204:205], v[134:135]
	v_pk_mul_f32 v[134:135], v[200:201], v[134:135]
	v_pk_fma_f32 v[142:143], v[200:201], v[130:131], v[142:143] neg_lo:[0,0,1] neg_hi:[0,0,1]
	v_pk_fma_f32 v[130:131], v[204:205], v[130:131], v[134:135]
	v_pk_mul_f32 v[134:135], v[198:199], v[202:203]
	v_pk_mul_f32 v[200:201], v[198:199], v[194:195]
	v_pk_fma_f32 v[134:135], v[196:197], v[194:195], v[134:135] neg_lo:[0,0,1] neg_hi:[0,0,1]
	v_pk_fma_f32 v[200:201], v[196:197], v[202:203], v[200:201]
	s_nop 0
	v_pk_mul_f32 v[204:205], v[200:201], v[126:127]
	v_pk_mul_f32 v[126:127], v[134:135], v[126:127]
	v_pk_fma_f32 v[204:205], v[134:135], v[122:123], v[204:205] neg_lo:[0,0,1] neg_hi:[0,0,1]
	v_pk_fma_f32 v[122:123], v[200:201], v[122:123], v[126:127]
	v_pk_mul_f32 v[126:127], v[198:199], v[118:119]
	v_pk_mul_f32 v[118:119], v[196:197], v[118:119]
	v_pk_mul_f32 v[134:135], v[164:165], v[190:191]
	v_pk_fma_f32 v[126:127], v[196:197], v[114:115], v[126:127] neg_lo:[0,0,1] neg_hi:[0,0,1]
	v_pk_fma_f32 v[114:115], v[198:199], v[114:115], v[118:119]
	v_pk_mul_f32 v[118:119], v[164:165], v[192:193]
	v_pk_fma_f32 v[134:135], v[144:145], v[192:193], v[134:135]
	v_pk_fma_f32 v[118:119], v[144:145], v[190:191], v[118:119] neg_lo:[0,0,1] neg_hi:[0,0,1]
	v_pk_mul_f32 v[196:197], v[202:203], v[134:135]
	v_pk_mul_f32 v[198:199], v[194:195], v[134:135]
	v_pk_fma_f32 v[196:197], v[194:195], v[118:119], v[196:197] neg_lo:[0,0,1] neg_hi:[0,0,1]
	v_pk_fma_f32 v[198:199], v[202:203], v[118:119], v[198:199]
	s_nop 0
	v_pk_mul_f32 v[200:201], v[198:199], v[110:111]
	v_pk_mul_f32 v[110:111], v[196:197], v[110:111]
	v_pk_fma_f32 v[200:201], v[196:197], v[106:107], v[200:201] neg_lo:[0,0,1] neg_hi:[0,0,1]
	v_pk_fma_f32 v[106:107], v[198:199], v[106:107], v[110:111]
	v_pk_mul_f32 v[110:111], v[134:135], v[22:23]
	v_pk_mul_f32 v[22:23], v[118:119], v[22:23]
	v_pk_fma_f32 v[110:111], v[118:119], v[18:19], v[110:111] neg_lo:[0,0,1] neg_hi:[0,0,1]
	v_pk_fma_f32 v[18:19], v[134:135], v[18:19], v[22:23]
	v_pk_mul_f32 v[22:23], v[164:165], v[202:203]
	v_pk_mul_f32 v[118:119], v[164:165], v[194:195]
	v_pk_fma_f32 v[22:23], v[144:145], v[194:195], v[22:23] neg_lo:[0,0,1] neg_hi:[0,0,1]
	v_pk_fma_f32 v[118:119], v[144:145], v[202:203], v[118:119]
	s_nop 0
	v_pk_mul_f32 v[134:135], v[118:119], v[14:15]
	v_pk_mul_f32 v[14:15], v[22:23], v[14:15]
	v_pk_fma_f32 v[134:135], v[22:23], v[10:11], v[134:135] neg_lo:[0,0,1] neg_hi:[0,0,1]
	v_pk_fma_f32 v[10:11], v[118:119], v[10:11], v[14:15]
	v_pk_mul_f32 v[14:15], v[164:165], v[2:3]
	v_pk_mul_f32 v[2:3], v[144:145], v[2:3]
	v_pk_mul_f32 v[22:23], v[188:189], v[190:191]
	v_pk_fma_f32 v[14:15], v[144:145], v[6:7], v[14:15] neg_lo:[0,0,1] neg_hi:[0,0,1]
	v_pk_fma_f32 v[2:3], v[164:165], v[6:7], v[2:3]
	v_pk_mul_f32 v[6:7], v[188:189], v[192:193]
	v_pk_fma_f32 v[22:23], v[166:167], v[192:193], v[22:23]
	v_pk_fma_f32 v[6:7], v[166:167], v[190:191], v[6:7] neg_lo:[0,0,1] neg_hi:[0,0,1]
	v_pk_mul_f32 v[144:145], v[194:195], v[22:23]
	v_pk_mul_f32 v[118:119], v[202:203], v[22:23]
	v_pk_fma_f32 v[144:145], v[202:203], v[6:7], v[144:145]
	v_pk_fma_f32 v[118:119], v[194:195], v[6:7], v[118:119] neg_lo:[0,0,1] neg_hi:[0,0,1]
	v_pk_mul_f32 v[164:165], v[144:145], v[140:141]
	s_nop 0
	v_pk_fma_f32 v[164:165], v[136:137], v[118:119], v[164:165] neg_lo:[0,0,1] neg_hi:[0,0,1]
	v_pk_mul_f32 v[118:119], v[118:119], v[140:141]
	v_pk_add_f32 v[140:141], v[126:127], v[204:205]
	v_pk_fma_f32 v[118:119], v[136:137], v[144:145], v[118:119]
	v_pk_mul_f32 v[136:137], v[22:23], v[132:133]
	v_pk_add_f32 v[144:145], v[142:143], v[210:211]
	v_pk_fma_f32 v[136:137], v[128:129], v[6:7], v[136:137] neg_lo:[0,0,1] neg_hi:[0,0,1]
	v_pk_mul_f32 v[6:7], v[6:7], v[132:133]
	s_nop 0
	v_pk_fma_f32 v[6:7], v[128:129], v[22:23], v[6:7]
	v_pk_mul_f32 v[128:129], v[188:189], v[194:195]
	v_pk_mul_f32 v[22:23], v[188:189], v[202:203]
	v_pk_fma_f32 v[128:129], v[166:167], v[202:203], v[128:129]
	v_pk_fma_f32 v[22:23], v[166:167], v[194:195], v[22:23] neg_lo:[0,0,1] neg_hi:[0,0,1]
	v_pk_mul_f32 v[132:133], v[124:125], v[128:129]
	s_nop 0
	v_pk_fma_f32 v[132:133], v[120:121], v[22:23], v[132:133] neg_lo:[0,0,1] neg_hi:[0,0,1]
	v_pk_mul_f32 v[120:121], v[120:121], v[128:129]
	s_nop 0
	v_pk_fma_f32 v[22:23], v[124:125], v[22:23], v[120:121]
	v_pk_mul_f32 v[120:121], v[188:189], v[116:117]
	v_pk_mul_f32 v[116:117], v[166:167], v[116:117]
	v_pk_mul_f32 v[124:125], v[192:193], v[194:195]
	v_pk_fma_f32 v[120:121], v[112:113], v[166:167], v[120:121] neg_lo:[0,0,1] neg_hi:[0,0,1]
	v_pk_fma_f32 v[112:113], v[112:113], v[188:189], v[116:117]
	v_pk_mul_f32 v[116:117], v[192:193], v[202:203]
	v_pk_fma_f32 v[124:125], v[190:191], v[202:203], v[124:125]
	v_pk_fma_f32 v[116:117], v[190:191], v[194:195], v[116:117] neg_lo:[0,0,1] neg_hi:[0,0,1]
	v_pk_mul_f32 v[128:129], v[108:109], v[124:125]
	s_nop 0
	v_pk_fma_f32 v[128:129], v[104:105], v[116:117], v[128:129] neg_lo:[0,0,1] neg_hi:[0,0,1]
	v_pk_mul_f32 v[104:105], v[104:105], v[124:125]
	v_pk_add_f32 v[124:125], v[120:121], v[132:133]
	v_pk_fma_f32 v[104:105], v[108:109], v[116:117], v[104:105]
	v_pk_mul_f32 v[108:109], v[20:21], v[192:193]
	s_nop 0
	v_pk_fma_f32 v[108:109], v[16:17], v[190:191], v[108:109] neg_lo:[0,0,1] neg_hi:[0,0,1]
	v_pk_mul_f32 v[16:17], v[16:17], v[192:193]
	s_nop 0
	v_pk_fma_f32 v[16:17], v[20:21], v[190:191], v[16:17]
	v_pk_mul_f32 v[20:21], v[12:13], v[202:203]
	s_nop 0
	v_pk_fma_f32 v[20:21], v[8:9], v[194:195], v[20:21] neg_lo:[0,0,1] neg_hi:[0,0,1]
	v_pk_mul_f32 v[8:9], v[8:9], v[202:203]
	v_pk_add_f32 v[116:117], v[4:5], v[20:21]
	v_pk_fma_f32 v[8:9], v[12:13], v[194:195], v[8:9]
	v_pk_add_f32 v[4:5], v[4:5], v[20:21] neg_lo:[0,1] neg_hi:[0,1]
	v_pk_add_f32 v[12:13], v[0:1], v[8:9]
	v_pk_add_f32 v[0:1], v[0:1], v[8:9] neg_lo:[0,1] neg_hi:[0,1]
	v_pk_add_f32 v[8:9], v[16:17], v[104:105]
	v_pk_add_f32 v[20:21], v[108:109], v[128:129]
	v_pk_add_f32 v[16:17], v[16:17], v[104:105] neg_lo:[0,1] neg_hi:[0,1]
	v_pk_add_f32 v[104:105], v[108:109], v[128:129] neg_lo:[0,1] neg_hi:[0,1]
	v_pk_add_f32 v[108:109], v[112:113], v[22:23]
	v_pk_add_f32 v[22:23], v[112:113], v[22:23] neg_lo:[0,1] neg_hi:[0,1]
	v_pk_add_f32 v[112:113], v[120:121], v[132:133] neg_lo:[0,1] neg_hi:[0,1]
	v_pk_add_f32 v[120:121], v[6:7], v[118:119]
	v_pk_add_f32 v[128:129], v[136:137], v[164:165]
	v_pk_add_f32 v[6:7], v[6:7], v[118:119] neg_lo:[0,1] neg_hi:[0,1]
	v_pk_add_f32 v[118:119], v[136:137], v[164:165] neg_lo:[0,1] neg_hi:[0,1]
	v_pk_add_f32 v[132:133], v[2:3], v[10:11]
	v_pk_add_f32 v[136:137], v[14:15], v[134:135]
	v_pk_add_f32 v[2:3], v[2:3], v[10:11] neg_lo:[0,1] neg_hi:[0,1]
	v_pk_add_f32 v[10:11], v[14:15], v[134:135] neg_lo:[0,1] neg_hi:[0,1]
	v_pk_add_f32 v[14:15], v[18:19], v[106:107]
	v_pk_add_f32 v[134:135], v[110:111], v[200:201]
	v_pk_add_f32 v[18:19], v[18:19], v[106:107] neg_lo:[0,1] neg_hi:[0,1]
	v_pk_add_f32 v[106:107], v[110:111], v[200:201] neg_lo:[0,1] neg_hi:[0,1]
	v_pk_add_f32 v[110:111], v[114:115], v[122:123]
	v_pk_add_f32 v[114:115], v[114:115], v[122:123] neg_lo:[0,1] neg_hi:[0,1]
	v_pk_add_f32 v[122:123], v[126:127], v[204:205] neg_lo:[0,1] neg_hi:[0,1]
	v_pk_add_f32 v[126:127], v[130:131], v[138:139]
	v_pk_add_f32 v[130:131], v[130:131], v[138:139] neg_lo:[0,1] neg_hi:[0,1]
	v_pk_add_f32 v[138:139], v[142:143], v[210:211] neg_lo:[0,1] neg_hi:[0,1]
	v_pk_add_f32 v[142:143], v[12:13], v[8:9]
	v_pk_add_f32 v[164:165], v[116:117], v[20:21]
	v_pk_add_f32 v[8:9], v[12:13], v[8:9] neg_lo:[0,1] neg_hi:[0,1]
	v_pk_add_f32 v[12:13], v[116:117], v[20:21] neg_lo:[0,1] neg_hi:[0,1]
	v_pk_add_f32 v[20:21], v[0:1], v[104:105] neg_lo:[0,1] neg_hi:[0,1]
	v_pk_add_f32 v[116:117], v[4:5], v[16:17]
	v_pk_add_f32 v[0:1], v[0:1], v[104:105]
	v_pk_add_f32 v[4:5], v[4:5], v[16:17] neg_lo:[0,1] neg_hi:[0,1]
	v_pk_add_f32 v[16:17], v[108:109], v[120:121]
	v_pk_add_f32 v[104:105], v[124:125], v[128:129]
	v_pk_add_f32 v[108:109], v[108:109], v[120:121] neg_lo:[0,1] neg_hi:[0,1]
	v_pk_add_f32 v[120:121], v[124:125], v[128:129] neg_lo:[0,1] neg_hi:[0,1]
	v_pk_add_f32 v[124:125], v[22:23], v[118:119] neg_lo:[0,1] neg_hi:[0,1]
	v_pk_add_f32 v[128:129], v[112:113], v[6:7]
	v_pk_add_f32 v[6:7], v[112:113], v[6:7] neg_lo:[0,1] neg_hi:[0,1]
	v_pk_mul_f32 v[124:125], v[124:125], s[82:83] op_sel_hi:[1,0]
	v_pk_add_f32 v[22:23], v[22:23], v[118:119]
	v_pk_add_f32 v[112:113], v[132:133], v[14:15]
	v_pk_add_f32 v[118:119], v[136:137], v[134:135]
	v_pk_add_f32 v[14:15], v[132:133], v[14:15] neg_lo:[0,1] neg_hi:[0,1]
	v_pk_add_f32 v[132:133], v[136:137], v[134:135] neg_lo:[0,1] neg_hi:[0,1]
	v_pk_add_f32 v[134:135], v[2:3], v[106:107] neg_lo:[0,1] neg_hi:[0,1]
	v_pk_add_f32 v[136:137], v[10:11], v[18:19]
	v_pk_add_f32 v[2:3], v[2:3], v[106:107]
	v_pk_add_f32 v[10:11], v[10:11], v[18:19] neg_lo:[0,1] neg_hi:[0,1]
	v_pk_add_f32 v[18:19], v[110:111], v[126:127]
	v_pk_add_f32 v[106:107], v[140:141], v[144:145]
	v_pk_add_f32 v[110:111], v[110:111], v[126:127] neg_lo:[0,1] neg_hi:[0,1]
	v_pk_add_f32 v[126:127], v[140:141], v[144:145] neg_lo:[0,1] neg_hi:[0,1]
	v_pk_add_f32 v[144:145], v[122:123], v[130:131]
	v_pk_add_f32 v[122:123], v[122:123], v[130:131] neg_lo:[0,1] neg_hi:[0,1]
	v_pk_add_f32 v[130:131], v[142:143], v[16:17]
	v_pk_add_f32 v[16:17], v[142:143], v[16:17] neg_lo:[0,1] neg_hi:[0,1]
	v_pk_fma_f32 v[142:143], v[128:129], s[82:83], v[124:125] op_sel_hi:[1,0,1] neg_lo:[1,0,0] neg_hi:[1,0,0]
	v_pk_mul_f32 v[6:7], v[6:7], s[82:83] op_sel_hi:[1,0]
	v_pk_add_f32 v[140:141], v[114:115], v[138:139] neg_lo:[0,1] neg_hi:[0,1]
	v_pk_fma_f32 v[124:125], v[128:129], s[82:83], v[124:125] op_sel_hi:[1,0,1]
	v_pk_add_f32 v[128:129], v[20:21], v[142:143]
	v_pk_add_f32 v[20:21], v[20:21], v[142:143] neg_lo:[0,1] neg_hi:[0,1]
	v_pk_add_f32 v[142:143], v[12:13], v[108:109]
	v_pk_add_f32 v[12:13], v[12:13], v[108:109] neg_lo:[0,1] neg_hi:[0,1]
	v_pk_fma_f32 v[108:109], v[22:23], s[54:55], v[6:7] op_sel_hi:[1,0,1] neg_lo:[0,0,1] neg_hi:[0,0,1]
	v_pk_fma_f32 v[6:7], v[22:23], s[82:83], v[6:7] op_sel_hi:[1,0,1] neg_lo:[0,0,1] neg_hi:[0,0,1]
	v_pk_add_f32 v[114:115], v[114:115], v[138:139]
	v_pk_add_f32 v[138:139], v[164:165], v[104:105]
	v_pk_add_f32 v[104:105], v[164:165], v[104:105] neg_lo:[0,1] neg_hi:[0,1]
	v_pk_add_f32 v[164:165], v[116:117], v[124:125]
	v_pk_add_f32 v[116:117], v[116:117], v[124:125] neg_lo:[0,1] neg_hi:[0,1]
	v_pk_add_f32 v[124:125], v[8:9], v[120:121] neg_lo:[0,1] neg_hi:[0,1]
	v_pk_add_f32 v[8:9], v[8:9], v[120:121]
	v_pk_add_f32 v[120:121], v[4:5], v[6:7]
	v_pk_add_f32 v[4:5], v[4:5], v[6:7] neg_lo:[0,1] neg_hi:[0,1]
	v_pk_add_f32 v[6:7], v[112:113], v[18:19]
	v_pk_add_f32 v[18:19], v[112:113], v[18:19] neg_lo:[0,1] neg_hi:[0,1]
	v_pk_mul_f32 v[112:113], v[140:141], s[82:83] op_sel_hi:[1,0]
	v_pk_add_f32 v[22:23], v[0:1], v[108:109]
	v_pk_add_f32 v[0:1], v[0:1], v[108:109] neg_lo:[0,1] neg_hi:[0,1]
	v_pk_add_f32 v[108:109], v[118:119], v[106:107]
	v_pk_add_f32 v[106:107], v[118:119], v[106:107] neg_lo:[0,1] neg_hi:[0,1]
	v_pk_fma_f32 v[118:119], v[144:145], s[82:83], v[112:113] op_sel_hi:[1,0,1] neg_lo:[1,0,0] neg_hi:[1,0,0]
	v_pk_fma_f32 v[112:113], v[144:145], s[82:83], v[112:113] op_sel_hi:[1,0,1]
	v_pk_mul_f32 v[122:123], v[122:123], s[82:83] op_sel_hi:[1,0]
	v_pk_add_f32 v[140:141], v[134:135], v[118:119]
	v_pk_add_f32 v[144:145], v[136:137], v[112:113]
	v_pk_add_f32 v[118:119], v[134:135], v[118:119] neg_lo:[0,1] neg_hi:[0,1]
	v_pk_add_f32 v[134:135], v[14:15], v[126:127] neg_lo:[0,1] neg_hi:[0,1]
	v_pk_add_f32 v[14:15], v[14:15], v[126:127]
	v_pk_fma_f32 v[126:127], v[114:115], s[54:55], v[122:123] op_sel_hi:[1,0,1] neg_lo:[0,0,1] neg_hi:[0,0,1]
	v_pk_fma_f32 v[114:115], v[114:115], s[82:83], v[122:123] op_sel_hi:[1,0,1] neg_lo:[0,0,1] neg_hi:[0,0,1]
	v_pk_add_f32 v[112:113], v[136:137], v[112:113] neg_lo:[0,1] neg_hi:[0,1]
	v_pk_add_f32 v[136:137], v[132:133], v[110:111]
	v_pk_add_f32 v[110:111], v[132:133], v[110:111] neg_lo:[0,1] neg_hi:[0,1]
	v_pk_add_f32 v[122:123], v[2:3], v[126:127]
	v_pk_add_f32 v[132:133], v[10:11], v[114:115]
	v_pk_add_f32 v[2:3], v[2:3], v[126:127] neg_lo:[0,1] neg_hi:[0,1]
	v_pk_add_f32 v[10:11], v[10:11], v[114:115] neg_lo:[0,1] neg_hi:[0,1]
	v_pk_add_f32 v[114:115], v[130:131], v[6:7]
	v_pk_add_f32 v[126:127], v[138:139], v[108:109]
	v_pk_add_f32 v[6:7], v[130:131], v[6:7] neg_lo:[0,1] neg_hi:[0,1]
	v_pk_add_f32 v[108:109], v[138:139], v[108:109] neg_lo:[0,1] neg_hi:[0,1]
	v_pk_mul_f32 v[130:131], v[144:145], s[80:81] op_sel_hi:[1,0]
	v_pk_mul_f32 v[138:139], v[144:145], s[72:73] op_sel_hi:[1,0]
	v_pk_fma_f32 v[130:131], v[140:141], s[72:73], v[130:131] op_sel_hi:[1,0,1] neg_lo:[0,0,1] neg_hi:[0,0,1]
	v_pk_fma_f32 v[138:139], v[140:141], s[80:81], v[138:139] op_sel_hi:[1,0,1]
	v_pk_mul_f32 v[134:135], v[134:135], s[82:83] op_sel_hi:[1,0]
	v_pk_add_f32 v[140:141], v[128:129], v[130:131]
	v_pk_add_f32 v[144:145], v[164:165], v[138:139]
	v_pk_add_f32 v[128:129], v[128:129], v[130:131] neg_lo:[0,1] neg_hi:[0,1]
	v_pk_add_f32 v[130:131], v[164:165], v[138:139] neg_lo:[0,1] neg_hi:[0,1]
	v_pk_fma_f32 v[138:139], v[136:137], s[82:83], v[134:135] op_sel_hi:[1,0,1] neg_lo:[1,0,0] neg_hi:[1,0,0]
	v_pk_fma_f32 v[134:135], v[136:137], s[82:83], v[134:135] op_sel_hi:[1,0,1]
	v_pk_add_f32 v[136:137], v[124:125], v[138:139]
	v_pk_add_f32 v[124:125], v[124:125], v[138:139] neg_lo:[0,1] neg_hi:[0,1]
	v_pk_mul_f32 v[138:139], v[132:133], s[72:73] op_sel_hi:[1,0]
	v_pk_mul_f32 v[132:133], v[132:133], s[80:81] op_sel_hi:[1,0]
	v_pk_fma_f32 v[138:139], v[122:123], s[80:81], v[138:139] op_sel_hi:[1,0,1] neg_lo:[0,0,1] neg_hi:[0,0,1]
	v_pk_fma_f32 v[122:123], v[122:123], s[72:73], v[132:133] op_sel_hi:[1,0,1]
	v_pk_add_f32 v[164:165], v[142:143], v[134:135]
	v_pk_add_f32 v[134:135], v[142:143], v[134:135] neg_lo:[0,1] neg_hi:[0,1]
	v_pk_add_f32 v[132:133], v[22:23], v[138:139]
	v_pk_add_f32 v[142:143], v[120:121], v[122:123]
	v_pk_add_f32 v[22:23], v[22:23], v[138:139] neg_lo:[0,1] neg_hi:[0,1]
	v_pk_add_f32 v[120:121], v[120:121], v[122:123] neg_lo:[0,1] neg_hi:[0,1]
	v_pk_add_f32 v[122:123], v[16:17], v[106:107] neg_lo:[0,1] neg_hi:[0,1]
	v_pk_add_f32 v[138:139], v[104:105], v[18:19]
	v_pk_add_f32 v[16:17], v[16:17], v[106:107]
	v_pk_add_f32 v[18:19], v[104:105], v[18:19] neg_lo:[0,1] neg_hi:[0,1]
	v_pk_mul_f32 v[104:105], v[112:113], s[72:73] op_sel_hi:[1,0]
	v_pk_mul_f32 v[106:107], v[112:113], s[80:81] op_sel_hi:[1,0]
	v_pk_fma_f32 v[104:105], v[118:119], s[84:85], v[104:105] op_sel_hi:[1,0,1] neg_lo:[0,0,1] neg_hi:[0,0,1]
	v_pk_fma_f32 v[106:107], v[118:119], s[72:73], v[106:107] op_sel_hi:[1,0,1] neg_lo:[0,0,1] neg_hi:[0,0,1]
	v_pk_add_f32 v[112:113], v[20:21], v[104:105]
	v_pk_add_f32 v[118:119], v[116:117], v[106:107]
	v_pk_add_f32 v[20:21], v[20:21], v[104:105] neg_lo:[0,1] neg_hi:[0,1]
	v_pk_add_f32 v[104:105], v[116:117], v[106:107] neg_lo:[0,1] neg_hi:[0,1]
	v_pk_mul_f32 v[106:107], v[110:111], s[82:83] op_sel_hi:[1,0]
	s_nop 0
	v_pk_fma_f32 v[110:111], v[14:15], s[54:55], v[106:107] op_sel_hi:[1,0,1] neg_lo:[0,0,1] neg_hi:[0,0,1]
	v_pk_fma_f32 v[14:15], v[14:15], s[82:83], v[106:107] op_sel_hi:[1,0,1] neg_lo:[0,0,1] neg_hi:[0,0,1]
	v_pk_add_f32 v[106:107], v[8:9], v[110:111]
	v_pk_add_f32 v[116:117], v[12:13], v[14:15]
	v_pk_add_f32 v[12:13], v[12:13], v[14:15] neg_lo:[0,1] neg_hi:[0,1]
	v_pk_mul_f32 v[14:15], v[10:11], s[80:81] op_sel_hi:[1,0]
	v_pk_mul_f32 v[10:11], v[10:11], s[72:73] op_sel_hi:[1,0]
	v_pk_fma_f32 v[14:15], v[2:3], s[52:53], v[14:15] op_sel_hi:[1,0,1] neg_lo:[0,0,1] neg_hi:[0,0,1]
	v_pk_fma_f32 v[2:3], v[2:3], s[80:81], v[10:11] op_sel_hi:[1,0,1] neg_lo:[0,0,1] neg_hi:[0,0,1]
	v_pk_add_f32 v[10:11], v[0:1], v[14:15]
	v_pk_add_f32 v[0:1], v[0:1], v[14:15] neg_lo:[0,1] neg_hi:[0,1]
	v_pk_add_f32 v[8:9], v[8:9], v[110:111] neg_lo:[0,1] neg_hi:[0,1]
	v_pk_add_f32 v[110:111], v[4:5], v[2:3]
	v_pk_add_f32 v[2:3], v[4:5], v[2:3] neg_lo:[0,1] neg_hi:[0,1]
	ds_write2_b64 v162, v[114:115], v[140:141] offset1:34
	ds_write2_b64 v187, v[126:127], v[144:145] offset1:34
	ds_write2_b64 v162, v[136:137], v[132:133] offset0:68 offset1:102
	ds_write2_b64 v187, v[164:165], v[142:143] offset0:68 offset1:102
	ds_write2_b64 v162, v[122:123], v[112:113] offset0:136 offset1:170
	ds_write2_b64 v187, v[138:139], v[118:119] offset0:136 offset1:170
	ds_write2_b64 v162, v[106:107], v[10:11] offset0:204 offset1:238
	ds_write2_b64 v187, v[116:117], v[110:111] offset0:204 offset1:238
	ds_write2_b64 v213, v[6:7], v[128:129] offset0:16 offset1:50
	ds_write2_b64 v212, v[108:109], v[130:131] offset0:16 offset1:50
	ds_write2_b64 v213, v[124:125], v[22:23] offset0:84 offset1:118
	ds_write2_b64 v212, v[134:135], v[120:121] offset0:84 offset1:118
	ds_write2_b64 v213, v[16:17], v[20:21] offset0:152 offset1:186
	ds_write2_b64 v212, v[18:19], v[104:105] offset0:152 offset1:186
	ds_write2_b64 v213, v[8:9], v[0:1] offset0:220 offset1:254
	ds_write2_b64 v212, v[12:13], v[2:3] offset0:220 offset1:254
	v_mov_b32_e32 v0, v163
	s_waitcnt lgkmcnt(0)
	s_barrier
	s_nop 0
	s_nop 0
	v_ashrrev_i32_e32 v2, 31, v0
	v_lshlrev_b32_e32 v1, 1, v0
	v_lshrrev_b32_e32 v2, 23, v2
	v_and_b32_e32 v1, 0x3fe, v1
	v_add_lshl_u32 v0, v0, v2, 5
	v_and_or_b32 v0, v0, s85, v1
	v_ashrrev_i32_e32 v2, 4, v0
	v_and_b32_e32 v2, 0x3ffffc3c, v2
	v_add_lshl_u32 v4, v2, v0, 2
	v_cvt_f32_u32_e32 v0, v1
	v_or_b32_e32 v1, 1, v1
	v_cvt_f32_u32_e32 v1, v1
	v_add_u32_e32 v187, 0, v4
	v_mul_f32_e32 v0, 0x38800000, v0
	v_sin_f32_e64 v120, -v0
	v_mul_f32_e32 v1, 0x38800000, v1
	v_sin_f32_e64 v121, -v1
	v_cos_f32_e32 v118, v0
	v_cos_f32_e32 v119, v1
	v_add_u32_e32 v188, s91, v4
	v_pk_mul_f32 v[0:1], v[120:121], v[120:121]
	ds_read_b64 v[4:5], v187
	ds_read_b64 v[6:7], v188
	ds_read_b64 v[196:197], v188 offset:34816
	ds_read_b64 v[198:199], v187 offset:34816
	ds_read_b64 v[164:165], v188 offset:17408
	ds_read_b64 v[166:167], v187 offset:17408
	ds_read_b64 v[204:205], v188 offset:52224
	ds_read_b64 v[206:207], v187 offset:52224
	ds_read_b64 v[200:201], v188 offset:8704
	ds_read_b64 v[202:203], v187 offset:8704
	s_waitcnt lgkmcnt(6)
	v_pk_fma_f32 v[22:23], v[118:119], v[118:119], v[0:1] neg_lo:[0,0,1] neg_hi:[0,0,1]
	v_pk_mul_f32 v[0:1], v[118:119], v[120:121]
	s_nop 0
	v_pk_add_f32 v[104:105], v[0:1], v[0:1]
	s_nop 0
	v_pk_mul_f32 v[0:1], v[120:121], v[104:105]
	s_nop 0
	v_pk_fma_f32 v[134:135], v[118:119], v[22:23], v[0:1] neg_lo:[0,0,1] neg_hi:[0,0,1]
	v_pk_mul_f32 v[0:1], v[120:121], v[22:23]
	s_nop 0
	v_pk_fma_f32 v[144:145], v[118:119], v[104:105], v[0:1]
	v_pk_mul_f32 v[0:1], v[104:105], v[104:105]
	s_nop 0
	v_pk_fma_f32 v[14:15], v[22:23], v[22:23], v[0:1] neg_lo:[0,0,1] neg_hi:[0,0,1]
	v_pk_mul_f32 v[0:1], v[22:23], v[104:105]
	s_nop 0
	v_pk_add_f32 v[16:17], v[0:1], v[0:1]
	s_nop 0
	v_pk_mul_f32 v[0:1], v[120:121], v[16:17]
	s_nop 0
	v_pk_fma_f32 v[126:127], v[118:119], v[14:15], v[0:1] neg_lo:[0,0,1] neg_hi:[0,0,1]
	v_pk_mul_f32 v[0:1], v[120:121], v[14:15]
	s_nop 0
	v_pk_fma_f32 v[128:129], v[118:119], v[16:17], v[0:1]
	v_pk_mul_f32 v[0:1], v[104:105], v[16:17]
	s_nop 0
	v_pk_fma_f32 v[110:111], v[22:23], v[14:15], v[0:1] neg_lo:[0,0,1] neg_hi:[0,0,1]
	v_pk_mul_f32 v[0:1], v[104:105], v[14:15]
	s_nop 0
	v_pk_fma_f32 v[112:113], v[22:23], v[16:17], v[0:1]
	v_pk_mul_f32 v[0:1], v[16:17], v[144:145]
	s_nop 0
	v_pk_fma_f32 v[136:137], v[14:15], v[134:135], v[0:1] neg_lo:[0,0,1] neg_hi:[0,0,1]
	v_pk_mul_f32 v[0:1], v[14:15], v[144:145]
	s_nop 0
	v_pk_fma_f32 v[138:139], v[16:17], v[134:135], v[0:1]
	v_pk_mul_f32 v[0:1], v[16:17], v[16:17]
	s_nop 0
	v_pk_fma_f32 v[10:11], v[14:15], v[14:15], v[0:1] neg_lo:[0,0,1] neg_hi:[0,0,1]
	v_pk_mul_f32 v[0:1], v[14:15], v[16:17]
	v_pk_mul_f32 v[2:3], v[10:11], v[138:139]
	v_pk_add_f32 v[12:13], v[0:1], v[0:1]
	s_nop 0
	v_pk_mul_f32 v[0:1], v[120:121], v[12:13]
	v_pk_fma_f32 v[2:3], v[12:13], v[136:137], v[2:3]
	v_pk_fma_f32 v[122:123], v[118:119], v[10:11], v[0:1] neg_lo:[0,0,1] neg_hi:[0,0,1]
	v_pk_mul_f32 v[0:1], v[120:121], v[10:11]
	v_pk_mul_f32 v[8:9], v[196:197], v[12:13]
	v_pk_fma_f32 v[124:125], v[118:119], v[12:13], v[0:1]
	v_pk_mul_f32 v[0:1], v[104:105], v[12:13]
	v_pk_fma_f32 v[8:9], v[198:199], v[10:11], v[8:9]
	v_pk_fma_f32 v[106:107], v[22:23], v[10:11], v[0:1] neg_lo:[0,0,1] neg_hi:[0,0,1]
	v_pk_mul_f32 v[0:1], v[104:105], v[10:11]
	s_nop 0
	v_pk_fma_f32 v[108:109], v[22:23], v[12:13], v[0:1]
	v_pk_mul_f32 v[0:1], v[144:145], v[12:13]
	s_nop 0
	v_pk_fma_f32 v[140:141], v[134:135], v[10:11], v[0:1] neg_lo:[0,0,1] neg_hi:[0,0,1]
	v_pk_mul_f32 v[0:1], v[144:145], v[10:11]
	s_nop 0
	v_pk_fma_f32 v[142:143], v[134:135], v[12:13], v[0:1]
	v_pk_mul_f32 v[0:1], v[16:17], v[12:13]
	s_nop 0
	v_pk_fma_f32 v[18:19], v[14:15], v[10:11], v[0:1] neg_lo:[0,0,1] neg_hi:[0,0,1]
	v_pk_mul_f32 v[0:1], v[16:17], v[10:11]
	s_nop 0
	v_pk_fma_f32 v[20:21], v[14:15], v[12:13], v[0:1]
	v_pk_mul_f32 v[0:1], v[12:13], v[128:129]
	s_nop 0
	v_pk_fma_f32 v[130:131], v[10:11], v[126:127], v[0:1] neg_lo:[0,0,1] neg_hi:[0,0,1]
	v_pk_mul_f32 v[0:1], v[10:11], v[128:129]
	s_nop 0
	v_pk_fma_f32 v[132:133], v[12:13], v[126:127], v[0:1]
	v_pk_mul_f32 v[0:1], v[12:13], v[112:113]
	s_nop 0
	v_pk_fma_f32 v[114:115], v[10:11], v[110:111], v[0:1] neg_lo:[0,0,1] neg_hi:[0,0,1]
	v_pk_mul_f32 v[0:1], v[10:11], v[112:113]
	s_nop 0
	v_pk_fma_f32 v[116:117], v[12:13], v[110:111], v[0:1]
	v_pk_mul_f32 v[0:1], v[12:13], v[138:139]
	v_pk_mul_f32 v[12:13], v[198:199], v[12:13]
	v_pk_fma_f32 v[0:1], v[10:11], v[136:137], v[0:1] neg_lo:[0,0,1] neg_hi:[0,0,1]
	v_pk_fma_f32 v[10:11], v[196:197], v[10:11], v[12:13] neg_lo:[0,0,1] neg_hi:[0,0,1]
	ds_read_b64 v[196:197], v188 offset:43520
	ds_read_b64 v[198:199], v187 offset:43520
	s_waitcnt lgkmcnt(6)
	v_pk_mul_f32 v[12:13], v[164:165], v[16:17]
	v_pk_mul_f32 v[16:17], v[166:167], v[16:17]
	v_pk_fma_f32 v[12:13], v[166:167], v[14:15], v[12:13]
	v_pk_fma_f32 v[14:15], v[164:165], v[14:15], v[16:17] neg_lo:[0,0,1] neg_hi:[0,0,1]
	ds_read_b64 v[164:165], v188 offset:26112
	ds_read_b64 v[166:167], v187 offset:26112
	s_waitcnt lgkmcnt(6)
	v_pk_mul_f32 v[16:17], v[204:205], v[20:21]
	v_pk_mul_f32 v[20:21], v[206:207], v[20:21]
	v_pk_fma_f32 v[16:17], v[206:207], v[18:19], v[16:17]
	v_pk_fma_f32 v[18:19], v[204:205], v[18:19], v[20:21] neg_lo:[0,0,1] neg_hi:[0,0,1]
	ds_read_b64 v[204:205], v188 offset:60928
	ds_read_b64 v[206:207], v187 offset:60928
	s_waitcnt lgkmcnt(6)
	v_pk_mul_f32 v[20:21], v[22:23], v[202:203]
	s_nop 0
	v_pk_fma_f32 v[20:21], v[200:201], v[104:105], v[20:21]
	v_pk_mul_f32 v[104:105], v[104:105], v[202:203]
	s_nop 0
	v_pk_fma_f32 v[22:23], v[200:201], v[22:23], v[104:105] neg_lo:[0,0,1] neg_hi:[0,0,1]
	ds_read_b64 v[200:201], v188 offset:4352
	ds_read_b64 v[202:203], v187 offset:4352
	s_waitcnt lgkmcnt(6)
	v_pk_mul_f32 v[104:105], v[196:197], v[108:109]
	v_pk_mul_f32 v[108:109], v[198:199], v[108:109]
	v_pk_fma_f32 v[104:105], v[198:199], v[106:107], v[104:105]
	v_pk_fma_f32 v[106:107], v[196:197], v[106:107], v[108:109] neg_lo:[0,0,1] neg_hi:[0,0,1]
	ds_read_b64 v[196:197], v188 offset:39168
	ds_read_b64 v[198:199], v187 offset:39168
	s_waitcnt lgkmcnt(6)
	v_pk_mul_f32 v[108:109], v[110:111], v[166:167]
	s_nop 0
	v_pk_fma_f32 v[108:109], v[164:165], v[112:113], v[108:109]
	v_pk_mul_f32 v[112:113], v[112:113], v[166:167]
	s_nop 0
	v_pk_fma_f32 v[110:111], v[164:165], v[110:111], v[112:113] neg_lo:[0,0,1] neg_hi:[0,0,1]
	ds_read_b64 v[164:165], v188 offset:21760
	ds_read_b64 v[166:167], v187 offset:21760
	s_waitcnt lgkmcnt(6)
	v_pk_mul_f32 v[112:113], v[114:115], v[206:207]
	s_nop 0
	v_pk_fma_f32 v[112:113], v[204:205], v[116:117], v[112:113]
	v_pk_mul_f32 v[116:117], v[116:117], v[206:207]
	s_nop 0
	v_pk_fma_f32 v[114:115], v[204:205], v[114:115], v[116:117] neg_lo:[0,0,1] neg_hi:[0,0,1]
	ds_read_b64 v[204:205], v188 offset:56576
	ds_read_b64 v[206:207], v187 offset:56576
	s_waitcnt lgkmcnt(6)
	v_pk_mul_f32 v[116:117], v[118:119], v[202:203]
	s_nop 0
	v_pk_fma_f32 v[116:117], v[120:121], v[200:201], v[116:117]
	v_pk_mul_f32 v[120:121], v[120:121], v[202:203]
	s_nop 0
	v_pk_fma_f32 v[118:119], v[118:119], v[200:201], v[120:121] neg_lo:[0,0,1] neg_hi:[0,0,1]
	ds_read_b64 v[200:201], v188 offset:13056
	ds_read_b64 v[202:203], v187 offset:13056
	s_waitcnt lgkmcnt(6)
	v_pk_mul_f32 v[120:121], v[122:123], v[198:199]
	s_nop 0
	v_pk_fma_f32 v[120:121], v[124:125], v[196:197], v[120:121]
	v_pk_mul_f32 v[124:125], v[124:125], v[198:199]
	s_nop 0
	v_pk_fma_f32 v[122:123], v[122:123], v[196:197], v[124:125] neg_lo:[0,0,1] neg_hi:[0,0,1]
	ds_read_b64 v[196:197], v188 offset:47872
	ds_read_b64 v[198:199], v187 offset:47872
	s_waitcnt lgkmcnt(6)
	v_pk_mul_f32 v[124:125], v[126:127], v[166:167]
	s_nop 0
	v_pk_fma_f32 v[124:125], v[128:129], v[164:165], v[124:125]
	v_pk_mul_f32 v[128:129], v[128:129], v[166:167]
	s_nop 0
	v_pk_fma_f32 v[126:127], v[126:127], v[164:165], v[128:129] neg_lo:[0,0,1] neg_hi:[0,0,1]
	ds_read_b64 v[164:165], v188 offset:30464
	ds_read_b64 v[166:167], v187 offset:30464
	s_waitcnt lgkmcnt(6)
	v_pk_mul_f32 v[128:129], v[130:131], v[206:207]
	s_nop 0
	v_pk_fma_f32 v[128:129], v[132:133], v[204:205], v[128:129]
	v_pk_mul_f32 v[132:133], v[132:133], v[206:207]
	s_nop 0
	v_pk_fma_f32 v[130:131], v[130:131], v[204:205], v[132:133] neg_lo:[0,0,1] neg_hi:[0,0,1]
	s_waitcnt lgkmcnt(4)
	v_pk_mul_f32 v[132:133], v[134:135], v[202:203]
	s_nop 0
	v_pk_fma_f32 v[132:133], v[144:145], v[200:201], v[132:133]
	v_pk_mul_f32 v[144:145], v[144:145], v[202:203]
	s_nop 0
	v_pk_fma_f32 v[134:135], v[134:135], v[200:201], v[144:145] neg_lo:[0,0,1] neg_hi:[0,0,1]
	s_waitcnt lgkmcnt(2)
	v_pk_mul_f32 v[144:145], v[140:141], v[198:199]
	s_nop 0
	v_pk_fma_f32 v[144:145], v[142:143], v[196:197], v[144:145]
	v_pk_mul_f32 v[142:143], v[142:143], v[198:199]
	s_nop 0
	v_pk_fma_f32 v[140:141], v[140:141], v[196:197], v[142:143] neg_lo:[0,0,1] neg_hi:[0,0,1]
	s_waitcnt lgkmcnt(0)
	v_pk_mul_f32 v[142:143], v[136:137], v[166:167]
	s_nop 0
	v_pk_fma_f32 v[142:143], v[138:139], v[164:165], v[142:143]
	v_pk_mul_f32 v[138:139], v[138:139], v[166:167]
	s_nop 0
	v_pk_fma_f32 v[136:137], v[136:137], v[164:165], v[138:139] neg_lo:[0,0,1] neg_hi:[0,0,1]
	ds_read_b64 v[138:139], v188 offset:65280
	ds_read_b64 v[164:165], v187 offset:65280
	s_waitcnt lgkmcnt(0)
	v_pk_mul_f32 v[166:167], v[2:3], v[164:165]
	s_nop 0
	v_pk_fma_f32 v[166:167], v[0:1], v[138:139], v[166:167] neg_lo:[0,0,1] neg_hi:[0,0,1]
	v_pk_mul_f32 v[0:1], v[0:1], v[164:165]
	s_nop 0
	v_pk_fma_f32 v[0:1], v[2:3], v[138:139], v[0:1]
	v_pk_add_f32 v[2:3], v[4:5], v[8:9]
	v_pk_add_f32 v[138:139], v[6:7], v[10:11]
	v_pk_add_f32 v[4:5], v[4:5], v[8:9] neg_lo:[0,1] neg_hi:[0,1]
	v_pk_add_f32 v[6:7], v[6:7], v[10:11] neg_lo:[0,1] neg_hi:[0,1]
	v_pk_add_f32 v[8:9], v[12:13], v[16:17]
	v_pk_add_f32 v[10:11], v[14:15], v[18:19]
	v_pk_add_f32 v[12:13], v[12:13], v[16:17] neg_lo:[0,1] neg_hi:[0,1]
	v_pk_add_f32 v[14:15], v[14:15], v[18:19] neg_lo:[0,1] neg_hi:[0,1]
	v_pk_add_f32 v[16:17], v[20:21], v[104:105]
	v_pk_add_f32 v[18:19], v[22:23], v[106:107]
	v_pk_add_f32 v[20:21], v[20:21], v[104:105] neg_lo:[0,1] neg_hi:[0,1]
	v_pk_add_f32 v[22:23], v[22:23], v[106:107] neg_lo:[0,1] neg_hi:[0,1]
	v_pk_add_f32 v[104:105], v[108:109], v[112:113]
	v_pk_add_f32 v[106:107], v[110:111], v[114:115]
	v_pk_add_f32 v[108:109], v[108:109], v[112:113] neg_lo:[0,1] neg_hi:[0,1]
	v_pk_add_f32 v[110:111], v[110:111], v[114:115] neg_lo:[0,1] neg_hi:[0,1]
	v_pk_add_f32 v[112:113], v[116:117], v[120:121]
	v_pk_add_f32 v[114:115], v[118:119], v[122:123]
	v_pk_add_f32 v[116:117], v[116:117], v[120:121] neg_lo:[0,1] neg_hi:[0,1]
	v_pk_add_f32 v[118:119], v[118:119], v[122:123] neg_lo:[0,1] neg_hi:[0,1]
	v_pk_add_f32 v[120:121], v[124:125], v[128:129]
	v_pk_add_f32 v[122:123], v[126:127], v[130:131]
	v_pk_add_f32 v[124:125], v[124:125], v[128:129] neg_lo:[0,1] neg_hi:[0,1]
	v_pk_add_f32 v[126:127], v[126:127], v[130:131] neg_lo:[0,1] neg_hi:[0,1]
	v_pk_add_f32 v[128:129], v[132:133], v[144:145]
	v_pk_add_f32 v[130:131], v[134:135], v[140:141]
	v_pk_add_f32 v[132:133], v[132:133], v[144:145] neg_lo:[0,1] neg_hi:[0,1]
	v_pk_add_f32 v[134:135], v[134:135], v[140:141] neg_lo:[0,1] neg_hi:[0,1]
	v_pk_add_f32 v[140:141], v[142:143], v[0:1]
	v_pk_add_f32 v[144:145], v[136:137], v[166:167]
	v_pk_add_f32 v[136:137], v[136:137], v[166:167] neg_lo:[0,1] neg_hi:[0,1]
	v_pk_add_f32 v[0:1], v[142:143], v[0:1] neg_lo:[0,1] neg_hi:[0,1]
	v_pk_add_f32 v[142:143], v[2:3], v[8:9]
	v_pk_add_f32 v[164:165], v[138:139], v[10:11]
	v_pk_add_f32 v[2:3], v[2:3], v[8:9] neg_lo:[0,1] neg_hi:[0,1]
	v_pk_add_f32 v[8:9], v[138:139], v[10:11] neg_lo:[0,1] neg_hi:[0,1]
	v_pk_add_f32 v[138:139], v[6:7], v[12:13]
	v_pk_add_f32 v[6:7], v[6:7], v[12:13] neg_lo:[0,1] neg_hi:[0,1]
	v_pk_add_f32 v[12:13], v[16:17], v[104:105]
	v_pk_add_f32 v[16:17], v[16:17], v[104:105] neg_lo:[0,1] neg_hi:[0,1]
	v_pk_add_f32 v[104:105], v[20:21], v[110:111] neg_lo:[0,1] neg_hi:[0,1]
	v_pk_add_f32 v[20:21], v[20:21], v[110:111]
	v_pk_add_f32 v[110:111], v[114:115], v[122:123]
	v_pk_add_f32 v[114:115], v[114:115], v[122:123] neg_lo:[0,1] neg_hi:[0,1]
	v_pk_add_f32 v[122:123], v[118:119], v[124:125]
	v_pk_add_f32 v[118:119], v[118:119], v[124:125] neg_lo:[0,1] neg_hi:[0,1]
	v_pk_add_f32 v[124:125], v[128:129], v[140:141]
	v_pk_add_f32 v[128:129], v[128:129], v[140:141] neg_lo:[0,1] neg_hi:[0,1]
	v_pk_add_f32 v[140:141], v[132:133], v[136:137] neg_lo:[0,1] neg_hi:[0,1]
	v_pk_add_f32 v[10:11], v[4:5], v[14:15] neg_lo:[0,1] neg_hi:[0,1]
	v_pk_add_f32 v[4:5], v[4:5], v[14:15]
	v_pk_add_f32 v[14:15], v[18:19], v[106:107]
	v_pk_add_f32 v[18:19], v[18:19], v[106:107] neg_lo:[0,1] neg_hi:[0,1]
	v_pk_add_f32 v[106:107], v[22:23], v[108:109]
	v_pk_add_f32 v[22:23], v[22:23], v[108:109] neg_lo:[0,1] neg_hi:[0,1]
	v_pk_add_f32 v[108:109], v[112:113], v[120:121]
	v_pk_add_f32 v[112:113], v[112:113], v[120:121] neg_lo:[0,1] neg_hi:[0,1]
	v_pk_add_f32 v[120:121], v[116:117], v[126:127] neg_lo:[0,1] neg_hi:[0,1]
	v_pk_add_f32 v[116:117], v[116:117], v[126:127]
	v_pk_add_f32 v[126:127], v[130:131], v[144:145]
	v_pk_add_f32 v[130:131], v[130:131], v[144:145] neg_lo:[0,1] neg_hi:[0,1]
	v_pk_add_f32 v[144:145], v[134:135], v[0:1]
	v_pk_add_f32 v[0:1], v[134:135], v[0:1] neg_lo:[0,1] neg_hi:[0,1]
	v_pk_mul_f32 v[140:141], v[140:141], s[82:83] op_sel_hi:[1,0]
	v_pk_add_f32 v[132:133], v[132:133], v[136:137]
	v_pk_fma_f32 v[192:193], v[144:145], s[82:83], v[140:141] op_sel_hi:[1,0,1] neg_lo:[1,0,0] neg_hi:[1,0,0]
	v_pk_fma_f32 v[140:141], v[144:145], s[82:83], v[140:141] op_sel_hi:[1,0,1]
	v_pk_mul_f32 v[0:1], v[0:1], s[82:83] op_sel_hi:[1,0]
	v_pk_mul_f32 v[104:105], v[104:105], s[82:83] op_sel_hi:[1,0]
	v_pk_add_f32 v[144:145], v[120:121], v[192:193]
	v_pk_add_f32 v[194:195], v[122:123], v[140:141]
	v_pk_add_f32 v[120:121], v[120:121], v[192:193] neg_lo:[0,1] neg_hi:[0,1]
	v_pk_add_f32 v[192:193], v[114:115], v[128:129]
	v_pk_add_f32 v[114:115], v[114:115], v[128:129] neg_lo:[0,1] neg_hi:[0,1]
	v_pk_fma_f32 v[128:129], v[132:133], s[54:55], v[0:1] op_sel_hi:[1,0,1] neg_lo:[0,0,1] neg_hi:[0,0,1]
	v_pk_fma_f32 v[0:1], v[132:133], s[82:83], v[0:1] op_sel_hi:[1,0,1] neg_lo:[0,0,1] neg_hi:[0,0,1]
	v_pk_fma_f32 v[166:167], v[106:107], s[82:83], v[104:105] op_sel_hi:[1,0,1] neg_lo:[1,0,0] neg_hi:[1,0,0]
	v_pk_fma_f32 v[104:105], v[106:107], s[82:83], v[104:105] op_sel_hi:[1,0,1]
	v_pk_add_f32 v[122:123], v[122:123], v[140:141] neg_lo:[0,1] neg_hi:[0,1]
	v_pk_add_f32 v[140:141], v[112:113], v[130:131] neg_lo:[0,1] neg_hi:[0,1]
	v_pk_add_f32 v[112:113], v[112:113], v[130:131]
	v_pk_add_f32 v[130:131], v[116:117], v[128:129]
	v_pk_add_f32 v[132:133], v[118:119], v[0:1]
	v_pk_add_f32 v[116:117], v[116:117], v[128:129] neg_lo:[0,1] neg_hi:[0,1]
	v_pk_add_f32 v[0:1], v[118:119], v[0:1] neg_lo:[0,1] neg_hi:[0,1]
	v_pk_mul_f32 v[118:119], v[194:195], s[80:81] op_sel_hi:[1,0]
	v_pk_mul_f32 v[128:129], v[194:195], s[72:73] op_sel_hi:[1,0]
	v_pk_add_f32 v[106:107], v[10:11], v[166:167]
	v_pk_add_f32 v[190:191], v[138:139], v[104:105]
	v_pk_fma_f32 v[118:119], v[144:145], s[72:73], v[118:119] op_sel_hi:[1,0,1] neg_lo:[0,0,1] neg_hi:[0,0,1]
	v_pk_fma_f32 v[128:129], v[144:145], s[80:81], v[128:129] op_sel_hi:[1,0,1]
	v_pk_add_f32 v[106:107], v[106:107], v[118:119]
	v_pk_add_f32 v[118:119], v[190:191], v[128:129]
	v_pk_mul_f32 v[128:129], v[140:141], s[82:83] op_sel_hi:[1,0]
	v_pk_add_f32 v[10:11], v[10:11], v[166:167] neg_lo:[0,1] neg_hi:[0,1]
	v_pk_add_f32 v[104:105], v[138:139], v[104:105] neg_lo:[0,1] neg_hi:[0,1]
	v_pk_add_f32 v[138:139], v[2:3], v[18:19] neg_lo:[0,1] neg_hi:[0,1]
	v_pk_add_f32 v[166:167], v[8:9], v[16:17]
	v_pk_add_f32 v[8:9], v[8:9], v[16:17] neg_lo:[0,1] neg_hi:[0,1]
	v_pk_mul_f32 v[16:17], v[22:23], s[82:83] op_sel_hi:[1,0]
	v_pk_fma_f32 v[140:141], v[192:193], s[82:83], v[128:129] op_sel_hi:[1,0,1] neg_lo:[1,0,0] neg_hi:[1,0,0]
	v_pk_add_f32 v[2:3], v[2:3], v[18:19]
	v_pk_fma_f32 v[18:19], v[20:21], s[54:55], v[16:17] op_sel_hi:[1,0,1] neg_lo:[0,0,1] neg_hi:[0,0,1]
	v_pk_fma_f32 v[16:17], v[20:21], s[82:83], v[16:17] op_sel_hi:[1,0,1] neg_lo:[0,0,1] neg_hi:[0,0,1]
	v_pk_add_f32 v[138:139], v[138:139], v[140:141]
	v_pk_mul_f32 v[140:141], v[132:133], s[72:73] op_sel_hi:[1,0]
	v_pk_mul_f32 v[132:133], v[132:133], s[80:81] op_sel_hi:[1,0]
	v_pk_add_f32 v[22:23], v[6:7], v[16:17]
	v_pk_fma_f32 v[140:141], v[130:131], s[80:81], v[140:141] op_sel_hi:[1,0,1] neg_lo:[0,0,1] neg_hi:[0,0,1]
	v_pk_fma_f32 v[130:131], v[130:131], s[72:73], v[132:133] op_sel_hi:[1,0,1]
	v_pk_mul_f32 v[114:115], v[114:115], s[82:83] op_sel_hi:[1,0]
	v_pk_add_f32 v[22:23], v[22:23], v[130:131]
	v_pk_mul_f32 v[130:131], v[122:123], s[72:73] op_sel_hi:[1,0]
	v_pk_mul_f32 v[122:123], v[122:123], s[80:81] op_sel_hi:[1,0]
	v_pk_fma_f32 v[130:131], v[120:121], s[84:85], v[130:131] op_sel_hi:[1,0,1] neg_lo:[0,0,1] neg_hi:[0,0,1]
	v_pk_fma_f32 v[120:121], v[120:121], s[72:73], v[122:123] op_sel_hi:[1,0,1] neg_lo:[0,0,1] neg_hi:[0,0,1]
	v_pk_add_f32 v[6:7], v[6:7], v[16:17] neg_lo:[0,1] neg_hi:[0,1]
	v_pk_add_f32 v[104:105], v[104:105], v[120:121]
	v_pk_fma_f32 v[120:121], v[112:113], s[54:55], v[114:115] op_sel_hi:[1,0,1] neg_lo:[0,0,1] neg_hi:[0,0,1]
	v_pk_fma_f32 v[112:113], v[112:113], s[82:83], v[114:115] op_sel_hi:[1,0,1] neg_lo:[0,0,1] neg_hi:[0,0,1]
	v_pk_add_f32 v[136:137], v[164:165], v[14:15] neg_lo:[0,1] neg_hi:[0,1]
	v_pk_add_f32 v[8:9], v[8:9], v[112:113]
	v_pk_mul_f32 v[112:113], v[0:1], s[80:81] op_sel_hi:[1,0]
	v_pk_mul_f32 v[0:1], v[0:1], s[72:73] op_sel_hi:[1,0]
	v_pk_add_f32 v[134:135], v[142:143], v[12:13] neg_lo:[0,1] neg_hi:[0,1]
	v_pk_fma_f32 v[0:1], v[116:117], s[80:81], v[0:1] op_sel_hi:[1,0,1] neg_lo:[0,0,1] neg_hi:[0,0,1]
	v_pk_add_f32 v[12:13], v[142:143], v[12:13]
	v_pk_add_f32 v[0:1], v[6:7], v[0:1]
	v_pk_add_f32 v[6:7], v[164:165], v[14:15]
	v_pk_add_f32 v[14:15], v[110:111], v[126:127]
	v_pk_add_f32 v[20:21], v[4:5], v[18:19]
	v_pk_add_f32 v[6:7], v[6:7], v[14:15]
	v_pk_add_f32 v[14:15], v[108:109], v[124:125]
	v_pk_add_f32 v[4:5], v[4:5], v[18:19] neg_lo:[0,1] neg_hi:[0,1]
	v_pk_add_f32 v[16:17], v[108:109], v[124:125] neg_lo:[0,1] neg_hi:[0,1]
	v_pk_add_f32 v[18:19], v[110:111], v[126:127] neg_lo:[0,1] neg_hi:[0,1]
	v_pk_fma_f32 v[128:129], v[192:193], s[82:83], v[128:129] op_sel_hi:[1,0,1]
	v_pk_add_f32 v[2:3], v[2:3], v[120:121]
	v_pk_fma_f32 v[112:113], v[116:117], s[52:53], v[112:113] op_sel_hi:[1,0,1] neg_lo:[0,0,1] neg_hi:[0,0,1]
	v_pk_add_f32 v[12:13], v[12:13], v[14:15]
	v_pk_add_f32 v[128:129], v[166:167], v[128:129]
	v_pk_add_f32 v[20:21], v[20:21], v[140:141]
	v_pk_add_f32 v[18:19], v[134:135], v[18:19] neg_lo:[0,1] neg_hi:[0,1]
	v_pk_add_f32 v[16:17], v[136:137], v[16:17]
	v_pk_add_f32 v[10:11], v[10:11], v[130:131]
	v_pk_add_f32 v[4:5], v[4:5], v[112:113]
	ds_write_b64 v187, v[12:13]
	ds_write_b64 v188, v[6:7]
	ds_write_b64 v187, v[106:107] offset:4352
	ds_write_b64 v188, v[118:119] offset:4352
	ds_write_b64 v187, v[138:139] offset:8704
	ds_write_b64 v188, v[128:129] offset:8704
	ds_write_b64 v187, v[20:21] offset:13056
	ds_write_b64 v188, v[22:23] offset:13056
	ds_write_b64 v187, v[18:19] offset:17408
	ds_write_b64 v188, v[16:17] offset:17408
	ds_write_b64 v187, v[10:11] offset:21760
	ds_write_b64 v188, v[104:105] offset:21760
	ds_write_b64 v187, v[2:3] offset:26112
	ds_write_b64 v188, v[8:9] offset:26112
	ds_write_b64 v187, v[4:5] offset:30464
	ds_write_b64 v188, v[0:1] offset:30464
	s_waitcnt lgkmcnt(0)
	s_barrier
	ds_read_b64 v[16:17], v172
	ds_read_b64 v[18:19], v173
	ds_read_b64 v[12:13], v160 offset:4096
	ds_read_b64 v[14:15], v169
	ds_read_b64 v[8:9], v158 offset:8192
	ds_read_b64 v[10:11], v159
	ds_read_b64 v[0:1], v156 offset:12288
	ds_read_b64 v[2:3], v157
	s_waitcnt lgkmcnt(6)
	v_lshlrev_b32_e32 v4, 16, v186
	v_and_b32_e32 v5, 0xffff0000, v186
	v_pk_fma_f32 v[16:17], v[24:25], v[100:101], v[16:17]
	s_nop 0
	v_pk_mul_f32 v[16:17], v[16:17], v[4:5]
	v_lshlrev_b32_e32 v4, 16, v185
	v_and_b32_e32 v5, 0xffff0000, v185
	v_pk_fma_f32 v[18:19], v[24:25], v[102:103], v[18:19]
	s_nop 0
	v_pk_mul_f32 v[18:19], v[18:19], v[4:5]
	ds_write_b64 v172, v[16:17]
	ds_write_b64 v173, v[18:19]
	v_cvt_pk_bf16_f32 v113, v16, v17
	v_cvt_pk_bf16_f32 v112, v18, v19
	ds_read_b64 v[16:17], v154 offset:16384
	ds_read_b64 v[18:19], v155
	s_waitcnt lgkmcnt(8)
	v_lshlrev_b32_e32 v4, 16, v184
	v_and_b32_e32 v5, 0xffff0000, v184
	v_pk_fma_f32 v[12:13], v[24:25], v[96:97], v[12:13]
	s_nop 0
	v_pk_mul_f32 v[12:13], v[12:13], v[4:5]
	v_lshlrev_b32_e32 v4, 16, v183
	v_and_b32_e32 v5, 0xffff0000, v183
	v_pk_fma_f32 v[14:15], v[24:25], v[98:99], v[14:15]
	s_nop 0
	v_pk_mul_f32 v[14:15], v[14:15], v[4:5]
	ds_write_b64 v160, v[12:13] offset:4096
	ds_write_b64 v169, v[14:15]
	v_cvt_pk_bf16_f32 v111, v12, v13
	v_cvt_pk_bf16_f32 v110, v14, v15
	ds_read_b64 v[12:13], v152 offset:20480
	ds_read_b64 v[14:15], v153
	s_waitcnt lgkmcnt(10)
	v_lshlrev_b32_e32 v4, 16, v182
	v_and_b32_e32 v5, 0xffff0000, v182
	v_pk_fma_f32 v[8:9], v[24:25], v[92:93], v[8:9]
	s_nop 0
	v_pk_mul_f32 v[8:9], v[8:9], v[4:5]
	v_lshlrev_b32_e32 v4, 16, v181
	v_and_b32_e32 v5, 0xffff0000, v181
	v_pk_fma_f32 v[10:11], v[24:25], v[94:95], v[10:11]
	s_nop 0
	v_pk_mul_f32 v[10:11], v[10:11], v[4:5]
	ds_write_b64 v158, v[8:9] offset:8192
	ds_write_b64 v159, v[10:11]
	v_cvt_pk_bf16_f32 v109, v8, v9
	v_cvt_pk_bf16_f32 v108, v10, v11
	ds_read_b64 v[8:9], v150 offset:24576
	ds_read_b64 v[10:11], v151
	s_waitcnt lgkmcnt(12)
	v_lshlrev_b32_e32 v4, 16, v180
	v_and_b32_e32 v5, 0xffff0000, v180
	v_pk_fma_f32 v[0:1], v[24:25], v[88:89], v[0:1]
	s_nop 0
	v_pk_mul_f32 v[0:1], v[0:1], v[4:5]
	v_lshlrev_b32_e32 v4, 16, v178
	v_and_b32_e32 v5, 0xffff0000, v178
	v_pk_fma_f32 v[2:3], v[24:25], v[90:91], v[2:3]
	s_nop 0
	v_pk_mul_f32 v[2:3], v[2:3], v[4:5]
	ds_write_b64 v156, v[0:1] offset:12288
	ds_write_b64 v157, v[2:3]
	v_cvt_pk_bf16_f32 v107, v0, v1
	v_cvt_pk_bf16_f32 v106, v2, v3
	ds_read_b64 v[0:1], v148 offset:28672
	ds_read_b64 v[2:3], v149
	s_waitcnt lgkmcnt(12)
	v_lshlrev_b32_e32 v4, 16, v179
	v_and_b32_e32 v5, 0xffff0000, v179
	v_pk_fma_f32 v[16:17], v[24:25], v[84:85], v[16:17]
	s_nop 0
	v_pk_mul_f32 v[16:17], v[16:17], v[4:5]
	v_lshlrev_b32_e32 v4, 16, v177
	v_and_b32_e32 v5, 0xffff0000, v177
	v_pk_fma_f32 v[18:19], v[24:25], v[86:87], v[18:19]
	s_nop 0
	v_pk_mul_f32 v[18:19], v[18:19], v[4:5]
	ds_write_b64 v154, v[16:17] offset:16384
	ds_write_b64 v155, v[18:19]
	v_cvt_pk_bf16_f32 v105, v16, v17
	v_cvt_pk_bf16_f32 v104, v18, v19
	s_waitcnt lgkmcnt(10)
	v_lshlrev_b32_e32 v4, 16, v176
	v_and_b32_e32 v5, 0xffff0000, v176
	v_pk_fma_f32 v[12:13], v[24:25], v[80:81], v[12:13]
	s_nop 0
	v_pk_mul_f32 v[12:13], v[12:13], v[4:5]
	v_lshlrev_b32_e32 v4, 16, v175
	v_and_b32_e32 v5, 0xffff0000, v175
	v_pk_fma_f32 v[14:15], v[24:25], v[82:83], v[14:15]
	s_nop 0
	v_pk_mul_f32 v[14:15], v[14:15], v[4:5]
	ds_write_b64 v152, v[12:13] offset:20480
	ds_write_b64 v153, v[14:15]
	v_cvt_pk_bf16_f32 v103, v12, v13
	v_cvt_pk_bf16_f32 v102, v14, v15
	s_waitcnt lgkmcnt(8)
	v_lshlrev_b32_e32 v4, 16, v174
	v_and_b32_e32 v5, 0xffff0000, v174
	v_pk_fma_f32 v[8:9], v[24:25], v[76:77], v[8:9]
	s_nop 0
	v_pk_mul_f32 v[8:9], v[8:9], v[4:5]
	v_lshlrev_b32_e32 v4, 16, v171
	v_and_b32_e32 v5, 0xffff0000, v171
	v_pk_fma_f32 v[10:11], v[24:25], v[78:79], v[10:11]
	s_nop 0
	v_pk_mul_f32 v[10:11], v[10:11], v[4:5]
	ds_write_b64 v150, v[8:9] offset:24576
	ds_write_b64 v151, v[10:11]
	v_cvt_pk_bf16_f32 v101, v8, v9
	v_cvt_pk_bf16_f32 v100, v10, v11
	s_waitcnt lgkmcnt(6)
	v_lshlrev_b32_e32 v4, 16, v170
	v_and_b32_e32 v5, 0xffff0000, v170
	v_pk_fma_f32 v[0:1], v[24:25], v[72:73], v[0:1]
	s_nop 0
	v_pk_mul_f32 v[0:1], v[0:1], v[4:5]
	v_lshlrev_b32_e32 v4, 16, v168
	v_and_b32_e32 v5, 0xffff0000, v168
	v_pk_fma_f32 v[2:3], v[24:25], v[74:75], v[2:3]
	s_nop 0
	v_pk_mul_f32 v[2:3], v[2:3], v[4:5]
	ds_write_b64 v148, v[0:1] offset:28672
	ds_write_b64 v149, v[2:3]
	v_cvt_pk_bf16_f32 v99, v0, v1
	v_lshl_add_u64 v[0:1], s[4:5], 0, v[68:69]
	v_cvt_pk_bf16_f32 v98, v2, v3
	global_load_dword v128, v[0:1], off
	v_lshl_add_u64 v[0:1], s[6:7], 0, v[68:69]
	global_load_dword v129, v[0:1], off
	v_lshl_add_u64 v[0:1], s[4:5], 0, v[70:71]
	global_load_dword v126, v[0:1], off
	v_lshl_add_u64 v[0:1], s[6:7], 0, v[70:71]
	global_load_dword v127, v[0:1], off
	v_lshl_add_u64 v[0:1], s[4:5], 0, v[66:67]
	global_load_dword v123, v[0:1], off
	v_lshl_add_u64 v[0:1], s[6:7], 0, v[66:67]
	global_load_dword v124, v[0:1], off
	v_lshl_add_u64 v[0:1], s[4:5], 0, v[64:65]
	global_load_dword v120, v[0:1], off
	v_lshl_add_u64 v[0:1], s[6:7], 0, v[64:65]
	global_load_dword v125, v[0:1], off
	v_lshl_add_u64 v[0:1], s[4:5], 0, v[62:63]
	global_load_dword v121, v[0:1], off
	v_lshl_add_u64 v[0:1], s[6:7], 0, v[62:63]
	global_load_dword v122, v[0:1], off
	v_lshl_add_u64 v[0:1], s[4:5], 0, v[60:61]
	global_load_dword v118, v[0:1], off
	v_lshl_add_u64 v[0:1], s[6:7], 0, v[60:61]
	global_load_dword v119, v[0:1], off
	v_lshl_add_u64 v[0:1], s[4:5], 0, v[58:59]
	global_load_dword v115, v[0:1], off
	v_lshl_add_u64 v[0:1], s[6:7], 0, v[58:59]
	global_load_dword v116, v[0:1], off
	v_lshl_add_u64 v[0:1], s[4:5], 0, v[56:57]
	global_load_dword v114, v[0:1], off
	v_lshl_add_u64 v[0:1], s[6:7], 0, v[56:57]
	global_load_dword v117, v[0:1], off
	v_mov_b32_e32 v0, v163
	s_waitcnt lgkmcnt(0)
	s_barrier
	s_nop 0
	s_nop 0
	v_ashrrev_i32_e32 v2, 31, v0
	v_lshlrev_b32_e32 v1, 1, v0
	v_lshrrev_b32_e32 v2, 23, v2
	v_and_b32_e32 v1, 0x3fe, v1
	v_add_lshl_u32 v0, v0, v2, 5
	v_and_or_b32 v0, v0, s85, v1
	v_ashrrev_i32_e32 v2, 4, v0
	v_and_b32_e32 v2, 0x3ffffc3c, v2
	v_add_lshl_u32 v88, v2, v0, 2
	v_cvt_f32_u32_e32 v0, v1
	v_or_b32_e32 v1, 1, v1
	v_cvt_f32_u32_e32 v1, v1
	v_add_u32_e32 v162, 0, v88
	v_mul_f32_e32 v2, 0x38800000, v0
	v_add_u32_e32 v168, s91, v88
	v_mul_f32_e32 v3, 0x38800000, v1
	ds_read_b64 v[88:89], v162
	ds_read_b64 v[90:91], v168
	ds_read_b64 v[92:93], v162 offset:4352
	ds_read_b64 v[94:95], v168 offset:4352
	ds_read_b64 v[96:97], v162 offset:8704
	ds_read_b64 v[130:131], v168 offset:8704
	ds_read_b64 v[132:133], v162 offset:13056
	ds_read_b64 v[134:135], v168 offset:13056
	ds_read_b64 v[136:137], v162 offset:17408
	ds_read_b64 v[138:139], v168 offset:17408
	ds_read_b64 v[140:141], v162 offset:21760
	ds_read_b64 v[142:143], v168 offset:21760
	ds_read_b64 v[144:145], v162 offset:26112
	ds_read_b64 v[164:165], v168 offset:26112
	ds_read_b64 v[166:167], v162 offset:30464
	ds_read_b64 v[170:171], v168 offset:30464
	v_sin_f32_e64 v14, -v2
	v_sin_f32_e64 v15, -v3
	s_waitcnt lgkmcnt(12)
	v_pk_mul_f32 v[182:183], v[94:95], s[80:81] op_sel_hi:[1,0]
	v_cos_f32_e32 v0, v2
	v_cos_f32_e32 v1, v3
	v_pk_add_f32 v[178:179], v[92:93], 0 op_sel_hi:[1,0]
	v_pk_fma_f32 v[182:183], v[92:93], s[72:73], v[182:183] op_sel_hi:[1,0,1]
	v_pk_mul_f32 v[92:93], v[92:93], s[80:81] op_sel_hi:[1,0]
	v_pk_add_f32 v[180:181], v[94:95], 0 op_sel_hi:[1,0]
	v_pk_fma_f32 v[92:93], v[94:95], s[72:73], v[92:93] op_sel_hi:[1,0,1] neg_lo:[0,0,1] neg_hi:[0,0,1]
	s_waitcnt lgkmcnt(11)
	v_pk_add_f32 v[94:95], v[96:97], 0 op_sel_hi:[1,0]
	v_pk_mul_f32 v[96:97], v[96:97], s[82:83] op_sel_hi:[1,0]
	s_waitcnt lgkmcnt(8)
	v_pk_mul_f32 v[190:191], v[134:135], s[72:73] op_sel_hi:[1,0]
	v_pk_add_f32 v[184:185], v[130:131], 0 op_sel_hi:[1,0]
	v_pk_fma_f32 v[186:187], v[130:131], s[82:83], v[96:97] op_sel_hi:[1,0,1]
	v_pk_fma_f32 v[96:97], v[130:131], s[82:83], v[96:97] op_sel_hi:[1,0,1] neg_lo:[0,0,1] neg_hi:[0,0,1]
	v_pk_add_f32 v[130:131], v[132:133], 0 op_sel_hi:[1,0]
	v_pk_fma_f32 v[190:191], v[132:133], s[80:81], v[190:191] op_sel_hi:[1,0,1]
	v_pk_mul_f32 v[132:133], v[132:133], s[72:73] op_sel_hi:[1,0]
	s_waitcnt lgkmcnt(5)
	v_pk_mul_f32 v[198:199], v[140:141], s[80:81] op_sel_hi:[1,0]
	s_waitcnt lgkmcnt(1)
	v_pk_mul_f32 v[206:207], v[166:167], s[72:73] op_sel_hi:[1,0]
	v_pk_mul_f32 v[2:3], v[14:15], v[14:15]
	v_pk_add_f32 v[174:175], v[88:89], 0 op_sel_hi:[1,0]
	v_pk_add_f32 v[176:177], v[90:91], 0 op_sel_hi:[1,0]
	v_pk_add_f32 v[188:189], v[134:135], 0 op_sel_hi:[1,0]
	v_pk_fma_f32 v[132:133], v[134:135], s[80:81], v[132:133] op_sel_hi:[1,0,1] neg_lo:[0,0,1] neg_hi:[0,0,1]
	v_pk_add_f32 v[134:135], v[136:137], 0 op_sel_hi:[1,0]
	v_pk_add_f32 v[192:193], v[138:139], 0 op_sel_hi:[1,0]
	v_pk_add_f32 v[194:195], v[140:141], 0 op_sel_hi:[1,0]
	v_pk_add_f32 v[196:197], v[142:143], 0 op_sel_hi:[1,0]
	v_pk_fma_f32 v[198:199], v[142:143], s[72:73], v[198:199] op_sel_hi:[1,0,1] neg_lo:[0,0,1] neg_hi:[0,0,1]
	v_pk_mul_f32 v[142:143], v[142:143], s[80:81] op_sel_hi:[1,0]
	v_pk_add_f32 v[200:201], v[164:165], 0 op_sel_hi:[1,0]
	v_pk_mul_f32 v[164:165], v[164:165], s[54:55] op_sel_hi:[1,0]
	s_waitcnt lgkmcnt(0)
	v_pk_add_f32 v[204:205], v[170:171], 0 op_sel_hi:[1,0]
	v_pk_fma_f32 v[206:207], v[170:171], s[80:81], v[206:207] op_sel_hi:[1,0,1] neg_lo:[0,0,1] neg_hi:[0,0,1]
	v_pk_mul_f32 v[170:171], v[170:171], s[72:73] op_sel_hi:[1,0]
	v_pk_fma_f32 v[58:59], v[0:1], v[0:1], v[2:3] neg_lo:[0,0,1] neg_hi:[0,0,1]
	v_pk_mul_f32 v[2:3], v[0:1], v[14:15]
	v_pk_fma_f32 v[140:141], v[140:141], s[52:53], v[142:143] op_sel_hi:[1,0,1] neg_lo:[0,0,1] neg_hi:[0,0,1]
	v_pk_add_f32 v[142:143], v[144:145], 0 op_sel_hi:[1,0]
	v_pk_fma_f32 v[202:203], v[144:145], s[54:55], v[164:165] op_sel_hi:[1,0,1] neg_lo:[0,0,1] neg_hi:[0,0,1]
	v_pk_fma_f32 v[144:145], v[144:145], s[54:55], v[164:165] op_sel_hi:[1,0,1]
	v_pk_add_f32 v[164:165], v[166:167], 0 op_sel_hi:[1,0]
	v_pk_fma_f32 v[166:167], v[166:167], s[84:85], v[170:171] op_sel_hi:[1,0,1] neg_lo:[0,0,1] neg_hi:[0,0,1]
	v_pk_add_f32 v[170:171], v[174:175], v[134:135]
	v_pk_add_f32 v[208:209], v[176:177], v[192:193]
	v_pk_add_f32 v[134:135], v[174:175], v[134:135] neg_lo:[0,1] neg_hi:[0,1]
	v_pk_add_f32 v[174:175], v[176:177], v[192:193] neg_lo:[0,1] neg_hi:[0,1]
	v_pk_add_f32 v[176:177], v[178:179], v[194:195]
	v_pk_add_f32 v[178:179], v[178:179], v[194:195] neg_lo:[0,1] neg_hi:[0,1]
	v_pk_add_f32 v[64:65], v[2:3], v[2:3]
	v_pk_add_f32 v[192:193], v[180:181], v[196:197]
	v_pk_add_f32 v[180:181], v[180:181], v[196:197] neg_lo:[0,1] neg_hi:[0,1]
	v_pk_mul_f32 v[178:179], v[178:179], s[82:83] op_sel_hi:[1,0]
	v_pk_mul_f32 v[2:3], v[14:15], v[64:65]
	v_pk_fma_f32 v[194:195], v[180:181], s[82:83], v[178:179] op_sel_hi:[1,0,1]
	v_pk_fma_f32 v[178:179], v[180:181], s[82:83], v[178:179] op_sel_hi:[1,0,1] neg_lo:[0,0,1] neg_hi:[0,0,1]
	v_pk_add_f32 v[180:181], v[94:95], v[142:143]
	v_pk_add_f32 v[196:197], v[184:185], v[200:201]
	v_pk_add_f32 v[94:95], v[94:95], v[142:143] neg_lo:[0,1] neg_hi:[0,1]
	v_pk_add_f32 v[142:143], v[184:185], v[200:201] neg_lo:[0,1] neg_hi:[0,1]
	v_pk_add_f32 v[184:185], v[130:131], v[164:165]
	v_pk_add_f32 v[130:131], v[130:131], v[164:165] neg_lo:[0,1] neg_hi:[0,1]
	v_pk_add_f32 v[164:165], v[188:189], v[204:205] neg_lo:[0,1] neg_hi:[0,1]
	v_pk_fma_f32 v[6:7], v[0:1], v[58:59], v[2:3] neg_lo:[0,0,1] neg_hi:[0,0,1]
	v_pk_mul_f32 v[2:3], v[14:15], v[58:59]
	v_pk_add_f32 v[200:201], v[188:189], v[204:205]
	v_pk_mul_f32 v[164:165], v[164:165], s[54:55] op_sel_hi:[1,0]
	v_pk_add_f32 v[204:205], v[90:91], v[136:137] neg_lo:[0,1] neg_hi:[0,1]
	v_pk_add_f32 v[90:91], v[90:91], v[136:137]
	v_pk_add_f32 v[136:137], v[182:183], v[198:199]
	v_pk_add_f32 v[182:183], v[182:183], v[198:199] neg_lo:[0,1] neg_hi:[0,1]
	v_pk_fma_f32 v[12:13], v[0:1], v[64:65], v[2:3]
	v_pk_mul_f32 v[2:3], v[64:65], v[64:65]
	v_pk_fma_f32 v[188:189], v[130:131], s[54:55], v[164:165] op_sel_hi:[1,0,1] neg_lo:[0,0,1] neg_hi:[0,0,1]
	v_pk_fma_f32 v[130:131], v[130:131], s[54:55], v[164:165] op_sel_hi:[1,0,1]
	v_pk_add_f32 v[164:165], v[88:89], v[138:139]
	v_pk_add_f32 v[88:89], v[88:89], v[138:139] neg_lo:[0,1] neg_hi:[0,1]
	v_pk_add_f32 v[138:139], v[92:93], v[140:141]
	v_pk_add_f32 v[92:93], v[92:93], v[140:141] neg_lo:[0,1] neg_hi:[0,1]
	v_pk_mul_f32 v[140:141], v[182:183], s[82:83] op_sel_hi:[1,0]
	v_pk_fma_f32 v[72:73], v[58:59], v[58:59], v[2:3] neg_lo:[0,0,1] neg_hi:[0,0,1]
	v_pk_mul_f32 v[2:3], v[58:59], v[64:65]
	v_pk_fma_f32 v[182:183], v[92:93], s[82:83], v[140:141] op_sel_hi:[1,0,1]
	v_pk_fma_f32 v[92:93], v[92:93], s[82:83], v[140:141] op_sel_hi:[1,0,1] neg_lo:[0,0,1] neg_hi:[0,0,1]
	v_pk_add_f32 v[140:141], v[186:187], v[202:203]
	v_pk_add_f32 v[186:187], v[186:187], v[202:203] neg_lo:[0,1] neg_hi:[0,1]
	v_pk_add_f32 v[202:203], v[132:133], v[166:167]
	v_pk_add_f32 v[132:133], v[132:133], v[166:167] neg_lo:[0,1] neg_hi:[0,1]
	v_pk_add_f32 v[74:75], v[2:3], v[2:3]
	v_pk_add_f32 v[198:199], v[96:97], v[144:145]
	v_pk_add_f32 v[96:97], v[96:97], v[144:145] neg_lo:[0,1] neg_hi:[0,1]
	v_pk_add_f32 v[144:145], v[190:191], v[206:207]
	v_pk_add_f32 v[190:191], v[190:191], v[206:207] neg_lo:[0,1] neg_hi:[0,1]
	v_pk_mul_f32 v[132:133], v[132:133], s[54:55] op_sel_hi:[1,0]
	v_pk_mul_f32 v[2:3], v[14:15], v[74:75]
	v_pk_mul_f32 v[8:9], v[74:75], v[74:75]
	v_pk_mul_f32 v[10:11], v[72:73], v[74:75]
	v_pk_fma_f32 v[166:167], v[190:191], s[54:55], v[132:133] op_sel_hi:[1,0,1] neg_lo:[0,0,1] neg_hi:[0,0,1]
	v_pk_fma_f32 v[132:133], v[190:191], s[54:55], v[132:133] op_sel_hi:[1,0,1]
	v_pk_add_f32 v[190:191], v[170:171], v[180:181]
	v_pk_add_f32 v[206:207], v[208:209], v[196:197]
	v_pk_add_f32 v[170:171], v[170:171], v[180:181] neg_lo:[0,1] neg_hi:[0,1]
	v_pk_add_f32 v[180:181], v[208:209], v[196:197] neg_lo:[0,1] neg_hi:[0,1]
	v_pk_add_f32 v[196:197], v[176:177], v[184:185]
	v_pk_add_f32 v[208:209], v[192:193], v[200:201]
	v_pk_fma_f32 v[16:17], v[0:1], v[72:73], v[2:3] neg_lo:[0,0,1] neg_hi:[0,0,1]
	v_pk_mul_f32 v[2:3], v[14:15], v[72:73]
	v_pk_fma_f32 v[8:9], v[72:73], v[72:73], v[8:9] neg_lo:[0,0,1] neg_hi:[0,0,1]
	v_pk_add_f32 v[10:11], v[10:11], v[10:11]
	v_pk_add_f32 v[176:177], v[176:177], v[184:185] neg_lo:[0,1] neg_hi:[0,1]
	v_pk_add_f32 v[184:185], v[192:193], v[200:201] neg_lo:[0,1] neg_hi:[0,1]
	v_pk_add_f32 v[192:193], v[134:135], v[142:143]
	v_pk_add_f32 v[200:201], v[174:175], v[94:95] neg_lo:[0,1] neg_hi:[0,1]
	v_pk_add_f32 v[134:135], v[134:135], v[142:143] neg_lo:[0,1] neg_hi:[0,1]
	v_pk_add_f32 v[94:95], v[174:175], v[94:95]
	v_pk_add_f32 v[142:143], v[194:195], v[188:189]
	v_pk_add_f32 v[174:175], v[178:179], v[130:131]
	v_pk_add_f32 v[188:189], v[194:195], v[188:189] neg_lo:[0,1] neg_hi:[0,1]
	v_pk_add_f32 v[130:131], v[178:179], v[130:131] neg_lo:[0,1] neg_hi:[0,1]
	v_pk_add_f32 v[178:179], v[164:165], v[140:141]
	v_pk_add_f32 v[194:195], v[204:205], v[198:199]
	v_pk_add_f32 v[140:141], v[164:165], v[140:141] neg_lo:[0,1] neg_hi:[0,1]
	v_pk_add_f32 v[164:165], v[204:205], v[198:199] neg_lo:[0,1] neg_hi:[0,1]
	v_pk_add_f32 v[198:199], v[136:137], v[144:145]
	v_pk_add_f32 v[204:205], v[138:139], v[202:203]
	v_pk_add_f32 v[136:137], v[136:137], v[144:145] neg_lo:[0,1] neg_hi:[0,1]
	v_pk_add_f32 v[138:139], v[138:139], v[202:203] neg_lo:[0,1] neg_hi:[0,1]
	v_pk_add_f32 v[144:145], v[88:89], v[96:97]
	v_pk_add_f32 v[202:203], v[90:91], v[186:187] neg_lo:[0,1] neg_hi:[0,1]
	v_pk_add_f32 v[88:89], v[88:89], v[96:97] neg_lo:[0,1] neg_hi:[0,1]
	v_pk_add_f32 v[90:91], v[90:91], v[186:187]
	v_pk_add_f32 v[96:97], v[182:183], v[166:167]
	v_pk_add_f32 v[186:187], v[92:93], v[132:133]
	v_pk_add_f32 v[166:167], v[182:183], v[166:167] neg_lo:[0,1] neg_hi:[0,1]
	v_pk_add_f32 v[92:93], v[92:93], v[132:133] neg_lo:[0,1] neg_hi:[0,1]
	v_pk_add_f32 v[132:133], v[190:191], v[196:197]
	v_pk_add_f32 v[182:183], v[206:207], v[208:209]
	v_pk_add_f32 v[190:191], v[190:191], v[196:197] neg_lo:[0,1] neg_hi:[0,1]
	v_pk_add_f32 v[196:197], v[206:207], v[208:209] neg_lo:[0,1] neg_hi:[0,1]
	v_pk_fma_f32 v[18:19], v[0:1], v[74:75], v[2:3]
	v_pk_mul_f32 v[2:3], v[64:65], v[74:75]
	ds_write_b64 v162, v[132:133]
	ds_write_b64 v168, v[182:183]
	v_pk_mul_f32 v[132:133], v[8:9], v[196:197]
	v_pk_mul_f32 v[182:183], v[10:11], v[196:197]
	v_pk_fma_f32 v[66:67], v[58:59], v[72:73], v[2:3] neg_lo:[0,0,1] neg_hi:[0,0,1]
	v_pk_mul_f32 v[2:3], v[64:65], v[72:73]
	v_pk_mul_f32 v[4:5], v[72:73], v[12:13]
	v_pk_mul_f32 v[62:63], v[74:75], v[10:11]
	v_pk_add_f32 v[206:207], v[170:171], v[184:185]
	v_pk_add_f32 v[208:209], v[180:181], v[176:177] neg_lo:[0,1] neg_hi:[0,1]
	v_pk_fma_f32 v[132:133], v[10:11], v[190:191], v[132:133]
	v_pk_fma_f32 v[182:183], v[8:9], v[190:191], v[182:183] neg_lo:[0,0,1] neg_hi:[0,0,1]
	v_pk_fma_f32 v[70:71], v[58:59], v[74:75], v[2:3]
	v_pk_mul_f32 v[2:3], v[74:75], v[12:13]
	v_pk_fma_f32 v[4:5], v[74:75], v[6:7], v[4:5]
	v_pk_fma_f32 v[80:81], v[72:73], v[8:9], v[62:63] neg_lo:[0,0,1] neg_hi:[0,0,1]
	v_pk_mul_f32 v[62:63], v[74:75], v[8:9]
	ds_write_b64 v162, v[182:183] offset:34816
	ds_write_b64 v168, v[132:133] offset:34816
	v_pk_mul_f32 v[132:133], v[74:75], v[206:207]
	v_pk_mul_f32 v[74:75], v[74:75], v[208:209]
	v_pk_fma_f32 v[2:3], v[72:73], v[6:7], v[2:3] neg_lo:[0,0,1] neg_hi:[0,0,1]
	v_pk_mul_f32 v[20:21], v[14:15], v[10:11]
	v_pk_fma_f32 v[82:83], v[72:73], v[10:11], v[62:63]
	v_pk_add_f32 v[170:171], v[170:171], v[184:185] neg_lo:[0,1] neg_hi:[0,1]
	v_pk_add_f32 v[176:177], v[180:181], v[176:177]
	v_pk_fma_f32 v[132:133], v[72:73], v[208:209], v[132:133]
	v_pk_fma_f32 v[72:73], v[72:73], v[206:207], v[74:75] neg_lo:[0,0,1] neg_hi:[0,0,1]
	v_pk_fma_f32 v[56:57], v[0:1], v[8:9], v[20:21] neg_lo:[0,0,1] neg_hi:[0,0,1]
	v_pk_mul_f32 v[20:21], v[14:15], v[8:9]
	ds_write_b64 v162, v[72:73] offset:17408
	ds_write_b64 v168, v[132:133] offset:17408
	v_pk_mul_f32 v[72:73], v[82:83], v[170:171]
	v_pk_mul_f32 v[74:75], v[82:83], v[176:177]
	v_pk_fma_f32 v[60:61], v[0:1], v[10:11], v[20:21]
	v_pk_mul_f32 v[20:21], v[64:65], v[10:11]
	v_pk_add_f32 v[180:181], v[192:193], v[142:143]
	v_pk_add_f32 v[184:185], v[200:201], v[174:175]
	v_pk_fma_f32 v[72:73], v[80:81], v[176:177], v[72:73]
	v_pk_fma_f32 v[74:75], v[80:81], v[170:171], v[74:75] neg_lo:[0,0,1] neg_hi:[0,0,1]
	v_pk_fma_f32 v[76:77], v[58:59], v[8:9], v[20:21] neg_lo:[0,0,1] neg_hi:[0,0,1]
	v_pk_mul_f32 v[20:21], v[64:65], v[8:9]
	ds_write_b64 v162, v[74:75] offset:52224
	ds_write_b64 v168, v[72:73] offset:52224
	v_pk_mul_f32 v[72:73], v[64:65], v[180:181]
	v_pk_mul_f32 v[64:65], v[64:65], v[184:185]
	v_pk_fma_f32 v[78:79], v[58:59], v[10:11], v[20:21]
	v_pk_add_f32 v[142:143], v[192:193], v[142:143] neg_lo:[0,1] neg_hi:[0,1]
	v_pk_add_f32 v[174:175], v[200:201], v[174:175] neg_lo:[0,1] neg_hi:[0,1]
	v_pk_fma_f32 v[72:73], v[58:59], v[184:185], v[72:73]
	v_pk_fma_f32 v[58:59], v[58:59], v[180:181], v[64:65] neg_lo:[0,0,1] neg_hi:[0,0,1]
	ds_write_b64 v162, v[58:59] offset:8704
	ds_write_b64 v168, v[72:73] offset:8704
	v_pk_mul_f32 v[58:59], v[78:79], v[142:143]
	v_pk_mul_f32 v[64:65], v[78:79], v[174:175]
	v_pk_add_f32 v[192:193], v[134:135], v[130:131]
	v_pk_add_f32 v[200:201], v[94:95], v[188:189] neg_lo:[0,1] neg_hi:[0,1]
	v_pk_fma_f32 v[58:59], v[76:77], v[174:175], v[58:59]
	v_pk_fma_f32 v[64:65], v[76:77], v[142:143], v[64:65] neg_lo:[0,0,1] neg_hi:[0,0,1]
	v_pk_mul_f32 v[86:87], v[8:9], v[70:71]
	ds_write_b64 v162, v[64:65] offset:43520
	ds_write_b64 v168, v[58:59] offset:43520
	v_pk_mul_f32 v[58:59], v[70:71], v[192:193]
	v_pk_mul_f32 v[64:65], v[70:71], v[200:201]
	v_pk_mul_f32 v[84:85], v[10:11], v[70:71]
	v_pk_fma_f32 v[86:87], v[10:11], v[66:67], v[86:87]
	v_pk_add_f32 v[130:131], v[134:135], v[130:131] neg_lo:[0,1] neg_hi:[0,1]
	v_pk_add_f32 v[94:95], v[94:95], v[188:189]
	v_pk_fma_f32 v[58:59], v[66:67], v[200:201], v[58:59]
	v_pk_fma_f32 v[64:65], v[66:67], v[192:193], v[64:65] neg_lo:[0,0,1] neg_hi:[0,0,1]
	v_pk_fma_f32 v[84:85], v[8:9], v[66:67], v[84:85] neg_lo:[0,0,1] neg_hi:[0,0,1]
	ds_write_b64 v162, v[64:65] offset:26112
	ds_write_b64 v168, v[58:59] offset:26112
	v_pk_mul_f32 v[58:59], v[86:87], v[130:131]
	v_pk_mul_f32 v[64:65], v[86:87], v[94:95]
	v_pk_add_f32 v[134:135], v[178:179], v[198:199]
	v_pk_add_f32 v[188:189], v[194:195], v[204:205]
	v_pk_fma_f32 v[58:59], v[84:85], v[94:95], v[58:59]
	v_pk_fma_f32 v[64:65], v[84:85], v[130:131], v[64:65] neg_lo:[0,0,1] neg_hi:[0,0,1]
	ds_write_b64 v162, v[64:65] offset:60928
	ds_write_b64 v168, v[58:59] offset:60928
	v_pk_mul_f32 v[58:59], v[14:15], v[134:135]
	v_pk_mul_f32 v[14:15], v[14:15], v[188:189]
	v_pk_add_f32 v[178:179], v[178:179], v[198:199] neg_lo:[0,1] neg_hi:[0,1]
	v_pk_add_f32 v[194:195], v[194:195], v[204:205] neg_lo:[0,1] neg_hi:[0,1]
	v_pk_fma_f32 v[58:59], v[0:1], v[188:189], v[58:59]
	v_pk_fma_f32 v[0:1], v[0:1], v[134:135], v[14:15] neg_lo:[0,0,1] neg_hi:[0,0,1]
	ds_write_b64 v162, v[0:1] offset:4352
	ds_write_b64 v168, v[58:59] offset:4352
	v_pk_mul_f32 v[0:1], v[60:61], v[178:179]
	v_pk_mul_f32 v[14:15], v[60:61], v[194:195]
	v_pk_add_f32 v[198:199], v[140:141], v[138:139]
	v_pk_add_f32 v[204:205], v[164:165], v[136:137] neg_lo:[0,1] neg_hi:[0,1]
	v_pk_fma_f32 v[0:1], v[56:57], v[194:195], v[0:1]
	v_pk_fma_f32 v[14:15], v[56:57], v[178:179], v[14:15] neg_lo:[0,0,1] neg_hi:[0,0,1]
	v_pk_mul_f32 v[68:69], v[8:9], v[18:19]
	ds_write_b64 v162, v[14:15] offset:39168
	ds_write_b64 v168, v[0:1] offset:39168
	v_pk_mul_f32 v[0:1], v[18:19], v[198:199]
	v_pk_mul_f32 v[14:15], v[18:19], v[204:205]
	v_pk_mul_f32 v[62:63], v[10:11], v[18:19]
	v_pk_fma_f32 v[68:69], v[10:11], v[16:17], v[68:69]
	v_pk_add_f32 v[138:139], v[140:141], v[138:139] neg_lo:[0,1] neg_hi:[0,1]
	v_pk_add_f32 v[136:137], v[164:165], v[136:137]
	v_pk_fma_f32 v[0:1], v[16:17], v[204:205], v[0:1]
	v_pk_fma_f32 v[14:15], v[16:17], v[198:199], v[14:15] neg_lo:[0,0,1] neg_hi:[0,0,1]
	v_pk_fma_f32 v[62:63], v[8:9], v[16:17], v[62:63] neg_lo:[0,0,1] neg_hi:[0,0,1]
	ds_write_b64 v162, v[14:15] offset:21760
	ds_write_b64 v168, v[0:1] offset:21760
	v_pk_mul_f32 v[0:1], v[68:69], v[138:139]
	v_pk_mul_f32 v[14:15], v[68:69], v[136:137]
	v_pk_add_f32 v[140:141], v[144:145], v[96:97]
	v_pk_add_f32 v[164:165], v[202:203], v[186:187]
	v_pk_fma_f32 v[0:1], v[62:63], v[136:137], v[0:1]
	v_pk_fma_f32 v[14:15], v[62:63], v[138:139], v[14:15] neg_lo:[0,0,1] neg_hi:[0,0,1]
	v_pk_mul_f32 v[20:21], v[12:13], v[10:11]
	v_pk_mul_f32 v[22:23], v[12:13], v[8:9]
	ds_write_b64 v162, v[14:15] offset:56576
	ds_write_b64 v168, v[0:1] offset:56576
	v_pk_mul_f32 v[0:1], v[12:13], v[140:141]
	v_pk_mul_f32 v[12:13], v[12:13], v[164:165]
	v_pk_fma_f32 v[20:21], v[6:7], v[8:9], v[20:21] neg_lo:[0,0,1] neg_hi:[0,0,1]
	v_pk_fma_f32 v[22:23], v[6:7], v[10:11], v[22:23]
	v_pk_add_f32 v[96:97], v[144:145], v[96:97] neg_lo:[0,1] neg_hi:[0,1]
	v_pk_add_f32 v[144:145], v[202:203], v[186:187] neg_lo:[0,1] neg_hi:[0,1]
	v_pk_fma_f32 v[0:1], v[6:7], v[164:165], v[0:1]
	v_pk_fma_f32 v[6:7], v[6:7], v[140:141], v[12:13] neg_lo:[0,0,1] neg_hi:[0,0,1]
	ds_write_b64 v162, v[6:7] offset:13056
	ds_write_b64 v168, v[0:1] offset:13056
	v_pk_mul_f32 v[6:7], v[22:23], v[144:145]
	v_pk_add_f32 v[202:203], v[90:91], v[166:167] neg_lo:[0,1] neg_hi:[0,1]
	v_pk_mul_f32 v[0:1], v[22:23], v[96:97]
	v_pk_fma_f32 v[6:7], v[20:21], v[96:97], v[6:7] neg_lo:[0,0,1] neg_hi:[0,0,1]
	v_pk_add_f32 v[186:187], v[88:89], v[92:93]
	v_pk_fma_f32 v[0:1], v[20:21], v[144:145], v[0:1]
	ds_write_b64 v162, v[6:7] offset:47872
	ds_write_b64 v168, v[0:1] offset:47872
	v_pk_mul_f32 v[6:7], v[4:5], v[202:203]
	v_pk_mul_f32 v[0:1], v[4:5], v[186:187]
	v_pk_fma_f32 v[6:7], v[2:3], v[186:187], v[6:7] neg_lo:[0,0,1] neg_hi:[0,0,1]
	v_pk_fma_f32 v[0:1], v[2:3], v[202:203], v[0:1]
	ds_write_b64 v162, v[6:7] offset:30464
	ds_write_b64 v168, v[0:1] offset:30464
	v_pk_mul_f32 v[6:7], v[10:11], v[4:5]
	v_pk_mul_f32 v[4:5], v[8:9], v[4:5]
	v_pk_fma_f32 v[6:7], v[8:9], v[2:3], v[6:7] neg_lo:[0,0,1] neg_hi:[0,0,1]
	v_pk_add_f32 v[12:13], v[88:89], v[92:93] neg_lo:[0,1] neg_hi:[0,1]
	v_pk_fma_f32 v[2:3], v[10:11], v[2:3], v[4:5]
	v_pk_add_f32 v[0:1], v[90:91], v[166:167]
	v_pk_mul_f32 v[4:5], v[2:3], v[12:13]
	s_nop 0
	v_pk_fma_f32 v[4:5], v[6:7], v[0:1], v[4:5]
	v_pk_mul_f32 v[0:1], v[2:3], v[0:1]
	s_nop 0
	v_pk_fma_f32 v[0:1], v[6:7], v[12:13], v[0:1] neg_lo:[0,0,1] neg_hi:[0,0,1]
	ds_write_b64 v162, v[0:1] offset:65280
	ds_write_b64 v168, v[4:5] offset:65280
	v_mov_b32_e32 v0, v163
	s_waitcnt lgkmcnt(0)
	s_barrier
	s_nop 0
	s_nop 0
	v_ashrrev_i32_e32 v2, 31, v0
	v_lshrrev_b32_e32 v2, 27, v2
	v_lshlrev_b32_e32 v1, 1, v0
	v_add_u32_e32 v0, v0, v2
	v_and_b32_e32 v1, 62, v1
	v_ashrrev_i32_e32 v0, 5, v0
	v_lshl_or_b32 v2, v0, 10, v1
	v_lshlrev_b32_e32 v0, 6, v0
	v_add_lshl_u32 v58, v2, v0, 2
	v_cvt_f32_ubyte0_e32 v0, v1
	v_or_b32_e32 v1, 1, v1
	v_cvt_f32_ubyte0_e32 v1, v1
	v_mul_f32_e32 v2, 0x3a800000, v0
	v_mul_f32_e32 v3, 0x3a800000, v1
	v_sin_f32_e64 v14, -v2
	v_sin_f32_e64 v15, -v3
	v_cos_f32_e32 v0, v2
	v_cos_f32_e32 v1, v3
	v_add_u32_e32 v162, 0, v58
	v_pk_mul_f32 v[2:3], v[14:15], v[14:15]
	v_add_u32_e32 v212, 0x800, v162
	v_pk_fma_f32 v[96:97], v[0:1], v[0:1], v[2:3] neg_lo:[0,0,1] neg_hi:[0,0,1]
	v_pk_mul_f32 v[2:3], v[0:1], v[14:15]
	v_add_u32_e32 v168, s91, v58
	v_pk_add_f32 v[164:165], v[2:3], v[2:3]
	v_add_u32_e32 v213, 0x800, v168
	v_pk_mul_f32 v[2:3], v[14:15], v[164:165]
	s_nop 0
	v_pk_fma_f32 v[6:7], v[0:1], v[96:97], v[2:3] neg_lo:[0,0,1] neg_hi:[0,0,1]
	v_pk_mul_f32 v[2:3], v[14:15], v[96:97]
	s_nop 0
	v_pk_fma_f32 v[12:13], v[0:1], v[164:165], v[2:3]
	v_pk_mul_f32 v[2:3], v[164:165], v[164:165]
	s_nop 0
	v_pk_fma_f32 v[166:167], v[96:97], v[96:97], v[2:3] neg_lo:[0,0,1] neg_hi:[0,0,1]
	v_pk_mul_f32 v[2:3], v[96:97], v[164:165]
	v_pk_mul_f32 v[4:5], v[166:167], v[12:13]
	v_pk_add_f32 v[170:171], v[2:3], v[2:3]
	s_nop 0
	v_pk_mul_f32 v[10:11], v[166:167], v[170:171]
	v_pk_mul_f32 v[2:3], v[14:15], v[170:171]
	v_pk_mul_f32 v[8:9], v[170:171], v[170:171]
	v_pk_add_f32 v[10:11], v[10:11], v[10:11]
	v_pk_fma_f32 v[16:17], v[0:1], v[166:167], v[2:3] neg_lo:[0,0,1] neg_hi:[0,0,1]
	v_pk_mul_f32 v[2:3], v[14:15], v[166:167]
	v_pk_fma_f32 v[8:9], v[166:167], v[166:167], v[8:9] neg_lo:[0,0,1] neg_hi:[0,0,1]
	v_pk_mul_f32 v[56:57], v[170:171], v[10:11]
	v_pk_fma_f32 v[18:19], v[0:1], v[170:171], v[2:3]
	v_pk_mul_f32 v[2:3], v[164:165], v[170:171]
	v_pk_fma_f32 v[194:195], v[166:167], v[8:9], v[56:57] neg_lo:[0,0,1] neg_hi:[0,0,1]
	v_pk_mul_f32 v[56:57], v[170:171], v[8:9]
	v_pk_fma_f32 v[182:183], v[96:97], v[166:167], v[2:3] neg_lo:[0,0,1] neg_hi:[0,0,1]
	v_pk_mul_f32 v[2:3], v[164:165], v[166:167]
	v_pk_fma_f32 v[196:197], v[166:167], v[10:11], v[56:57]
	v_pk_mul_f32 v[56:57], v[10:11], v[18:19]
	v_pk_fma_f32 v[184:185], v[96:97], v[170:171], v[2:3]
	v_pk_fma_f32 v[198:199], v[8:9], v[16:17], v[56:57] neg_lo:[0,0,1] neg_hi:[0,0,1]
	v_pk_mul_f32 v[56:57], v[8:9], v[18:19]
	v_pk_mul_f32 v[2:3], v[170:171], v[12:13]
	v_pk_fma_f32 v[200:201], v[10:11], v[16:17], v[56:57]
	v_pk_mul_f32 v[56:57], v[10:11], v[184:185]
	v_pk_fma_f32 v[4:5], v[170:171], v[6:7], v[4:5]
	v_pk_fma_f32 v[202:203], v[8:9], v[182:183], v[56:57] neg_lo:[0,0,1] neg_hi:[0,0,1]
	v_pk_mul_f32 v[56:57], v[8:9], v[184:185]
	v_pk_fma_f32 v[2:3], v[166:167], v[6:7], v[2:3] neg_lo:[0,0,1] neg_hi:[0,0,1]
	v_pk_fma_f32 v[204:205], v[10:11], v[182:183], v[56:57]
	ds_read2_b64 v[56:59], v162 offset1:34
	ds_read2_b64 v[60:63], v168 offset1:34
	ds_read2_b64 v[64:67], v162 offset0:68 offset1:102
	ds_read2_b64 v[68:71], v168 offset0:68 offset1:102
	ds_read2_b64 v[72:75], v162 offset0:136 offset1:170
	ds_read2_b64 v[76:79], v168 offset0:136 offset1:170
	ds_read2_b64 v[80:83], v162 offset0:204 offset1:238
	ds_read2_b64 v[84:87], v168 offset0:204 offset1:238
	ds_read2_b64 v[88:91], v212 offset0:16 offset1:50
	ds_read2_b64 v[92:95], v213 offset0:16 offset1:50
	ds_read2_b64 v[130:133], v212 offset0:84 offset1:118
	ds_read2_b64 v[134:137], v213 offset0:84 offset1:118
	ds_read2_b64 v[138:141], v212 offset0:152 offset1:186
	ds_read2_b64 v[142:145], v213 offset0:152 offset1:186
	ds_read2_b64 v[174:177], v212 offset0:220 offset1:254
	ds_read2_b64 v[178:181], v213 offset0:220 offset1:254
	s_waitcnt lgkmcnt(6)
	v_pk_add_f32 v[208:209], v[60:61], v[92:93]
	v_pk_add_f32 v[60:61], v[60:61], v[92:93] neg_lo:[0,1] neg_hi:[0,1]
	v_pk_add_f32 v[92:93], v[62:63], v[94:95]
	v_pk_add_f32 v[62:63], v[62:63], v[94:95] neg_lo:[0,1] neg_hi:[0,1]
	v_pk_add_f32 v[206:207], v[56:57], v[88:89]
	v_pk_add_f32 v[56:57], v[56:57], v[88:89] neg_lo:[0,1] neg_hi:[0,1]
	v_pk_add_f32 v[88:89], v[58:59], v[90:91]
	v_pk_add_f32 v[58:59], v[58:59], v[90:91] neg_lo:[0,1] neg_hi:[0,1]
	v_pk_mul_f32 v[90:91], v[62:63], s[80:81] op_sel_hi:[1,0]
	s_waitcnt lgkmcnt(4)
	v_pk_add_f32 v[94:95], v[68:69], v[134:135]
	v_pk_fma_f32 v[90:91], v[58:59], s[72:73], v[90:91] op_sel_hi:[1,0,1]
	v_pk_mul_f32 v[58:59], v[58:59], s[80:81] op_sel_hi:[1,0]
	v_pk_add_f32 v[68:69], v[68:69], v[134:135] neg_lo:[0,1] neg_hi:[0,1]
	v_pk_fma_f32 v[58:59], v[62:63], s[72:73], v[58:59] op_sel_hi:[1,0,1] neg_lo:[0,0,1] neg_hi:[0,0,1]
	v_pk_add_f32 v[62:63], v[64:65], v[130:131]
	v_pk_add_f32 v[64:65], v[64:65], v[130:131] neg_lo:[0,1] neg_hi:[0,1]
	v_pk_add_f32 v[134:135], v[70:71], v[136:137]
	v_pk_mul_f32 v[64:65], v[64:65], s[82:83] op_sel_hi:[1,0]
	v_pk_add_f32 v[70:71], v[70:71], v[136:137] neg_lo:[0,1] neg_hi:[0,1]
	v_pk_fma_f32 v[130:131], v[68:69], s[82:83], v[64:65] op_sel_hi:[1,0,1]
	v_pk_fma_f32 v[64:65], v[68:69], s[82:83], v[64:65] op_sel_hi:[1,0,1] neg_lo:[0,0,1] neg_hi:[0,0,1]
	v_pk_add_f32 v[68:69], v[66:67], v[132:133]
	v_pk_add_f32 v[66:67], v[66:67], v[132:133] neg_lo:[0,1] neg_hi:[0,1]
	v_pk_mul_f32 v[132:133], v[70:71], s[72:73] op_sel_hi:[1,0]
	s_waitcnt lgkmcnt(2)
	v_pk_add_f32 v[136:137], v[76:77], v[142:143]
	v_pk_fma_f32 v[132:133], v[66:67], s[80:81], v[132:133] op_sel_hi:[1,0,1]
	v_pk_mul_f32 v[66:67], v[66:67], s[72:73] op_sel_hi:[1,0]
	v_pk_add_f32 v[76:77], v[76:77], v[142:143] neg_lo:[0,1] neg_hi:[0,1]
	v_pk_fma_f32 v[66:67], v[70:71], s[80:81], v[66:67] op_sel_hi:[1,0,1] neg_lo:[0,0,1] neg_hi:[0,0,1]
	v_pk_add_f32 v[70:71], v[72:73], v[138:139]
	v_pk_add_f32 v[72:73], v[72:73], v[138:139] neg_lo:[0,1] neg_hi:[0,1]
	v_pk_add_f32 v[138:139], v[74:75], v[140:141]
	v_pk_add_f32 v[74:75], v[74:75], v[140:141] neg_lo:[0,1] neg_hi:[0,1]
	v_pk_add_f32 v[142:143], v[78:79], v[144:145]
	v_pk_add_f32 v[78:79], v[78:79], v[144:145] neg_lo:[0,1] neg_hi:[0,1]
	v_pk_mul_f32 v[140:141], v[74:75], s[80:81] op_sel_hi:[1,0]
	s_waitcnt lgkmcnt(0)
	v_pk_add_f32 v[144:145], v[84:85], v[178:179]
	v_pk_fma_f32 v[140:141], v[78:79], s[72:73], v[140:141] op_sel_hi:[1,0,1] neg_lo:[0,0,1] neg_hi:[0,0,1]
	v_pk_mul_f32 v[78:79], v[78:79], s[80:81] op_sel_hi:[1,0]
	v_pk_add_f32 v[84:85], v[84:85], v[178:179] neg_lo:[0,1] neg_hi:[0,1]
	v_pk_fma_f32 v[74:75], v[74:75], s[52:53], v[78:79] op_sel_hi:[1,0,1] neg_lo:[0,0,1] neg_hi:[0,0,1]
	v_pk_add_f32 v[78:79], v[80:81], v[174:175]
	v_pk_add_f32 v[80:81], v[80:81], v[174:175] neg_lo:[0,1] neg_hi:[0,1]
	v_pk_mul_f32 v[84:85], v[84:85], s[54:55] op_sel_hi:[1,0]
	v_pk_add_f32 v[178:179], v[86:87], v[180:181]
	v_pk_fma_f32 v[174:175], v[80:81], s[54:55], v[84:85] op_sel_hi:[1,0,1] neg_lo:[0,0,1] neg_hi:[0,0,1]
	v_pk_fma_f32 v[80:81], v[80:81], s[54:55], v[84:85] op_sel_hi:[1,0,1]
	v_pk_add_f32 v[84:85], v[82:83], v[176:177]
	v_pk_add_f32 v[82:83], v[82:83], v[176:177] neg_lo:[0,1] neg_hi:[0,1]
	v_pk_add_f32 v[86:87], v[86:87], v[180:181] neg_lo:[0,1] neg_hi:[0,1]
	v_pk_mul_f32 v[176:177], v[82:83], s[72:73] op_sel_hi:[1,0]
	v_pk_add_f32 v[180:181], v[208:209], v[136:137]
	v_pk_fma_f32 v[176:177], v[86:87], s[80:81], v[176:177] op_sel_hi:[1,0,1] neg_lo:[0,0,1] neg_hi:[0,0,1]
	v_pk_mul_f32 v[86:87], v[86:87], s[72:73] op_sel_hi:[1,0]
	v_pk_add_f32 v[136:137], v[208:209], v[136:137] neg_lo:[0,1] neg_hi:[0,1]
	v_pk_fma_f32 v[82:83], v[82:83], s[84:85], v[86:87] op_sel_hi:[1,0,1] neg_lo:[0,0,1] neg_hi:[0,0,1]
	v_pk_add_f32 v[86:87], v[206:207], v[70:71]
	v_pk_add_f32 v[70:71], v[206:207], v[70:71] neg_lo:[0,1] neg_hi:[0,1]
	v_pk_add_f32 v[206:207], v[88:89], v[138:139]
	v_pk_add_f32 v[88:89], v[88:89], v[138:139] neg_lo:[0,1] neg_hi:[0,1]
	v_pk_add_f32 v[208:209], v[92:93], v[142:143]
	v_pk_add_f32 v[92:93], v[92:93], v[142:143] neg_lo:[0,1] neg_hi:[0,1]
	v_pk_mul_f32 v[88:89], v[88:89], s[82:83] op_sel_hi:[1,0]
	v_pk_add_f32 v[142:143], v[94:95], v[144:145]
	v_pk_fma_f32 v[138:139], v[92:93], s[82:83], v[88:89] op_sel_hi:[1,0,1]
	v_pk_fma_f32 v[88:89], v[92:93], s[82:83], v[88:89] op_sel_hi:[1,0,1] neg_lo:[0,0,1] neg_hi:[0,0,1]
	v_pk_add_f32 v[92:93], v[62:63], v[78:79]
	v_pk_add_f32 v[62:63], v[62:63], v[78:79] neg_lo:[0,1] neg_hi:[0,1]
	v_pk_add_f32 v[78:79], v[94:95], v[144:145] neg_lo:[0,1] neg_hi:[0,1]
	v_pk_add_f32 v[94:95], v[68:69], v[84:85]
	v_pk_add_f32 v[68:69], v[68:69], v[84:85] neg_lo:[0,1] neg_hi:[0,1]
	v_pk_add_f32 v[84:85], v[134:135], v[178:179] neg_lo:[0,1] neg_hi:[0,1]
	v_pk_add_f32 v[144:145], v[134:135], v[178:179]
	v_pk_mul_f32 v[84:85], v[84:85], s[54:55] op_sel_hi:[1,0]
	v_pk_add_f32 v[178:179], v[60:61], v[72:73] neg_lo:[0,1] neg_hi:[0,1]
	v_pk_add_f32 v[60:61], v[60:61], v[72:73]
	v_pk_add_f32 v[72:73], v[90:91], v[140:141]
	v_pk_add_f32 v[90:91], v[90:91], v[140:141] neg_lo:[0,1] neg_hi:[0,1]
	v_pk_fma_f32 v[134:135], v[68:69], s[54:55], v[84:85] op_sel_hi:[1,0,1] neg_lo:[0,0,1] neg_hi:[0,0,1]
	v_pk_fma_f32 v[68:69], v[68:69], s[54:55], v[84:85] op_sel_hi:[1,0,1]
	v_pk_add_f32 v[84:85], v[56:57], v[76:77]
	v_pk_add_f32 v[56:57], v[56:57], v[76:77] neg_lo:[0,1] neg_hi:[0,1]
	v_pk_add_f32 v[76:77], v[58:59], v[74:75]
	v_pk_add_f32 v[58:59], v[58:59], v[74:75] neg_lo:[0,1] neg_hi:[0,1]
	v_pk_mul_f32 v[74:75], v[90:91], s[82:83] op_sel_hi:[1,0]
	v_pk_add_f32 v[140:141], v[64:65], v[80:81]
	v_pk_fma_f32 v[90:91], v[58:59], s[82:83], v[74:75] op_sel_hi:[1,0,1]
	v_pk_fma_f32 v[58:59], v[58:59], s[82:83], v[74:75] op_sel_hi:[1,0,1] neg_lo:[0,0,1] neg_hi:[0,0,1]
	v_pk_add_f32 v[74:75], v[130:131], v[174:175]
	v_pk_add_f32 v[130:131], v[130:131], v[174:175] neg_lo:[0,1] neg_hi:[0,1]
	v_pk_add_f32 v[174:175], v[66:67], v[82:83]
	v_pk_add_f32 v[66:67], v[66:67], v[82:83] neg_lo:[0,1] neg_hi:[0,1]
	v_pk_add_f32 v[64:65], v[64:65], v[80:81] neg_lo:[0,1] neg_hi:[0,1]
	v_pk_add_f32 v[80:81], v[132:133], v[176:177]
	v_pk_add_f32 v[132:133], v[132:133], v[176:177] neg_lo:[0,1] neg_hi:[0,1]
	v_pk_mul_f32 v[66:67], v[66:67], s[54:55] op_sel_hi:[1,0]
	v_pk_add_f32 v[176:177], v[180:181], v[142:143]
	v_pk_fma_f32 v[82:83], v[132:133], s[54:55], v[66:67] op_sel_hi:[1,0,1] neg_lo:[0,0,1] neg_hi:[0,0,1]
	v_pk_fma_f32 v[66:67], v[132:133], s[54:55], v[66:67] op_sel_hi:[1,0,1]
	v_pk_add_f32 v[132:133], v[86:87], v[92:93]
	v_pk_add_f32 v[86:87], v[86:87], v[92:93] neg_lo:[0,1] neg_hi:[0,1]
	v_pk_add_f32 v[92:93], v[180:181], v[142:143] neg_lo:[0,1] neg_hi:[0,1]
	v_pk_add_f32 v[142:143], v[206:207], v[94:95]
	v_pk_add_f32 v[180:181], v[208:209], v[144:145]
	v_pk_add_f32 v[94:95], v[206:207], v[94:95] neg_lo:[0,1] neg_hi:[0,1]
	v_pk_add_f32 v[144:145], v[208:209], v[144:145] neg_lo:[0,1] neg_hi:[0,1]
	v_pk_add_f32 v[206:207], v[70:71], v[78:79]
	v_pk_add_f32 v[208:209], v[136:137], v[62:63] neg_lo:[0,1] neg_hi:[0,1]
	v_pk_add_f32 v[70:71], v[70:71], v[78:79] neg_lo:[0,1] neg_hi:[0,1]
	v_pk_add_f32 v[62:63], v[136:137], v[62:63]
	v_pk_add_f32 v[78:79], v[138:139], v[134:135]
	v_pk_add_f32 v[136:137], v[88:89], v[68:69]
	v_pk_add_f32 v[134:135], v[138:139], v[134:135] neg_lo:[0,1] neg_hi:[0,1]
	v_pk_add_f32 v[68:69], v[88:89], v[68:69] neg_lo:[0,1] neg_hi:[0,1]
	v_pk_add_f32 v[88:89], v[84:85], v[74:75]
	v_pk_add_f32 v[138:139], v[178:179], v[140:141]
	v_pk_add_f32 v[74:75], v[84:85], v[74:75] neg_lo:[0,1] neg_hi:[0,1]
	v_pk_add_f32 v[84:85], v[178:179], v[140:141] neg_lo:[0,1] neg_hi:[0,1]
	v_pk_add_f32 v[178:179], v[76:77], v[174:175]
	v_pk_add_f32 v[76:77], v[76:77], v[174:175] neg_lo:[0,1] neg_hi:[0,1]
	v_pk_add_f32 v[174:175], v[60:61], v[130:131] neg_lo:[0,1] neg_hi:[0,1]
	v_pk_add_f32 v[60:61], v[60:61], v[130:131]
	v_pk_add_f32 v[130:131], v[58:59], v[66:67]
	v_pk_add_f32 v[58:59], v[58:59], v[66:67] neg_lo:[0,1] neg_hi:[0,1]
	v_pk_add_f32 v[66:67], v[132:133], v[142:143]
	v_pk_add_f32 v[132:133], v[132:133], v[142:143] neg_lo:[0,1] neg_hi:[0,1]
	v_pk_add_f32 v[142:143], v[176:177], v[180:181] neg_lo:[0,1] neg_hi:[0,1]
	v_pk_add_f32 v[140:141], v[72:73], v[80:81]
	v_pk_add_f32 v[72:73], v[72:73], v[80:81] neg_lo:[0,1] neg_hi:[0,1]
	v_pk_add_f32 v[80:81], v[56:57], v[64:65]
	v_pk_add_f32 v[56:57], v[56:57], v[64:65] neg_lo:[0,1] neg_hi:[0,1]
	v_pk_add_f32 v[64:65], v[90:91], v[82:83]
	v_pk_add_f32 v[82:83], v[90:91], v[82:83] neg_lo:[0,1] neg_hi:[0,1]
	v_pk_add_f32 v[90:91], v[176:177], v[180:181]
	v_pk_add_f32 v[176:177], v[86:87], v[144:145]
	v_pk_add_f32 v[180:181], v[92:93], v[94:95] neg_lo:[0,1] neg_hi:[0,1]
	v_pk_mul_f32 v[210:211], v[8:9], v[142:143]
	v_pk_mul_f32 v[142:143], v[10:11], v[142:143]
	v_pk_add_f32 v[86:87], v[86:87], v[144:145] neg_lo:[0,1] neg_hi:[0,1]
	v_pk_fma_f32 v[210:211], v[10:11], v[132:133], v[210:211]
	v_pk_fma_f32 v[132:133], v[8:9], v[132:133], v[142:143] neg_lo:[0,0,1] neg_hi:[0,0,1]
	v_pk_mul_f32 v[142:143], v[170:171], v[176:177]
	v_pk_mul_f32 v[170:171], v[170:171], v[180:181]
	v_pk_mul_f32 v[20:21], v[14:15], v[10:11]
	v_pk_add_f32 v[92:93], v[92:93], v[94:95]
	v_pk_fma_f32 v[142:143], v[166:167], v[180:181], v[142:143]
	v_pk_fma_f32 v[166:167], v[166:167], v[176:177], v[170:171] neg_lo:[0,0,1] neg_hi:[0,0,1]
	v_pk_mul_f32 v[170:171], v[196:197], v[86:87]
	v_pk_fma_f32 v[186:187], v[0:1], v[8:9], v[20:21] neg_lo:[0,0,1] neg_hi:[0,0,1]
	v_pk_mul_f32 v[20:21], v[14:15], v[8:9]
	v_pk_add_f32 v[94:95], v[206:207], v[78:79]
	v_pk_fma_f32 v[170:171], v[194:195], v[92:93], v[170:171]
	v_pk_mul_f32 v[92:93], v[196:197], v[92:93]
	v_pk_fma_f32 v[188:189], v[0:1], v[10:11], v[20:21]
	v_pk_mul_f32 v[20:21], v[164:165], v[10:11]
	v_pk_add_f32 v[144:145], v[208:209], v[136:137]
	v_pk_add_f32 v[78:79], v[206:207], v[78:79] neg_lo:[0,1] neg_hi:[0,1]
	v_pk_add_f32 v[206:207], v[70:71], v[68:69]
	v_pk_add_f32 v[68:69], v[70:71], v[68:69] neg_lo:[0,1] neg_hi:[0,1]
	v_pk_fma_f32 v[86:87], v[194:195], v[86:87], v[92:93] neg_lo:[0,0,1] neg_hi:[0,0,1]
	v_pk_mul_f32 v[92:93], v[164:165], v[94:95]
	v_pk_fma_f32 v[190:191], v[96:97], v[8:9], v[20:21] neg_lo:[0,0,1] neg_hi:[0,0,1]
	v_pk_mul_f32 v[20:21], v[164:165], v[8:9]
	v_pk_add_f32 v[136:137], v[208:209], v[136:137] neg_lo:[0,1] neg_hi:[0,1]
	v_pk_add_f32 v[208:209], v[62:63], v[134:135] neg_lo:[0,1] neg_hi:[0,1]
	v_pk_add_f32 v[62:63], v[62:63], v[134:135]
	v_pk_fma_f32 v[92:93], v[96:97], v[144:145], v[92:93]
	v_pk_mul_f32 v[144:145], v[164:165], v[144:145]
	v_pk_mul_f32 v[164:165], v[204:205], v[68:69]
	v_pk_add_f32 v[70:71], v[88:89], v[140:141]
	v_pk_add_f32 v[134:135], v[138:139], v[178:179]
	v_pk_fma_f32 v[164:165], v[202:203], v[62:63], v[164:165]
	v_pk_mul_f32 v[62:63], v[204:205], v[62:63]
	v_pk_add_f32 v[88:89], v[88:89], v[140:141] neg_lo:[0,1] neg_hi:[0,1]
	v_pk_fma_f32 v[62:63], v[202:203], v[68:69], v[62:63] neg_lo:[0,0,1] neg_hi:[0,0,1]
	v_pk_mul_f32 v[68:69], v[14:15], v[70:71]
	v_pk_mul_f32 v[14:15], v[14:15], v[134:135]
	v_pk_add_f32 v[138:139], v[138:139], v[178:179] neg_lo:[0,1] neg_hi:[0,1]
	v_pk_fma_f32 v[68:69], v[0:1], v[134:135], v[68:69]
	v_pk_fma_f32 v[0:1], v[0:1], v[70:71], v[14:15] neg_lo:[0,0,1] neg_hi:[0,0,1]
	ds_write2_b64 v162, v[66:67], v[0:1] offset1:34
	ds_write2_b64 v168, v[90:91], v[68:69] offset1:34
	v_pk_mul_f32 v[0:1], v[188:189], v[88:89]
	v_pk_mul_f32 v[14:15], v[188:189], v[138:139]
	v_pk_add_f32 v[140:141], v[74:75], v[76:77]
	v_pk_add_f32 v[178:179], v[84:85], v[72:73] neg_lo:[0,1] neg_hi:[0,1]
	v_pk_fma_f32 v[0:1], v[186:187], v[138:139], v[0:1]
	v_pk_fma_f32 v[14:15], v[186:187], v[88:89], v[14:15] neg_lo:[0,0,1] neg_hi:[0,0,1]
	ds_write2_b64 v212, v[132:133], v[14:15] offset0:16 offset1:50
	ds_write2_b64 v213, v[210:211], v[0:1] offset0:16 offset1:50
	v_pk_mul_f32 v[0:1], v[18:19], v[140:141]
	v_pk_mul_f32 v[14:15], v[18:19], v[178:179]
	v_pk_add_f32 v[74:75], v[74:75], v[76:77] neg_lo:[0,1] neg_hi:[0,1]
	v_pk_add_f32 v[72:73], v[84:85], v[72:73]
	v_pk_fma_f32 v[0:1], v[16:17], v[178:179], v[0:1]
	v_pk_fma_f32 v[14:15], v[16:17], v[140:141], v[14:15] neg_lo:[0,0,1] neg_hi:[0,0,1]
	ds_write2_b64 v162, v[166:167], v[14:15] offset0:136 offset1:170
	ds_write2_b64 v168, v[142:143], v[0:1] offset0:136 offset1:170
	v_pk_mul_f32 v[0:1], v[200:201], v[74:75]
	v_pk_mul_f32 v[14:15], v[200:201], v[72:73]
	v_pk_add_f32 v[76:77], v[80:81], v[64:65]
	v_pk_add_f32 v[84:85], v[174:175], v[130:131]
	v_pk_fma_f32 v[0:1], v[198:199], v[72:73], v[0:1]
	v_pk_fma_f32 v[14:15], v[198:199], v[74:75], v[14:15] neg_lo:[0,0,1] neg_hi:[0,0,1]
	v_pk_fma_f32 v[192:193], v[96:97], v[10:11], v[20:21]
	v_pk_mul_f32 v[20:21], v[12:13], v[10:11]
	v_pk_mul_f32 v[22:23], v[12:13], v[8:9]
	ds_write2_b64 v212, v[86:87], v[14:15] offset0:152 offset1:186
	ds_write2_b64 v213, v[170:171], v[0:1] offset0:152 offset1:186
	v_pk_mul_f32 v[0:1], v[12:13], v[76:77]
	v_pk_mul_f32 v[12:13], v[12:13], v[84:85]
	v_pk_fma_f32 v[20:21], v[6:7], v[8:9], v[20:21] neg_lo:[0,0,1] neg_hi:[0,0,1]
	v_pk_fma_f32 v[22:23], v[6:7], v[10:11], v[22:23]
	v_pk_add_f32 v[64:65], v[80:81], v[64:65] neg_lo:[0,1] neg_hi:[0,1]
	v_pk_add_f32 v[80:81], v[174:175], v[130:131] neg_lo:[0,1] neg_hi:[0,1]
	v_pk_fma_f32 v[94:95], v[96:97], v[94:95], v[144:145] neg_lo:[0,0,1] neg_hi:[0,0,1]
	v_pk_mul_f32 v[96:97], v[192:193], v[78:79]
	v_pk_fma_f32 v[0:1], v[6:7], v[84:85], v[0:1]
	v_pk_fma_f32 v[6:7], v[6:7], v[76:77], v[12:13] neg_lo:[0,0,1] neg_hi:[0,0,1]
	v_pk_fma_f32 v[96:97], v[190:191], v[136:137], v[96:97]
	v_pk_mul_f32 v[136:137], v[192:193], v[136:137]
	ds_write2_b64 v162, v[94:95], v[6:7] offset0:68 offset1:102
	ds_write2_b64 v168, v[92:93], v[0:1] offset0:68 offset1:102
	v_pk_mul_f32 v[6:7], v[22:23], v[80:81]
	v_pk_add_f32 v[174:175], v[60:61], v[82:83] neg_lo:[0,1] neg_hi:[0,1]
	v_pk_fma_f32 v[78:79], v[190:191], v[78:79], v[136:137] neg_lo:[0,0,1] neg_hi:[0,0,1]
	v_pk_mul_f32 v[0:1], v[22:23], v[64:65]
	v_pk_fma_f32 v[6:7], v[20:21], v[64:65], v[6:7] neg_lo:[0,0,1] neg_hi:[0,0,1]
	v_pk_add_f32 v[130:131], v[56:57], v[58:59]
	v_pk_mul_f32 v[144:145], v[184:185], v[208:209]
	v_pk_fma_f32 v[0:1], v[20:21], v[80:81], v[0:1]
	ds_write2_b64 v212, v[78:79], v[6:7] offset0:84 offset1:118
	ds_write2_b64 v213, v[96:97], v[0:1] offset0:84 offset1:118
	v_pk_mul_f32 v[6:7], v[4:5], v[174:175]
	v_pk_mul_f32 v[136:137], v[184:185], v[206:207]
	v_pk_fma_f32 v[144:145], v[182:183], v[206:207], v[144:145] neg_lo:[0,0,1] neg_hi:[0,0,1]
	v_pk_mul_f32 v[0:1], v[4:5], v[130:131]
	v_pk_fma_f32 v[6:7], v[2:3], v[130:131], v[6:7] neg_lo:[0,0,1] neg_hi:[0,0,1]
	v_pk_fma_f32 v[136:137], v[182:183], v[208:209], v[136:137]
	v_pk_fma_f32 v[0:1], v[2:3], v[174:175], v[0:1]
	ds_write2_b64 v162, v[144:145], v[6:7] offset0:204 offset1:238
	ds_write2_b64 v168, v[136:137], v[0:1] offset0:204 offset1:238
	v_pk_mul_f32 v[6:7], v[10:11], v[4:5]
	v_pk_mul_f32 v[4:5], v[8:9], v[4:5]
	v_pk_fma_f32 v[6:7], v[8:9], v[2:3], v[6:7] neg_lo:[0,0,1] neg_hi:[0,0,1]
	v_pk_add_f32 v[12:13], v[56:57], v[58:59] neg_lo:[0,1] neg_hi:[0,1]
	v_pk_fma_f32 v[2:3], v[10:11], v[2:3], v[4:5]
	v_pk_add_f32 v[0:1], v[60:61], v[82:83]
	v_pk_mul_f32 v[4:5], v[2:3], v[12:13]
	s_nop 0
	v_pk_fma_f32 v[4:5], v[6:7], v[0:1], v[4:5]
	v_pk_mul_f32 v[0:1], v[2:3], v[0:1]
	s_nop 0
	v_pk_fma_f32 v[0:1], v[6:7], v[12:13], v[0:1] neg_lo:[0,0,1] neg_hi:[0,0,1]
	ds_write2_b64 v212, v[62:63], v[0:1] offset0:220 offset1:254
	ds_write2_b64 v213, v[164:165], v[4:5] offset0:220 offset1:254
	v_mov_b32_e32 v0, v163
	s_waitcnt lgkmcnt(0)
	s_barrier
	v_lshlrev_b32_e32 v219, 5, v163
	global_load_dwordx4 v[220:223], v219, s[94:95] offset:16
	global_load_dwordx4 v[224:227], v219, s[94:95]
	global_load_dwordx4 v[228:231], v219, s[30:31] offset:16
	global_load_dwordx4 v[232:235], v219, s[30:31]
	s_nop 0
	s_nop 0
	v_lshlrev_b32_e32 v1, 1, v0
	v_and_b32_e32 v162, 2, v1
	v_lshrrev_b32_e32 v1, 31, v0
	v_add_u32_e32 v0, v0, v1
	v_ashrrev_i32_e32 v168, 1, v0
	v_lshl_or_b32 v0, v168, 6, v162
	v_lshlrev_b32_e32 v1, 2, v168
	v_add_lshl_u32 v74, v0, v1, 2
	v_add_u32_e32 v190, 0, v74
	v_add_u32_e32 v218, s91, v74
	ds_read2_b64 v[74:77], v190 offset1:2
	ds_read2_b64 v[78:81], v190 offset0:4 offset1:6
	ds_read2_b64 v[82:85], v218 offset1:2
	ds_read2_b64 v[86:89], v218 offset0:4 offset1:6
	ds_read2_b64 v[90:93], v190 offset0:8 offset1:10
	ds_read2_b64 v[94:97], v218 offset0:8 offset1:10
	ds_read2_b64 v[130:133], v190 offset0:12 offset1:14
	ds_read2_b64 v[134:137], v218 offset0:12 offset1:14
	ds_read2_b64 v[138:141], v190 offset0:16 offset1:18
	ds_read2_b64 v[142:145], v218 offset0:16 offset1:18
	ds_read2_b64 v[174:177], v190 offset0:20 offset1:22
	ds_read2_b64 v[178:181], v218 offset0:20 offset1:22
	ds_read2_b64 v[182:185], v190 offset0:24 offset1:26
	ds_read2_b64 v[186:189], v218 offset0:24 offset1:26
	ds_read2_b64 v[190:193], v190 offset0:28 offset1:30
	ds_read2_b64 v[194:197], v218 offset0:28 offset1:30
	s_waitcnt lgkmcnt(6)
	v_pk_add_f32 v[204:205], v[82:83], v[142:143]
	v_pk_add_f32 v[82:83], v[82:83], v[142:143] neg_lo:[0,1] neg_hi:[0,1]
	v_pk_add_f32 v[142:143], v[84:85], v[144:145]
	v_pk_add_f32 v[84:85], v[84:85], v[144:145] neg_lo:[0,1] neg_hi:[0,1]
	v_pk_add_f32 v[202:203], v[74:75], v[138:139]
	v_pk_add_f32 v[74:75], v[74:75], v[138:139] neg_lo:[0,1] neg_hi:[0,1]
	v_pk_add_f32 v[138:139], v[76:77], v[140:141]
	v_pk_add_f32 v[76:77], v[76:77], v[140:141] neg_lo:[0,1] neg_hi:[0,1]
	v_pk_mul_f32 v[140:141], v[84:85], s[80:81] op_sel_hi:[1,0]
	s_waitcnt lgkmcnt(4)
	v_pk_add_f32 v[144:145], v[86:87], v[178:179]
	v_pk_fma_f32 v[140:141], v[76:77], s[72:73], v[140:141] op_sel_hi:[1,0,1]
	v_pk_mul_f32 v[76:77], v[76:77], s[80:81] op_sel_hi:[1,0]
	v_pk_add_f32 v[86:87], v[86:87], v[178:179] neg_lo:[0,1] neg_hi:[0,1]
	v_pk_fma_f32 v[76:77], v[84:85], s[72:73], v[76:77] op_sel_hi:[1,0,1] neg_lo:[0,0,1] neg_hi:[0,0,1]
	v_pk_add_f32 v[84:85], v[78:79], v[174:175]
	v_pk_add_f32 v[78:79], v[78:79], v[174:175] neg_lo:[0,1] neg_hi:[0,1]
	v_pk_add_f32 v[178:179], v[88:89], v[180:181]
	v_pk_mul_f32 v[78:79], v[78:79], s[82:83] op_sel_hi:[1,0]
	v_pk_add_f32 v[88:89], v[88:89], v[180:181] neg_lo:[0,1] neg_hi:[0,1]
	v_pk_fma_f32 v[174:175], v[86:87], s[82:83], v[78:79] op_sel_hi:[1,0,1]
	v_pk_fma_f32 v[78:79], v[86:87], s[82:83], v[78:79] op_sel_hi:[1,0,1] neg_lo:[0,0,1] neg_hi:[0,0,1]
	v_pk_add_f32 v[86:87], v[80:81], v[176:177]
	v_pk_add_f32 v[80:81], v[80:81], v[176:177] neg_lo:[0,1] neg_hi:[0,1]
	v_pk_mul_f32 v[176:177], v[88:89], s[72:73] op_sel_hi:[1,0]
	v_or_b32_e32 v1, 1, v162
	v_pk_fma_f32 v[176:177], v[80:81], s[80:81], v[176:177] op_sel_hi:[1,0,1]
	v_pk_mul_f32 v[80:81], v[80:81], s[72:73] op_sel_hi:[1,0]
	v_cvt_f32_ubyte0_e32 v0, v162
	v_cvt_f32_ubyte0_e32 v1, v1
	v_pk_fma_f32 v[80:81], v[88:89], s[80:81], v[80:81] op_sel_hi:[1,0,1] neg_lo:[0,0,1] neg_hi:[0,0,1]
	s_waitcnt lgkmcnt(3)
	v_pk_add_f32 v[88:89], v[90:91], v[182:183]
	v_pk_add_f32 v[90:91], v[90:91], v[182:183] neg_lo:[0,1] neg_hi:[0,1]
	v_pk_add_f32 v[182:183], v[92:93], v[184:185]
	v_pk_add_f32 v[92:93], v[92:93], v[184:185] neg_lo:[0,1] neg_hi:[0,1]
	v_mul_f32_e32 v0, 0x3c800000, v0
	v_mul_f32_e32 v1, 0x3c800000, v1
	s_waitcnt lgkmcnt(2)
	v_pk_add_f32 v[180:181], v[94:95], v[186:187]
	v_pk_add_f32 v[94:95], v[94:95], v[186:187] neg_lo:[0,1] neg_hi:[0,1]
	v_pk_add_f32 v[186:187], v[96:97], v[188:189]
	v_pk_add_f32 v[96:97], v[96:97], v[188:189] neg_lo:[0,1] neg_hi:[0,1]
	v_pk_mul_f32 v[184:185], v[92:93], s[80:81] op_sel_hi:[1,0]
	v_sin_f32_e64 v164, -v0
	v_sin_f32_e64 v165, -v1
	v_pk_fma_f32 v[184:185], v[96:97], s[72:73], v[184:185] op_sel_hi:[1,0,1] neg_lo:[0,0,1] neg_hi:[0,0,1]
	v_pk_mul_f32 v[96:97], v[96:97], s[80:81] op_sel_hi:[1,0]
	s_waitcnt lgkmcnt(0)
	v_pk_add_f32 v[188:189], v[134:135], v[194:195]
	v_pk_add_f32 v[134:135], v[134:135], v[194:195] neg_lo:[0,1] neg_hi:[0,1]
	v_cos_f32_e32 v72, v0
	v_cos_f32_e32 v73, v1
	v_pk_fma_f32 v[92:93], v[92:93], s[52:53], v[96:97] op_sel_hi:[1,0,1] neg_lo:[0,0,1] neg_hi:[0,0,1]
	v_pk_add_f32 v[96:97], v[130:131], v[190:191]
	v_pk_add_f32 v[130:131], v[130:131], v[190:191] neg_lo:[0,1] neg_hi:[0,1]
	v_pk_mul_f32 v[134:135], v[134:135], s[54:55] op_sel_hi:[1,0]
	v_pk_add_f32 v[194:195], v[136:137], v[196:197]
	v_pk_fma_f32 v[190:191], v[130:131], s[54:55], v[134:135] op_sel_hi:[1,0,1] neg_lo:[0,0,1] neg_hi:[0,0,1]
	v_pk_fma_f32 v[130:131], v[130:131], s[54:55], v[134:135] op_sel_hi:[1,0,1]
	v_pk_add_f32 v[134:135], v[132:133], v[192:193]
	v_pk_add_f32 v[132:133], v[132:133], v[192:193] neg_lo:[0,1] neg_hi:[0,1]
	v_pk_add_f32 v[136:137], v[136:137], v[196:197] neg_lo:[0,1] neg_hi:[0,1]
	v_pk_mul_f32 v[192:193], v[132:133], s[72:73] op_sel_hi:[1,0]
	v_pk_mul_f32 v[0:1], v[164:165], v[164:165]
	v_pk_fma_f32 v[192:193], v[136:137], s[80:81], v[192:193] op_sel_hi:[1,0,1] neg_lo:[0,0,1] neg_hi:[0,0,1]
	v_pk_mul_f32 v[136:137], v[136:137], s[72:73] op_sel_hi:[1,0]
	v_pk_fma_f32 v[166:167], v[72:73], v[72:73], v[0:1] neg_lo:[0,0,1] neg_hi:[0,0,1]
	v_pk_mul_f32 v[0:1], v[72:73], v[164:165]
	v_pk_fma_f32 v[132:133], v[132:133], s[84:85], v[136:137] op_sel_hi:[1,0,1] neg_lo:[0,0,1] neg_hi:[0,0,1]
	v_pk_add_f32 v[136:137], v[202:203], v[88:89]
	v_pk_add_f32 v[88:89], v[202:203], v[88:89] neg_lo:[0,1] neg_hi:[0,1]
	v_pk_add_f32 v[202:203], v[138:139], v[182:183]
	v_pk_add_f32 v[138:139], v[138:139], v[182:183] neg_lo:[0,1] neg_hi:[0,1]
	v_pk_add_f32 v[170:171], v[0:1], v[0:1]
	v_pk_add_f32 v[196:197], v[204:205], v[180:181]
	v_pk_add_f32 v[180:181], v[204:205], v[180:181] neg_lo:[0,1] neg_hi:[0,1]
	v_pk_add_f32 v[204:205], v[142:143], v[186:187]
	v_pk_add_f32 v[142:143], v[142:143], v[186:187] neg_lo:[0,1] neg_hi:[0,1]
	v_pk_mul_f32 v[138:139], v[138:139], s[82:83] op_sel_hi:[1,0]
	v_pk_mul_f32 v[0:1], v[164:165], v[170:171]
	v_pk_fma_f32 v[182:183], v[142:143], s[82:83], v[138:139] op_sel_hi:[1,0,1]
	v_pk_fma_f32 v[138:139], v[142:143], s[82:83], v[138:139] op_sel_hi:[1,0,1] neg_lo:[0,0,1] neg_hi:[0,0,1]
	v_pk_add_f32 v[142:143], v[84:85], v[96:97]
	v_pk_add_f32 v[186:187], v[144:145], v[188:189]
	v_pk_add_f32 v[84:85], v[84:85], v[96:97] neg_lo:[0,1] neg_hi:[0,1]
	v_pk_add_f32 v[96:97], v[144:145], v[188:189] neg_lo:[0,1] neg_hi:[0,1]
	v_pk_add_f32 v[144:145], v[86:87], v[134:135]
	v_pk_add_f32 v[86:87], v[86:87], v[134:135] neg_lo:[0,1] neg_hi:[0,1]
	v_pk_add_f32 v[134:135], v[178:179], v[194:195] neg_lo:[0,1] neg_hi:[0,1]
	v_pk_fma_f32 v[198:199], v[72:73], v[166:167], v[0:1] neg_lo:[0,0,1] neg_hi:[0,0,1]
	v_pk_mul_f32 v[0:1], v[164:165], v[166:167]
	v_pk_add_f32 v[188:189], v[178:179], v[194:195]
	v_pk_mul_f32 v[134:135], v[134:135], s[54:55] op_sel_hi:[1,0]
	v_pk_add_f32 v[194:195], v[82:83], v[90:91] neg_lo:[0,1] neg_hi:[0,1]
	v_pk_add_f32 v[82:83], v[82:83], v[90:91]
	v_pk_add_f32 v[90:91], v[140:141], v[184:185]
	v_pk_add_f32 v[140:141], v[140:141], v[184:185] neg_lo:[0,1] neg_hi:[0,1]
	v_pk_fma_f32 v[200:201], v[72:73], v[170:171], v[0:1]
	v_pk_mul_f32 v[0:1], v[170:171], v[170:171]
	v_pk_fma_f32 v[178:179], v[86:87], s[54:55], v[134:135] op_sel_hi:[1,0,1] neg_lo:[0,0,1] neg_hi:[0,0,1]
	v_pk_fma_f32 v[86:87], v[86:87], s[54:55], v[134:135] op_sel_hi:[1,0,1]
	v_pk_add_f32 v[134:135], v[74:75], v[94:95]
	v_pk_add_f32 v[74:75], v[74:75], v[94:95] neg_lo:[0,1] neg_hi:[0,1]
	v_pk_add_f32 v[94:95], v[76:77], v[92:93]
	v_pk_add_f32 v[76:77], v[76:77], v[92:93] neg_lo:[0,1] neg_hi:[0,1]
	v_pk_mul_f32 v[92:93], v[140:141], s[82:83] op_sel_hi:[1,0]
	v_pk_fma_f32 v[64:65], v[166:167], v[166:167], v[0:1] neg_lo:[0,0,1] neg_hi:[0,0,1]
	v_pk_mul_f32 v[0:1], v[166:167], v[170:171]
	v_pk_fma_f32 v[140:141], v[76:77], s[82:83], v[92:93] op_sel_hi:[1,0,1]
	v_pk_fma_f32 v[76:77], v[76:77], s[82:83], v[92:93] op_sel_hi:[1,0,1] neg_lo:[0,0,1] neg_hi:[0,0,1]
	v_pk_add_f32 v[92:93], v[174:175], v[190:191]
	v_pk_add_f32 v[174:175], v[174:175], v[190:191] neg_lo:[0,1] neg_hi:[0,1]
	v_pk_add_f32 v[190:191], v[80:81], v[132:133]
	v_pk_add_f32 v[80:81], v[80:81], v[132:133] neg_lo:[0,1] neg_hi:[0,1]
	v_pk_add_f32 v[68:69], v[0:1], v[0:1]
	v_pk_add_f32 v[184:185], v[78:79], v[130:131]
	v_pk_add_f32 v[78:79], v[78:79], v[130:131] neg_lo:[0,1] neg_hi:[0,1]
	v_pk_add_f32 v[130:131], v[176:177], v[192:193]
	v_pk_add_f32 v[176:177], v[176:177], v[192:193] neg_lo:[0,1] neg_hi:[0,1]
	v_pk_mul_f32 v[80:81], v[80:81], s[54:55] op_sel_hi:[1,0]
	v_pk_mul_f32 v[8:9], v[64:65], v[68:69]
	v_pk_fma_f32 v[132:133], v[176:177], s[54:55], v[80:81] op_sel_hi:[1,0,1] neg_lo:[0,0,1] neg_hi:[0,0,1]
	v_pk_fma_f32 v[80:81], v[176:177], s[54:55], v[80:81] op_sel_hi:[1,0,1]
	v_pk_add_f32 v[176:177], v[136:137], v[142:143]
	v_pk_add_f32 v[192:193], v[196:197], v[186:187]
	v_pk_add_f32 v[136:137], v[136:137], v[142:143] neg_lo:[0,1] neg_hi:[0,1]
	v_pk_add_f32 v[142:143], v[196:197], v[186:187] neg_lo:[0,1] neg_hi:[0,1]
	v_pk_add_f32 v[186:187], v[202:203], v[144:145]
	v_pk_add_f32 v[196:197], v[204:205], v[188:189]
	v_pk_add_f32 v[144:145], v[202:203], v[144:145] neg_lo:[0,1] neg_hi:[0,1]
	v_pk_add_f32 v[188:189], v[204:205], v[188:189] neg_lo:[0,1] neg_hi:[0,1]
	v_pk_add_f32 v[202:203], v[88:89], v[96:97]
	v_pk_add_f32 v[204:205], v[180:181], v[84:85] neg_lo:[0,1] neg_hi:[0,1]
	v_pk_add_f32 v[88:89], v[88:89], v[96:97] neg_lo:[0,1] neg_hi:[0,1]
	v_pk_add_f32 v[84:85], v[180:181], v[84:85]
	v_pk_add_f32 v[96:97], v[182:183], v[178:179]
	v_pk_add_f32 v[180:181], v[138:139], v[86:87]
	v_pk_add_f32 v[178:179], v[182:183], v[178:179] neg_lo:[0,1] neg_hi:[0,1]
	v_pk_add_f32 v[86:87], v[138:139], v[86:87] neg_lo:[0,1] neg_hi:[0,1]
	v_pk_add_f32 v[138:139], v[134:135], v[92:93]
	v_pk_add_f32 v[182:183], v[194:195], v[184:185]
	v_pk_add_f32 v[92:93], v[134:135], v[92:93] neg_lo:[0,1] neg_hi:[0,1]
	v_pk_add_f32 v[134:135], v[194:195], v[184:185] neg_lo:[0,1] neg_hi:[0,1]
	v_pk_add_f32 v[194:195], v[94:95], v[190:191]
	v_pk_mul_f32 v[4:5], v[68:69], v[68:69]
	v_pk_add_f32 v[8:9], v[8:9], v[8:9]
	v_mul_lo_u32 v168, v168, s49
	v_pk_add_f32 v[184:185], v[90:91], v[130:131]
	v_pk_add_f32 v[212:213], v[182:183], v[194:195] neg_lo:[0,1] neg_hi:[0,1]
	v_pk_add_f32 v[182:183], v[182:183], v[194:195]
	v_pk_mul_f32 v[0:1], v[164:165], v[68:69]
	v_pk_fma_f32 v[4:5], v[64:65], v[64:65], v[4:5] neg_lo:[0,0,1] neg_hi:[0,0,1]
	v_pk_mul_f32 v[12:13], v[164:165], v[8:9]
	v_pk_add_f32 v[90:91], v[90:91], v[130:131] neg_lo:[0,1] neg_hi:[0,1]
	v_pk_add_f32 v[94:95], v[94:95], v[190:191] neg_lo:[0,1] neg_hi:[0,1]
	v_pk_add_f32 v[130:131], v[74:75], v[78:79]
	v_pk_add_f32 v[190:191], v[82:83], v[174:175] neg_lo:[0,1] neg_hi:[0,1]
	v_pk_add_f32 v[74:75], v[74:75], v[78:79] neg_lo:[0,1] neg_hi:[0,1]
	v_pk_add_f32 v[78:79], v[82:83], v[174:175]
	v_pk_add_f32 v[174:175], v[76:77], v[80:81]
	v_pk_add_f32 v[76:77], v[76:77], v[80:81] neg_lo:[0,1] neg_hi:[0,1]
	v_pk_add_f32 v[80:81], v[176:177], v[186:187] neg_lo:[0,1] neg_hi:[0,1]
	v_pk_add_f32 v[210:211], v[138:139], v[184:185] neg_lo:[0,1] neg_hi:[0,1]
	v_or_b32_e32 v162, v168, v162
	v_pk_add_f32 v[138:139], v[138:139], v[184:185]
	v_pk_add_f32 v[176:177], v[176:177], v[186:187]
	v_pk_mul_f32 v[186:187], v[164:165], v[182:183]
	v_pk_fma_f32 v[66:67], v[72:73], v[64:65], v[0:1] neg_lo:[0,0,1] neg_hi:[0,0,1]
	v_pk_mul_f32 v[0:1], v[164:165], v[64:65]
	v_pk_fma_f32 v[60:61], v[72:73], v[4:5], v[12:13] neg_lo:[0,0,1] neg_hi:[0,0,1]
	v_pk_mul_f32 v[12:13], v[164:165], v[4:5]
	v_pk_fma_f32 v[186:187], v[72:73], v[138:139], v[186:187] neg_lo:[0,0,1] neg_hi:[0,0,1]
	v_pk_mul_f32 v[138:139], v[164:165], v[138:139]
	v_lshlrev_b32_e32 v162, 2, v162
	v_pk_fma_f32 v[70:71], v[72:73], v[68:69], v[0:1]
	v_pk_fma_f32 v[62:63], v[72:73], v[8:9], v[12:13]
	v_pk_add_f32 v[184:185], v[192:193], v[196:197]
	v_pk_fma_f32 v[72:73], v[72:73], v[182:183], v[138:139]
	v_mov_b32_e32 v138, v176
	v_mov_b32_e32 v139, v186
	v_add_u32_e32 v164, 0, v162
	v_mov_b32_e32 v186, v177
	v_pk_add_f32 v[206:207], v[136:137], v[188:189]
	v_pk_add_f32 v[136:137], v[136:137], v[188:189] neg_lo:[0,1] neg_hi:[0,1]
	v_pk_add_f32 v[188:189], v[204:205], v[180:181]
	ds_write2_b64 v164, v[138:139], v[186:187] offset1:2
	v_mov_b32_e32 v138, v184
	v_mov_b32_e32 v139, v72
	v_add_u32_e32 v162, s91, v162
	v_mov_b32_e32 v72, v185
	v_pk_mul_f32 v[12:13], v[170:171], v[8:9]
	v_pk_add_f32 v[82:83], v[140:141], v[132:133]
	v_pk_add_f32 v[208:209], v[142:143], v[144:145] neg_lo:[0,1] neg_hi:[0,1]
	v_pk_add_f32 v[142:143], v[142:143], v[144:145]
	v_pk_add_f32 v[144:145], v[202:203], v[96:97]
	v_pk_add_f32 v[216:217], v[134:135], v[90:91] neg_lo:[0,1] neg_hi:[0,1]
	v_pk_add_f32 v[90:91], v[134:135], v[90:91]
	v_pk_add_f32 v[134:135], v[190:191], v[174:175]
	ds_write2_b64 v162, v[138:139], v[72:73] offset1:2
	v_pk_mul_f32 v[138:139], v[170:171], v[188:189]
	v_pk_fma_f32 v[20:21], v[166:167], v[4:5], v[12:13] neg_lo:[0,0,1] neg_hi:[0,0,1]
	v_pk_mul_f32 v[12:13], v[170:171], v[4:5]
	v_pk_add_f32 v[214:215], v[92:93], v[94:95]
	v_pk_add_f32 v[92:93], v[92:93], v[94:95] neg_lo:[0,1] neg_hi:[0,1]
	v_pk_add_f32 v[94:95], v[130:131], v[82:83]
	v_pk_mul_f32 v[72:73], v[170:171], v[144:145]
	v_pk_fma_f32 v[138:139], v[166:167], v[144:145], v[138:139] neg_lo:[0,0,1] neg_hi:[0,0,1]
	v_pk_mul_f32 v[144:145], v[200:201], v[134:135]
	v_pk_mul_f32 v[0:1], v[170:171], v[68:69]
	v_pk_fma_f32 v[56:57], v[166:167], v[8:9], v[12:13]
	v_pk_mul_f32 v[12:13], v[200:201], v[8:9]
	v_pk_fma_f32 v[144:145], v[198:199], v[94:95], v[144:145] neg_lo:[0,0,1] neg_hi:[0,0,1]
	v_pk_mul_f32 v[94:95], v[200:201], v[94:95]
	v_pk_fma_f32 v[6:7], v[166:167], v[64:65], v[0:1] neg_lo:[0,0,1] neg_hi:[0,0,1]
	v_pk_mul_f32 v[0:1], v[170:171], v[64:65]
	v_pk_mul_f32 v[2:3], v[64:65], v[200:201]
	v_pk_fma_f32 v[22:23], v[198:199], v[4:5], v[12:13] neg_lo:[0,0,1] neg_hi:[0,0,1]
	v_pk_mul_f32 v[12:13], v[200:201], v[4:5]
	v_pk_fma_f32 v[72:73], v[166:167], v[188:189], v[72:73]
	v_pk_fma_f32 v[94:95], v[198:199], v[134:135], v[94:95]
	v_mov_b32_e32 v134, v138
	v_mov_b32_e32 v135, v144
	v_mov_b32_e32 v144, v139
	v_pk_fma_f32 v[10:11], v[166:167], v[68:69], v[0:1]
	v_pk_mul_f32 v[0:1], v[68:69], v[200:201]
	v_pk_fma_f32 v[2:3], v[68:69], v[198:199], v[2:3]
	v_pk_fma_f32 v[58:59], v[198:199], v[8:9], v[12:13]
	v_pk_mul_f32 v[12:13], v[68:69], v[8:9]
	v_pk_mul_f32 v[14:15], v[68:69], v[4:5]
	ds_write2_b64 v164, v[134:135], v[144:145] offset0:4 offset1:6
	v_mov_b32_e32 v134, v72
	v_mov_b32_e32 v135, v94
	v_mov_b32_e32 v94, v73
	v_pk_mul_f32 v[72:73], v[68:69], v[206:207]
	v_pk_mul_f32 v[68:69], v[68:69], v[208:209]
	v_pk_fma_f32 v[0:1], v[64:65], v[198:199], v[0:1] neg_lo:[0,0,1] neg_hi:[0,0,1]
	v_pk_fma_f32 v[12:13], v[64:65], v[4:5], v[12:13] neg_lo:[0,0,1] neg_hi:[0,0,1]
	v_pk_fma_f32 v[16:17], v[64:65], v[8:9], v[14:15]
	v_pk_mul_f32 v[14:15], v[8:9], v[70:71]
	v_pk_mul_f32 v[18:19], v[4:5], v[70:71]
	v_pk_fma_f32 v[72:73], v[64:65], v[208:209], v[72:73]
	v_pk_fma_f32 v[64:65], v[64:65], v[206:207], v[68:69] neg_lo:[0,0,1] neg_hi:[0,0,1]
	v_pk_mul_f32 v[68:69], v[70:71], v[216:217]
	v_pk_mul_f32 v[70:71], v[70:71], v[214:215]
	v_pk_fma_f32 v[14:15], v[4:5], v[66:67], v[14:15] neg_lo:[0,0,1] neg_hi:[0,0,1]
	v_pk_fma_f32 v[18:19], v[8:9], v[66:67], v[18:19]
	v_pk_add_f32 v[132:133], v[140:141], v[132:133] neg_lo:[0,1] neg_hi:[0,1]
	v_pk_fma_f32 v[68:69], v[66:67], v[214:215], v[68:69] neg_lo:[0,0,1] neg_hi:[0,0,1]
	v_pk_fma_f32 v[66:67], v[66:67], v[216:217], v[70:71]
	v_pk_add_f32 v[96:97], v[202:203], v[96:97] neg_lo:[0,1] neg_hi:[0,1]
	v_pk_add_f32 v[180:181], v[204:205], v[180:181] neg_lo:[0,1] neg_hi:[0,1]
	v_pk_add_f32 v[202:203], v[88:89], v[86:87]
	v_pk_add_f32 v[204:205], v[84:85], v[178:179] neg_lo:[0,1] neg_hi:[0,1]
	v_pk_add_f32 v[82:83], v[130:131], v[82:83] neg_lo:[0,1] neg_hi:[0,1]
	v_pk_add_f32 v[130:131], v[190:191], v[174:175] neg_lo:[0,1] neg_hi:[0,1]
	v_pk_add_f32 v[174:175], v[74:75], v[76:77]
	v_pk_add_f32 v[190:191], v[78:79], v[132:133] neg_lo:[0,1] neg_hi:[0,1]
	v_mov_b32_e32 v70, v64
	v_mov_b32_e32 v71, v68
	v_mov_b32_e32 v68, v65
	v_mov_b32_e32 v64, v72
	v_mov_b32_e32 v65, v66
	v_mov_b32_e32 v66, v73
	ds_write2_b64 v162, v[134:135], v[94:95] offset0:4 offset1:6
	ds_write2_b64 v164, v[70:71], v[68:69] offset0:8 offset1:10
	ds_write2_b64 v218, v[64:65], v[66:67] offset0:8 offset1:10
	v_pk_mul_f32 v[64:65], v[10:11], v[202:203]
	v_pk_mul_f32 v[66:67], v[10:11], v[204:205]
	v_pk_mul_f32 v[68:69], v[2:3], v[190:191]
	v_pk_mul_f32 v[70:71], v[2:3], v[174:175]
	v_pk_fma_f32 v[64:65], v[6:7], v[204:205], v[64:65]
	v_pk_fma_f32 v[66:67], v[6:7], v[202:203], v[66:67] neg_lo:[0,0,1] neg_hi:[0,0,1]
	v_pk_fma_f32 v[68:69], v[0:1], v[174:175], v[68:69] neg_lo:[0,0,1] neg_hi:[0,0,1]
	v_pk_fma_f32 v[70:71], v[0:1], v[190:191], v[70:71]
	v_pk_add_f32 v[140:141], v[192:193], v[196:197] neg_lo:[0,1] neg_hi:[0,1]
	v_mov_b32_e32 v72, v66
	v_mov_b32_e32 v73, v68
	v_mov_b32_e32 v68, v67
	v_mov_b32_e32 v66, v64
	v_mov_b32_e32 v67, v70
	v_mov_b32_e32 v70, v65
	ds_write2_b64 v164, v[72:73], v[68:69] offset0:12 offset1:14
	ds_write2_b64 v162, v[66:67], v[70:71] offset0:12 offset1:14
	v_pk_mul_f32 v[66:67], v[8:9], v[140:141]
	v_pk_mul_f32 v[68:69], v[62:63], v[212:213]
	v_pk_mul_f32 v[64:65], v[4:5], v[140:141]
	v_pk_fma_f32 v[66:67], v[4:5], v[80:81], v[66:67] neg_lo:[0,0,1] neg_hi:[0,0,1]
	v_pk_fma_f32 v[68:69], v[60:61], v[210:211], v[68:69] neg_lo:[0,0,1] neg_hi:[0,0,1]
	v_pk_mul_f32 v[62:63], v[62:63], v[210:211]
	v_pk_fma_f32 v[64:65], v[8:9], v[80:81], v[64:65]
	v_pk_fma_f32 v[60:61], v[60:61], v[212:213], v[62:63]
	v_mov_b32_e32 v62, v66
	v_mov_b32_e32 v63, v68
	v_mov_b32_e32 v68, v67
	ds_write2_b64 v164, v[62:63], v[68:69] offset0:16 offset1:18
	v_mov_b32_e32 v62, v64
	v_mov_b32_e32 v63, v60
	v_mov_b32_e32 v60, v65
	ds_write2_b64 v218, v[62:63], v[60:61] offset0:16 offset1:18
	v_pk_mul_f32 v[60:61], v[56:57], v[96:97]
	v_pk_mul_f32 v[56:57], v[56:57], v[180:181]
	v_pk_fma_f32 v[60:61], v[20:21], v[180:181], v[60:61]
	v_pk_fma_f32 v[20:21], v[20:21], v[96:97], v[56:57] neg_lo:[0,0,1] neg_hi:[0,0,1]
	v_pk_mul_f32 v[56:57], v[58:59], v[130:131]
	v_pk_mul_f32 v[58:59], v[58:59], v[82:83]
	v_pk_fma_f32 v[56:57], v[22:23], v[82:83], v[56:57] neg_lo:[0,0,1] neg_hi:[0,0,1]
	v_pk_fma_f32 v[22:23], v[22:23], v[130:131], v[58:59]
	v_mov_b32_e32 v58, v20
	v_mov_b32_e32 v59, v56
	v_mov_b32_e32 v56, v21
	v_mov_b32_e32 v20, v60
	v_mov_b32_e32 v21, v22
	v_mov_b32_e32 v22, v61
	ds_write2_b64 v162, v[20:21], v[22:23] offset0:20 offset1:22
	v_pk_mul_f32 v[20:21], v[16:17], v[136:137]
	v_pk_mul_f32 v[16:17], v[16:17], v[142:143]
	v_pk_fma_f32 v[20:21], v[12:13], v[142:143], v[20:21]
	v_pk_fma_f32 v[12:13], v[12:13], v[136:137], v[16:17] neg_lo:[0,0,1] neg_hi:[0,0,1]
	v_pk_mul_f32 v[16:17], v[18:19], v[90:91]
	v_pk_mul_f32 v[18:19], v[18:19], v[92:93]
	v_pk_fma_f32 v[16:17], v[14:15], v[92:93], v[16:17] neg_lo:[0,0,1] neg_hi:[0,0,1]
	v_pk_fma_f32 v[14:15], v[14:15], v[90:91], v[18:19]
	v_mov_b32_e32 v18, v12
	v_mov_b32_e32 v19, v16
	v_mov_b32_e32 v16, v13
	v_mov_b32_e32 v12, v20
	v_mov_b32_e32 v13, v14
	v_mov_b32_e32 v14, v21
	ds_write2_b64 v164, v[58:59], v[56:57] offset0:20 offset1:22
	ds_write2_b64 v164, v[18:19], v[16:17] offset0:24 offset1:26
	ds_write2_b64 v218, v[12:13], v[14:15] offset0:24 offset1:26
	v_pk_mul_f32 v[14:15], v[8:9], v[10:11]
	v_pk_mul_f32 v[10:11], v[4:5], v[10:11]
	v_pk_add_f32 v[12:13], v[84:85], v[178:179]
	v_pk_fma_f32 v[14:15], v[4:5], v[6:7], v[14:15] neg_lo:[0,0,1] neg_hi:[0,0,1]
	v_pk_add_f32 v[16:17], v[88:89], v[86:87] neg_lo:[0,1] neg_hi:[0,1]
	v_pk_fma_f32 v[6:7], v[8:9], v[6:7], v[10:11]
	s_nop 0
	v_pk_mul_f32 v[10:11], v[6:7], v[16:17]
	v_pk_mul_f32 v[6:7], v[6:7], v[12:13]
	v_pk_fma_f32 v[10:11], v[14:15], v[12:13], v[10:11]
	v_pk_fma_f32 v[6:7], v[14:15], v[16:17], v[6:7] neg_lo:[0,0,1] neg_hi:[0,0,1]
	v_pk_mul_f32 v[16:17], v[4:5], v[2:3]
	v_pk_add_f32 v[12:13], v[78:79], v[132:133]
	v_pk_fma_f32 v[16:17], v[8:9], v[0:1], v[16:17]
	v_pk_mul_f32 v[2:3], v[8:9], v[2:3]
	v_pk_add_f32 v[14:15], v[74:75], v[76:77] neg_lo:[0,1] neg_hi:[0,1]
	v_pk_fma_f32 v[0:1], v[4:5], v[0:1], v[2:3] neg_lo:[0,0,1] neg_hi:[0,0,1]
	v_pk_mul_f32 v[2:3], v[16:17], v[12:13]
	v_pk_mul_f32 v[4:5], v[16:17], v[14:15]
	v_pk_fma_f32 v[2:3], v[0:1], v[14:15], v[2:3] neg_lo:[0,0,1] neg_hi:[0,0,1]
	v_pk_fma_f32 v[0:1], v[0:1], v[12:13], v[4:5]
	v_mov_b32_e32 v4, v6
	v_mov_b32_e32 v5, v2
	v_mov_b32_e32 v2, v7
	ds_write2_b64 v164, v[4:5], v[2:3] offset0:28 offset1:30
	v_mov_b32_e32 v2, v10
	v_mov_b32_e32 v3, v0
	v_mov_b32_e32 v0, v11
	ds_write2_b64 v162, v[2:3], v[0:1] offset0:28 offset1:30
	v_mov_b32_e32 v0, v163
	s_waitcnt lgkmcnt(0)
	s_barrier
	v_lshlrev_b32_e32 v236, 5, v163
	v_add_u32_e32 v236, 0x4000, v236
	global_load_dwordx4 v[176:179], v236, s[94:95] offset:16
	global_load_dwordx4 v[180:183], v236, s[94:95]
	global_load_dwordx4 v[184:187], v236, s[30:31] offset:16
	global_load_dwordx4 v[188:191], v236, s[30:31]
	v_add_u32_e32 v236, 0x4000, v236
	global_load_dwordx4 v[192:195], v236, s[94:95] offset:16
	global_load_dwordx4 v[196:199], v236, s[94:95]
	global_load_dwordx4 v[208:211], v236, s[30:31] offset:16
	global_load_dwordx4 v[212:215], v236, s[30:31]
	v_add_u32_e32 v236, 0x4000, v236
	global_load_dwordx4 v[72:75], v236, s[94:95] offset:16
	global_load_dwordx4 v[76:79], v236, s[94:95]
	global_load_dwordx4 v[80:83], v236, s[30:31] offset:16
	global_load_dwordx4 v[84:87], v236, s[30:31]
	s_nop 0
	s_nop 0
	v_lshlrev_b32_e32 v18, 3, v0
	v_ashrrev_i32_e32 v2, 3, v0
	v_and_b32_e32 v1, 56, v18
	v_mul_lo_u32 v2, v2, s49
	v_add_lshl_u32 v10, v2, v1, 2
	v_add_u32_e32 v68, 0, v10
	ds_read_b128 v[2:5], v68
	ds_read_b128 v[6:9], v68 offset:16
	v_add_u32_e32 v69, s91, v10
	ds_read_b128 v[10:13], v69
	ds_read_b128 v[14:17], v69 offset:16
	v_ashrrev_i32_e32 v19, 31, v18
	s_waitcnt lgkmcnt(3)
	v_pk_add_f32 v[20:21], v[2:3], v[4:5]
	v_pk_add_f32 v[2:3], v[2:3], v[4:5] neg_lo:[0,1] neg_hi:[0,1]
	s_waitcnt lgkmcnt(1)
	v_pk_add_f32 v[22:23], v[10:11], v[12:13]
	v_pk_add_f32 v[4:5], v[10:11], v[12:13] neg_lo:[0,1] neg_hi:[0,1]
	v_pk_add_f32 v[10:11], v[6:7], v[8:9]
	v_pk_add_f32 v[6:7], v[6:7], v[8:9] neg_lo:[0,1] neg_hi:[0,1]
	v_pk_add_f32 v[56:57], v[20:21], v[10:11]
	v_pk_add_f32 v[20:21], v[20:21], v[10:11] neg_lo:[0,1] neg_hi:[0,1]
	v_lshlrev_b64 v[10:11], 2, v[18:19]
	s_waitcnt lgkmcnt(0)
	v_pk_add_f32 v[12:13], v[14:15], v[16:17]
	v_pk_add_f32 v[8:9], v[14:15], v[16:17] neg_lo:[0,1] neg_hi:[0,1]
	v_pk_add_f32 v[62:63], v[4:5], v[6:7] neg_lo:[0,1] neg_hi:[0,1]
	v_pk_add_f32 v[66:67], v[6:7], v[4:5]
	v_lshl_add_u64 v[6:7], s[94:95], 0, v[10:11]
	v_lshl_add_u64 v[14:15], s[30:31], 0, v[10:11]
	v_pk_add_f32 v[58:59], v[22:23], v[12:13]
	v_pk_add_f32 v[22:23], v[22:23], v[12:13] neg_lo:[0,1] neg_hi:[0,1]
	v_pk_add_f32 v[60:61], v[2:3], v[8:9]
	v_pk_add_f32 v[64:65], v[2:3], v[8:9] neg_lo:[0,1] neg_hi:[0,1]
	s_waitcnt vmcnt(12)
	v_pk_mul_f32 v[18:19], v[58:59], v[232:233]
	v_pk_mul_f32 v[14:15], v[56:57], v[232:233]
	v_pk_fma_f32 v[18:19], v[56:57], v[224:225], v[18:19] neg_lo:[0,0,1] neg_hi:[0,0,1]
	v_pk_fma_f32 v[6:7], v[224:225], v[58:59], v[14:15]
	v_pk_mul_f32 v[14:15], v[22:23], v[234:235]
	v_pk_mul_f32 v[16:17], v[20:21], v[234:235]
	v_pk_fma_f32 v[14:15], v[20:21], v[226:227], v[14:15] neg_lo:[0,0,1] neg_hi:[0,0,1]
	v_pk_fma_f32 v[8:9], v[226:227], v[22:23], v[16:17]
	v_pk_mul_f32 v[16:17], v[62:63], v[228:229]
	v_pk_mul_f32 v[10:11], v[60:61], v[228:229]
	v_pk_fma_f32 v[16:17], v[60:61], v[220:221], v[16:17] neg_lo:[0,0,1] neg_hi:[0,0,1]
	v_pk_fma_f32 v[2:3], v[62:63], v[220:221], v[10:11]
	v_pk_mul_f32 v[10:11], v[66:67], v[230:231]
	v_pk_mul_f32 v[12:13], v[64:65], v[230:231]
	v_pk_fma_f32 v[10:11], v[64:65], v[222:223], v[10:11] neg_lo:[0,0,1] neg_hi:[0,0,1]
	v_pk_fma_f32 v[4:5], v[66:67], v[222:223], v[12:13]
	v_pk_add_f32 v[12:13], v[18:19], v[14:15]
	v_pk_add_f32 v[20:21], v[6:7], v[8:9]
	v_pk_add_f32 v[22:23], v[6:7], v[8:9] neg_lo:[0,1] neg_hi:[0,1]
	v_pk_add_f32 v[8:9], v[16:17], v[10:11]
	v_pk_add_f32 v[18:19], v[18:19], v[14:15] neg_lo:[0,1] neg_hi:[0,1]
	v_pk_add_f32 v[14:15], v[2:3], v[4:5]
	v_pk_add_f32 v[16:17], v[16:17], v[10:11] neg_lo:[0,1] neg_hi:[0,1]
	v_pk_add_f32 v[56:57], v[2:3], v[4:5] neg_lo:[0,1] neg_hi:[0,1]
	v_pk_add_f32 v[2:3], v[12:13], v[8:9]
	v_pk_add_f32 v[4:5], v[12:13], v[8:9] neg_lo:[0,1] neg_hi:[0,1]
	v_add_u32_e32 v66, 0x200, v0
	v_pk_add_f32 v[6:7], v[20:21], v[14:15]
	v_pk_add_f32 v[8:9], v[20:21], v[14:15] neg_lo:[0,1] neg_hi:[0,1]
	v_pk_add_f32 v[10:11], v[18:19], v[56:57] neg_lo:[0,1] neg_hi:[0,1]
	v_pk_add_f32 v[14:15], v[22:23], v[16:17]
	v_pk_add_f32 v[12:13], v[18:19], v[56:57]
	v_pk_add_f32 v[16:17], v[22:23], v[16:17] neg_lo:[0,1] neg_hi:[0,1]
	ds_write_b128 v68, v[2:5]
	ds_write_b128 v68, v[10:13] offset:16
	ds_write_b128 v69, v[6:9]
	ds_write_b128 v69, v[14:17] offset:16
	v_ashrrev_i32_e32 v2, 3, v66
	v_mul_lo_u32 v2, v2, s49
	v_add_lshl_u32 v10, v2, v1, 2
	v_add_u32_e32 v68, 0, v10
	v_add_u32_e32 v69, s91, v10
	ds_read_b128 v[2:5], v68
	ds_read_b128 v[6:9], v68 offset:16
	ds_read_b128 v[10:13], v69
	ds_read_b128 v[14:17], v69 offset:16
	s_waitcnt lgkmcnt(3)
	v_pk_add_f32 v[18:19], v[2:3], v[4:5]
	s_waitcnt lgkmcnt(1)
	v_pk_add_f32 v[20:21], v[10:11], v[12:13]
	v_pk_add_f32 v[2:3], v[2:3], v[4:5] neg_lo:[0,1] neg_hi:[0,1]
	v_pk_add_f32 v[4:5], v[10:11], v[12:13] neg_lo:[0,1] neg_hi:[0,1]
	v_pk_add_f32 v[10:11], v[6:7], v[8:9]
	v_pk_add_f32 v[6:7], v[6:7], v[8:9] neg_lo:[0,1] neg_hi:[0,1]
	s_waitcnt lgkmcnt(0)
	v_pk_add_f32 v[8:9], v[14:15], v[16:17] neg_lo:[0,1] neg_hi:[0,1]
	v_pk_add_f32 v[22:23], v[18:19], v[10:11]
	v_pk_add_f32 v[58:59], v[2:3], v[8:9]
	v_pk_add_f32 v[62:63], v[2:3], v[8:9] neg_lo:[0,1] neg_hi:[0,1]
	v_lshlrev_b32_e32 v2, 3, v66
	v_ashrrev_i32_e32 v3, 31, v2
	v_pk_add_f32 v[18:19], v[18:19], v[10:11] neg_lo:[0,1] neg_hi:[0,1]
	v_lshlrev_b64 v[10:11], 2, v[2:3]
	v_pk_add_f32 v[12:13], v[14:15], v[16:17]
	v_pk_add_f32 v[60:61], v[4:5], v[6:7] neg_lo:[0,1] neg_hi:[0,1]
	v_pk_add_f32 v[64:65], v[6:7], v[4:5]
	v_lshl_add_u64 v[6:7], s[94:95], 0, v[10:11]
	v_lshl_add_u64 v[14:15], s[30:31], 0, v[10:11]
	v_pk_add_f32 v[56:57], v[20:21], v[12:13]
	v_pk_add_f32 v[20:21], v[20:21], v[12:13] neg_lo:[0,1] neg_hi:[0,1]
	s_waitcnt vmcnt(8)
	v_pk_mul_f32 v[66:67], v[56:57], v[188:189]
	v_pk_mul_f32 v[14:15], v[22:23], v[188:189]
	v_pk_fma_f32 v[66:67], v[22:23], v[180:181], v[66:67] neg_lo:[0,0,1] neg_hi:[0,0,1]
	v_pk_fma_f32 v[6:7], v[180:181], v[56:57], v[14:15]
	v_pk_mul_f32 v[14:15], v[20:21], v[190:191]
	v_pk_mul_f32 v[16:17], v[18:19], v[190:191]
	v_pk_fma_f32 v[14:15], v[18:19], v[182:183], v[14:15] neg_lo:[0,0,1] neg_hi:[0,0,1]
	v_pk_fma_f32 v[8:9], v[182:183], v[20:21], v[16:17]
	v_pk_mul_f32 v[16:17], v[60:61], v[184:185]
	v_pk_mul_f32 v[10:11], v[58:59], v[184:185]
	v_pk_fma_f32 v[16:17], v[58:59], v[176:177], v[16:17] neg_lo:[0,0,1] neg_hi:[0,0,1]
	v_pk_fma_f32 v[2:3], v[60:61], v[176:177], v[10:11]
	v_pk_mul_f32 v[10:11], v[64:65], v[186:187]
	v_pk_mul_f32 v[12:13], v[62:63], v[186:187]
	v_pk_fma_f32 v[10:11], v[62:63], v[178:179], v[10:11] neg_lo:[0,0,1] neg_hi:[0,0,1]
	v_pk_fma_f32 v[4:5], v[64:65], v[178:179], v[12:13]
	v_pk_add_f32 v[12:13], v[66:67], v[14:15]
	v_pk_add_f32 v[18:19], v[6:7], v[8:9]
	v_pk_add_f32 v[22:23], v[6:7], v[8:9] neg_lo:[0,1] neg_hi:[0,1]
	v_pk_add_f32 v[8:9], v[16:17], v[10:11]
	v_pk_add_f32 v[20:21], v[66:67], v[14:15] neg_lo:[0,1] neg_hi:[0,1]
	v_pk_add_f32 v[14:15], v[2:3], v[4:5]
	v_pk_add_f32 v[16:17], v[16:17], v[10:11] neg_lo:[0,1] neg_hi:[0,1]
	v_pk_add_f32 v[56:57], v[2:3], v[4:5] neg_lo:[0,1] neg_hi:[0,1]
	v_pk_add_f32 v[2:3], v[12:13], v[8:9]
	v_pk_add_f32 v[4:5], v[12:13], v[8:9] neg_lo:[0,1] neg_hi:[0,1]
	v_add_u32_e32 v66, 0x400, v0
	v_pk_add_f32 v[6:7], v[18:19], v[14:15]
	v_pk_add_f32 v[8:9], v[18:19], v[14:15] neg_lo:[0,1] neg_hi:[0,1]
	v_pk_add_f32 v[10:11], v[20:21], v[56:57] neg_lo:[0,1] neg_hi:[0,1]
	v_pk_add_f32 v[14:15], v[22:23], v[16:17]
	v_pk_add_f32 v[12:13], v[20:21], v[56:57]
	v_pk_add_f32 v[16:17], v[22:23], v[16:17] neg_lo:[0,1] neg_hi:[0,1]
	ds_write_b128 v68, v[2:5]
	ds_write_b128 v68, v[10:13] offset:16
	ds_write_b128 v69, v[6:9]
	ds_write_b128 v69, v[14:17] offset:16
	v_ashrrev_i32_e32 v2, 3, v66
	v_mul_lo_u32 v2, v2, s49
	v_add_lshl_u32 v10, v2, v1, 2
	v_add_u32_e32 v68, 0, v10
	v_add_u32_e32 v69, s91, v10
	ds_read_b128 v[2:5], v68
	ds_read_b128 v[6:9], v68 offset:16
	ds_read_b128 v[10:13], v69
	ds_read_b128 v[14:17], v69 offset:16
	s_waitcnt lgkmcnt(3)
	v_pk_add_f32 v[18:19], v[2:3], v[4:5]
	s_waitcnt lgkmcnt(1)
	v_pk_add_f32 v[20:21], v[10:11], v[12:13]
	v_pk_add_f32 v[2:3], v[2:3], v[4:5] neg_lo:[0,1] neg_hi:[0,1]
	v_pk_add_f32 v[4:5], v[10:11], v[12:13] neg_lo:[0,1] neg_hi:[0,1]
	v_pk_add_f32 v[10:11], v[6:7], v[8:9]
	v_pk_add_f32 v[6:7], v[6:7], v[8:9] neg_lo:[0,1] neg_hi:[0,1]
	s_waitcnt lgkmcnt(0)
	v_pk_add_f32 v[8:9], v[14:15], v[16:17] neg_lo:[0,1] neg_hi:[0,1]
	v_pk_add_f32 v[22:23], v[18:19], v[10:11]
	v_pk_add_f32 v[58:59], v[2:3], v[8:9]
	v_pk_add_f32 v[62:63], v[2:3], v[8:9] neg_lo:[0,1] neg_hi:[0,1]
	v_lshlrev_b32_e32 v2, 3, v66
	v_ashrrev_i32_e32 v3, 31, v2
	v_pk_add_f32 v[18:19], v[18:19], v[10:11] neg_lo:[0,1] neg_hi:[0,1]
	v_lshlrev_b64 v[10:11], 2, v[2:3]
	v_pk_add_f32 v[12:13], v[14:15], v[16:17]
	v_pk_add_f32 v[60:61], v[4:5], v[6:7] neg_lo:[0,1] neg_hi:[0,1]
	v_pk_add_f32 v[64:65], v[6:7], v[4:5]
	v_lshl_add_u64 v[6:7], s[94:95], 0, v[10:11]
	v_lshl_add_u64 v[14:15], s[30:31], 0, v[10:11]
	v_pk_add_f32 v[56:57], v[20:21], v[12:13]
	v_pk_add_f32 v[20:21], v[20:21], v[12:13] neg_lo:[0,1] neg_hi:[0,1]
	s_waitcnt vmcnt(4)
	v_pk_mul_f32 v[66:67], v[56:57], v[212:213]
	v_pk_mul_f32 v[14:15], v[22:23], v[212:213]
	v_pk_fma_f32 v[66:67], v[22:23], v[196:197], v[66:67] neg_lo:[0,0,1] neg_hi:[0,0,1]
	v_pk_fma_f32 v[6:7], v[196:197], v[56:57], v[14:15]
	v_pk_mul_f32 v[14:15], v[20:21], v[214:215]
	v_pk_mul_f32 v[16:17], v[18:19], v[214:215]
	v_pk_fma_f32 v[14:15], v[18:19], v[198:199], v[14:15] neg_lo:[0,0,1] neg_hi:[0,0,1]
	v_pk_fma_f32 v[8:9], v[198:199], v[20:21], v[16:17]
	v_pk_mul_f32 v[16:17], v[60:61], v[208:209]
	v_pk_mul_f32 v[10:11], v[58:59], v[208:209]
	v_pk_fma_f32 v[16:17], v[58:59], v[192:193], v[16:17] neg_lo:[0,0,1] neg_hi:[0,0,1]
	v_pk_fma_f32 v[2:3], v[60:61], v[192:193], v[10:11]
	v_pk_mul_f32 v[10:11], v[64:65], v[210:211]
	v_pk_mul_f32 v[12:13], v[62:63], v[210:211]
	v_pk_fma_f32 v[10:11], v[62:63], v[194:195], v[10:11] neg_lo:[0,0,1] neg_hi:[0,0,1]
	v_pk_fma_f32 v[4:5], v[64:65], v[194:195], v[12:13]
	v_pk_add_f32 v[12:13], v[66:67], v[14:15]
	v_pk_add_f32 v[20:21], v[66:67], v[14:15] neg_lo:[0,1] neg_hi:[0,1]
	v_add_u32_e32 v66, 0x600, v0
	v_pk_add_f32 v[18:19], v[6:7], v[8:9]
	v_pk_add_f32 v[22:23], v[6:7], v[8:9] neg_lo:[0,1] neg_hi:[0,1]
	v_pk_add_f32 v[8:9], v[16:17], v[10:11]
	v_pk_add_f32 v[14:15], v[2:3], v[4:5]
	v_ashrrev_i32_e32 v0, 3, v66
	v_pk_add_f32 v[16:17], v[16:17], v[10:11] neg_lo:[0,1] neg_hi:[0,1]
	v_pk_add_f32 v[56:57], v[2:3], v[4:5] neg_lo:[0,1] neg_hi:[0,1]
	v_pk_add_f32 v[2:3], v[12:13], v[8:9]
	v_pk_add_f32 v[4:5], v[12:13], v[8:9] neg_lo:[0,1] neg_hi:[0,1]
	v_pk_add_f32 v[8:9], v[18:19], v[14:15] neg_lo:[0,1] neg_hi:[0,1]
	v_mul_lo_u32 v0, v0, s49
	v_pk_add_f32 v[6:7], v[18:19], v[14:15]
	v_pk_add_f32 v[10:11], v[20:21], v[56:57] neg_lo:[0,1] neg_hi:[0,1]
	v_pk_add_f32 v[14:15], v[22:23], v[16:17]
	v_pk_add_f32 v[12:13], v[20:21], v[56:57]
	v_pk_add_f32 v[16:17], v[22:23], v[16:17] neg_lo:[0,1] neg_hi:[0,1]
	ds_write_b128 v68, v[2:5]
	ds_write_b128 v68, v[10:13] offset:16
	ds_write_b128 v69, v[6:9]
	ds_write_b128 v69, v[14:17] offset:16
	v_add_lshl_u32 v8, v0, v1, 2
	v_add_u32_e32 v65, 0, v8
	v_add_u32_e32 v64, s91, v8
	ds_read_b128 v[0:3], v65
	ds_read_b128 v[4:7], v65 offset:16
	ds_read_b128 v[8:11], v64
	ds_read_b128 v[12:15], v64 offset:16
	s_waitcnt lgkmcnt(3)
	v_pk_add_f32 v[16:17], v[0:1], v[2:3]
	s_waitcnt lgkmcnt(1)
	v_pk_add_f32 v[18:19], v[8:9], v[10:11]
	v_pk_add_f32 v[0:1], v[0:1], v[2:3] neg_lo:[0,1] neg_hi:[0,1]
	v_pk_add_f32 v[2:3], v[8:9], v[10:11] neg_lo:[0,1] neg_hi:[0,1]
	v_pk_add_f32 v[8:9], v[4:5], v[6:7]
	v_pk_add_f32 v[4:5], v[4:5], v[6:7] neg_lo:[0,1] neg_hi:[0,1]
	s_waitcnt lgkmcnt(0)
	v_pk_add_f32 v[6:7], v[12:13], v[14:15] neg_lo:[0,1] neg_hi:[0,1]
	v_pk_add_f32 v[60:61], v[16:17], v[8:9]
	v_pk_add_f32 v[56:57], v[16:17], v[8:9] neg_lo:[0,1] neg_hi:[0,1]
	v_pk_add_f32 v[20:21], v[0:1], v[6:7]
	v_pk_add_f32 v[16:17], v[0:1], v[6:7] neg_lo:[0,1] neg_hi:[0,1]
	v_lshlrev_b32_e32 v0, 3, v66
	v_pk_add_f32 v[10:11], v[12:13], v[14:15]
	v_ashrrev_i32_e32 v1, 31, v0
	v_pk_add_f32 v[62:63], v[18:19], v[10:11]
	v_pk_add_f32 v[58:59], v[18:19], v[10:11] neg_lo:[0,1] neg_hi:[0,1]
	v_pk_add_f32 v[22:23], v[2:3], v[4:5] neg_lo:[0,1] neg_hi:[0,1]
	v_pk_add_f32 v[18:19], v[4:5], v[2:3]
	v_lshlrev_b64 v[4:5], 2, v[0:1]
	v_lshl_add_u64 v[6:7], s[94:95], 0, v[4:5]
	v_lshl_add_u64 v[12:13], s[30:31], 0, v[4:5]
	s_waitcnt vmcnt(0)
	v_pk_mul_f32 v[66:67], v[62:63], v[84:85]
	v_pk_mul_f32 v[12:13], v[60:61], v[84:85]
	v_pk_fma_f32 v[66:67], v[60:61], v[76:77], v[66:67] neg_lo:[0,0,1] neg_hi:[0,0,1]
	v_pk_fma_f32 v[8:9], v[76:77], v[62:63], v[12:13]
	v_pk_mul_f32 v[12:13], v[58:59], v[86:87]
	v_pk_mul_f32 v[14:15], v[56:57], v[86:87]
	v_pk_fma_f32 v[12:13], v[56:57], v[78:79], v[12:13] neg_lo:[0,0,1] neg_hi:[0,0,1]
	v_pk_fma_f32 v[10:11], v[78:79], v[58:59], v[14:15]
	v_pk_mul_f32 v[14:15], v[22:23], v[80:81]
	v_pk_mul_f32 v[4:5], v[20:21], v[80:81]
	v_pk_fma_f32 v[14:15], v[20:21], v[72:73], v[14:15] neg_lo:[0,0,1] neg_hi:[0,0,1]
	v_pk_fma_f32 v[0:1], v[22:23], v[72:73], v[4:5]
	v_pk_mul_f32 v[4:5], v[18:19], v[82:83]
	v_pk_mul_f32 v[6:7], v[16:17], v[82:83]
	v_pk_fma_f32 v[4:5], v[16:17], v[74:75], v[4:5] neg_lo:[0,0,1] neg_hi:[0,0,1]
	v_pk_fma_f32 v[2:3], v[18:19], v[74:75], v[6:7]
	v_pk_add_f32 v[6:7], v[66:67], v[12:13]
	v_pk_add_f32 v[16:17], v[8:9], v[10:11]
	v_pk_add_f32 v[20:21], v[8:9], v[10:11] neg_lo:[0,1] neg_hi:[0,1]
	v_pk_add_f32 v[8:9], v[14:15], v[4:5]
	v_pk_add_f32 v[18:19], v[66:67], v[12:13] neg_lo:[0,1] neg_hi:[0,1]
	v_pk_add_f32 v[10:11], v[0:1], v[2:3]
	v_pk_add_f32 v[14:15], v[14:15], v[4:5] neg_lo:[0,1] neg_hi:[0,1]
	v_pk_add_f32 v[22:23], v[0:1], v[2:3] neg_lo:[0,1] neg_hi:[0,1]
	v_pk_add_f32 v[0:1], v[6:7], v[8:9]
	v_pk_add_f32 v[2:3], v[6:7], v[8:9] neg_lo:[0,1] neg_hi:[0,1]
	v_pk_add_f32 v[4:5], v[16:17], v[10:11]
	v_pk_add_f32 v[6:7], v[16:17], v[10:11] neg_lo:[0,1] neg_hi:[0,1]
	v_pk_add_f32 v[8:9], v[18:19], v[22:23] neg_lo:[0,1] neg_hi:[0,1]
	v_pk_add_f32 v[12:13], v[20:21], v[14:15]
	v_pk_add_f32 v[10:11], v[18:19], v[22:23]
	v_pk_add_f32 v[14:15], v[20:21], v[14:15] neg_lo:[0,1] neg_hi:[0,1]
	ds_write_b128 v65, v[0:3]
	ds_write_b128 v65, v[8:11] offset:16
	ds_write_b128 v64, v[4:7]
	ds_write_b128 v64, v[12:15] offset:16
	v_mov_b32_e32 v0, v163
	s_waitcnt lgkmcnt(0)
	s_barrier
	s_nop 0
	s_nop 0
	v_lshlrev_b32_e32 v1, 1, v0
	v_and_b32_e32 v162, 2, v1
	v_lshrrev_b32_e32 v1, 31, v0
	v_add_u32_e32 v0, v0, v1
	v_ashrrev_i32_e32 v168, 1, v0
	v_mul_lo_u32 v0, v168, s49
	v_or_b32_e32 v0, v0, v162
	v_lshlrev_b32_e32 v0, 2, v0
	v_add_u32_e32 v88, 0, v0
	v_add_u32_e32 v92, s91, v0
	ds_read2_b64 v[0:3], v88 offset1:2
	ds_read2_b64 v[8:11], v88 offset0:4 offset1:6
	ds_read2_b64 v[4:7], v92 offset1:2
	ds_read2_b64 v[12:15], v92 offset0:4 offset1:6
	ds_read2_b64 v[16:19], v88 offset0:8 offset1:10
	ds_read2_b64 v[20:23], v92 offset0:8 offset1:10
	ds_read2_b64 v[56:59], v88 offset0:12 offset1:14
	ds_read2_b64 v[60:63], v92 offset0:12 offset1:14
	ds_read2_b64 v[64:67], v88 offset0:16 offset1:18
	ds_read2_b64 v[68:71], v88 offset0:20 offset1:22
	ds_read2_b64 v[72:75], v92 offset0:16 offset1:18
	ds_read2_b64 v[76:79], v92 offset0:20 offset1:22
	ds_read2_b64 v[80:83], v88 offset0:24 offset1:26
	ds_read2_b64 v[84:87], v92 offset0:24 offset1:26
	ds_read2_b64 v[88:91], v88 offset0:28 offset1:30
	ds_read2_b64 v[92:95], v92 offset0:28 offset1:30
	s_mov_b64 s[4:5], 0x800
	s_waitcnt lgkmcnt(3)
	v_mov_b32_e32 v186, v81
	v_mov_b32_e32 v187, v83
	s_waitcnt lgkmcnt(1)
	v_mov_b32_e32 v178, v89
	s_waitcnt lgkmcnt(0)
	v_mov_b32_e32 v97, v95
	v_or_b32_e32 v95, 1, v162
	v_mov_b32_e32 v96, v93
	v_cvt_f32_ubyte0_e32 v93, v162
	v_cvt_f32_ubyte0_e32 v95, v95
	v_mul_f32_e32 v93, 0x3c800000, v93
	v_mul_f32_e32 v95, 0x3c800000, v95
	v_cos_f32_e32 v130, v93
	v_cos_f32_e32 v131, v95
	v_sin_f32_e64 v132, -v93
	v_sin_f32_e64 v133, -v95
	v_mov_b32_e32 v179, v91
	v_mov_b32_e32 v93, v94
	v_mov_b32_e32 v89, v90
	v_pk_mul_f32 v[134:135], v[132:133], v[132:133]
	v_pk_mul_f32 v[136:137], v[130:131], v[132:133]
	v_pk_fma_f32 v[134:135], v[130:131], v[130:131], v[134:135] neg_lo:[0,0,1] neg_hi:[0,0,1]
	v_pk_add_f32 v[136:137], v[136:137], v[136:137]
	v_pk_mul_f32 v[164:165], v[132:133], v[134:135]
	v_pk_mul_f32 v[138:139], v[136:137], v[136:137]
	v_pk_mul_f32 v[140:141], v[134:135], v[136:137]
	v_pk_fma_f32 v[138:139], v[134:135], v[134:135], v[138:139] neg_lo:[0,0,1] neg_hi:[0,0,1]
	v_pk_add_f32 v[140:141], v[140:141], v[140:141]
	v_pk_mul_f32 v[144:145], v[132:133], v[136:137]
	v_pk_fma_f32 v[164:165], v[130:131], v[136:137], v[164:165]
	v_pk_mul_f32 v[142:143], v[140:141], v[140:141]
	v_pk_fma_f32 v[144:145], v[130:131], v[134:135], v[144:145] neg_lo:[0,0,1] neg_hi:[0,0,1]
	v_pk_mul_f32 v[174:175], v[138:139], v[164:165]
	v_pk_fma_f32 v[142:143], v[138:139], v[138:139], v[142:143] neg_lo:[0,0,1] neg_hi:[0,0,1]
	v_pk_mul_f32 v[166:167], v[140:141], v[164:165]
	v_pk_mul_f32 v[170:171], v[138:139], v[140:141]
	v_pk_fma_f32 v[174:175], v[140:141], v[144:145], v[174:175]
	v_pk_fma_f32 v[166:167], v[138:139], v[144:145], v[166:167] neg_lo:[0,0,1] neg_hi:[0,0,1]
	v_pk_add_f32 v[170:171], v[170:171], v[170:171]
	v_pk_mul_f32 v[180:181], v[142:143], v[174:175]
	v_pk_mul_f32 v[176:177], v[170:171], v[174:175]
	v_pk_fma_f32 v[180:181], v[170:171], v[166:167], v[180:181]
	v_pk_fma_f32 v[176:177], v[142:143], v[166:167], v[176:177] neg_lo:[0,0,1] neg_hi:[0,0,1]
	v_pk_mul_f32 v[182:183], v[180:181], v[178:179]
	v_pk_mul_f32 v[94:95], v[136:137], v[140:141]
	v_pk_fma_f32 v[182:183], v[176:177], v[96:97], v[182:183] neg_lo:[0,0,1] neg_hi:[0,0,1]
	v_pk_mul_f32 v[96:97], v[180:181], v[96:97]
	v_pk_fma_f32 v[94:95], v[134:135], v[138:139], v[94:95] neg_lo:[0,0,1] neg_hi:[0,0,1]
	v_pk_fma_f32 v[96:97], v[176:177], v[178:179], v[96:97]
	v_pk_mul_f32 v[176:177], v[136:137], v[138:139]
	v_mov_b32_e32 v81, v82
	v_pk_fma_f32 v[176:177], v[134:135], v[140:141], v[176:177]
	v_pk_mul_f32 v[82:83], v[140:141], v[142:143]
	v_pk_mul_f32 v[90:91], v[142:143], v[176:177]
	v_pk_mul_f32 v[178:179], v[170:171], v[176:177]
	v_pk_fma_f32 v[90:91], v[170:171], v[94:95], v[90:91]
	v_pk_fma_f32 v[178:179], v[142:143], v[94:95], v[178:179] neg_lo:[0,0,1] neg_hi:[0,0,1]
	v_pk_mul_f32 v[180:181], v[90:91], v[88:89]
	v_pk_mul_f32 v[90:91], v[90:91], v[92:93]
	v_pk_fma_f32 v[180:181], v[178:179], v[92:93], v[180:181] neg_lo:[0,0,1] neg_hi:[0,0,1]
	v_pk_fma_f32 v[88:89], v[178:179], v[88:89], v[90:91]
	v_pk_mul_f32 v[178:179], v[132:133], v[138:139]
	v_pk_mul_f32 v[92:93], v[132:133], v[140:141]
	v_pk_fma_f32 v[178:179], v[130:131], v[140:141], v[178:179]
	v_pk_fma_f32 v[92:93], v[130:131], v[138:139], v[92:93] neg_lo:[0,0,1] neg_hi:[0,0,1]
	v_pk_mul_f32 v[188:189], v[142:143], v[178:179]
	v_pk_mul_f32 v[184:185], v[170:171], v[178:179]
	v_pk_fma_f32 v[188:189], v[170:171], v[92:93], v[188:189]
	v_mov_b32_e32 v90, v85
	v_mov_b32_e32 v91, v87
	v_pk_fma_f32 v[184:185], v[142:143], v[92:93], v[184:185] neg_lo:[0,0,1] neg_hi:[0,0,1]
	v_pk_mul_f32 v[190:191], v[188:189], v[186:187]
	v_mov_b32_e32 v85, v86
	v_pk_fma_f32 v[190:191], v[184:185], v[90:91], v[190:191] neg_lo:[0,0,1] neg_hi:[0,0,1]
	v_pk_mul_f32 v[90:91], v[188:189], v[90:91]
	v_pk_mul_f32 v[86:87], v[140:141], v[170:171]
	v_pk_fma_f32 v[82:83], v[138:139], v[170:171], v[82:83]
	v_pk_fma_f32 v[90:91], v[184:185], v[186:187], v[90:91]
	v_pk_fma_f32 v[86:87], v[138:139], v[142:143], v[86:87] neg_lo:[0,0,1] neg_hi:[0,0,1]
	v_pk_mul_f32 v[184:185], v[82:83], v[80:81]
	v_pk_mul_f32 v[82:83], v[82:83], v[84:85]
	v_pk_mul_f32 v[186:187], v[164:165], v[142:143]
	v_pk_fma_f32 v[184:185], v[86:87], v[84:85], v[184:185] neg_lo:[0,0,1] neg_hi:[0,0,1]
	v_pk_fma_f32 v[80:81], v[86:87], v[80:81], v[82:83]
	v_pk_mul_f32 v[84:85], v[164:165], v[170:171]
	v_mov_b32_e32 v86, v69
	v_mov_b32_e32 v87, v71
	v_pk_fma_f32 v[186:187], v[144:145], v[170:171], v[186:187]
	v_mov_b32_e32 v82, v77
	v_mov_b32_e32 v83, v79
	v_pk_fma_f32 v[84:85], v[144:145], v[142:143], v[84:85] neg_lo:[0,0,1] neg_hi:[0,0,1]
	v_pk_mul_f32 v[188:189], v[186:187], v[86:87]
	v_mov_b32_e32 v69, v70
	v_pk_mul_f32 v[70:71], v[136:137], v[142:143]
	v_pk_fma_f32 v[188:189], v[84:85], v[82:83], v[188:189] neg_lo:[0,0,1] neg_hi:[0,0,1]
	v_pk_mul_f32 v[82:83], v[186:187], v[82:83]
	v_mov_b32_e32 v77, v78
	v_pk_mul_f32 v[78:79], v[136:137], v[170:171]
	v_pk_fma_f32 v[70:71], v[134:135], v[170:171], v[70:71]
	v_pk_fma_f32 v[82:83], v[84:85], v[86:87], v[82:83]
	v_pk_fma_f32 v[78:79], v[134:135], v[142:143], v[78:79] neg_lo:[0,0,1] neg_hi:[0,0,1]
	v_pk_mul_f32 v[84:85], v[70:71], v[68:69]
	v_pk_mul_f32 v[70:71], v[70:71], v[76:77]
	v_pk_mul_f32 v[86:87], v[132:133], v[142:143]
	v_pk_fma_f32 v[84:85], v[78:79], v[76:77], v[84:85] neg_lo:[0,0,1] neg_hi:[0,0,1]
	v_pk_fma_f32 v[68:69], v[78:79], v[68:69], v[70:71]
	v_pk_mul_f32 v[76:77], v[132:133], v[170:171]
	v_mov_b32_e32 v78, v65
	v_mov_b32_e32 v79, v67
	v_pk_fma_f32 v[86:87], v[130:131], v[170:171], v[86:87]
	v_mov_b32_e32 v65, v66
	v_mov_b32_e32 v70, v73
	v_mov_b32_e32 v71, v75
	v_pk_fma_f32 v[76:77], v[130:131], v[142:143], v[76:77] neg_lo:[0,0,1] neg_hi:[0,0,1]
	v_pk_mul_f32 v[186:187], v[86:87], v[78:79]
	v_mov_b32_e32 v73, v74
	v_pk_mul_f32 v[66:67], v[170:171], v[64:65]
	v_pk_fma_f32 v[186:187], v[76:77], v[70:71], v[186:187] neg_lo:[0,0,1] neg_hi:[0,0,1]
	v_pk_mul_f32 v[70:71], v[86:87], v[70:71]
	v_pk_fma_f32 v[66:67], v[142:143], v[72:73], v[66:67] neg_lo:[0,0,1] neg_hi:[0,0,1]
	v_pk_mul_f32 v[72:73], v[170:171], v[72:73]
	v_mov_b32_e32 v74, v57
	v_mov_b32_e32 v75, v59
	v_mov_b32_e32 v57, v58
	v_pk_fma_f32 v[70:71], v[76:77], v[78:79], v[70:71]
	v_pk_fma_f32 v[64:65], v[142:143], v[64:65], v[72:73]
	v_mov_b32_e32 v72, v61
	v_mov_b32_e32 v73, v63
	v_pk_mul_f32 v[76:77], v[174:175], v[74:75]
	v_mov_b32_e32 v61, v62
	v_pk_mul_f32 v[58:59], v[176:177], v[56:57]
	v_pk_fma_f32 v[76:77], v[166:167], v[72:73], v[76:77] neg_lo:[0,0,1] neg_hi:[0,0,1]
	v_pk_mul_f32 v[72:73], v[174:175], v[72:73]
	v_pk_fma_f32 v[58:59], v[94:95], v[60:61], v[58:59] neg_lo:[0,0,1] neg_hi:[0,0,1]
	v_pk_mul_f32 v[60:61], v[176:177], v[60:61]
	v_mov_b32_e32 v62, v17
	v_mov_b32_e32 v63, v19
	v_mov_b32_e32 v17, v18
	v_pk_fma_f32 v[72:73], v[166:167], v[74:75], v[72:73]
	v_pk_fma_f32 v[56:57], v[94:95], v[56:57], v[60:61]
	v_mov_b32_e32 v60, v21
	v_mov_b32_e32 v61, v23
	v_pk_mul_f32 v[74:75], v[62:63], v[178:179]
	v_mov_b32_e32 v21, v22
	v_pk_mul_f32 v[18:19], v[16:17], v[140:141]
	v_pk_fma_f32 v[74:75], v[60:61], v[92:93], v[74:75] neg_lo:[0,0,1] neg_hi:[0,0,1]
	v_pk_mul_f32 v[60:61], v[60:61], v[178:179]
	v_pk_fma_f32 v[18:19], v[138:139], v[20:21], v[18:19] neg_lo:[0,0,1] neg_hi:[0,0,1]
	v_pk_mul_f32 v[20:21], v[140:141], v[20:21]
	v_mov_b32_e32 v22, v9
	v_mov_b32_e32 v23, v11
	v_mov_b32_e32 v9, v10
	v_pk_fma_f32 v[60:61], v[62:63], v[92:93], v[60:61]
	v_pk_fma_f32 v[16:17], v[16:17], v[138:139], v[20:21]
	v_mov_b32_e32 v20, v13
	v_mov_b32_e32 v21, v15
	v_pk_mul_f32 v[62:63], v[22:23], v[164:165]
	v_mov_b32_e32 v13, v14
	v_pk_mul_f32 v[10:11], v[8:9], v[136:137]
	v_pk_fma_f32 v[62:63], v[20:21], v[144:145], v[62:63] neg_lo:[0,0,1] neg_hi:[0,0,1]
	v_pk_mul_f32 v[20:21], v[20:21], v[164:165]
	v_pk_fma_f32 v[10:11], v[12:13], v[134:135], v[10:11] neg_lo:[0,0,1] neg_hi:[0,0,1]
	v_pk_mul_f32 v[12:13], v[12:13], v[136:137]
	v_mov_b32_e32 v14, v1
	v_mov_b32_e32 v15, v3
	v_pk_fma_f32 v[20:21], v[22:23], v[144:145], v[20:21]
	v_pk_fma_f32 v[8:9], v[8:9], v[134:135], v[12:13]
	v_mov_b32_e32 v12, v5
	v_mov_b32_e32 v13, v7
	v_pk_mul_f32 v[22:23], v[14:15], v[132:133]
	v_mov_b32_e32 v1, v2
	v_lshl_or_b32 v2, v168, 6, v162
	v_lshlrev_b32_e32 v3, 2, v168
	v_pk_fma_f32 v[22:23], v[12:13], v[130:131], v[22:23] neg_lo:[0,0,1] neg_hi:[0,0,1]
	v_pk_mul_f32 v[12:13], v[12:13], v[132:133]
	v_mov_b32_e32 v5, v6
	v_add_lshl_u32 v2, v2, v3, 2
	v_pk_fma_f32 v[12:13], v[14:15], v[130:131], v[12:13]
	v_add_u32_e32 v132, 0, v2
	v_add_u32_e32 v133, s91, v2
	v_pk_add_f32 v[2:3], v[0:1], v[64:65]
	v_pk_add_f32 v[6:7], v[4:5], v[66:67]
	v_pk_add_f32 v[0:1], v[0:1], v[64:65] neg_lo:[0,1] neg_hi:[0,1]
	v_pk_add_f32 v[4:5], v[4:5], v[66:67] neg_lo:[0,1] neg_hi:[0,1]
	v_pk_add_f32 v[14:15], v[16:17], v[80:81]
	v_pk_add_f32 v[64:65], v[18:19], v[184:185]
	v_pk_add_f32 v[16:17], v[16:17], v[80:81] neg_lo:[0,1] neg_hi:[0,1]
	v_pk_add_f32 v[18:19], v[18:19], v[184:185] neg_lo:[0,1] neg_hi:[0,1]
	v_pk_add_f32 v[66:67], v[8:9], v[68:69]
	v_pk_add_f32 v[78:79], v[10:11], v[84:85]
	v_pk_add_f32 v[8:9], v[8:9], v[68:69] neg_lo:[0,1] neg_hi:[0,1]
	v_pk_add_f32 v[68:69], v[56:57], v[88:89]
	v_pk_add_f32 v[80:81], v[58:59], v[180:181]
	v_pk_add_f32 v[58:59], v[58:59], v[180:181] neg_lo:[0,1] neg_hi:[0,1]
	v_pk_add_f32 v[10:11], v[10:11], v[84:85] neg_lo:[0,1] neg_hi:[0,1]
	v_pk_add_f32 v[56:57], v[56:57], v[88:89] neg_lo:[0,1] neg_hi:[0,1]
	v_pk_add_f32 v[84:85], v[12:13], v[70:71]
	v_pk_add_f32 v[12:13], v[12:13], v[70:71] neg_lo:[0,1] neg_hi:[0,1]
	v_pk_add_f32 v[70:71], v[60:61], v[90:91]
	v_pk_add_f32 v[60:61], v[60:61], v[90:91] neg_lo:[0,1] neg_hi:[0,1]
	v_pk_add_f32 v[90:91], v[20:21], v[82:83]
	v_pk_add_f32 v[20:21], v[20:21], v[82:83] neg_lo:[0,1] neg_hi:[0,1]
	v_pk_add_f32 v[82:83], v[72:73], v[96:97]
	v_pk_add_f32 v[72:73], v[72:73], v[96:97] neg_lo:[0,1] neg_hi:[0,1]
	v_pk_add_f32 v[96:97], v[2:3], v[14:15]
	v_pk_add_f32 v[130:131], v[6:7], v[64:65]
	v_pk_add_f32 v[2:3], v[2:3], v[14:15] neg_lo:[0,1] neg_hi:[0,1]
	v_pk_add_f32 v[6:7], v[6:7], v[64:65] neg_lo:[0,1] neg_hi:[0,1]
	v_pk_add_f32 v[14:15], v[0:1], v[18:19] neg_lo:[0,1] neg_hi:[0,1]
	v_pk_add_f32 v[64:65], v[4:5], v[16:17]
	v_pk_add_f32 v[0:1], v[0:1], v[18:19]
	v_pk_add_f32 v[4:5], v[4:5], v[16:17] neg_lo:[0,1] neg_hi:[0,1]
	v_pk_add_f32 v[16:17], v[66:67], v[68:69]
	v_pk_add_f32 v[18:19], v[78:79], v[80:81]
	v_pk_add_f32 v[66:67], v[66:67], v[68:69] neg_lo:[0,1] neg_hi:[0,1]
	v_pk_add_f32 v[68:69], v[78:79], v[80:81] neg_lo:[0,1] neg_hi:[0,1]
	v_pk_add_f32 v[78:79], v[8:9], v[58:59] neg_lo:[0,1] neg_hi:[0,1]
	v_pk_add_f32 v[86:87], v[22:23], v[186:187]
	v_pk_add_f32 v[22:23], v[22:23], v[186:187] neg_lo:[0,1] neg_hi:[0,1]
	v_pk_add_f32 v[88:89], v[74:75], v[190:191]
	v_pk_add_f32 v[74:75], v[74:75], v[190:191] neg_lo:[0,1] neg_hi:[0,1]
	v_pk_add_f32 v[92:93], v[62:63], v[188:189]
	v_pk_add_f32 v[62:63], v[62:63], v[188:189] neg_lo:[0,1] neg_hi:[0,1]
	v_pk_add_f32 v[94:95], v[76:77], v[182:183]
	v_pk_add_f32 v[80:81], v[10:11], v[56:57]
	v_pk_add_f32 v[10:11], v[10:11], v[56:57] neg_lo:[0,1] neg_hi:[0,1]
	v_pk_mul_f32 v[78:79], v[78:79], s[82:83] op_sel_hi:[1,0]
	v_pk_add_f32 v[76:77], v[76:77], v[182:183] neg_lo:[0,1] neg_hi:[0,1]
	v_pk_add_f32 v[8:9], v[8:9], v[58:59]
	v_pk_add_f32 v[56:57], v[84:85], v[70:71]
	v_pk_add_f32 v[58:59], v[86:87], v[88:89]
	v_pk_add_f32 v[70:71], v[84:85], v[70:71] neg_lo:[0,1] neg_hi:[0,1]
	v_pk_add_f32 v[84:85], v[86:87], v[88:89] neg_lo:[0,1] neg_hi:[0,1]
	v_pk_add_f32 v[86:87], v[12:13], v[74:75] neg_lo:[0,1] neg_hi:[0,1]
	v_pk_add_f32 v[88:89], v[22:23], v[60:61]
	v_pk_add_f32 v[12:13], v[12:13], v[74:75]
	v_pk_add_f32 v[22:23], v[22:23], v[60:61] neg_lo:[0,1] neg_hi:[0,1]
	v_pk_add_f32 v[60:61], v[90:91], v[82:83]
	v_pk_add_f32 v[74:75], v[92:93], v[94:95]
	v_pk_add_f32 v[82:83], v[90:91], v[82:83] neg_lo:[0,1] neg_hi:[0,1]
	v_pk_add_f32 v[90:91], v[92:93], v[94:95] neg_lo:[0,1] neg_hi:[0,1]
	v_pk_add_f32 v[94:95], v[62:63], v[72:73]
	v_pk_add_f32 v[62:63], v[62:63], v[72:73] neg_lo:[0,1] neg_hi:[0,1]
	v_pk_add_f32 v[72:73], v[96:97], v[16:17]
	v_pk_add_f32 v[16:17], v[96:97], v[16:17] neg_lo:[0,1] neg_hi:[0,1]
	v_pk_fma_f32 v[96:97], v[80:81], s[82:83], v[78:79] op_sel_hi:[1,0,1] neg_lo:[1,0,0] neg_hi:[1,0,0]
	v_pk_mul_f32 v[10:11], v[10:11], s[82:83] op_sel_hi:[1,0]
	v_pk_add_f32 v[92:93], v[20:21], v[76:77] neg_lo:[0,1] neg_hi:[0,1]
	v_pk_fma_f32 v[78:79], v[80:81], s[82:83], v[78:79] op_sel_hi:[1,0,1]
	v_pk_add_f32 v[80:81], v[14:15], v[96:97]
	v_pk_add_f32 v[14:15], v[14:15], v[96:97] neg_lo:[0,1] neg_hi:[0,1]
	v_pk_add_f32 v[96:97], v[6:7], v[66:67]
	v_pk_add_f32 v[6:7], v[6:7], v[66:67] neg_lo:[0,1] neg_hi:[0,1]
	v_pk_fma_f32 v[66:67], v[8:9], s[54:55], v[10:11] op_sel_hi:[1,0,1] neg_lo:[0,0,1] neg_hi:[0,0,1]
	v_pk_fma_f32 v[8:9], v[8:9], s[82:83], v[10:11] op_sel_hi:[1,0,1] neg_lo:[0,0,1] neg_hi:[0,0,1]
	v_pk_add_f32 v[20:21], v[20:21], v[76:77]
	v_pk_add_f32 v[76:77], v[130:131], v[18:19]
	v_pk_add_f32 v[18:19], v[130:131], v[18:19] neg_lo:[0,1] neg_hi:[0,1]
	v_pk_add_f32 v[130:131], v[64:65], v[78:79]
	v_pk_add_f32 v[64:65], v[64:65], v[78:79] neg_lo:[0,1] neg_hi:[0,1]
	v_pk_add_f32 v[78:79], v[2:3], v[68:69] neg_lo:[0,1] neg_hi:[0,1]
	v_pk_add_f32 v[2:3], v[2:3], v[68:69]
	v_pk_add_f32 v[68:69], v[4:5], v[8:9]
	v_pk_add_f32 v[4:5], v[4:5], v[8:9] neg_lo:[0,1] neg_hi:[0,1]
	v_pk_add_f32 v[8:9], v[56:57], v[60:61]
	v_pk_add_f32 v[56:57], v[56:57], v[60:61] neg_lo:[0,1] neg_hi:[0,1]
	v_pk_mul_f32 v[60:61], v[92:93], s[82:83] op_sel_hi:[1,0]
	v_pk_add_f32 v[10:11], v[0:1], v[66:67]
	v_pk_add_f32 v[0:1], v[0:1], v[66:67] neg_lo:[0,1] neg_hi:[0,1]
	v_pk_add_f32 v[66:67], v[58:59], v[74:75]
	v_pk_add_f32 v[58:59], v[58:59], v[74:75] neg_lo:[0,1] neg_hi:[0,1]
	v_pk_fma_f32 v[74:75], v[94:95], s[82:83], v[60:61] op_sel_hi:[1,0,1] neg_lo:[1,0,0] neg_hi:[1,0,0]
	v_pk_fma_f32 v[60:61], v[94:95], s[82:83], v[60:61] op_sel_hi:[1,0,1]
	v_pk_mul_f32 v[62:63], v[62:63], s[82:83] op_sel_hi:[1,0]
	v_pk_add_f32 v[94:95], v[88:89], v[60:61]
	v_pk_add_f32 v[60:61], v[88:89], v[60:61] neg_lo:[0,1] neg_hi:[0,1]
	v_pk_add_f32 v[88:89], v[84:85], v[82:83]
	v_pk_add_f32 v[82:83], v[84:85], v[82:83] neg_lo:[0,1] neg_hi:[0,1]
	v_pk_fma_f32 v[84:85], v[20:21], s[54:55], v[62:63] op_sel_hi:[1,0,1] neg_lo:[0,0,1] neg_hi:[0,0,1]
	v_pk_fma_f32 v[20:21], v[20:21], s[82:83], v[62:63] op_sel_hi:[1,0,1] neg_lo:[0,0,1] neg_hi:[0,0,1]
	v_pk_add_f32 v[92:93], v[86:87], v[74:75]
	v_pk_add_f32 v[74:75], v[86:87], v[74:75] neg_lo:[0,1] neg_hi:[0,1]
	v_pk_add_f32 v[86:87], v[70:71], v[90:91] neg_lo:[0,1] neg_hi:[0,1]
	v_pk_add_f32 v[70:71], v[70:71], v[90:91]
	v_pk_add_f32 v[90:91], v[22:23], v[20:21]
	v_pk_add_f32 v[20:21], v[22:23], v[20:21] neg_lo:[0,1] neg_hi:[0,1]
	v_pk_add_f32 v[22:23], v[72:73], v[8:9]
	v_pk_add_f32 v[8:9], v[72:73], v[8:9] neg_lo:[0,1] neg_hi:[0,1]
	v_pk_mul_f32 v[72:73], v[94:95], s[80:81] op_sel_hi:[1,0]
	v_pk_add_f32 v[62:63], v[12:13], v[84:85]
	v_pk_add_f32 v[12:13], v[12:13], v[84:85] neg_lo:[0,1] neg_hi:[0,1]
	v_pk_add_f32 v[84:85], v[76:77], v[66:67]
	v_pk_add_f32 v[66:67], v[76:77], v[66:67] neg_lo:[0,1] neg_hi:[0,1]
	v_pk_fma_f32 v[72:73], v[92:93], s[72:73], v[72:73] op_sel_hi:[1,0,1] neg_lo:[0,0,1] neg_hi:[0,0,1]
	v_pk_mul_f32 v[76:77], v[94:95], s[72:73] op_sel_hi:[1,0]
	s_andn2_b64 vcc, exec, s[2:3]
	v_pk_fma_f32 v[76:77], v[92:93], s[80:81], v[76:77] op_sel_hi:[1,0,1]
	v_pk_add_f32 v[92:93], v[80:81], v[72:73]
	v_pk_add_f32 v[72:73], v[80:81], v[72:73] neg_lo:[0,1] neg_hi:[0,1]
	v_pk_mul_f32 v[80:81], v[86:87], s[82:83] op_sel_hi:[1,0]
	v_pk_add_f32 v[94:95], v[130:131], v[76:77]
	v_pk_fma_f32 v[86:87], v[88:89], s[82:83], v[80:81] op_sel_hi:[1,0,1] neg_lo:[1,0,0] neg_hi:[1,0,0]
	v_pk_fma_f32 v[80:81], v[88:89], s[82:83], v[80:81] op_sel_hi:[1,0,1]
	v_pk_add_f32 v[88:89], v[78:79], v[86:87]
	v_pk_add_f32 v[78:79], v[78:79], v[86:87] neg_lo:[0,1] neg_hi:[0,1]
	v_pk_mul_f32 v[86:87], v[90:91], s[72:73] op_sel_hi:[1,0]
	v_pk_mul_f32 v[90:91], v[90:91], s[80:81] op_sel_hi:[1,0]
	v_pk_fma_f32 v[86:87], v[62:63], s[80:81], v[86:87] op_sel_hi:[1,0,1] neg_lo:[0,0,1] neg_hi:[0,0,1]
	v_pk_fma_f32 v[62:63], v[62:63], s[72:73], v[90:91] op_sel_hi:[1,0,1]
	v_pk_add_f32 v[76:77], v[130:131], v[76:77] neg_lo:[0,1] neg_hi:[0,1]
	v_pk_add_f32 v[130:131], v[96:97], v[80:81]
	v_pk_add_f32 v[80:81], v[96:97], v[80:81] neg_lo:[0,1] neg_hi:[0,1]
	v_pk_add_f32 v[90:91], v[10:11], v[86:87]
	v_pk_add_f32 v[96:97], v[68:69], v[62:63]
	v_pk_add_f32 v[10:11], v[10:11], v[86:87] neg_lo:[0,1] neg_hi:[0,1]
	v_pk_add_f32 v[62:63], v[68:69], v[62:63] neg_lo:[0,1] neg_hi:[0,1]
	v_pk_add_f32 v[68:69], v[16:17], v[58:59] neg_lo:[0,1] neg_hi:[0,1]
	v_pk_add_f32 v[86:87], v[18:19], v[56:57]
	v_pk_add_f32 v[16:17], v[16:17], v[58:59]
	v_pk_add_f32 v[18:19], v[18:19], v[56:57] neg_lo:[0,1] neg_hi:[0,1]
	v_pk_mul_f32 v[56:57], v[60:61], s[72:73] op_sel_hi:[1,0]
	v_pk_mul_f32 v[58:59], v[60:61], s[80:81] op_sel_hi:[1,0]
	v_pk_fma_f32 v[56:57], v[74:75], s[84:85], v[56:57] op_sel_hi:[1,0,1] neg_lo:[0,0,1] neg_hi:[0,0,1]
	v_pk_fma_f32 v[58:59], v[74:75], s[72:73], v[58:59] op_sel_hi:[1,0,1] neg_lo:[0,0,1] neg_hi:[0,0,1]
	v_pk_add_f32 v[60:61], v[14:15], v[56:57]
	v_pk_add_f32 v[74:75], v[64:65], v[58:59]
	v_pk_add_f32 v[14:15], v[14:15], v[56:57] neg_lo:[0,1] neg_hi:[0,1]
	v_pk_add_f32 v[56:57], v[64:65], v[58:59] neg_lo:[0,1] neg_hi:[0,1]
	v_pk_mul_f32 v[58:59], v[82:83], s[82:83] op_sel_hi:[1,0]
	s_mov_b64 s[2:3], 0
	v_pk_fma_f32 v[64:65], v[70:71], s[54:55], v[58:59] op_sel_hi:[1,0,1] neg_lo:[0,0,1] neg_hi:[0,0,1]
	v_pk_fma_f32 v[58:59], v[70:71], s[82:83], v[58:59] op_sel_hi:[1,0,1] neg_lo:[0,0,1] neg_hi:[0,0,1]
	v_pk_add_f32 v[70:71], v[2:3], v[64:65]
	v_pk_add_f32 v[82:83], v[6:7], v[58:59]
	v_pk_add_f32 v[6:7], v[6:7], v[58:59] neg_lo:[0,1] neg_hi:[0,1]
	v_pk_mul_f32 v[58:59], v[20:21], s[80:81] op_sel_hi:[1,0]
	v_pk_mul_f32 v[20:21], v[20:21], s[72:73] op_sel_hi:[1,0]
	v_pk_fma_f32 v[58:59], v[12:13], s[52:53], v[58:59] op_sel_hi:[1,0,1] neg_lo:[0,0,1] neg_hi:[0,0,1]
	v_pk_fma_f32 v[12:13], v[12:13], s[80:81], v[20:21] op_sel_hi:[1,0,1] neg_lo:[0,0,1] neg_hi:[0,0,1]
	v_pk_add_f32 v[20:21], v[0:1], v[58:59]
	v_pk_add_f32 v[0:1], v[0:1], v[58:59] neg_lo:[0,1] neg_hi:[0,1]
	v_pk_add_f32 v[2:3], v[2:3], v[64:65] neg_lo:[0,1] neg_hi:[0,1]
	v_pk_add_f32 v[64:65], v[4:5], v[12:13]
	v_pk_add_f32 v[4:5], v[4:5], v[12:13] neg_lo:[0,1] neg_hi:[0,1]
	ds_write2_b64 v132, v[22:23], v[92:93] offset1:2
	ds_write2_b64 v133, v[84:85], v[94:95] offset1:2
	ds_write2_b64 v132, v[88:89], v[90:91] offset0:4 offset1:6
	ds_write2_b64 v133, v[130:131], v[96:97] offset0:4 offset1:6
	ds_write2_b64 v132, v[68:69], v[60:61] offset0:8 offset1:10
	ds_write2_b64 v133, v[86:87], v[74:75] offset0:8 offset1:10
	ds_write2_b64 v132, v[70:71], v[20:21] offset0:12 offset1:14
	ds_write2_b64 v133, v[82:83], v[64:65] offset0:12 offset1:14
	ds_write2_b64 v132, v[8:9], v[72:73] offset0:16 offset1:18
	ds_write2_b64 v133, v[66:67], v[76:77] offset0:16 offset1:18
	ds_write2_b64 v132, v[78:79], v[10:11] offset0:20 offset1:22
	ds_write2_b64 v133, v[80:81], v[62:63] offset0:20 offset1:22
	ds_write2_b64 v132, v[16:17], v[14:15] offset0:24 offset1:26
	ds_write2_b64 v133, v[18:19], v[56:57] offset0:24 offset1:26
	ds_write2_b64 v132, v[2:3], v[0:1] offset0:28 offset1:30
	ds_write2_b64 v133, v[6:7], v[4:5] offset0:28 offset1:30
	v_mov_b32_e32 v0, v163
	s_waitcnt lgkmcnt(0)
	s_barrier
	s_nop 0
	s_nop 0
	v_lshlrev_b32_e32 v1, 1, v0
	v_and_b32_e32 v97, 62, v1
	v_ashrrev_i32_e32 v1, 31, v0
	v_lshrrev_b32_e32 v1, 27, v1
	v_add_u32_e32 v0, v0, v1
	v_ashrrev_i32_e32 v0, 5, v0
	v_lshl_or_b32 v1, v0, 10, v97
	v_cvt_f32_ubyte0_e32 v96, v97
	v_or_b32_e32 v97, 1, v97
	v_cvt_f32_ubyte0_e32 v97, v97
	v_mul_f32_e32 v130, 0x3a800000, v96
	v_mul_f32_e32 v131, 0x3a800000, v97
	v_cos_f32_e32 v96, v130
	v_cos_f32_e32 v97, v131
	v_sin_f32_e64 v130, -v130
	v_sin_f32_e64 v131, -v131
	v_lshlrev_b32_e32 v0, 6, v0
	v_add_lshl_u32 v0, v1, v0, 2
	v_add_u32_e32 v162, 0, v0
	v_pk_mul_f32 v[132:133], v[130:131], v[130:131]
	v_pk_mul_f32 v[134:135], v[96:97], v[130:131]
	v_add_u32_e32 v168, s91, v0
	v_pk_fma_f32 v[132:133], v[96:97], v[96:97], v[132:133] neg_lo:[0,0,1] neg_hi:[0,0,1]
	v_pk_add_f32 v[134:135], v[134:135], v[134:135]
	v_add_u32_e32 v180, 0x800, v168
	v_add_u32_e32 v181, 0x800, v162
	v_pk_mul_f32 v[136:137], v[134:135], v[134:135]
	v_pk_mul_f32 v[138:139], v[132:133], v[134:135]
	v_pk_mul_f32 v[144:145], v[130:131], v[132:133]
	ds_read2_b64 v[0:3], v162 offset1:34
	ds_read2_b64 v[4:7], v168 offset1:34
	ds_read2_b64 v[8:11], v180 offset0:16 offset1:50
	ds_read2_b64 v[12:15], v181 offset0:16 offset1:50
	ds_read2_b64 v[16:19], v168 offset0:136 offset1:170
	ds_read2_b64 v[20:23], v162 offset0:136 offset1:170
	ds_read2_b64 v[56:59], v180 offset0:152 offset1:186
	ds_read2_b64 v[60:63], v181 offset0:152 offset1:186
	ds_read2_b64 v[64:67], v168 offset0:68 offset1:102
	ds_read2_b64 v[68:71], v162 offset0:68 offset1:102
	ds_read2_b64 v[72:75], v180 offset0:84 offset1:118
	ds_read2_b64 v[76:79], v181 offset0:84 offset1:118
	ds_read2_b64 v[80:83], v168 offset0:204 offset1:238
	ds_read2_b64 v[84:87], v162 offset0:204 offset1:238
	ds_read2_b64 v[88:91], v180 offset0:220 offset1:254
	ds_read2_b64 v[92:95], v181 offset0:220 offset1:254
	v_pk_fma_f32 v[136:137], v[132:133], v[132:133], v[136:137] neg_lo:[0,0,1] neg_hi:[0,0,1]
	v_pk_add_f32 v[138:139], v[138:139], v[138:139]
	v_pk_mul_f32 v[142:143], v[130:131], v[134:135]
	v_pk_fma_f32 v[144:145], v[96:97], v[134:135], v[144:145]
	v_pk_mul_f32 v[140:141], v[138:139], v[138:139]
	v_pk_fma_f32 v[142:143], v[96:97], v[132:133], v[142:143] neg_lo:[0,0,1] neg_hi:[0,0,1]
	v_pk_mul_f32 v[166:167], v[136:137], v[138:139]
	v_pk_mul_f32 v[170:171], v[136:137], v[144:145]
	v_pk_fma_f32 v[140:141], v[136:137], v[136:137], v[140:141] neg_lo:[0,0,1] neg_hi:[0,0,1]
	v_pk_mul_f32 v[164:165], v[138:139], v[144:145]
	v_pk_add_f32 v[166:167], v[166:167], v[166:167]
	v_pk_fma_f32 v[170:171], v[138:139], v[142:143], v[170:171]
	v_pk_fma_f32 v[164:165], v[136:137], v[142:143], v[164:165] neg_lo:[0,0,1] neg_hi:[0,0,1]
	v_pk_mul_f32 v[174:175], v[166:167], v[170:171]
	v_pk_mul_f32 v[176:177], v[140:141], v[170:171]
	v_pk_fma_f32 v[174:175], v[140:141], v[164:165], v[174:175] neg_lo:[0,0,1] neg_hi:[0,0,1]
	v_pk_fma_f32 v[176:177], v[166:167], v[164:165], v[176:177]
	s_waitcnt lgkmcnt(0)
	v_pk_mul_f32 v[178:179], v[176:177], v[94:95]
	v_pk_mul_f32 v[94:95], v[174:175], v[94:95]
	v_pk_fma_f32 v[178:179], v[174:175], v[90:91], v[178:179] neg_lo:[0,0,1] neg_hi:[0,0,1]
	v_pk_fma_f32 v[90:91], v[176:177], v[90:91], v[94:95]
	v_pk_mul_f32 v[94:95], v[170:171], v[86:87]
	v_pk_mul_f32 v[86:87], v[164:165], v[86:87]
	v_pk_fma_f32 v[94:95], v[164:165], v[82:83], v[94:95] neg_lo:[0,0,1] neg_hi:[0,0,1]
	v_pk_fma_f32 v[82:83], v[170:171], v[82:83], v[86:87]
	v_pk_mul_f32 v[86:87], v[144:145], v[166:167]
	v_pk_mul_f32 v[164:165], v[144:145], v[140:141]
	v_pk_fma_f32 v[86:87], v[142:143], v[140:141], v[86:87] neg_lo:[0,0,1] neg_hi:[0,0,1]
	v_pk_fma_f32 v[164:165], v[142:143], v[166:167], v[164:165]
	s_nop 0
	v_pk_mul_f32 v[170:171], v[164:165], v[78:79]
	v_pk_mul_f32 v[78:79], v[86:87], v[78:79]
	v_pk_fma_f32 v[170:171], v[86:87], v[74:75], v[170:171] neg_lo:[0,0,1] neg_hi:[0,0,1]
	v_pk_fma_f32 v[74:75], v[164:165], v[74:75], v[78:79]
	v_pk_mul_f32 v[78:79], v[144:145], v[70:71]
	v_pk_mul_f32 v[70:71], v[142:143], v[70:71]
	v_pk_mul_f32 v[86:87], v[130:131], v[136:137]
	v_pk_fma_f32 v[78:79], v[142:143], v[66:67], v[78:79] neg_lo:[0,0,1] neg_hi:[0,0,1]
	v_pk_fma_f32 v[66:67], v[144:145], v[66:67], v[70:71]
	v_pk_mul_f32 v[70:71], v[130:131], v[138:139]
	v_pk_fma_f32 v[86:87], v[96:97], v[138:139], v[86:87]
	v_pk_fma_f32 v[70:71], v[96:97], v[136:137], v[70:71] neg_lo:[0,0,1] neg_hi:[0,0,1]
	v_pk_mul_f32 v[142:143], v[166:167], v[86:87]
	v_pk_mul_f32 v[144:145], v[140:141], v[86:87]
	v_pk_fma_f32 v[142:143], v[140:141], v[70:71], v[142:143] neg_lo:[0,0,1] neg_hi:[0,0,1]
	v_pk_fma_f32 v[144:145], v[166:167], v[70:71], v[144:145]
	s_nop 0
	v_pk_mul_f32 v[164:165], v[144:145], v[62:63]
	v_pk_mul_f32 v[62:63], v[142:143], v[62:63]
	v_pk_fma_f32 v[164:165], v[142:143], v[58:59], v[164:165] neg_lo:[0,0,1] neg_hi:[0,0,1]
	v_pk_fma_f32 v[58:59], v[144:145], v[58:59], v[62:63]
	v_pk_mul_f32 v[62:63], v[86:87], v[22:23]
	v_pk_mul_f32 v[22:23], v[70:71], v[22:23]
	v_pk_fma_f32 v[62:63], v[70:71], v[18:19], v[62:63] neg_lo:[0,0,1] neg_hi:[0,0,1]
	v_pk_fma_f32 v[18:19], v[86:87], v[18:19], v[22:23]
	v_pk_mul_f32 v[22:23], v[130:131], v[166:167]
	v_pk_mul_f32 v[70:71], v[130:131], v[140:141]
	v_pk_fma_f32 v[22:23], v[96:97], v[140:141], v[22:23] neg_lo:[0,0,1] neg_hi:[0,0,1]
	v_pk_fma_f32 v[70:71], v[96:97], v[166:167], v[70:71]
	s_nop 0
	v_pk_mul_f32 v[86:87], v[70:71], v[14:15]
	v_pk_mul_f32 v[14:15], v[22:23], v[14:15]
	v_pk_fma_f32 v[86:87], v[22:23], v[10:11], v[86:87] neg_lo:[0,0,1] neg_hi:[0,0,1]
	v_pk_fma_f32 v[10:11], v[70:71], v[10:11], v[14:15]
	v_pk_mul_f32 v[14:15], v[130:131], v[2:3]
	v_pk_mul_f32 v[2:3], v[96:97], v[2:3]
	v_pk_mul_f32 v[22:23], v[134:135], v[136:137]
	v_pk_fma_f32 v[14:15], v[96:97], v[6:7], v[14:15] neg_lo:[0,0,1] neg_hi:[0,0,1]
	v_pk_fma_f32 v[2:3], v[130:131], v[6:7], v[2:3]
	v_pk_mul_f32 v[6:7], v[134:135], v[138:139]
	v_pk_fma_f32 v[22:23], v[132:133], v[138:139], v[22:23]
	v_pk_fma_f32 v[6:7], v[132:133], v[136:137], v[6:7] neg_lo:[0,0,1] neg_hi:[0,0,1]
	v_pk_mul_f32 v[96:97], v[140:141], v[22:23]
	v_pk_mul_f32 v[70:71], v[166:167], v[22:23]
	v_pk_fma_f32 v[96:97], v[166:167], v[6:7], v[96:97]
	v_pk_fma_f32 v[70:71], v[140:141], v[6:7], v[70:71] neg_lo:[0,0,1] neg_hi:[0,0,1]
	v_pk_mul_f32 v[130:131], v[96:97], v[92:93]
	s_nop 0
	v_pk_fma_f32 v[130:131], v[88:89], v[70:71], v[130:131] neg_lo:[0,0,1] neg_hi:[0,0,1]
	v_pk_mul_f32 v[70:71], v[70:71], v[92:93]
	v_pk_add_f32 v[92:93], v[78:79], v[170:171]
	v_pk_fma_f32 v[70:71], v[88:89], v[96:97], v[70:71]
	v_pk_mul_f32 v[88:89], v[22:23], v[84:85]
	v_pk_add_f32 v[96:97], v[94:95], v[178:179]
	v_pk_fma_f32 v[88:89], v[80:81], v[6:7], v[88:89] neg_lo:[0,0,1] neg_hi:[0,0,1]
	v_pk_mul_f32 v[6:7], v[6:7], v[84:85]
	s_nop 0
	v_pk_fma_f32 v[6:7], v[80:81], v[22:23], v[6:7]
	v_pk_mul_f32 v[80:81], v[134:135], v[140:141]
	v_pk_mul_f32 v[22:23], v[134:135], v[166:167]
	v_pk_fma_f32 v[80:81], v[132:133], v[166:167], v[80:81]
	v_pk_fma_f32 v[22:23], v[132:133], v[140:141], v[22:23] neg_lo:[0,0,1] neg_hi:[0,0,1]
	v_pk_mul_f32 v[84:85], v[76:77], v[80:81]
	s_nop 0
	v_pk_fma_f32 v[84:85], v[72:73], v[22:23], v[84:85] neg_lo:[0,0,1] neg_hi:[0,0,1]
	v_pk_mul_f32 v[72:73], v[72:73], v[80:81]
	s_nop 0
	v_pk_fma_f32 v[22:23], v[76:77], v[22:23], v[72:73]
	v_pk_mul_f32 v[72:73], v[134:135], v[68:69]
	v_pk_mul_f32 v[68:69], v[132:133], v[68:69]
	v_pk_mul_f32 v[76:77], v[138:139], v[140:141]
	v_pk_fma_f32 v[72:73], v[64:65], v[132:133], v[72:73] neg_lo:[0,0,1] neg_hi:[0,0,1]
	v_pk_fma_f32 v[64:65], v[64:65], v[134:135], v[68:69]
	v_pk_mul_f32 v[68:69], v[138:139], v[166:167]
	v_pk_fma_f32 v[76:77], v[136:137], v[166:167], v[76:77]
	v_pk_fma_f32 v[68:69], v[136:137], v[140:141], v[68:69] neg_lo:[0,0,1] neg_hi:[0,0,1]
	v_pk_mul_f32 v[80:81], v[60:61], v[76:77]
	s_nop 0
	v_pk_fma_f32 v[80:81], v[56:57], v[68:69], v[80:81] neg_lo:[0,0,1] neg_hi:[0,0,1]
	v_pk_mul_f32 v[56:57], v[56:57], v[76:77]
	v_pk_add_f32 v[76:77], v[72:73], v[84:85]
	v_pk_fma_f32 v[56:57], v[60:61], v[68:69], v[56:57]
	v_pk_mul_f32 v[60:61], v[20:21], v[138:139]
	s_nop 0
	v_pk_fma_f32 v[60:61], v[16:17], v[136:137], v[60:61] neg_lo:[0,0,1] neg_hi:[0,0,1]
	v_pk_mul_f32 v[16:17], v[16:17], v[138:139]
	s_nop 0
	v_pk_fma_f32 v[16:17], v[20:21], v[136:137], v[16:17]
	v_pk_mul_f32 v[20:21], v[12:13], v[166:167]
	s_nop 0
	v_pk_fma_f32 v[20:21], v[8:9], v[140:141], v[20:21] neg_lo:[0,0,1] neg_hi:[0,0,1]
	v_pk_mul_f32 v[8:9], v[8:9], v[166:167]
	v_pk_add_f32 v[68:69], v[4:5], v[20:21]
	v_pk_fma_f32 v[8:9], v[12:13], v[140:141], v[8:9]
	v_pk_add_f32 v[4:5], v[4:5], v[20:21] neg_lo:[0,1] neg_hi:[0,1]
	v_pk_add_f32 v[12:13], v[0:1], v[8:9]
	v_pk_add_f32 v[0:1], v[0:1], v[8:9] neg_lo:[0,1] neg_hi:[0,1]
	v_pk_add_f32 v[8:9], v[16:17], v[56:57]
	v_pk_add_f32 v[20:21], v[60:61], v[80:81]
	v_pk_add_f32 v[16:17], v[16:17], v[56:57] neg_lo:[0,1] neg_hi:[0,1]
	v_pk_add_f32 v[56:57], v[60:61], v[80:81] neg_lo:[0,1] neg_hi:[0,1]
	v_pk_add_f32 v[60:61], v[64:65], v[22:23]
	v_pk_add_f32 v[22:23], v[64:65], v[22:23] neg_lo:[0,1] neg_hi:[0,1]
	v_pk_add_f32 v[64:65], v[72:73], v[84:85] neg_lo:[0,1] neg_hi:[0,1]
	v_pk_add_f32 v[72:73], v[6:7], v[70:71]
	v_pk_add_f32 v[80:81], v[88:89], v[130:131]
	v_pk_add_f32 v[6:7], v[6:7], v[70:71] neg_lo:[0,1] neg_hi:[0,1]
	v_pk_add_f32 v[70:71], v[88:89], v[130:131] neg_lo:[0,1] neg_hi:[0,1]
	v_pk_add_f32 v[84:85], v[2:3], v[10:11]
	v_pk_add_f32 v[88:89], v[14:15], v[86:87]
	v_pk_add_f32 v[2:3], v[2:3], v[10:11] neg_lo:[0,1] neg_hi:[0,1]
	v_pk_add_f32 v[10:11], v[14:15], v[86:87] neg_lo:[0,1] neg_hi:[0,1]
	v_pk_add_f32 v[14:15], v[18:19], v[58:59]
	v_pk_add_f32 v[86:87], v[62:63], v[164:165]
	v_pk_add_f32 v[18:19], v[18:19], v[58:59] neg_lo:[0,1] neg_hi:[0,1]
	v_pk_add_f32 v[58:59], v[62:63], v[164:165] neg_lo:[0,1] neg_hi:[0,1]
	v_pk_add_f32 v[62:63], v[66:67], v[74:75]
	v_pk_add_f32 v[66:67], v[66:67], v[74:75] neg_lo:[0,1] neg_hi:[0,1]
	v_pk_add_f32 v[74:75], v[78:79], v[170:171] neg_lo:[0,1] neg_hi:[0,1]
	v_pk_add_f32 v[78:79], v[82:83], v[90:91]
	v_pk_add_f32 v[82:83], v[82:83], v[90:91] neg_lo:[0,1] neg_hi:[0,1]
	v_pk_add_f32 v[90:91], v[94:95], v[178:179] neg_lo:[0,1] neg_hi:[0,1]
	v_pk_add_f32 v[94:95], v[12:13], v[8:9]
	v_pk_add_f32 v[130:131], v[68:69], v[20:21]
	v_pk_add_f32 v[8:9], v[12:13], v[8:9] neg_lo:[0,1] neg_hi:[0,1]
	v_pk_add_f32 v[12:13], v[68:69], v[20:21] neg_lo:[0,1] neg_hi:[0,1]
	v_pk_add_f32 v[20:21], v[0:1], v[56:57] neg_lo:[0,1] neg_hi:[0,1]
	v_pk_add_f32 v[68:69], v[4:5], v[16:17]
	v_pk_add_f32 v[0:1], v[0:1], v[56:57]
	v_pk_add_f32 v[4:5], v[4:5], v[16:17] neg_lo:[0,1] neg_hi:[0,1]
	v_pk_add_f32 v[16:17], v[60:61], v[72:73]
	v_pk_add_f32 v[56:57], v[76:77], v[80:81]
	v_pk_add_f32 v[60:61], v[60:61], v[72:73] neg_lo:[0,1] neg_hi:[0,1]
	v_pk_add_f32 v[72:73], v[76:77], v[80:81] neg_lo:[0,1] neg_hi:[0,1]
	v_pk_add_f32 v[76:77], v[22:23], v[70:71] neg_lo:[0,1] neg_hi:[0,1]
	v_pk_add_f32 v[80:81], v[64:65], v[6:7]
	v_pk_add_f32 v[6:7], v[64:65], v[6:7] neg_lo:[0,1] neg_hi:[0,1]
	v_pk_mul_f32 v[76:77], v[76:77], s[82:83] op_sel_hi:[1,0]
	v_pk_add_f32 v[22:23], v[22:23], v[70:71]
	v_pk_add_f32 v[64:65], v[84:85], v[14:15]
	v_pk_add_f32 v[70:71], v[88:89], v[86:87]
	v_pk_add_f32 v[14:15], v[84:85], v[14:15] neg_lo:[0,1] neg_hi:[0,1]
	v_pk_add_f32 v[84:85], v[88:89], v[86:87] neg_lo:[0,1] neg_hi:[0,1]
	v_pk_add_f32 v[86:87], v[2:3], v[58:59] neg_lo:[0,1] neg_hi:[0,1]
	v_pk_add_f32 v[88:89], v[10:11], v[18:19]
	v_pk_add_f32 v[2:3], v[2:3], v[58:59]
	v_pk_add_f32 v[10:11], v[10:11], v[18:19] neg_lo:[0,1] neg_hi:[0,1]
	v_pk_add_f32 v[18:19], v[62:63], v[78:79]
	v_pk_add_f32 v[58:59], v[92:93], v[96:97]
	v_pk_add_f32 v[62:63], v[62:63], v[78:79] neg_lo:[0,1] neg_hi:[0,1]
	v_pk_add_f32 v[78:79], v[92:93], v[96:97] neg_lo:[0,1] neg_hi:[0,1]
	v_pk_add_f32 v[96:97], v[74:75], v[82:83]
	v_pk_add_f32 v[74:75], v[74:75], v[82:83] neg_lo:[0,1] neg_hi:[0,1]
	v_pk_add_f32 v[82:83], v[94:95], v[16:17]
	v_pk_add_f32 v[16:17], v[94:95], v[16:17] neg_lo:[0,1] neg_hi:[0,1]
	v_pk_fma_f32 v[94:95], v[80:81], s[82:83], v[76:77] op_sel_hi:[1,0,1] neg_lo:[1,0,0] neg_hi:[1,0,0]
	v_pk_mul_f32 v[6:7], v[6:7], s[82:83] op_sel_hi:[1,0]
	v_pk_add_f32 v[92:93], v[66:67], v[90:91] neg_lo:[0,1] neg_hi:[0,1]
	v_pk_fma_f32 v[76:77], v[80:81], s[82:83], v[76:77] op_sel_hi:[1,0,1]
	v_pk_add_f32 v[80:81], v[20:21], v[94:95]
	v_pk_add_f32 v[20:21], v[20:21], v[94:95] neg_lo:[0,1] neg_hi:[0,1]
	v_pk_add_f32 v[94:95], v[12:13], v[60:61]
	v_pk_add_f32 v[12:13], v[12:13], v[60:61] neg_lo:[0,1] neg_hi:[0,1]
	v_pk_fma_f32 v[60:61], v[22:23], s[54:55], v[6:7] op_sel_hi:[1,0,1] neg_lo:[0,0,1] neg_hi:[0,0,1]
	v_pk_fma_f32 v[6:7], v[22:23], s[82:83], v[6:7] op_sel_hi:[1,0,1] neg_lo:[0,0,1] neg_hi:[0,0,1]
	v_pk_add_f32 v[66:67], v[66:67], v[90:91]
	v_pk_add_f32 v[90:91], v[130:131], v[56:57]
	v_pk_add_f32 v[56:57], v[130:131], v[56:57] neg_lo:[0,1] neg_hi:[0,1]
	v_pk_add_f32 v[130:131], v[68:69], v[76:77]
	v_pk_add_f32 v[68:69], v[68:69], v[76:77] neg_lo:[0,1] neg_hi:[0,1]
	v_pk_add_f32 v[76:77], v[8:9], v[72:73] neg_lo:[0,1] neg_hi:[0,1]
	v_pk_add_f32 v[8:9], v[8:9], v[72:73]
	v_pk_add_f32 v[72:73], v[4:5], v[6:7]
	v_pk_add_f32 v[4:5], v[4:5], v[6:7] neg_lo:[0,1] neg_hi:[0,1]
	v_pk_add_f32 v[6:7], v[64:65], v[18:19]
	v_pk_add_f32 v[18:19], v[64:65], v[18:19] neg_lo:[0,1] neg_hi:[0,1]
	v_pk_mul_f32 v[64:65], v[92:93], s[82:83] op_sel_hi:[1,0]
	v_pk_add_f32 v[22:23], v[0:1], v[60:61]
	v_pk_add_f32 v[0:1], v[0:1], v[60:61] neg_lo:[0,1] neg_hi:[0,1]
	v_pk_add_f32 v[60:61], v[70:71], v[58:59]
	v_pk_add_f32 v[58:59], v[70:71], v[58:59] neg_lo:[0,1] neg_hi:[0,1]
	v_pk_fma_f32 v[70:71], v[96:97], s[82:83], v[64:65] op_sel_hi:[1,0,1] neg_lo:[1,0,0] neg_hi:[1,0,0]
	v_pk_fma_f32 v[64:65], v[96:97], s[82:83], v[64:65] op_sel_hi:[1,0,1]
	v_pk_mul_f32 v[74:75], v[74:75], s[82:83] op_sel_hi:[1,0]
	v_pk_add_f32 v[92:93], v[86:87], v[70:71]
	v_pk_add_f32 v[96:97], v[88:89], v[64:65]
	v_pk_add_f32 v[70:71], v[86:87], v[70:71] neg_lo:[0,1] neg_hi:[0,1]
	v_pk_add_f32 v[86:87], v[14:15], v[78:79] neg_lo:[0,1] neg_hi:[0,1]
	v_pk_add_f32 v[14:15], v[14:15], v[78:79]
	v_pk_fma_f32 v[78:79], v[66:67], s[54:55], v[74:75] op_sel_hi:[1,0,1] neg_lo:[0,0,1] neg_hi:[0,0,1]
	v_pk_fma_f32 v[66:67], v[66:67], s[82:83], v[74:75] op_sel_hi:[1,0,1] neg_lo:[0,0,1] neg_hi:[0,0,1]
	v_pk_add_f32 v[64:65], v[88:89], v[64:65] neg_lo:[0,1] neg_hi:[0,1]
	v_pk_add_f32 v[88:89], v[84:85], v[62:63]
	v_pk_add_f32 v[62:63], v[84:85], v[62:63] neg_lo:[0,1] neg_hi:[0,1]
	v_pk_add_f32 v[74:75], v[2:3], v[78:79]
	v_pk_add_f32 v[84:85], v[10:11], v[66:67]
	v_pk_add_f32 v[2:3], v[2:3], v[78:79] neg_lo:[0,1] neg_hi:[0,1]
	v_pk_add_f32 v[10:11], v[10:11], v[66:67] neg_lo:[0,1] neg_hi:[0,1]
	v_pk_add_f32 v[66:67], v[82:83], v[6:7]
	v_pk_add_f32 v[78:79], v[90:91], v[60:61]
	v_pk_add_f32 v[6:7], v[82:83], v[6:7] neg_lo:[0,1] neg_hi:[0,1]
	v_pk_add_f32 v[60:61], v[90:91], v[60:61] neg_lo:[0,1] neg_hi:[0,1]
	v_pk_mul_f32 v[82:83], v[96:97], s[80:81] op_sel_hi:[1,0]
	v_pk_mul_f32 v[90:91], v[96:97], s[72:73] op_sel_hi:[1,0]
	v_pk_fma_f32 v[82:83], v[92:93], s[72:73], v[82:83] op_sel_hi:[1,0,1] neg_lo:[0,0,1] neg_hi:[0,0,1]
	v_pk_fma_f32 v[90:91], v[92:93], s[80:81], v[90:91] op_sel_hi:[1,0,1]
	v_pk_mul_f32 v[86:87], v[86:87], s[82:83] op_sel_hi:[1,0]
	v_pk_add_f32 v[92:93], v[80:81], v[82:83]
	v_pk_add_f32 v[96:97], v[130:131], v[90:91]
	v_pk_add_f32 v[80:81], v[80:81], v[82:83] neg_lo:[0,1] neg_hi:[0,1]
	v_pk_add_f32 v[82:83], v[130:131], v[90:91] neg_lo:[0,1] neg_hi:[0,1]
	v_pk_fma_f32 v[90:91], v[88:89], s[82:83], v[86:87] op_sel_hi:[1,0,1] neg_lo:[1,0,0] neg_hi:[1,0,0]
	v_pk_fma_f32 v[86:87], v[88:89], s[82:83], v[86:87] op_sel_hi:[1,0,1]
	v_pk_add_f32 v[88:89], v[76:77], v[90:91]
	v_pk_add_f32 v[76:77], v[76:77], v[90:91] neg_lo:[0,1] neg_hi:[0,1]
	v_pk_mul_f32 v[90:91], v[84:85], s[72:73] op_sel_hi:[1,0]
	v_pk_mul_f32 v[84:85], v[84:85], s[80:81] op_sel_hi:[1,0]
	v_pk_fma_f32 v[90:91], v[74:75], s[80:81], v[90:91] op_sel_hi:[1,0,1] neg_lo:[0,0,1] neg_hi:[0,0,1]
	v_pk_fma_f32 v[74:75], v[74:75], s[72:73], v[84:85] op_sel_hi:[1,0,1]
	v_pk_add_f32 v[130:131], v[94:95], v[86:87]
	v_pk_add_f32 v[86:87], v[94:95], v[86:87] neg_lo:[0,1] neg_hi:[0,1]
	v_pk_add_f32 v[84:85], v[22:23], v[90:91]
	v_pk_add_f32 v[94:95], v[72:73], v[74:75]
	v_pk_add_f32 v[22:23], v[22:23], v[90:91] neg_lo:[0,1] neg_hi:[0,1]
	v_pk_add_f32 v[72:73], v[72:73], v[74:75] neg_lo:[0,1] neg_hi:[0,1]
	v_pk_add_f32 v[74:75], v[16:17], v[58:59] neg_lo:[0,1] neg_hi:[0,1]
	v_pk_add_f32 v[90:91], v[56:57], v[18:19]
	v_pk_add_f32 v[16:17], v[16:17], v[58:59]
	v_pk_add_f32 v[18:19], v[56:57], v[18:19] neg_lo:[0,1] neg_hi:[0,1]
	v_pk_mul_f32 v[56:57], v[64:65], s[72:73] op_sel_hi:[1,0]
	v_pk_mul_f32 v[58:59], v[64:65], s[80:81] op_sel_hi:[1,0]
	v_pk_fma_f32 v[56:57], v[70:71], s[84:85], v[56:57] op_sel_hi:[1,0,1] neg_lo:[0,0,1] neg_hi:[0,0,1]
	v_pk_fma_f32 v[58:59], v[70:71], s[72:73], v[58:59] op_sel_hi:[1,0,1] neg_lo:[0,0,1] neg_hi:[0,0,1]
	v_pk_add_f32 v[64:65], v[20:21], v[56:57]
	v_pk_add_f32 v[70:71], v[68:69], v[58:59]
	v_pk_add_f32 v[20:21], v[20:21], v[56:57] neg_lo:[0,1] neg_hi:[0,1]
	v_pk_add_f32 v[56:57], v[68:69], v[58:59] neg_lo:[0,1] neg_hi:[0,1]
	v_pk_mul_f32 v[58:59], v[62:63], s[82:83] op_sel_hi:[1,0]
	s_nop 0
	v_pk_fma_f32 v[62:63], v[14:15], s[54:55], v[58:59] op_sel_hi:[1,0,1] neg_lo:[0,0,1] neg_hi:[0,0,1]
	v_pk_fma_f32 v[14:15], v[14:15], s[82:83], v[58:59] op_sel_hi:[1,0,1] neg_lo:[0,0,1] neg_hi:[0,0,1]
	v_pk_add_f32 v[58:59], v[8:9], v[62:63]
	v_pk_add_f32 v[68:69], v[12:13], v[14:15]
	v_pk_add_f32 v[12:13], v[12:13], v[14:15] neg_lo:[0,1] neg_hi:[0,1]
	v_pk_mul_f32 v[14:15], v[10:11], s[80:81] op_sel_hi:[1,0]
	v_pk_mul_f32 v[10:11], v[10:11], s[72:73] op_sel_hi:[1,0]
	v_pk_fma_f32 v[14:15], v[2:3], s[52:53], v[14:15] op_sel_hi:[1,0,1] neg_lo:[0,0,1] neg_hi:[0,0,1]
	v_pk_fma_f32 v[2:3], v[2:3], s[80:81], v[10:11] op_sel_hi:[1,0,1] neg_lo:[0,0,1] neg_hi:[0,0,1]
	v_pk_add_f32 v[10:11], v[0:1], v[14:15]
	v_pk_add_f32 v[0:1], v[0:1], v[14:15] neg_lo:[0,1] neg_hi:[0,1]
	v_pk_add_f32 v[8:9], v[8:9], v[62:63] neg_lo:[0,1] neg_hi:[0,1]
	v_pk_add_f32 v[62:63], v[4:5], v[2:3]
	v_pk_add_f32 v[2:3], v[4:5], v[2:3] neg_lo:[0,1] neg_hi:[0,1]
	ds_write2_b64 v162, v[66:67], v[92:93] offset1:34
	ds_write2_b64 v168, v[78:79], v[96:97] offset1:34
	ds_write2_b64 v162, v[88:89], v[84:85] offset0:68 offset1:102
	ds_write2_b64 v168, v[130:131], v[94:95] offset0:68 offset1:102
	ds_write2_b64 v162, v[74:75], v[64:65] offset0:136 offset1:170
	ds_write2_b64 v168, v[90:91], v[70:71] offset0:136 offset1:170
	ds_write2_b64 v162, v[58:59], v[10:11] offset0:204 offset1:238
	ds_write2_b64 v168, v[68:69], v[62:63] offset0:204 offset1:238
	ds_write2_b64 v181, v[6:7], v[80:81] offset0:16 offset1:50
	ds_write2_b64 v180, v[60:61], v[82:83] offset0:16 offset1:50
	ds_write2_b64 v181, v[76:77], v[22:23] offset0:84 offset1:118
	ds_write2_b64 v180, v[86:87], v[72:73] offset0:84 offset1:118
	ds_write2_b64 v181, v[16:17], v[20:21] offset0:152 offset1:186
	ds_write2_b64 v180, v[18:19], v[56:57] offset0:152 offset1:186
	ds_write2_b64 v181, v[8:9], v[0:1] offset0:220 offset1:254
	ds_write2_b64 v180, v[12:13], v[2:3] offset0:220 offset1:254
	v_mov_b32_e32 v0, v163
	s_waitcnt lgkmcnt(0)
	s_barrier
	s_nop 0
	s_nop 0
	v_ashrrev_i32_e32 v2, 31, v0
	v_lshlrev_b32_e32 v1, 1, v0
	v_lshrrev_b32_e32 v2, 23, v2
	v_and_b32_e32 v1, 0x3fe, v1
	v_add_lshl_u32 v0, v0, v2, 5
	v_and_or_b32 v0, v0, s85, v1
	v_ashrrev_i32_e32 v2, 4, v0
	v_and_b32_e32 v2, 0x3ffffc3c, v2
	v_add_lshl_u32 v4, v2, v0, 2
	v_cvt_f32_u32_e32 v0, v1
	v_or_b32_e32 v1, 1, v1
	v_cvt_f32_u32_e32 v1, v1
	v_add_u32_e32 v130, 0, v4
	v_mul_f32_e32 v0, 0x38800000, v0
	v_sin_f32_e64 v72, -v0
	v_mul_f32_e32 v1, 0x38800000, v1
	v_sin_f32_e64 v73, -v1
	v_cos_f32_e32 v70, v0
	v_cos_f32_e32 v71, v1
	v_add_u32_e32 v131, s91, v4
	v_pk_mul_f32 v[0:1], v[72:73], v[72:73]
	ds_read_b64 v[4:5], v130
	ds_read_b64 v[6:7], v131
	ds_read_b64 v[164:165], v131 offset:34816
	ds_read_b64 v[166:167], v130 offset:34816
	ds_read_b64 v[132:133], v131 offset:17408
	ds_read_b64 v[134:135], v130 offset:17408
	ds_read_b64 v[180:181], v131 offset:52224
	ds_read_b64 v[182:183], v130 offset:52224
	ds_read_b64 v[176:177], v131 offset:8704
	ds_read_b64 v[178:179], v130 offset:8704
	s_waitcnt lgkmcnt(6)
	v_pk_fma_f32 v[22:23], v[70:71], v[70:71], v[0:1] neg_lo:[0,0,1] neg_hi:[0,0,1]
	v_pk_mul_f32 v[0:1], v[70:71], v[72:73]
	s_nop 0
	v_pk_add_f32 v[56:57], v[0:1], v[0:1]
	s_nop 0
	v_pk_mul_f32 v[0:1], v[72:73], v[56:57]
	s_nop 0
	v_pk_fma_f32 v[86:87], v[70:71], v[22:23], v[0:1] neg_lo:[0,0,1] neg_hi:[0,0,1]
	v_pk_mul_f32 v[0:1], v[72:73], v[22:23]
	s_nop 0
	v_pk_fma_f32 v[96:97], v[70:71], v[56:57], v[0:1]
	v_pk_mul_f32 v[0:1], v[56:57], v[56:57]
	s_nop 0
	v_pk_fma_f32 v[14:15], v[22:23], v[22:23], v[0:1] neg_lo:[0,0,1] neg_hi:[0,0,1]
	v_pk_mul_f32 v[0:1], v[22:23], v[56:57]
	s_nop 0
	v_pk_add_f32 v[16:17], v[0:1], v[0:1]
	s_nop 0
	v_pk_mul_f32 v[0:1], v[72:73], v[16:17]
	s_nop 0
	v_pk_fma_f32 v[78:79], v[70:71], v[14:15], v[0:1] neg_lo:[0,0,1] neg_hi:[0,0,1]
	v_pk_mul_f32 v[0:1], v[72:73], v[14:15]
	s_nop 0
	v_pk_fma_f32 v[80:81], v[70:71], v[16:17], v[0:1]
	v_pk_mul_f32 v[0:1], v[56:57], v[16:17]
	s_nop 0
	v_pk_fma_f32 v[62:63], v[22:23], v[14:15], v[0:1] neg_lo:[0,0,1] neg_hi:[0,0,1]
	v_pk_mul_f32 v[0:1], v[56:57], v[14:15]
	s_nop 0
	v_pk_fma_f32 v[64:65], v[22:23], v[16:17], v[0:1]
	v_pk_mul_f32 v[0:1], v[16:17], v[96:97]
	s_nop 0
	v_pk_fma_f32 v[88:89], v[14:15], v[86:87], v[0:1] neg_lo:[0,0,1] neg_hi:[0,0,1]
	v_pk_mul_f32 v[0:1], v[14:15], v[96:97]
	s_nop 0
	v_pk_fma_f32 v[90:91], v[16:17], v[86:87], v[0:1]
	v_pk_mul_f32 v[0:1], v[16:17], v[16:17]
	s_nop 0
	v_pk_fma_f32 v[10:11], v[14:15], v[14:15], v[0:1] neg_lo:[0,0,1] neg_hi:[0,0,1]
	v_pk_mul_f32 v[0:1], v[14:15], v[16:17]
	v_pk_mul_f32 v[2:3], v[10:11], v[90:91]
	v_pk_add_f32 v[12:13], v[0:1], v[0:1]
	s_nop 0
	v_pk_mul_f32 v[0:1], v[72:73], v[12:13]
	v_pk_fma_f32 v[2:3], v[12:13], v[88:89], v[2:3]
	v_pk_fma_f32 v[74:75], v[70:71], v[10:11], v[0:1] neg_lo:[0,0,1] neg_hi:[0,0,1]
	v_pk_mul_f32 v[0:1], v[72:73], v[10:11]
	v_pk_mul_f32 v[8:9], v[164:165], v[12:13]
	v_pk_fma_f32 v[76:77], v[70:71], v[12:13], v[0:1]
	v_pk_mul_f32 v[0:1], v[56:57], v[12:13]
	v_pk_fma_f32 v[8:9], v[166:167], v[10:11], v[8:9]
	v_pk_fma_f32 v[58:59], v[22:23], v[10:11], v[0:1] neg_lo:[0,0,1] neg_hi:[0,0,1]
	v_pk_mul_f32 v[0:1], v[56:57], v[10:11]
	s_nop 0
	v_pk_fma_f32 v[60:61], v[22:23], v[12:13], v[0:1]
	v_pk_mul_f32 v[0:1], v[96:97], v[12:13]
	s_nop 0
	v_pk_fma_f32 v[92:93], v[86:87], v[10:11], v[0:1] neg_lo:[0,0,1] neg_hi:[0,0,1]
	v_pk_mul_f32 v[0:1], v[96:97], v[10:11]
	s_nop 0
	v_pk_fma_f32 v[94:95], v[86:87], v[12:13], v[0:1]
	v_pk_mul_f32 v[0:1], v[16:17], v[12:13]
	s_nop 0
	v_pk_fma_f32 v[18:19], v[14:15], v[10:11], v[0:1] neg_lo:[0,0,1] neg_hi:[0,0,1]
	v_pk_mul_f32 v[0:1], v[16:17], v[10:11]
	s_nop 0
	v_pk_fma_f32 v[20:21], v[14:15], v[12:13], v[0:1]
	v_pk_mul_f32 v[0:1], v[12:13], v[80:81]
	s_nop 0
	v_pk_fma_f32 v[82:83], v[10:11], v[78:79], v[0:1] neg_lo:[0,0,1] neg_hi:[0,0,1]
	v_pk_mul_f32 v[0:1], v[10:11], v[80:81]
	s_nop 0
	v_pk_fma_f32 v[84:85], v[12:13], v[78:79], v[0:1]
	v_pk_mul_f32 v[0:1], v[12:13], v[64:65]
	s_nop 0
	v_pk_fma_f32 v[66:67], v[10:11], v[62:63], v[0:1] neg_lo:[0,0,1] neg_hi:[0,0,1]
	v_pk_mul_f32 v[0:1], v[10:11], v[64:65]
	s_nop 0
	v_pk_fma_f32 v[68:69], v[12:13], v[62:63], v[0:1]
	v_pk_mul_f32 v[0:1], v[12:13], v[90:91]
	v_pk_mul_f32 v[12:13], v[166:167], v[12:13]
	v_pk_fma_f32 v[0:1], v[10:11], v[88:89], v[0:1] neg_lo:[0,0,1] neg_hi:[0,0,1]
	v_pk_fma_f32 v[10:11], v[164:165], v[10:11], v[12:13] neg_lo:[0,0,1] neg_hi:[0,0,1]
	ds_read_b64 v[164:165], v131 offset:43520
	ds_read_b64 v[166:167], v130 offset:43520
	s_waitcnt lgkmcnt(6)
	v_pk_mul_f32 v[12:13], v[132:133], v[16:17]
	v_pk_mul_f32 v[16:17], v[134:135], v[16:17]
	v_pk_fma_f32 v[12:13], v[134:135], v[14:15], v[12:13]
	v_pk_fma_f32 v[14:15], v[132:133], v[14:15], v[16:17] neg_lo:[0,0,1] neg_hi:[0,0,1]
	ds_read_b64 v[132:133], v131 offset:26112
	ds_read_b64 v[134:135], v130 offset:26112
	s_waitcnt lgkmcnt(6)
	v_pk_mul_f32 v[16:17], v[180:181], v[20:21]
	v_pk_mul_f32 v[20:21], v[182:183], v[20:21]
	v_pk_fma_f32 v[16:17], v[182:183], v[18:19], v[16:17]
	v_pk_fma_f32 v[18:19], v[180:181], v[18:19], v[20:21] neg_lo:[0,0,1] neg_hi:[0,0,1]
	ds_read_b64 v[180:181], v131 offset:60928
	ds_read_b64 v[182:183], v130 offset:60928
	s_waitcnt lgkmcnt(6)
	v_pk_mul_f32 v[20:21], v[22:23], v[178:179]
	s_nop 0
	v_pk_fma_f32 v[20:21], v[176:177], v[56:57], v[20:21]
	v_pk_mul_f32 v[56:57], v[56:57], v[178:179]
	s_nop 0
	v_pk_fma_f32 v[22:23], v[176:177], v[22:23], v[56:57] neg_lo:[0,0,1] neg_hi:[0,0,1]
	ds_read_b64 v[176:177], v131 offset:4352
	ds_read_b64 v[178:179], v130 offset:4352
	s_waitcnt lgkmcnt(6)
	v_pk_mul_f32 v[56:57], v[164:165], v[60:61]
	v_pk_mul_f32 v[60:61], v[166:167], v[60:61]
	v_pk_fma_f32 v[56:57], v[166:167], v[58:59], v[56:57]
	v_pk_fma_f32 v[58:59], v[164:165], v[58:59], v[60:61] neg_lo:[0,0,1] neg_hi:[0,0,1]
	ds_read_b64 v[164:165], v131 offset:39168
	ds_read_b64 v[166:167], v130 offset:39168
	s_waitcnt lgkmcnt(6)
	v_pk_mul_f32 v[60:61], v[62:63], v[134:135]
	s_nop 0
	v_pk_fma_f32 v[60:61], v[132:133], v[64:65], v[60:61]
	v_pk_mul_f32 v[64:65], v[64:65], v[134:135]
	s_nop 0
	v_pk_fma_f32 v[62:63], v[132:133], v[62:63], v[64:65] neg_lo:[0,0,1] neg_hi:[0,0,1]
	ds_read_b64 v[132:133], v131 offset:21760
	ds_read_b64 v[134:135], v130 offset:21760
	s_waitcnt lgkmcnt(6)
	v_pk_mul_f32 v[64:65], v[66:67], v[182:183]
	s_nop 0
	v_pk_fma_f32 v[64:65], v[180:181], v[68:69], v[64:65]
	v_pk_mul_f32 v[68:69], v[68:69], v[182:183]
	s_nop 0
	v_pk_fma_f32 v[66:67], v[180:181], v[66:67], v[68:69] neg_lo:[0,0,1] neg_hi:[0,0,1]
	ds_read_b64 v[180:181], v131 offset:56576
	ds_read_b64 v[182:183], v130 offset:56576
	s_waitcnt lgkmcnt(6)
	v_pk_mul_f32 v[68:69], v[70:71], v[178:179]
	s_nop 0
	v_pk_fma_f32 v[68:69], v[72:73], v[176:177], v[68:69]
	v_pk_mul_f32 v[72:73], v[72:73], v[178:179]
	s_nop 0
	v_pk_fma_f32 v[70:71], v[70:71], v[176:177], v[72:73] neg_lo:[0,0,1] neg_hi:[0,0,1]
	ds_read_b64 v[176:177], v131 offset:13056
	ds_read_b64 v[178:179], v130 offset:13056
	s_waitcnt lgkmcnt(6)
	v_pk_mul_f32 v[72:73], v[74:75], v[166:167]
	s_nop 0
	v_pk_fma_f32 v[72:73], v[76:77], v[164:165], v[72:73]
	v_pk_mul_f32 v[76:77], v[76:77], v[166:167]
	s_nop 0
	v_pk_fma_f32 v[74:75], v[74:75], v[164:165], v[76:77] neg_lo:[0,0,1] neg_hi:[0,0,1]
	ds_read_b64 v[164:165], v131 offset:47872
	ds_read_b64 v[166:167], v130 offset:47872
	s_waitcnt lgkmcnt(6)
	v_pk_mul_f32 v[76:77], v[78:79], v[134:135]
	s_nop 0
	v_pk_fma_f32 v[76:77], v[80:81], v[132:133], v[76:77]
	v_pk_mul_f32 v[80:81], v[80:81], v[134:135]
	s_nop 0
	v_pk_fma_f32 v[78:79], v[78:79], v[132:133], v[80:81] neg_lo:[0,0,1] neg_hi:[0,0,1]
	ds_read_b64 v[132:133], v131 offset:30464
	ds_read_b64 v[134:135], v130 offset:30464
	s_waitcnt lgkmcnt(6)
	v_pk_mul_f32 v[80:81], v[82:83], v[182:183]
	s_nop 0
	v_pk_fma_f32 v[80:81], v[84:85], v[180:181], v[80:81]
	v_pk_mul_f32 v[84:85], v[84:85], v[182:183]
	s_nop 0
	v_pk_fma_f32 v[82:83], v[82:83], v[180:181], v[84:85] neg_lo:[0,0,1] neg_hi:[0,0,1]
	s_waitcnt lgkmcnt(4)
	v_pk_mul_f32 v[84:85], v[86:87], v[178:179]
	s_nop 0
	v_pk_fma_f32 v[84:85], v[96:97], v[176:177], v[84:85]
	v_pk_mul_f32 v[96:97], v[96:97], v[178:179]
	s_nop 0
	v_pk_fma_f32 v[86:87], v[86:87], v[176:177], v[96:97] neg_lo:[0,0,1] neg_hi:[0,0,1]
	s_waitcnt lgkmcnt(2)
	v_pk_mul_f32 v[96:97], v[92:93], v[166:167]
	s_nop 0
	v_pk_fma_f32 v[96:97], v[94:95], v[164:165], v[96:97]
	v_pk_mul_f32 v[94:95], v[94:95], v[166:167]
	s_nop 0
	v_pk_fma_f32 v[92:93], v[92:93], v[164:165], v[94:95] neg_lo:[0,0,1] neg_hi:[0,0,1]
	s_waitcnt lgkmcnt(0)
	v_pk_mul_f32 v[94:95], v[88:89], v[134:135]
	s_nop 0
	v_pk_fma_f32 v[94:95], v[90:91], v[132:133], v[94:95]
	v_pk_mul_f32 v[90:91], v[90:91], v[134:135]
	s_nop 0
	v_pk_fma_f32 v[88:89], v[88:89], v[132:133], v[90:91] neg_lo:[0,0,1] neg_hi:[0,0,1]
	ds_read_b64 v[90:91], v131 offset:65280
	ds_read_b64 v[132:133], v130 offset:65280
	s_waitcnt lgkmcnt(0)
	v_pk_mul_f32 v[134:135], v[2:3], v[132:133]
	s_nop 0
	v_pk_fma_f32 v[134:135], v[0:1], v[90:91], v[134:135] neg_lo:[0,0,1] neg_hi:[0,0,1]
	v_pk_mul_f32 v[0:1], v[0:1], v[132:133]
	s_nop 0
	v_pk_fma_f32 v[0:1], v[2:3], v[90:91], v[0:1]
	v_pk_add_f32 v[2:3], v[4:5], v[8:9]
	v_pk_add_f32 v[90:91], v[6:7], v[10:11]
	v_pk_add_f32 v[4:5], v[4:5], v[8:9] neg_lo:[0,1] neg_hi:[0,1]
	v_pk_add_f32 v[6:7], v[6:7], v[10:11] neg_lo:[0,1] neg_hi:[0,1]
	v_pk_add_f32 v[8:9], v[12:13], v[16:17]
	v_pk_add_f32 v[10:11], v[14:15], v[18:19]
	v_pk_add_f32 v[12:13], v[12:13], v[16:17] neg_lo:[0,1] neg_hi:[0,1]
	v_pk_add_f32 v[14:15], v[14:15], v[18:19] neg_lo:[0,1] neg_hi:[0,1]
	v_pk_add_f32 v[16:17], v[20:21], v[56:57]
	v_pk_add_f32 v[18:19], v[22:23], v[58:59]
	v_pk_add_f32 v[20:21], v[20:21], v[56:57] neg_lo:[0,1] neg_hi:[0,1]
	v_pk_add_f32 v[22:23], v[22:23], v[58:59] neg_lo:[0,1] neg_hi:[0,1]
	v_pk_add_f32 v[56:57], v[60:61], v[64:65]
	v_pk_add_f32 v[58:59], v[62:63], v[66:67]
	v_pk_add_f32 v[60:61], v[60:61], v[64:65] neg_lo:[0,1] neg_hi:[0,1]
	v_pk_add_f32 v[62:63], v[62:63], v[66:67] neg_lo:[0,1] neg_hi:[0,1]
	v_pk_add_f32 v[64:65], v[68:69], v[72:73]
	v_pk_add_f32 v[66:67], v[70:71], v[74:75]
	v_pk_add_f32 v[68:69], v[68:69], v[72:73] neg_lo:[0,1] neg_hi:[0,1]
	v_pk_add_f32 v[70:71], v[70:71], v[74:75] neg_lo:[0,1] neg_hi:[0,1]
	v_pk_add_f32 v[72:73], v[76:77], v[80:81]
	v_pk_add_f32 v[74:75], v[78:79], v[82:83]
	v_pk_add_f32 v[76:77], v[76:77], v[80:81] neg_lo:[0,1] neg_hi:[0,1]
	v_pk_add_f32 v[78:79], v[78:79], v[82:83] neg_lo:[0,1] neg_hi:[0,1]
	v_pk_add_f32 v[80:81], v[84:85], v[96:97]
	v_pk_add_f32 v[82:83], v[86:87], v[92:93]
	v_pk_add_f32 v[84:85], v[84:85], v[96:97] neg_lo:[0,1] neg_hi:[0,1]
	v_pk_add_f32 v[86:87], v[86:87], v[92:93] neg_lo:[0,1] neg_hi:[0,1]
	v_pk_add_f32 v[92:93], v[94:95], v[0:1]
	v_pk_add_f32 v[96:97], v[88:89], v[134:135]
	v_pk_add_f32 v[88:89], v[88:89], v[134:135] neg_lo:[0,1] neg_hi:[0,1]
	v_pk_add_f32 v[0:1], v[94:95], v[0:1] neg_lo:[0,1] neg_hi:[0,1]
	v_pk_add_f32 v[94:95], v[2:3], v[8:9]
	v_pk_add_f32 v[132:133], v[90:91], v[10:11]
	v_pk_add_f32 v[2:3], v[2:3], v[8:9] neg_lo:[0,1] neg_hi:[0,1]
	v_pk_add_f32 v[8:9], v[90:91], v[10:11] neg_lo:[0,1] neg_hi:[0,1]
	v_pk_add_f32 v[90:91], v[6:7], v[12:13]
	v_pk_add_f32 v[6:7], v[6:7], v[12:13] neg_lo:[0,1] neg_hi:[0,1]
	v_pk_add_f32 v[12:13], v[16:17], v[56:57]
	v_pk_add_f32 v[16:17], v[16:17], v[56:57] neg_lo:[0,1] neg_hi:[0,1]
	v_pk_add_f32 v[56:57], v[20:21], v[62:63] neg_lo:[0,1] neg_hi:[0,1]
	v_pk_add_f32 v[20:21], v[20:21], v[62:63]
	v_pk_add_f32 v[62:63], v[66:67], v[74:75]
	v_pk_add_f32 v[66:67], v[66:67], v[74:75] neg_lo:[0,1] neg_hi:[0,1]
	v_pk_add_f32 v[74:75], v[70:71], v[76:77]
	v_pk_add_f32 v[70:71], v[70:71], v[76:77] neg_lo:[0,1] neg_hi:[0,1]
	v_pk_add_f32 v[76:77], v[80:81], v[92:93]
	v_pk_add_f32 v[80:81], v[80:81], v[92:93] neg_lo:[0,1] neg_hi:[0,1]
	v_pk_add_f32 v[92:93], v[84:85], v[88:89] neg_lo:[0,1] neg_hi:[0,1]
	v_pk_add_f32 v[10:11], v[4:5], v[14:15] neg_lo:[0,1] neg_hi:[0,1]
	v_pk_add_f32 v[4:5], v[4:5], v[14:15]
	v_pk_add_f32 v[14:15], v[18:19], v[58:59]
	v_pk_add_f32 v[18:19], v[18:19], v[58:59] neg_lo:[0,1] neg_hi:[0,1]
	v_pk_add_f32 v[58:59], v[22:23], v[60:61]
	v_pk_add_f32 v[22:23], v[22:23], v[60:61] neg_lo:[0,1] neg_hi:[0,1]
	v_pk_add_f32 v[60:61], v[64:65], v[72:73]
	v_pk_add_f32 v[64:65], v[64:65], v[72:73] neg_lo:[0,1] neg_hi:[0,1]
	v_pk_add_f32 v[72:73], v[68:69], v[78:79] neg_lo:[0,1] neg_hi:[0,1]
	v_pk_add_f32 v[68:69], v[68:69], v[78:79]
	v_pk_add_f32 v[78:79], v[82:83], v[96:97]
	v_pk_add_f32 v[82:83], v[82:83], v[96:97] neg_lo:[0,1] neg_hi:[0,1]
	v_pk_add_f32 v[96:97], v[86:87], v[0:1]
	v_pk_add_f32 v[0:1], v[86:87], v[0:1] neg_lo:[0,1] neg_hi:[0,1]
	v_pk_mul_f32 v[92:93], v[92:93], s[82:83] op_sel_hi:[1,0]
	v_pk_add_f32 v[84:85], v[84:85], v[88:89]
	v_pk_fma_f32 v[138:139], v[96:97], s[82:83], v[92:93] op_sel_hi:[1,0,1] neg_lo:[1,0,0] neg_hi:[1,0,0]
	v_pk_fma_f32 v[92:93], v[96:97], s[82:83], v[92:93] op_sel_hi:[1,0,1]
	v_pk_mul_f32 v[0:1], v[0:1], s[82:83] op_sel_hi:[1,0]
	v_pk_mul_f32 v[56:57], v[56:57], s[82:83] op_sel_hi:[1,0]
	v_pk_add_f32 v[96:97], v[72:73], v[138:139]
	v_pk_add_f32 v[140:141], v[74:75], v[92:93]
	v_pk_add_f32 v[72:73], v[72:73], v[138:139] neg_lo:[0,1] neg_hi:[0,1]
	v_pk_add_f32 v[138:139], v[66:67], v[80:81]
	v_pk_add_f32 v[66:67], v[66:67], v[80:81] neg_lo:[0,1] neg_hi:[0,1]
	v_pk_fma_f32 v[80:81], v[84:85], s[54:55], v[0:1] op_sel_hi:[1,0,1] neg_lo:[0,0,1] neg_hi:[0,0,1]
	v_pk_fma_f32 v[0:1], v[84:85], s[82:83], v[0:1] op_sel_hi:[1,0,1] neg_lo:[0,0,1] neg_hi:[0,0,1]
	v_pk_fma_f32 v[134:135], v[58:59], s[82:83], v[56:57] op_sel_hi:[1,0,1] neg_lo:[1,0,0] neg_hi:[1,0,0]
	v_pk_fma_f32 v[56:57], v[58:59], s[82:83], v[56:57] op_sel_hi:[1,0,1]
	v_pk_add_f32 v[74:75], v[74:75], v[92:93] neg_lo:[0,1] neg_hi:[0,1]
	v_pk_add_f32 v[92:93], v[64:65], v[82:83] neg_lo:[0,1] neg_hi:[0,1]
	v_pk_add_f32 v[64:65], v[64:65], v[82:83]
	v_pk_add_f32 v[82:83], v[68:69], v[80:81]
	v_pk_add_f32 v[84:85], v[70:71], v[0:1]
	v_pk_add_f32 v[68:69], v[68:69], v[80:81] neg_lo:[0,1] neg_hi:[0,1]
	v_pk_add_f32 v[0:1], v[70:71], v[0:1] neg_lo:[0,1] neg_hi:[0,1]
	v_pk_mul_f32 v[70:71], v[140:141], s[80:81] op_sel_hi:[1,0]
	v_pk_mul_f32 v[80:81], v[140:141], s[72:73] op_sel_hi:[1,0]
	v_pk_add_f32 v[58:59], v[10:11], v[134:135]
	v_pk_add_f32 v[136:137], v[90:91], v[56:57]
	v_pk_fma_f32 v[70:71], v[96:97], s[72:73], v[70:71] op_sel_hi:[1,0,1] neg_lo:[0,0,1] neg_hi:[0,0,1]
	v_pk_fma_f32 v[80:81], v[96:97], s[80:81], v[80:81] op_sel_hi:[1,0,1]
	v_pk_add_f32 v[58:59], v[58:59], v[70:71]
	v_pk_add_f32 v[70:71], v[136:137], v[80:81]
	v_pk_mul_f32 v[80:81], v[92:93], s[82:83] op_sel_hi:[1,0]
	v_pk_add_f32 v[10:11], v[10:11], v[134:135] neg_lo:[0,1] neg_hi:[0,1]
	v_pk_add_f32 v[56:57], v[90:91], v[56:57] neg_lo:[0,1] neg_hi:[0,1]
	v_pk_add_f32 v[90:91], v[2:3], v[18:19] neg_lo:[0,1] neg_hi:[0,1]
	v_pk_add_f32 v[134:135], v[8:9], v[16:17]
	v_pk_add_f32 v[8:9], v[8:9], v[16:17] neg_lo:[0,1] neg_hi:[0,1]
	v_pk_mul_f32 v[16:17], v[22:23], s[82:83] op_sel_hi:[1,0]
	v_pk_fma_f32 v[92:93], v[138:139], s[82:83], v[80:81] op_sel_hi:[1,0,1] neg_lo:[1,0,0] neg_hi:[1,0,0]
	v_pk_add_f32 v[2:3], v[2:3], v[18:19]
	v_pk_fma_f32 v[18:19], v[20:21], s[54:55], v[16:17] op_sel_hi:[1,0,1] neg_lo:[0,0,1] neg_hi:[0,0,1]
	v_pk_fma_f32 v[16:17], v[20:21], s[82:83], v[16:17] op_sel_hi:[1,0,1] neg_lo:[0,0,1] neg_hi:[0,0,1]
	v_pk_add_f32 v[90:91], v[90:91], v[92:93]
	v_pk_mul_f32 v[92:93], v[84:85], s[72:73] op_sel_hi:[1,0]
	v_pk_mul_f32 v[84:85], v[84:85], s[80:81] op_sel_hi:[1,0]
	v_pk_add_f32 v[22:23], v[6:7], v[16:17]
	v_pk_fma_f32 v[92:93], v[82:83], s[80:81], v[92:93] op_sel_hi:[1,0,1] neg_lo:[0,0,1] neg_hi:[0,0,1]
	v_pk_fma_f32 v[82:83], v[82:83], s[72:73], v[84:85] op_sel_hi:[1,0,1]
	v_pk_mul_f32 v[66:67], v[66:67], s[82:83] op_sel_hi:[1,0]
	v_pk_add_f32 v[22:23], v[22:23], v[82:83]
	v_pk_mul_f32 v[82:83], v[74:75], s[72:73] op_sel_hi:[1,0]
	v_pk_mul_f32 v[74:75], v[74:75], s[80:81] op_sel_hi:[1,0]
	v_pk_fma_f32 v[82:83], v[72:73], s[84:85], v[82:83] op_sel_hi:[1,0,1] neg_lo:[0,0,1] neg_hi:[0,0,1]
	v_pk_fma_f32 v[72:73], v[72:73], s[72:73], v[74:75] op_sel_hi:[1,0,1] neg_lo:[0,0,1] neg_hi:[0,0,1]
	v_pk_add_f32 v[6:7], v[6:7], v[16:17] neg_lo:[0,1] neg_hi:[0,1]
	v_pk_add_f32 v[56:57], v[56:57], v[72:73]
	v_pk_fma_f32 v[72:73], v[64:65], s[54:55], v[66:67] op_sel_hi:[1,0,1] neg_lo:[0,0,1] neg_hi:[0,0,1]
	v_pk_fma_f32 v[64:65], v[64:65], s[82:83], v[66:67] op_sel_hi:[1,0,1] neg_lo:[0,0,1] neg_hi:[0,0,1]
	v_pk_add_f32 v[88:89], v[132:133], v[14:15] neg_lo:[0,1] neg_hi:[0,1]
	v_pk_add_f32 v[8:9], v[8:9], v[64:65]
	v_pk_mul_f32 v[64:65], v[0:1], s[80:81] op_sel_hi:[1,0]
	v_pk_mul_f32 v[0:1], v[0:1], s[72:73] op_sel_hi:[1,0]
	v_pk_add_f32 v[86:87], v[94:95], v[12:13] neg_lo:[0,1] neg_hi:[0,1]
	v_pk_fma_f32 v[0:1], v[68:69], s[80:81], v[0:1] op_sel_hi:[1,0,1] neg_lo:[0,0,1] neg_hi:[0,0,1]
	v_pk_add_f32 v[12:13], v[94:95], v[12:13]
	v_pk_add_f32 v[0:1], v[6:7], v[0:1]
	v_pk_add_f32 v[6:7], v[132:133], v[14:15]
	v_pk_add_f32 v[14:15], v[62:63], v[78:79]
	v_pk_add_f32 v[20:21], v[4:5], v[18:19]
	v_pk_add_f32 v[6:7], v[6:7], v[14:15]
	v_pk_add_f32 v[14:15], v[60:61], v[76:77]
	v_pk_add_f32 v[4:5], v[4:5], v[18:19] neg_lo:[0,1] neg_hi:[0,1]
	v_pk_add_f32 v[16:17], v[60:61], v[76:77] neg_lo:[0,1] neg_hi:[0,1]
	v_pk_add_f32 v[18:19], v[62:63], v[78:79] neg_lo:[0,1] neg_hi:[0,1]
	v_pk_fma_f32 v[80:81], v[138:139], s[82:83], v[80:81] op_sel_hi:[1,0,1]
	v_pk_add_f32 v[2:3], v[2:3], v[72:73]
	v_pk_fma_f32 v[64:65], v[68:69], s[52:53], v[64:65] op_sel_hi:[1,0,1] neg_lo:[0,0,1] neg_hi:[0,0,1]
	v_pk_add_f32 v[12:13], v[12:13], v[14:15]
	v_pk_add_f32 v[80:81], v[134:135], v[80:81]
	v_pk_add_f32 v[20:21], v[20:21], v[92:93]
	v_pk_add_f32 v[18:19], v[86:87], v[18:19] neg_lo:[0,1] neg_hi:[0,1]
	v_pk_add_f32 v[16:17], v[88:89], v[16:17]
	v_pk_add_f32 v[10:11], v[10:11], v[82:83]
	v_pk_add_f32 v[4:5], v[4:5], v[64:65]
	ds_write_b64 v130, v[12:13]
	ds_write_b64 v131, v[6:7]
	ds_write_b64 v130, v[58:59] offset:4352
	ds_write_b64 v131, v[70:71] offset:4352
	ds_write_b64 v130, v[90:91] offset:8704
	ds_write_b64 v131, v[80:81] offset:8704
	ds_write_b64 v130, v[20:21] offset:13056
	ds_write_b64 v131, v[22:23] offset:13056
	ds_write_b64 v130, v[18:19] offset:17408
	ds_write_b64 v131, v[16:17] offset:17408
	ds_write_b64 v130, v[10:11] offset:21760
	ds_write_b64 v131, v[56:57] offset:21760
	ds_write_b64 v130, v[2:3] offset:26112
	ds_write_b64 v131, v[8:9] offset:26112
	ds_write_b64 v130, v[4:5] offset:30464
	ds_write_b64 v131, v[0:1] offset:30464
	s_waitcnt lgkmcnt(0)
	s_barrier
	ds_read_b64 v[64:65], v172
	ds_read_b64 v[66:67], v173
	ds_read_b64 v[60:61], v160 offset:4096
	ds_read_b64 v[62:63], v169
	ds_read_b64 v[56:57], v158 offset:8192
	ds_read_b64 v[58:59], v159
	ds_read_b64 v[0:1], v156 offset:12288
	ds_read_b64 v[2:3], v157
	s_waitcnt lgkmcnt(6)
	v_lshlrev_b32_e32 v5, 16, v113
	v_lshlrev_b32_e32 v4, 16, v128
	v_and_b32_e32 v7, 0xffff0000, v113
	v_fmac_f32_e32 v64, v147, v5
	v_and_b32_e32 v6, 0xffff0000, v128
	v_lshlrev_b32_e32 v9, 16, v112
	v_and_b32_e32 v11, 0xffff0000, v112
	v_fma_f32 v65, v147, v7, v65
	v_mul_f32_e32 v64, v64, v4
	v_lshlrev_b32_e32 v8, 16, v129
	v_and_b32_e32 v10, 0xffff0000, v129
	v_fma_f32 v67, v147, v11, v67
	v_fmac_f32_e32 v66, v147, v9
	v_mul_f32_e32 v65, v65, v6
	v_cvt_pk_bf16_f32 v64, v64, v65
	v_mul_f32_e32 v67, v67, v10
	v_mul_f32_e32 v66, v66, v8
	global_store_dword v[50:51], v64, off
	v_cvt_pk_bf16_f32 v64, v66, v67
	global_store_dword v[54:55], v64, off
	ds_read_b64 v[64:65], v154 offset:16384
	ds_read_b64 v[66:67], v155
	s_waitcnt lgkmcnt(6)
	v_lshlrev_b32_e32 v5, 16, v111
	v_lshlrev_b32_e32 v4, 16, v126
	v_and_b32_e32 v7, 0xffff0000, v111
	v_fmac_f32_e32 v60, v147, v5
	v_and_b32_e32 v6, 0xffff0000, v126
	v_lshlrev_b32_e32 v9, 16, v110
	v_and_b32_e32 v11, 0xffff0000, v110
	v_fma_f32 v61, v147, v7, v61
	v_mul_f32_e32 v60, v60, v4
	v_lshlrev_b32_e32 v8, 16, v127
	v_and_b32_e32 v10, 0xffff0000, v127
	v_fma_f32 v63, v147, v11, v63
	v_fmac_f32_e32 v62, v147, v9
	v_mul_f32_e32 v61, v61, v6
	v_cvt_pk_bf16_f32 v60, v60, v61
	v_mul_f32_e32 v63, v63, v10
	v_mul_f32_e32 v62, v62, v8
	global_store_dword v[50:51], v60, off offset:2048
	v_cvt_pk_bf16_f32 v60, v62, v63
	global_store_dword v[52:53], v60, off
	ds_read_b64 v[60:61], v152 offset:20480
	ds_read_b64 v[62:63], v153
	s_waitcnt lgkmcnt(6)
	v_lshlrev_b32_e32 v5, 16, v109
	v_lshlrev_b32_e32 v4, 16, v123
	v_and_b32_e32 v7, 0xffff0000, v109
	v_fmac_f32_e32 v56, v147, v5
	v_and_b32_e32 v6, 0xffff0000, v123
	v_lshlrev_b32_e32 v9, 16, v108
	v_and_b32_e32 v11, 0xffff0000, v108
	v_fma_f32 v57, v147, v7, v57
	v_mul_f32_e32 v56, v56, v4
	v_lshlrev_b32_e32 v8, 16, v124
	v_and_b32_e32 v10, 0xffff0000, v124
	v_fma_f32 v59, v147, v11, v59
	v_fmac_f32_e32 v58, v147, v9
	v_mul_f32_e32 v57, v57, v6
	v_cvt_pk_bf16_f32 v56, v56, v57
	v_mul_f32_e32 v59, v59, v10
	v_mul_f32_e32 v58, v58, v8
	global_store_dword v[46:47], v56, off
	v_cvt_pk_bf16_f32 v56, v58, v59
	global_store_dword v[48:49], v56, off
	ds_read_b64 v[56:57], v150 offset:24576
	ds_read_b64 v[58:59], v151
	s_waitcnt lgkmcnt(6)
	v_lshlrev_b32_e32 v5, 16, v107
	v_lshlrev_b32_e32 v4, 16, v120
	v_and_b32_e32 v7, 0xffff0000, v107
	v_fmac_f32_e32 v0, v147, v5
	v_and_b32_e32 v6, 0xffff0000, v120
	v_lshlrev_b32_e32 v9, 16, v106
	v_and_b32_e32 v11, 0xffff0000, v106
	v_fma_f32 v1, v147, v7, v1
	v_mul_f32_e32 v0, v0, v4
	v_lshlrev_b32_e32 v8, 16, v125
	v_and_b32_e32 v10, 0xffff0000, v125
	v_fma_f32 v3, v147, v11, v3
	v_fmac_f32_e32 v2, v147, v9
	v_mul_f32_e32 v1, v1, v6
	v_cvt_pk_bf16_f32 v0, v0, v1
	v_mul_f32_e32 v3, v3, v10
	v_mul_f32_e32 v2, v2, v8
	global_store_dword v[38:39], v0, off
	v_cvt_pk_bf16_f32 v0, v2, v3
	global_store_dword v[40:41], v0, off
	ds_read_b64 v[0:1], v148 offset:28672
	ds_read_b64 v[2:3], v149
	s_waitcnt lgkmcnt(6)
	v_lshlrev_b32_e32 v5, 16, v105
	v_lshlrev_b32_e32 v4, 16, v121
	v_and_b32_e32 v7, 0xffff0000, v105
	v_fmac_f32_e32 v64, v147, v5
	v_and_b32_e32 v6, 0xffff0000, v121
	v_lshlrev_b32_e32 v9, 16, v104
	v_and_b32_e32 v11, 0xffff0000, v104
	v_fma_f32 v65, v147, v7, v65
	v_mul_f32_e32 v64, v64, v4
	v_lshlrev_b32_e32 v8, 16, v122
	v_and_b32_e32 v10, 0xffff0000, v122
	v_fma_f32 v67, v147, v11, v67
	v_fmac_f32_e32 v66, v147, v9
	v_mul_f32_e32 v65, v65, v6
	v_cvt_pk_bf16_f32 v64, v64, v65
	v_mul_f32_e32 v67, v67, v10
	v_mul_f32_e32 v66, v66, v8
	global_store_dword v[42:43], v64, off
	v_cvt_pk_bf16_f32 v64, v66, v67
	global_store_dword v[44:45], v64, off
	s_waitcnt lgkmcnt(4)
	v_lshlrev_b32_e32 v5, 16, v103
	v_lshlrev_b32_e32 v4, 16, v118
	v_and_b32_e32 v7, 0xffff0000, v103
	v_fmac_f32_e32 v60, v147, v5
	v_and_b32_e32 v6, 0xffff0000, v118
	v_lshlrev_b32_e32 v9, 16, v102
	v_and_b32_e32 v11, 0xffff0000, v102
	v_fma_f32 v61, v147, v7, v61
	v_mul_f32_e32 v60, v60, v4
	v_lshlrev_b32_e32 v8, 16, v119
	v_and_b32_e32 v10, 0xffff0000, v119
	v_fma_f32 v63, v147, v11, v63
	v_fmac_f32_e32 v62, v147, v9
	v_mul_f32_e32 v61, v61, v6
	v_cvt_pk_bf16_f32 v60, v60, v61
	v_mul_f32_e32 v63, v63, v10
	v_mul_f32_e32 v62, v62, v8
	global_store_dword v[34:35], v60, off
	v_cvt_pk_bf16_f32 v60, v62, v63
	global_store_dword v[36:37], v60, off
	s_waitcnt lgkmcnt(2)
	v_lshlrev_b32_e32 v5, 16, v101
	v_lshlrev_b32_e32 v4, 16, v115
	v_and_b32_e32 v7, 0xffff0000, v101
	v_fmac_f32_e32 v56, v147, v5
	v_and_b32_e32 v6, 0xffff0000, v115
	v_lshlrev_b32_e32 v9, 16, v100
	v_and_b32_e32 v11, 0xffff0000, v100
	v_fma_f32 v57, v147, v7, v57
	v_mul_f32_e32 v56, v56, v4
	v_lshlrev_b32_e32 v8, 16, v116
	v_and_b32_e32 v10, 0xffff0000, v116
	v_fma_f32 v59, v147, v11, v59
	v_fmac_f32_e32 v58, v147, v9
	v_mul_f32_e32 v57, v57, v6
	v_cvt_pk_bf16_f32 v56, v56, v57
	v_mul_f32_e32 v59, v59, v10
	v_mul_f32_e32 v58, v58, v8
	global_store_dword v[30:31], v56, off
	v_cvt_pk_bf16_f32 v56, v58, v59
	global_store_dword v[32:33], v56, off
	s_waitcnt lgkmcnt(0)
	v_lshlrev_b32_e32 v5, 16, v99
	v_lshlrev_b32_e32 v4, 16, v114
	v_and_b32_e32 v7, 0xffff0000, v99
	v_fmac_f32_e32 v0, v147, v5
	v_and_b32_e32 v6, 0xffff0000, v114
	v_lshlrev_b32_e32 v9, 16, v98
	v_and_b32_e32 v11, 0xffff0000, v98
	v_fma_f32 v1, v147, v7, v1
	v_mul_f32_e32 v0, v0, v4
	v_lshlrev_b32_e32 v8, 16, v117
	v_and_b32_e32 v10, 0xffff0000, v117
	v_fma_f32 v3, v147, v11, v3
	v_fmac_f32_e32 v2, v147, v9
	v_mul_f32_e32 v1, v1, v6
	v_cvt_pk_bf16_f32 v0, v0, v1
	v_mul_f32_e32 v3, v3, v10
	v_mul_f32_e32 v2, v2, v8
	global_store_dword v[26:27], v0, off
	v_cvt_pk_bf16_f32 v0, v2, v3
	global_store_dword v[28:29], v0, off
	s_barrier
	s_cbranch_vccz .LBB0_236
	v_readlane_b32 s12, v249, 12
	v_readlane_b32 s18, v249, 18
	s_add_i32 s0, s0, s18
	s_cmpk_gt_i32 s0, 0x3ff
	v_mov_b32_e32 v240, 0x358637bd
	v_bfrev_b32_e32 v248, 0.5
	v_readlane_b32 s13, v249, 13
	v_readlane_b32 s14, v249, 14
	v_readlane_b32 s15, v249, 15
	v_readlane_b32 s16, v249, 16
	v_readlane_b32 s17, v249, 17
	v_readlane_b32 s19, v249, 19
	s_cbranch_scc0 .LBB0_197
